# attention loop unrolled x6: immediate LDS/DMA addressing, countdown event handler for bias classes, one lgkmcnt wait per 2 MFMAs, 7-deep ring, shared out-of-line paths
# speedup vs baseline: 1.0408x; 1.0073x over previous
; __device__ __forceinline__ void attn_unit(LAS unsigned char* lds, const bf16_t* Z, bf16_t* A2, const float* tabg, int seq_base, int S, int h, int qb, float lam) {
;     ...
;     const int qlo = qb * 128 + rg * 32;
;     bf16x8 qf[4];
;     { const bf16_t* qrow = Z + (size_t)(seq_base + qlo + r32) * NZ + h * 128 + m * 64 + 8 * hi;
; #pragma unroll
;       for (int ds = 0; ds < 4; ++ds) qf[ds] = *(const bf16x8*)(qrow + 16 * ds); }
;     const char* kvbase = (const char*)(Z + (size_t)seq_base * NZ + h * 128);
;     unsigned koff[2], voff[2];
; #pragma unroll
;     for (int i = 0; i < 2; ++i) { const int row = (i * 8 + w) * 4 + (lane >> 4), cp = lane & 15;
;         koff[i] = (unsigned)(row * NZ + 512 + ((cp ^ (row & 15)) << 3)) * 2u; voff[i] = (unsigned)(row * NZ + 1024 + ((cp ^ (4 * (row & 3))) << 3)) * 2u; }
;     const unsigned kb_u = (unsigned)(size_t)Kb + (unsigned)w * 1024u, vb_u = (unsigned)(size_t)Vb + (unsigned)w * 1024u;
;     ...
;     ATT_STAGE(0, 0); ATT_STAGE(1, 1);
;     asm volatile("s_waitcnt vmcnt(4) lgkmcnt(0)" ::: "memory"); __builtin_amdgcn_s_barrier(); asm volatile("" ::: "memory");
; #pragma unroll
;     for (int ds = 0; ds < 4; ++ds) asm volatile("" : "+v"(qf[ds]));
;     const float tabL = tab[0], tabR = tab[448];
;     f32x16 O[4];
; #pragma unroll
;     for (int d = 0; d < 4; ++d)
; #pragma unroll
;         for (int r = 0; r < 16; ++r) O[d][r] = 0.f;
;     float mu = 0.f; f32x2 ls2 = {0.f, 0.f};
;     f32x16 cblk; float coff_cur = __builtin_nanf("");
; #pragma unroll
;     for (int r = 0; r < 16; ++r) cblk[r] = 0.f;
;     const int NT = S >> 6;
;     const unsigned kfo = r32 * 256 + ((unsigned)((m * 8 + hi) ^ (r32 & 15)) << 4);
;     const unsigned vj = (i16 >> 2) & 3;
;     const unsigned vfo = (4 * hi + (i16 >> 2)) * 256 + (vj << 6) + 32 * (g4 & 1) + 8 * (i16 & 3);
;     int bc = 0, bn = 2;
.LBB0_292:
	s_or_b64 exec, exec, s[8:9]
	s_waitcnt lgkmcnt(0)
	s_add_u32 s8, s4, 0x7800000
	s_addc_u32 s9, s5, 0
	s_lshl_b32 s10, s26, 11
	s_and_b32 s11, s10, 0x2000
	s_and_b32 s10, s25, 32
	s_ashr_i32 s15, s27, 6
	s_or_b32 s10, s10, s23
	s_and_b32 s17, s15, 3
	s_lshl_b32 s14, s10, 7
	s_lshl_b32 s10, s17, 5
	s_or_b32 s34, s10, s14
	v_and_b32_e32 v148, 31, v68
	s_or_b32 s14, s34, s11
	v_or_b32_e32 v2, s14, v148
	s_ashr_i32 s16, s27, 8
	v_lshlrev_b32_e32 v162, 12, v2
	v_lshl_add_u64 v[2:3], s[8:9], 0, v[162:163]
	s_lshl_b32 s48, s30, 8
	s_lshl_b32 s28, s16, 6
	v_bfe_u32 v159, v68, 5, 1
	v_lshl_add_u64 v[2:3], v[2:3], 0, s[48:49]
	s_ashr_i32 s29, s28, 31
	v_lshl_add_u64 v[2:3], s[28:29], 1, v[2:3]
	v_lshlrev_b32_e32 v162, 4, v159
	v_lshl_add_u64 v[2:3], v[2:3], 0, v[162:163]
	global_load_dwordx4 v[116:119], v[2:3], off
	global_load_dwordx4 v[120:123], v[2:3], off offset:32
	global_load_dwordx4 v[124:127], v[2:3], off offset:64
	global_load_dwordx4 v[128:131], v[2:3], off offset:96
	s_lshl_b32 s11, s11, 12
	s_add_u32 s8, s8, s11
	v_bfe_u32 v4, v68, 4, 2
	s_addc_u32 s9, s9, 0
	s_lshl_b32 s11, s15, 2
	v_or_b32_e32 v5, s11, v4
	v_lshlrev_b32_e32 v35, 5, v4
	v_bitop3_b32 v4, s11, v68, v4 bitop3:0x36
	v_lshlrev_b32_e32 v4, 3, v4
	v_and_b32_e32 v34, 15, v68
	v_lshlrev_b32_e32 v5, 11, v5
	v_and_b32_e32 v4, 0x78, v4
	v_lshlrev_b32_e32 v6, 3, v34
	v_or_b32_e32 v7, v4, v5
	v_lshl_or_b32 v149, v7, 1, v249
	v_bitop3_b32 v7, v5, v35, v6 bitop3:0xf6
	v_add_u32_e32 v5, 0x10000, v5
	v_or_b32_e32 v4, v4, v5
	s_add_u32 s8, s8, s48
	v_lshl_or_b32 v161, v4, 1, v249
	v_bitop3_b32 v4, v5, v35, v6 bitop3:0xf6
	s_addc_u32 s9, s9, 0
	s_lshl_b32 s29, s15, 10
	s_add_i32 s11, 0, 0xc000
	v_lshl_or_b32 v160, v7, 1, v250
	v_lshl_or_b32 v176, v4, 1, v250
	s_add_i32 s28, s29, 0
	s_add_i32 s29, s29, s11
	s_mov_b32 s15, m0
	s_mov_b32 m0, s28
	s_nop 0
	global_load_lds_dwordx4 v149, s[8:9]
	s_mov_b32 m0, s29
	s_nop 0
	global_load_lds_dwordx4 v160, s[8:9]
	s_add_u32 m0, s28, 0x2000
	s_nop 0
	global_load_lds_dwordx4 v161, s[8:9]
	s_add_u32 m0, s29, 0x2000
	s_nop 0
	global_load_lds_dwordx4 v176, s[8:9]
	s_mov_b32 m0, s15
	s_add_u32 s36, s8, 0x40000
	s_addc_u32 s37, s9, 0
	s_add_i32 s15, s28, 0x4000
	s_add_i32 s31, s29, 0x4000
	s_mov_b32 s33, m0
	s_mov_b32 m0, s15
	s_nop 0
	global_load_lds_dwordx4 v149, s[36:37]
	s_mov_b32 m0, s31
	s_nop 0
	global_load_lds_dwordx4 v160, s[36:37]
	s_add_u32 m0, s15, 0x2000
	s_nop 0
	global_load_lds_dwordx4 v161, s[36:37]
	s_add_u32 m0, s31, 0x2000
	s_nop 0
	global_load_lds_dwordx4 v176, s[36:37]
	s_mov_b32 m0, s33
	s_mov_b32 s32, m0
	s_mov_b32 s4, s8
	s_add_u32 s8, s8, 0x40000
	s_addc_u32 s9, s9, 0
	s_add_u32 s42, s8, 0x40000
	s_addc_u32 s43, s9, 0
	s_add_u32 m0, s28, 0x8000
	v_add_u32_e32 v236, 0x80000, v149
	global_load_lds_dwordx4 v149, s[42:43]
	s_add_u32 m0, s28, 0xa000
	v_add_u32_e32 v237, 0x80000, v161
	global_load_lds_dwordx4 v161, s[42:43]
	s_lshl_b32 s15, s30, 7
	s_and_b32 s37, s27, 0x3fffffc0
	s_lshl_b32 s37, s37, 2
	s_add_i32 s30, s37, 0x18000
	v_and_b32_e32 v183, 63, v68
	v_lshl_add_u32 v185, v159, 4, s30
	v_lshl_add_u32 v184, v148, 2, s30
	s_add_i32 s33, s34, 0x9f
	v_add_lshl_u32 v251, s34, v148, 2
	v_lshlrev_b32_e32 v252, 4, v159
	v_sub_u32_e32 v162, v252, v251
	s_add_i32 s34, s34, 0xffffff41
	s_ashr_i32 s11, s34, 6
	s_add_i32 s11, s11, 1
	s_lshl_b32 s11, s11, 6
	s_max_i32 s11, s11, 0
	s_add_i32 s31, s33, 63
	s_andn2_b32 s31, s31, 63
	s_sub_u32 s31, s31, 64
	s_lshr_b32 s10, s11, 6
	s_sub_i32 s10, s10, 2
	s_max_i32 s10, s10, 0
	s_lshl_b32 s37, s16, 3
	v_lshlrev_b32_e32 v19, 8, v148
	v_bitop3_b32 v251, s37, v34, v159 bitop3:0x36
	v_lshlrev_b32_e32 v252, 2, v159
	v_lshrrev_b32_e32 v253, 2, v34
	v_lshlrev_b32_e32 v254, 3, v68
	v_lshl_add_u32 v19, v251, 4, v19
	v_or_b32_e32 v252, v252, v253
	v_and_b32_e32 v254, 24, v254
	v_and_b32_e32 v251, 32, v35
	v_lshlrev_b32_e32 v252, 8, v252
	v_lshl_or_b32 v253, v253, 6, v254
	v_xor_b32_e32 v180, 32, v19
	v_or3_b32 v179, v252, v251, v253
	v_xor_b32_e32 v181, 64, v19
	v_xor_b32_e32 v182, 0x60, v19
	v_add_u32_e32 v228, 0xc000, v179
	v_xor_b32_e32 v229, 0x40, v179
	v_add_u32_e32 v229, 0xc000, v229
	v_xor_b32_e32 v230, 0x80, v179
	v_add_u32_e32 v230, 0xc000, v230
	v_xor_b32_e32 v231, 0xc0, v179
	v_add_u32_e32 v231, 0xc000, v231
	v_mov_b64_e32 v[20:21], 0
	v_mov_b64_e32 v[22:23], 0
	v_mov_b64_e32 v[24:25], 0
	v_mov_b64_e32 v[26:27], 0
	v_mov_b64_e32 v[28:29], 0
	v_mov_b64_e32 v[30:31], 0
	v_mov_b64_e32 v[32:33], 0
	v_mov_b64_e32 v[34:35], 0
	v_mov_b64_e32 v[36:37], 0
	v_mov_b64_e32 v[38:39], 0
	v_mov_b64_e32 v[40:41], 0
	v_mov_b64_e32 v[42:43], 0
	v_mov_b64_e32 v[44:45], 0
	v_mov_b64_e32 v[46:47], 0
	v_mov_b64_e32 v[48:49], 0
	v_mov_b64_e32 v[50:51], 0
	v_mov_b64_e32 v[52:53], 0
	v_mov_b64_e32 v[54:55], 0
	v_mov_b64_e32 v[56:57], 0
	v_mov_b64_e32 v[58:59], 0
	v_mov_b64_e32 v[60:61], 0
	v_mov_b64_e32 v[62:63], 0
	v_mov_b64_e32 v[64:65], 0
	v_mov_b64_e32 v[66:67], 0
	v_mov_b64_e32 v[68:69], 0
	v_mov_b64_e32 v[70:71], 0
	v_mov_b64_e32 v[72:73], 0
	v_mov_b64_e32 v[74:75], 0
	v_mov_b64_e32 v[76:77], 0
	v_mov_b64_e32 v[78:79], 0
	v_mov_b64_e32 v[80:81], 0
	v_mov_b64_e32 v[82:83], 0
	v_mov_b64_e32 v[150:151], 0
	v_mov_b32_e32 v186, 0
	s_waitcnt vmcnt(6) lgkmcnt(0)
	s_barrier
; __device__ __forceinline__ void attn_unit(LAS unsigned char* lds, const bf16_t* Z, bf16_t* A2, const float* tabg, int seq_base, int S, int h, int qb, float lam) {
;     ...
;         bool near = true; float cc = 0.f;
;         if (kv0 - (qlo + 31) >= 128) { near = false; cc = tabR; } else if (qlo - (kv0 + 63) >= 128) { near = false; cc = tabL; }
;         { const float coff = cc - mu;
;           if (__any(!(coff == coff_cur))) { coff_cur = coff;
; #pragma unroll
;               for (int r = 0; r < 16; ++r) cblk[r] = coff;
;               asm volatile("" : "+v"(cblk)); } }
;         f32x16 p0, p1;
;         {
;             bf16x8 kf[8];
; #pragma unroll
;             for (int ds = 0; ds < 4; ++ds) { kf[2 * ds] = *(const LAS bf16x8*)(Kt + (kfo ^ (unsigned)(ds << 5))); kf[2 * ds + 1] = *(const LAS bf16x8*)(Kt + 32 * 256 + (kfo ^ (unsigned)(ds << 5))); }
;             __builtin_amdgcn_sched_barrier(0);
;             p0 = __builtin_amdgcn_mfma_f32_32x32x16_bf16(kf[0], qf[0], cblk, 0, 0, 0);
;             p1 = __builtin_amdgcn_mfma_f32_32x32x16_bf16(kf[1], qf[0], cblk, 0, 0, 0);
; #pragma unroll
;             for (int ds = 1; ds < 4; ++ds) {
;                 p0 = __builtin_amdgcn_mfma_f32_32x32x16_bf16(kf[2 * ds], qf[ds], p0, 0, 0, 0);
;                 p1 = __builtin_amdgcn_mfma_f32_32x32x16_bf16(kf[2 * ds + 1], qf[ds], p1, 0, 0, 0);
;             }
;         }
;     ...
;         const unsigned vbase = (unsigned)(size_t)Vt + vfo;
;         s16x4 va[8], vb[8];
;         VREADS1(va, 0);
;         if (near) {
;             const LAS float* tp = tab + (kv0 + 4 * hi - (qlo + r32) + 224);
; #pragma unroll
;             for (int r = 0; r < 16; ++r) { p0[r] += tp[(r & 3) + 8 * (r >> 2)]; p1[r] += tp[32 + (r & 3) + 8 * (r >> 2)]; }
;         }
;         float mx = max2f(max16f(p0), max16f(p1));
;         const bool first = (t == 0);
;         if (first || __any(mx > THR)) {
;             { auto rr = __builtin_amdgcn_permlane32_swap(__float_as_uint(mx), __float_as_uint(mx), false, false); mx = max2f(__uint_as_float(rr[0]), __uint_as_float(rr[1])); }
;             const float delta = first ? mx : fmaxf(mx, 0.f);
;             const float alpha = first ? 1.0f : __builtin_amdgcn_exp2f(-delta);
;             mu += delta; ls2 *= alpha;
;             if (!first) {
;                 asm volatile("" ::: "memory");
;                 scr[r32] = alpha;
	v_mov_b32_e32 v187, 0x18800
	ds_read_b32 v177, v187
	ds_read_b32 v178, v187 offset:1792
	ds_read_b128 v[132:135], v19
	ds_read_b128 v[136:139], v19 offset:8192
	ds_read_b128 v[140:143], v180
	ds_read_b128 v[144:147], v180 offset:8192
	ds_read_b128 v[220:223], v181
	ds_read_b128 v[224:227], v181 offset:8192
	ds_read_b128 v[232:235], v182
	ds_read_b128 v[80:83], v182 offset:8192
	s_waitcnt lgkmcnt(8)
	s_cmp_eq_u32 s11, 0
	s_cselect_b32 s37, 0, 1
	s_mov_b32 s35, s37
	v_mov_b32_e32 v251, 0
	s_cmp_eq_u32 s37, 1
	s_cselect_b64 vcc, -1, 0
	v_cndmask_b32_e32 v251, v251, v177, vcc
	s_cmp_eq_u32 s37, 2
	s_cselect_b64 vcc, -1, 0
	v_cndmask_b32_e32 v251, v251, v178, vcc
	v_sub_f32_e32 v2, v251, v186
	v_mov_b32_e32 v3, v2
	v_mov_b64_e32 v[4:5], v[2:3]
	v_mov_b64_e32 v[6:7], v[2:3]
	v_mov_b64_e32 v[8:9], v[2:3]
	v_mov_b64_e32 v[10:11], v[2:3]
	v_mov_b64_e32 v[12:13], v[2:3]
	v_mov_b64_e32 v[14:15], v[2:3]
	v_mov_b64_e32 v[16:17], v[2:3]
	s_waitcnt lgkmcnt(7)
	v_mfma_f32_32x32x16_bf16 v[84:99], v[132:135], v[116:119], v[2:17]
	s_waitcnt lgkmcnt(6)
	v_mfma_f32_32x32x16_bf16 v[100:115], v[136:139], v[116:119], v[2:17]
	s_waitcnt lgkmcnt(5)
	v_mfma_f32_32x32x16_bf16 v[84:99], v[140:143], v[120:123], v[84:99]
	s_waitcnt lgkmcnt(4)
	v_mfma_f32_32x32x16_bf16 v[100:115], v[144:147], v[120:123], v[100:115]
	s_waitcnt lgkmcnt(3)
	v_mfma_f32_32x32x16_bf16 v[84:99], v[220:223], v[124:127], v[84:99]
	s_waitcnt lgkmcnt(2)
	v_mfma_f32_32x32x16_bf16 v[100:115], v[224:227], v[124:127], v[100:115]
	s_waitcnt lgkmcnt(1)
	v_mfma_f32_32x32x16_bf16 v[84:99], v[232:235], v[128:131], v[84:99]
	s_waitcnt lgkmcnt(0)
	v_mfma_f32_32x32x16_bf16 v[100:115], v[80:83], v[128:131], v[100:115]
	s_nop 15
	s_nop 15
	v_mov_b64_e32 v[80:81], 0
	v_mov_b64_e32 v[82:83], 0
	s_mov_b32 s5, 0
	s_cmp_lg_u32 s11, 0
	s_cbranch_scc1 .LatA_p0_nonear
	s_lshl_b32 s38, s5, 2
	s_add_i32 s38, s38, 0x18b80
	v_add_u32_e32 v187, s38, v162
	ds_read2_b32 v[132:133], v187 offset0:0 offset1:1
	ds_read2_b32 v[134:135], v187 offset0:2 offset1:3
	ds_read2_b32 v[136:137], v187 offset0:8 offset1:9
	ds_read2_b32 v[138:139], v187 offset0:10 offset1:11
	s_waitcnt lgkmcnt(0)
	v_pk_add_f32 v[84:85], v[84:85], v[132:133]
	v_pk_add_f32 v[86:87], v[86:87], v[134:135]
	v_pk_add_f32 v[88:89], v[88:89], v[136:137]
	v_pk_add_f32 v[90:91], v[90:91], v[138:139]
	ds_read2_b32 v[132:133], v187 offset0:16 offset1:17
	ds_read2_b32 v[134:135], v187 offset0:18 offset1:19
	ds_read2_b32 v[136:137], v187 offset0:24 offset1:25
	ds_read2_b32 v[138:139], v187 offset0:26 offset1:27
	s_waitcnt lgkmcnt(0)
	v_pk_add_f32 v[92:93], v[92:93], v[132:133]
	v_pk_add_f32 v[94:95], v[94:95], v[134:135]
	v_pk_add_f32 v[96:97], v[96:97], v[136:137]
	v_pk_add_f32 v[98:99], v[98:99], v[138:139]
	ds_read2_b32 v[132:133], v187 offset0:32 offset1:33
	ds_read2_b32 v[134:135], v187 offset0:34 offset1:35
	ds_read2_b32 v[136:137], v187 offset0:40 offset1:41
	ds_read2_b32 v[138:139], v187 offset0:42 offset1:43
	s_waitcnt lgkmcnt(0)
	v_pk_add_f32 v[100:101], v[100:101], v[132:133]
	v_pk_add_f32 v[102:103], v[102:103], v[134:135]
	v_pk_add_f32 v[104:105], v[104:105], v[136:137]
	v_pk_add_f32 v[106:107], v[106:107], v[138:139]
	ds_read2_b32 v[132:133], v187 offset0:48 offset1:49
	ds_read2_b32 v[134:135], v187 offset0:50 offset1:51
	ds_read2_b32 v[136:137], v187 offset0:56 offset1:57
	ds_read2_b32 v[138:139], v187 offset0:58 offset1:59
	s_waitcnt lgkmcnt(0)
	v_pk_add_f32 v[108:109], v[108:109], v[132:133]
	v_pk_add_f32 v[110:111], v[110:111], v[134:135]
	v_pk_add_f32 v[112:113], v[112:113], v[136:137]
	v_pk_add_f32 v[114:115], v[114:115], v[138:139]
.LatA_p0_nonear:
	v_max3_f32 v251, v84, v85, v86
	v_max3_f32 v252, v87, v88, v89
	v_max3_f32 v251, v251, v90, v91
	v_max3_f32 v252, v252, v92, v93
	v_max3_f32 v251, v251, v94, v95
	v_max3_f32 v252, v252, v96, v97
	v_max3_f32 v251, v251, v98, v99
	v_max3_f32 v252, v252, v100, v101
	v_max3_f32 v251, v251, v102, v103
	v_max3_f32 v252, v252, v104, v105
	v_max3_f32 v251, v251, v106, v107
	v_max3_f32 v252, v252, v108, v109
	v_max3_f32 v251, v251, v110, v111
	v_max3_f32 v252, v252, v112, v113
	v_max3_f32 v251, v251, v114, v115
	v_max_f32_e32 v251, v251, v252
	v_mov_b32_e32 v252, v251
	s_nop 1
	v_permlane32_swap_b32_e32 v251, v252
	v_max_f32_e32 v186, v251, v252
	v_sub_f32_e32 v84, v84, v186
	v_sub_f32_e32 v85, v85, v186
	v_sub_f32_e32 v86, v86, v186
	v_sub_f32_e32 v87, v87, v186
	v_sub_f32_e32 v88, v88, v186
	v_sub_f32_e32 v89, v89, v186
	v_sub_f32_e32 v90, v90, v186
	v_sub_f32_e32 v91, v91, v186
	v_sub_f32_e32 v92, v92, v186
	v_sub_f32_e32 v93, v93, v186
	v_sub_f32_e32 v94, v94, v186
	v_sub_f32_e32 v95, v95, v186
	v_sub_f32_e32 v96, v96, v186
	v_sub_f32_e32 v97, v97, v186
	v_sub_f32_e32 v98, v98, v186
	v_sub_f32_e32 v99, v99, v186
	v_sub_f32_e32 v100, v100, v186
	v_sub_f32_e32 v101, v101, v186
	v_sub_f32_e32 v102, v102, v186
	v_sub_f32_e32 v103, v103, v186
	v_sub_f32_e32 v104, v104, v186
	v_sub_f32_e32 v105, v105, v186
	v_sub_f32_e32 v106, v106, v186
	v_sub_f32_e32 v107, v107, v186
	v_sub_f32_e32 v108, v108, v186
	v_sub_f32_e32 v109, v109, v186
	v_sub_f32_e32 v110, v110, v186
	v_sub_f32_e32 v111, v111, v186
	v_sub_f32_e32 v112, v112, v186
	v_sub_f32_e32 v113, v113, v186
	v_sub_f32_e32 v114, v114, v186
	v_sub_f32_e32 v115, v115, v186
	s_add_u32 s38, s5, 64
	s_cmp_lt_u32 s38, s11
	s_cselect_b32 s37, 1, 0
	s_cmp_gt_u32 s38, s31
	s_cselect_b32 s40, 2, 0
	s_or_b32 s37, s37, s40
	s_mov_b32 s35, s37
	v_mov_b32_e32 v251, 0
	s_cmp_eq_u32 s37, 1
	s_cselect_b64 vcc, -1, 0
	v_cndmask_b32_e32 v251, v251, v177, vcc
	s_cmp_eq_u32 s37, 2
	s_cselect_b64 vcc, -1, 0
	v_cndmask_b32_e32 v251, v251, v178, vcc
	v_sub_f32_e32 v2, v251, v186
	v_mov_b32_e32 v3, v2
	v_mov_b64_e32 v[4:5], v[2:3]
	v_mov_b64_e32 v[6:7], v[2:3]
	v_mov_b64_e32 v[8:9], v[2:3]
	v_mov_b64_e32 v[10:11], v[2:3]
	v_mov_b64_e32 v[12:13], v[2:3]
	v_mov_b64_e32 v[14:15], v[2:3]
	v_mov_b64_e32 v[16:17], v[2:3]
	s_waitcnt vmcnt(0)
	s_barrier
	ds_read_b128 v[132:135], v19 offset:16384
	ds_read_b128 v[136:139], v19 offset:24576
	ds_read_b128 v[140:143], v180 offset:16384
	ds_read_b128 v[144:147], v180 offset:24576
	ds_read_b128 v[220:223], v181 offset:16384
	ds_read_b128 v[224:227], v181 offset:24576
	ds_read_b128 v[232:235], v182 offset:16384
	v_max3_f32 v251, v84, v85, v86
	v_max3_f32 v252, v87, v88, v89
	v_max3_f32 v251, v251, v90, v91
	v_max3_f32 v252, v252, v92, v93
	v_max3_f32 v251, v251, v94, v95
	v_max3_f32 v252, v252, v96, v97
	v_max3_f32 v251, v251, v98, v99
	v_max3_f32 v252, v252, v100, v101
	v_max3_f32 v251, v251, v102, v103
	v_max3_f32 v252, v252, v104, v105
	v_max3_f32 v251, v251, v106, v107
	v_max3_f32 v252, v252, v108, v109
	v_max3_f32 v251, v251, v110, v111
	v_max3_f32 v252, v252, v112, v113
	v_max3_f32 v251, v251, v114, v115
	v_max_f32_e32 v251, v251, v252
	v_cmp_lt_f32_e32 vcc, 0x41000000, v251
	s_cbranch_vccnz .LatA_rs_h0
; __device__ __forceinline__ void attn_unit(LAS unsigned char* lds, const bf16_t* Z, bf16_t* A2, const float* tabg, int seq_base, int S, int h, int qb, float lam) {
;     ...
;         f32x16 p0, p1;
;         {
;             bf16x8 kf[8];
; #pragma unroll
;             for (int ds = 0; ds < 4; ++ds) { kf[2 * ds] = *(const LAS bf16x8*)(Kt + (kfo ^ (unsigned)(ds << 5))); kf[2 * ds + 1] = *(const LAS bf16x8*)(Kt + 32 * 256 + (kfo ^ (unsigned)(ds << 5))); }
;             __builtin_amdgcn_sched_barrier(0);
;             p0 = __builtin_amdgcn_mfma_f32_32x32x16_bf16(kf[0], qf[0], cblk, 0, 0, 0);
;             p1 = __builtin_amdgcn_mfma_f32_32x32x16_bf16(kf[1], qf[0], cblk, 0, 0, 0);
; #pragma unroll
;             for (int ds = 1; ds < 4; ++ds) {
;                 p0 = __builtin_amdgcn_mfma_f32_32x32x16_bf16(kf[2 * ds], qf[ds], p0, 0, 0, 0);
;                 p1 = __builtin_amdgcn_mfma_f32_32x32x16_bf16(kf[2 * ds + 1], qf[ds], p1, 0, 0, 0);
;             }
;         }
;     ...
;         const unsigned vbase = (unsigned)(size_t)Vt + vfo;
;         s16x4 va[8], vb[8];
;         VREADS1(va, 0);
;         if (near) {
;             const LAS float* tp = tab + (kv0 + 4 * hi - (qlo + r32) + 224);
; #pragma unroll
;             for (int r = 0; r < 16; ++r) { p0[r] += tp[(r & 3) + 8 * (r >> 2)]; p1[r] += tp[32 + (r & 3) + 8 * (r >> 2)]; }
;         }
;         float mx = max2f(max16f(p0), max16f(p1));
;         const bool first = (t == 0);
;         if (first || __any(mx > THR)) {
;             { auto rr = __builtin_amdgcn_permlane32_swap(__float_as_uint(mx), __float_as_uint(mx), false, false); mx = max2f(__uint_as_float(rr[0]), __uint_as_float(rr[1])); }
;             const float delta = first ? mx : fmaxf(mx, 0.f);
;             const float alpha = first ? 1.0f : __builtin_amdgcn_exp2f(-delta);
;             mu += delta; ls2 *= alpha;
;             if (!first) {
;                 asm volatile("" ::: "memory");
;                 scr[r32] = alpha;
;                 asm volatile("s_waitcnt lgkmcnt(0)" ::: "memory");
; #pragma unroll
;                 for (int g = 0; g < 4; ++g) { const f32x4 a4 = *(const LAS f32x4*)(scr + 8 * g + 4 * hi);
; #pragma unroll
;                     for (int d = 0; d < 4; ++d) { O[d][4 * g + 0] *= a4[0]; O[d][4 * g + 1] *= a4[1]; O[d][4 * g + 2] *= a4[2]; O[d][4 * g + 3] *= a4[3]; } }
;                 asm volatile("s_waitcnt lgkmcnt(0)" ::: "memory");
.LatA_rareret_h0:
	s_waitcnt lgkmcnt(5)
	v_mfma_f32_32x32x16_bf16 v[188:203], v[132:135], v[116:119], v[2:17]
	ds_read_b128 v[132:135], v182 offset:24576
	v_exp_f32_e32 v84, v84
	v_exp_f32_e32 v85, v85
	v_exp_f32_e32 v86, v86
	v_exp_f32_e32 v87, v87
	v_pk_add_f32 v[150:151], v[150:151], v[84:85]
	v_pk_add_f32 v[150:151], v[150:151], v[86:87]
	v_exp_f32_e32 v88, v88
	s_mov_b32 m0, s28
	v_mfma_f32_32x32x16_bf16 v[204:219], v[136:139], v[116:119], v[2:17]
	global_load_lds_dwordx4 v236, s[8:9]
	v_exp_f32_e32 v89, v89
	v_cvt_pk_bf16_f32 v84, v84, v85
	v_cvt_pk_bf16_f32 v85, v86, v87
	v_exp_f32_e32 v90, v90
	v_exp_f32_e32 v91, v91
	v_pk_add_f32 v[150:151], v[150:151], v[88:89]
	v_pk_add_f32 v[150:151], v[150:151], v[90:91]
	v_cvt_pk_bf16_f32 v86, v88, v89
	v_cvt_pk_bf16_f32 v87, v90, v91
	s_waitcnt lgkmcnt(4)
	v_mfma_f32_32x32x16_bf16 v[188:203], v[140:143], v[120:123], v[188:203]
	v_exp_f32_e32 v92, v92
	v_exp_f32_e32 v93, v93
	v_exp_f32_e32 v94, v94
	v_exp_f32_e32 v95, v95
	v_pk_add_f32 v[150:151], v[150:151], v[92:93]
	v_pk_add_f32 v[150:151], v[150:151], v[94:95]
	v_exp_f32_e32 v96, v96
	s_add_u32 m0, s28, 0x2000
	v_mfma_f32_32x32x16_bf16 v[204:219], v[144:147], v[120:123], v[204:219]
	global_load_lds_dwordx4 v237, s[8:9]
	v_exp_f32_e32 v97, v97
	v_cvt_pk_bf16_f32 v88, v92, v93
	v_cvt_pk_bf16_f32 v89, v94, v95
	v_exp_f32_e32 v98, v98
	v_exp_f32_e32 v99, v99
	v_pk_add_f32 v[150:151], v[150:151], v[96:97]
	v_pk_add_f32 v[150:151], v[150:151], v[98:99]
	v_cvt_pk_bf16_f32 v90, v96, v97
	v_cvt_pk_bf16_f32 v91, v98, v99
	s_waitcnt lgkmcnt(2)
	v_mfma_f32_32x32x16_bf16 v[188:203], v[220:223], v[124:127], v[188:203]
	v_exp_f32_e32 v100, v100
	v_exp_f32_e32 v101, v101
	v_exp_f32_e32 v102, v102
	v_exp_f32_e32 v103, v103
	v_pk_add_f32 v[150:151], v[150:151], v[100:101]
	v_pk_add_f32 v[150:151], v[150:151], v[102:103]
	v_exp_f32_e32 v104, v104
	v_mfma_f32_32x32x16_bf16 v[204:219], v[224:227], v[124:127], v[204:219]
	v_exp_f32_e32 v105, v105
	v_cvt_pk_bf16_f32 v100, v100, v101
	v_cvt_pk_bf16_f32 v101, v102, v103
	v_exp_f32_e32 v106, v106
	v_exp_f32_e32 v107, v107
	v_pk_add_f32 v[150:151], v[150:151], v[104:105]
	v_pk_add_f32 v[150:151], v[150:151], v[106:107]
	v_cvt_pk_bf16_f32 v102, v104, v105
	v_cvt_pk_bf16_f32 v103, v106, v107
	s_waitcnt lgkmcnt(0)
	v_mfma_f32_32x32x16_bf16 v[188:203], v[232:235], v[128:131], v[188:203]
	v_exp_f32_e32 v108, v108
	v_exp_f32_e32 v109, v109
	v_exp_f32_e32 v110, v110
	v_exp_f32_e32 v111, v111
	v_pk_add_f32 v[150:151], v[150:151], v[108:109]
	v_pk_add_f32 v[150:151], v[150:151], v[110:111]
	v_exp_f32_e32 v112, v112
	v_mfma_f32_32x32x16_bf16 v[204:219], v[132:135], v[128:131], v[204:219]
	v_exp_f32_e32 v113, v113
	v_cvt_pk_bf16_f32 v104, v108, v109
	v_cvt_pk_bf16_f32 v105, v110, v111
	v_exp_f32_e32 v114, v114
	v_exp_f32_e32 v115, v115
	v_pk_add_f32 v[150:151], v[150:151], v[112:113]
	v_pk_add_f32 v[150:151], v[150:151], v[114:115]
	v_cvt_pk_bf16_f32 v106, v112, v113
	v_cvt_pk_bf16_f32 v107, v114, v115
	s_add_u32 s8, s8, 0x40000
	s_addc_u32 s9, s9, 0
	s_waitcnt vmcnt(2) lgkmcnt(0)
	s_barrier
	s_sub_u32 s10, s10, 1
	s_cbranch_scc1 .LatA_evs_h1
.LatA_evret_h1:
	ds_read_b64_tr_b16 v[132:133], v228 offset:0
	ds_read_b64_tr_b16 v[134:135], v228 offset:2048
	ds_read_b64_tr_b16 v[136:137], v229 offset:0
	ds_read_b64_tr_b16 v[138:139], v229 offset:2048
	ds_read_b64_tr_b16 v[140:141], v230 offset:0
	ds_read_b64_tr_b16 v[142:143], v230 offset:2048
	ds_read_b64_tr_b16 v[144:145], v231 offset:0
	ds_read_b64_tr_b16 v[146:147], v231 offset:2048
	ds_read_b64_tr_b16 v[220:221], v228 offset:4096
	ds_read_b64_tr_b16 v[222:223], v228 offset:6144
	ds_read_b64_tr_b16 v[224:225], v229 offset:4096
	ds_read_b64_tr_b16 v[226:227], v229 offset:6144
	ds_read_b64_tr_b16 v[232:233], v230 offset:4096
	ds_read_b64_tr_b16 v[234:235], v230 offset:6144
	v_max3_f32 v251, v188, v189, v190
	v_max3_f32 v252, v191, v192, v193
	v_max3_f32 v251, v251, v194, v195
	v_max3_f32 v252, v252, v196, v197
	v_max3_f32 v251, v251, v198, v199
	v_max3_f32 v252, v252, v200, v201
	v_max3_f32 v251, v251, v202, v203
	v_max3_f32 v252, v252, v204, v205
	v_max3_f32 v251, v251, v206, v207
	v_max3_f32 v252, v252, v208, v209
	v_max3_f32 v251, v251, v210, v211
	v_max3_f32 v252, v252, v212, v213
	v_max3_f32 v251, v251, v214, v215
	v_max3_f32 v252, v252, v216, v217
	v_max3_f32 v251, v251, v218, v219
	v_max_f32_e32 v251, v251, v252
	v_cmp_lt_f32_e32 vcc, 0x41000000, v251
	s_cbranch_vccnz .LatA_rs_h1
; #define LAS __attribute__((address_space(3)))
; __device__ __forceinline__ void attn_unit(LAS unsigned char* lds, const bf16_t* Z, bf16_t* A2, const float* tabg, int seq_base, int S, int h, int qb, float lam) {
;     ...
;             for (int ds = 0; ds < 4; ++ds) { kf[2 * ds] = *(const LAS bf16x8*)(Kt + (kfo ^ (unsigned)(ds << 5))); kf[2 * ds + 1] = *(const LAS bf16x8*)(Kt + 32 * 256 + (kfo ^ (unsigned)(ds << 5))); }
;             __builtin_amdgcn_sched_barrier(0);
;             p0 = __builtin_amdgcn_mfma_f32_32x32x16_bf16(kf[0], qf[0], cblk, 0, 0, 0);
;             p1 = __builtin_amdgcn_mfma_f32_32x32x16_bf16(kf[1], qf[0], cblk, 0, 0, 0);
; #pragma unroll
;             for (int ds = 1; ds < 4; ++ds) {
;                 p0 = __builtin_amdgcn_mfma_f32_32x32x16_bf16(kf[2 * ds], qf[ds], p0, 0, 0, 0);
;                 p1 = __builtin_amdgcn_mfma_f32_32x32x16_bf16(kf[2 * ds + 1], qf[ds], p1, 0, 0, 0);
;             }
;         }
;     ...
;         const unsigned vbase = (unsigned)(size_t)Vt + vfo;
;         s16x4 va[8], vb[8];
;         VREADS1(va, 0);
;         if (near) {
;             const LAS float* tp = tab + (kv0 + 4 * hi - (qlo + r32) + 224);
; #pragma unroll
;             for (int r = 0; r < 16; ++r) { p0[r] += tp[(r & 3) + 8 * (r >> 2)]; p1[r] += tp[32 + (r & 3) + 8 * (r >> 2)]; }
;         }
;         float mx = max2f(max16f(p0), max16f(p1));
;         const bool first = (t == 0);
;         if (first || __any(mx > THR)) {
;             { auto rr = __builtin_amdgcn_permlane32_swap(__float_as_uint(mx), __float_as_uint(mx), false, false); mx = max2f(__uint_as_float(rr[0]), __uint_as_float(rr[1])); }
;             const float delta = first ? mx : fmaxf(mx, 0.f);
;             const float alpha = first ? 1.0f : __builtin_amdgcn_exp2f(-delta);
;             mu += delta; ls2 *= alpha;
;             if (!first) {
;                 asm volatile("" ::: "memory");
;                 scr[r32] = alpha;
;                 asm volatile("s_waitcnt lgkmcnt(0)" ::: "memory");
; #pragma unroll
;                 for (int g = 0; g < 4; ++g) { const f32x4 a4 = *(const LAS f32x4*)(scr + 8 * g + 4 * hi);
; #pragma unroll
;                     for (int d = 0; d < 4; ++d) { O[d][4 * g + 0] *= a4[0]; O[d][4 * g + 1] *= a4[1]; O[d][4 * g + 2] *= a4[2]; O[d][4 * g + 3] *= a4[3]; } }
;                 asm volatile("s_waitcnt lgkmcnt(0)" ::: "memory");
;             }
; #pragma unroll
.LatA_rareret_h1:
	s_waitcnt lgkmcnt(10)
	v_mfma_f32_32x32x16_bf16 v[20:35], v[84:87], v[132:135], v[20:35]
	ds_read_b64_tr_b16 v[132:133], v231 offset:4096
	ds_read_b64_tr_b16 v[134:135], v231 offset:6144
	v_exp_f32_e32 v188, v188
	v_exp_f32_e32 v189, v189
	v_mfma_f32_32x32x16_bf16 v[36:51], v[84:87], v[136:139], v[36:51]
	ds_read_b64_tr_b16 v[136:137], v228 offset:8192
	ds_read_b64_tr_b16 v[138:139], v228 offset:10240
	v_exp_f32_e32 v190, v190
	v_exp_f32_e32 v191, v191
	s_waitcnt lgkmcnt(10)
	v_mfma_f32_32x32x16_bf16 v[52:67], v[84:87], v[140:143], v[52:67]
	ds_read_b64_tr_b16 v[140:141], v229 offset:8192
	ds_read_b64_tr_b16 v[142:143], v229 offset:10240
	v_pk_add_f32 v[150:151], v[150:151], v[188:189]
	v_pk_add_f32 v[150:151], v[150:151], v[190:191]
	v_exp_f32_e32 v192, v192
	s_add_u32 m0, s28, 0x4000
	v_mfma_f32_32x32x16_bf16 v[68:83], v[84:87], v[144:147], v[68:83]
	global_load_lds_dwordx4 v236, s[8:9]
	ds_read_b64_tr_b16 v[144:145], v230 offset:8192
	ds_read_b64_tr_b16 v[146:147], v230 offset:10240
	v_exp_f32_e32 v193, v193
	v_cvt_pk_bf16_f32 v188, v188, v189
	v_cvt_pk_bf16_f32 v189, v190, v191
	s_waitcnt lgkmcnt(10)
	v_mfma_f32_32x32x16_bf16 v[20:35], v[88:91], v[220:223], v[20:35]
	ds_read_b64_tr_b16 v[220:221], v231 offset:8192
	ds_read_b64_tr_b16 v[222:223], v231 offset:10240
	v_exp_f32_e32 v194, v194
	v_exp_f32_e32 v195, v195
	v_mfma_f32_32x32x16_bf16 v[36:51], v[88:91], v[224:227], v[36:51]
	ds_read_b64_tr_b16 v[224:225], v228 offset:12288
	ds_read_b64_tr_b16 v[226:227], v228 offset:14336
	v_pk_add_f32 v[150:151], v[150:151], v[192:193]
	v_pk_add_f32 v[150:151], v[150:151], v[194:195]
	v_cvt_pk_bf16_f32 v190, v192, v193
	v_cvt_pk_bf16_f32 v191, v194, v195
	s_waitcnt lgkmcnt(10)
	v_mfma_f32_32x32x16_bf16 v[52:67], v[88:91], v[232:235], v[52:67]
	ds_read_b64_tr_b16 v[232:233], v229 offset:12288
	ds_read_b64_tr_b16 v[234:235], v229 offset:14336
	v_exp_f32_e32 v196, v196
	v_exp_f32_e32 v197, v197
	s_add_u32 m0, s29, 0x8000
	v_mfma_f32_32x32x16_bf16 v[68:83], v[88:91], v[132:135], v[68:83]
	global_load_lds_dwordx4 v160, s[8:9]
	ds_read_b64_tr_b16 v[132:133], v230 offset:12288
	ds_read_b64_tr_b16 v[134:135], v230 offset:14336
	v_exp_f32_e32 v198, v198
	v_exp_f32_e32 v199, v199
	s_waitcnt lgkmcnt(10)
	v_mfma_f32_32x32x16_bf16 v[20:35], v[100:103], v[136:139], v[20:35]
	ds_read_b64_tr_b16 v[136:137], v231 offset:12288
	ds_read_b64_tr_b16 v[138:139], v231 offset:14336
	v_pk_add_f32 v[150:151], v[150:151], v[196:197]
	v_pk_add_f32 v[150:151], v[150:151], v[198:199]
	v_exp_f32_e32 v200, v200
	v_mfma_f32_32x32x16_bf16 v[36:51], v[100:103], v[140:143], v[36:51]
	ds_read_b128 v[140:143], v19 offset:32768
	v_exp_f32_e32 v201, v201
	v_cvt_pk_bf16_f32 v192, v196, v197
	v_cvt_pk_bf16_f32 v193, v198, v199
	s_waitcnt lgkmcnt(9)
	v_mfma_f32_32x32x16_bf16 v[52:67], v[100:103], v[144:147], v[52:67]
	ds_read_b128 v[144:147], v19 offset:40960
	v_exp_f32_e32 v202, v202
	v_exp_f32_e32 v203, v203
	s_add_u32 m0, s28, 0x6000
	v_mfma_f32_32x32x16_bf16 v[68:83], v[100:103], v[220:223], v[68:83]
	global_load_lds_dwordx4 v237, s[8:9]
	ds_read_b128 v[220:223], v180 offset:32768
	v_pk_add_f32 v[150:151], v[150:151], v[200:201]
	v_pk_add_f32 v[150:151], v[150:151], v[202:203]
	v_cvt_pk_bf16_f32 v194, v200, v201
	v_cvt_pk_bf16_f32 v195, v202, v203
	s_waitcnt lgkmcnt(7)
	v_mfma_f32_32x32x16_bf16 v[20:35], v[104:107], v[224:227], v[20:35]
	ds_read_b128 v[224:227], v180 offset:40960
	v_exp_f32_e32 v204, v204
	v_exp_f32_e32 v205, v205
	v_mfma_f32_32x32x16_bf16 v[36:51], v[104:107], v[232:235], v[36:51]
	ds_read_b128 v[232:235], v181 offset:32768
	v_exp_f32_e32 v206, v206
	v_exp_f32_e32 v207, v207
	s_waitcnt lgkmcnt(5)
	v_mfma_f32_32x32x16_bf16 v[52:67], v[104:107], v[132:135], v[52:67]
	ds_read_b128 v[132:135], v181 offset:40960
	v_pk_add_f32 v[150:151], v[150:151], v[204:205]
	v_pk_add_f32 v[150:151], v[150:151], v[206:207]
	v_exp_f32_e32 v208, v208
	s_add_u32 m0, s29, 0xa000
	v_mfma_f32_32x32x16_bf16 v[68:83], v[104:107], v[136:139], v[68:83]
	global_load_lds_dwordx4 v176, s[8:9]
	ds_read_b128 v[136:139], v182 offset:32768
	v_exp_f32_e32 v209, v209
	v_cvt_pk_bf16_f32 v204, v204, v205
	v_cvt_pk_bf16_f32 v205, v206, v207
	s_waitcnt lgkmcnt(5)
	v_mfma_f32_32x32x16_bf16 v[84:99], v[140:143], v[116:119], v[2:17]
	ds_read_b128 v[140:143], v182 offset:40960
	v_exp_f32_e32 v210, v210
	v_exp_f32_e32 v211, v211
	v_mfma_f32_32x32x16_bf16 v[100:115], v[144:147], v[116:119], v[2:17]
	v_pk_add_f32 v[150:151], v[150:151], v[208:209]
	v_pk_add_f32 v[150:151], v[150:151], v[210:211]
	v_cvt_pk_bf16_f32 v206, v208, v209
	v_cvt_pk_bf16_f32 v207, v210, v211
	s_waitcnt lgkmcnt(4)
	v_mfma_f32_32x32x16_bf16 v[84:99], v[220:223], v[120:123], v[84:99]
	v_exp_f32_e32 v212, v212
	v_exp_f32_e32 v213, v213
	v_mfma_f32_32x32x16_bf16 v[100:115], v[224:227], v[120:123], v[100:115]
	v_exp_f32_e32 v214, v214
	v_exp_f32_e32 v215, v215
	s_waitcnt lgkmcnt(2)
	v_mfma_f32_32x32x16_bf16 v[84:99], v[232:235], v[124:127], v[84:99]
	v_pk_add_f32 v[150:151], v[150:151], v[212:213]
	v_pk_add_f32 v[150:151], v[150:151], v[214:215]
	v_exp_f32_e32 v216, v216
	v_mfma_f32_32x32x16_bf16 v[100:115], v[132:135], v[124:127], v[100:115]
	v_exp_f32_e32 v217, v217
	v_cvt_pk_bf16_f32 v208, v212, v213
	v_cvt_pk_bf16_f32 v209, v214, v215
	s_waitcnt lgkmcnt(0)
	v_mfma_f32_32x32x16_bf16 v[84:99], v[136:139], v[128:131], v[84:99]
	v_exp_f32_e32 v218, v218
	v_exp_f32_e32 v219, v219
	v_mfma_f32_32x32x16_bf16 v[100:115], v[140:143], v[128:131], v[100:115]
	v_pk_add_f32 v[150:151], v[150:151], v[216:217]
	v_pk_add_f32 v[150:151], v[150:151], v[218:219]
	v_cvt_pk_bf16_f32 v210, v216, v217
	v_cvt_pk_bf16_f32 v211, v218, v219
	s_add_u32 s8, s8, 0x40000
	s_addc_u32 s9, s9, 0
	s_waitcnt vmcnt(4) lgkmcnt(0)
	s_barrier
	s_sub_u32 s10, s10, 1
	s_cbranch_scc1 .LatA_evs_h2
; #define LAS __attribute__((address_space(3)))
; __device__ __forceinline__ void attn_unit(LAS unsigned char* lds, const bf16_t* Z, bf16_t* A2, const float* tabg, int seq_base, int S, int h, int qb, float lam) {
;     ...
;             for (int ds = 0; ds < 4; ++ds) { kf[2 * ds] = *(const LAS bf16x8*)(Kt + (kfo ^ (unsigned)(ds << 5))); kf[2 * ds + 1] = *(const LAS bf16x8*)(Kt + 32 * 256 + (kfo ^ (unsigned)(ds << 5))); }
;             __builtin_amdgcn_sched_barrier(0);
;             p0 = __builtin_amdgcn_mfma_f32_32x32x16_bf16(kf[0], qf[0], cblk, 0, 0, 0);
;             p1 = __builtin_amdgcn_mfma_f32_32x32x16_bf16(kf[1], qf[0], cblk, 0, 0, 0);
; #pragma unroll
;             for (int ds = 1; ds < 4; ++ds) {
;                 p0 = __builtin_amdgcn_mfma_f32_32x32x16_bf16(kf[2 * ds], qf[ds], p0, 0, 0, 0);
;                 p1 = __builtin_amdgcn_mfma_f32_32x32x16_bf16(kf[2 * ds + 1], qf[ds], p1, 0, 0, 0);
;             }
;         }
;     ...
;         const unsigned vbase = (unsigned)(size_t)Vt + vfo;
;         s16x4 va[8], vb[8];
;         VREADS1(va, 0);
;         if (near) {
;             const LAS float* tp = tab + (kv0 + 4 * hi - (qlo + r32) + 224);
; #pragma unroll
;             for (int r = 0; r < 16; ++r) { p0[r] += tp[(r & 3) + 8 * (r >> 2)]; p1[r] += tp[32 + (r & 3) + 8 * (r >> 2)]; }
;         }
;         float mx = max2f(max16f(p0), max16f(p1));
;         const bool first = (t == 0);
;         if (first || __any(mx > THR)) {
;             { auto rr = __builtin_amdgcn_permlane32_swap(__float_as_uint(mx), __float_as_uint(mx), false, false); mx = max2f(__uint_as_float(rr[0]), __uint_as_float(rr[1])); }
;             const float delta = first ? mx : fmaxf(mx, 0.f);
;             const float alpha = first ? 1.0f : __builtin_amdgcn_exp2f(-delta);
;             mu += delta; ls2 *= alpha;
;             if (!first) {
;                 asm volatile("" ::: "memory");
;                 scr[r32] = alpha;
;                 asm volatile("s_waitcnt lgkmcnt(0)" ::: "memory");
; #pragma unroll
;                 for (int g = 0; g < 4; ++g) { const f32x4 a4 = *(const LAS f32x4*)(scr + 8 * g + 4 * hi);
; #pragma unroll
;                     for (int d = 0; d < 4; ++d) { O[d][4 * g + 0] *= a4[0]; O[d][4 * g + 1] *= a4[1]; O[d][4 * g + 2] *= a4[2]; O[d][4 * g + 3] *= a4[3]; } }
;                 asm volatile("s_waitcnt lgkmcnt(0)" ::: "memory");
;             }
; #pragma unroll
.LatA_evret_h2:
	ds_read_b64_tr_b16 v[132:133], v228 offset:16384
	ds_read_b64_tr_b16 v[134:135], v228 offset:18432
	ds_read_b64_tr_b16 v[136:137], v229 offset:16384
	ds_read_b64_tr_b16 v[138:139], v229 offset:18432
	ds_read_b64_tr_b16 v[140:141], v230 offset:16384
	ds_read_b64_tr_b16 v[142:143], v230 offset:18432
	ds_read_b64_tr_b16 v[144:145], v231 offset:16384
	ds_read_b64_tr_b16 v[146:147], v231 offset:18432
	ds_read_b64_tr_b16 v[220:221], v228 offset:20480
	ds_read_b64_tr_b16 v[222:223], v228 offset:22528
	ds_read_b64_tr_b16 v[224:225], v229 offset:20480
	ds_read_b64_tr_b16 v[226:227], v229 offset:22528
	ds_read_b64_tr_b16 v[232:233], v230 offset:20480
	ds_read_b64_tr_b16 v[234:235], v230 offset:22528
	v_max3_f32 v251, v84, v85, v86
	v_max3_f32 v252, v87, v88, v89
	v_max3_f32 v251, v251, v90, v91
	v_max3_f32 v252, v252, v92, v93
	v_max3_f32 v251, v251, v94, v95
	v_max3_f32 v252, v252, v96, v97
	v_max3_f32 v251, v251, v98, v99
	v_max3_f32 v252, v252, v100, v101
	v_max3_f32 v251, v251, v102, v103
	v_max3_f32 v252, v252, v104, v105
	v_max3_f32 v251, v251, v106, v107
	v_max3_f32 v252, v252, v108, v109
	v_max3_f32 v251, v251, v110, v111
	v_max3_f32 v252, v252, v112, v113
	v_max3_f32 v251, v251, v114, v115
	v_max_f32_e32 v251, v251, v252
	v_cmp_lt_f32_e32 vcc, 0x41000000, v251
	s_cbranch_vccnz .LatA_rs_h2
.LatA_rareret_h2:
	s_waitcnt lgkmcnt(10)
	v_mfma_f32_32x32x16_bf16 v[20:35], v[188:191], v[132:135], v[20:35]
	ds_read_b64_tr_b16 v[132:133], v231 offset:20480
	ds_read_b64_tr_b16 v[134:135], v231 offset:22528
	v_exp_f32_e32 v84, v84
	v_exp_f32_e32 v85, v85
	v_mfma_f32_32x32x16_bf16 v[36:51], v[188:191], v[136:139], v[36:51]
	ds_read_b64_tr_b16 v[136:137], v228 offset:24576
	ds_read_b64_tr_b16 v[138:139], v228 offset:26624
	v_exp_f32_e32 v86, v86
	v_exp_f32_e32 v87, v87
	s_waitcnt lgkmcnt(10)
	v_mfma_f32_32x32x16_bf16 v[52:67], v[188:191], v[140:143], v[52:67]
	ds_read_b64_tr_b16 v[140:141], v229 offset:24576
	ds_read_b64_tr_b16 v[142:143], v229 offset:26624
	v_pk_add_f32 v[150:151], v[150:151], v[84:85]
	v_pk_add_f32 v[150:151], v[150:151], v[86:87]
	v_exp_f32_e32 v88, v88
	s_add_u32 m0, s28, 0x8000
	v_mfma_f32_32x32x16_bf16 v[68:83], v[188:191], v[144:147], v[68:83]
	global_load_lds_dwordx4 v236, s[8:9]
	ds_read_b64_tr_b16 v[144:145], v230 offset:24576
	ds_read_b64_tr_b16 v[146:147], v230 offset:26624
	v_exp_f32_e32 v89, v89
	v_cvt_pk_bf16_f32 v84, v84, v85
	v_cvt_pk_bf16_f32 v85, v86, v87
	s_waitcnt lgkmcnt(10)
	v_mfma_f32_32x32x16_bf16 v[20:35], v[192:195], v[220:223], v[20:35]
	ds_read_b64_tr_b16 v[220:221], v231 offset:24576
	ds_read_b64_tr_b16 v[222:223], v231 offset:26624
	v_exp_f32_e32 v90, v90
	v_exp_f32_e32 v91, v91
	v_mfma_f32_32x32x16_bf16 v[36:51], v[192:195], v[224:227], v[36:51]
	ds_read_b64_tr_b16 v[224:225], v228 offset:28672
	ds_read_b64_tr_b16 v[226:227], v228 offset:30720
	v_pk_add_f32 v[150:151], v[150:151], v[88:89]
	v_pk_add_f32 v[150:151], v[150:151], v[90:91]
	v_cvt_pk_bf16_f32 v86, v88, v89
	v_cvt_pk_bf16_f32 v87, v90, v91
	s_waitcnt lgkmcnt(10)
	v_mfma_f32_32x32x16_bf16 v[52:67], v[192:195], v[232:235], v[52:67]
	ds_read_b64_tr_b16 v[232:233], v229 offset:28672
	ds_read_b64_tr_b16 v[234:235], v229 offset:30720
	v_exp_f32_e32 v92, v92
	v_exp_f32_e32 v93, v93
	s_mov_b32 m0, s29
	v_mfma_f32_32x32x16_bf16 v[68:83], v[192:195], v[132:135], v[68:83]
	global_load_lds_dwordx4 v160, s[8:9]
	ds_read_b64_tr_b16 v[132:133], v230 offset:28672
	ds_read_b64_tr_b16 v[134:135], v230 offset:30720
	v_exp_f32_e32 v94, v94
	v_exp_f32_e32 v95, v95
	s_waitcnt lgkmcnt(10)
	v_mfma_f32_32x32x16_bf16 v[20:35], v[204:207], v[136:139], v[20:35]
	ds_read_b64_tr_b16 v[136:137], v231 offset:28672
	ds_read_b64_tr_b16 v[138:139], v231 offset:30720
	v_pk_add_f32 v[150:151], v[150:151], v[92:93]
	v_pk_add_f32 v[150:151], v[150:151], v[94:95]
	v_exp_f32_e32 v96, v96
	v_mfma_f32_32x32x16_bf16 v[36:51], v[204:207], v[140:143], v[36:51]
	ds_read_b128 v[140:143], v19
	v_exp_f32_e32 v97, v97
	v_cvt_pk_bf16_f32 v88, v92, v93
	v_cvt_pk_bf16_f32 v89, v94, v95
	s_waitcnt lgkmcnt(9)
	v_mfma_f32_32x32x16_bf16 v[52:67], v[204:207], v[144:147], v[52:67]
	ds_read_b128 v[144:147], v19 offset:8192
	v_exp_f32_e32 v98, v98
	v_exp_f32_e32 v99, v99
	s_add_u32 m0, s28, 0xa000
	v_mfma_f32_32x32x16_bf16 v[68:83], v[204:207], v[220:223], v[68:83]
	global_load_lds_dwordx4 v237, s[8:9]
	ds_read_b128 v[220:223], v180
	v_pk_add_f32 v[150:151], v[150:151], v[96:97]
	v_pk_add_f32 v[150:151], v[150:151], v[98:99]
	v_cvt_pk_bf16_f32 v90, v96, v97
	v_cvt_pk_bf16_f32 v91, v98, v99
	s_waitcnt lgkmcnt(7)
	v_mfma_f32_32x32x16_bf16 v[20:35], v[208:211], v[224:227], v[20:35]
	ds_read_b128 v[224:227], v180 offset:8192
	v_exp_f32_e32 v100, v100
	v_exp_f32_e32 v101, v101
	v_mfma_f32_32x32x16_bf16 v[36:51], v[208:211], v[232:235], v[36:51]
	ds_read_b128 v[232:235], v181
	v_exp_f32_e32 v102, v102
	v_exp_f32_e32 v103, v103
	s_waitcnt lgkmcnt(5)
	v_mfma_f32_32x32x16_bf16 v[52:67], v[208:211], v[132:135], v[52:67]
	ds_read_b128 v[132:135], v181 offset:8192
	v_pk_add_f32 v[150:151], v[150:151], v[100:101]
	v_pk_add_f32 v[150:151], v[150:151], v[102:103]
	v_exp_f32_e32 v104, v104
	s_add_u32 m0, s29, 0x2000
	v_mfma_f32_32x32x16_bf16 v[68:83], v[208:211], v[136:139], v[68:83]
	global_load_lds_dwordx4 v176, s[8:9]
	ds_read_b128 v[136:139], v182
	v_exp_f32_e32 v105, v105
	v_cvt_pk_bf16_f32 v100, v100, v101
	v_cvt_pk_bf16_f32 v101, v102, v103
	s_waitcnt lgkmcnt(5)
	v_mfma_f32_32x32x16_bf16 v[188:203], v[140:143], v[116:119], v[2:17]
	ds_read_b128 v[140:143], v182 offset:8192
	v_exp_f32_e32 v106, v106
	v_exp_f32_e32 v107, v107
	v_mfma_f32_32x32x16_bf16 v[204:219], v[144:147], v[116:119], v[2:17]
	v_pk_add_f32 v[150:151], v[150:151], v[104:105]
	v_pk_add_f32 v[150:151], v[150:151], v[106:107]
	v_cvt_pk_bf16_f32 v102, v104, v105
	v_cvt_pk_bf16_f32 v103, v106, v107
	s_waitcnt lgkmcnt(4)
	v_mfma_f32_32x32x16_bf16 v[188:203], v[220:223], v[120:123], v[188:203]
	v_exp_f32_e32 v108, v108
	v_exp_f32_e32 v109, v109
	v_mfma_f32_32x32x16_bf16 v[204:219], v[224:227], v[120:123], v[204:219]
	v_exp_f32_e32 v110, v110
	v_exp_f32_e32 v111, v111
	s_waitcnt lgkmcnt(2)
	v_mfma_f32_32x32x16_bf16 v[188:203], v[232:235], v[124:127], v[188:203]
	v_pk_add_f32 v[150:151], v[150:151], v[108:109]
	v_pk_add_f32 v[150:151], v[150:151], v[110:111]
	v_exp_f32_e32 v112, v112
	v_mfma_f32_32x32x16_bf16 v[204:219], v[132:135], v[124:127], v[204:219]
	v_exp_f32_e32 v113, v113
	v_cvt_pk_bf16_f32 v104, v108, v109
	v_cvt_pk_bf16_f32 v105, v110, v111
	s_waitcnt lgkmcnt(0)
	v_mfma_f32_32x32x16_bf16 v[188:203], v[136:139], v[128:131], v[188:203]
	v_exp_f32_e32 v114, v114
	v_exp_f32_e32 v115, v115
	v_mfma_f32_32x32x16_bf16 v[204:219], v[140:143], v[128:131], v[204:219]
	v_pk_add_f32 v[150:151], v[150:151], v[112:113]
	v_pk_add_f32 v[150:151], v[150:151], v[114:115]
	v_cvt_pk_bf16_f32 v106, v112, v113
	v_cvt_pk_bf16_f32 v107, v114, v115
	s_add_u32 s8, s8, 0x40000
	s_addc_u32 s9, s9, 0
	s_waitcnt vmcnt(4) lgkmcnt(0)
	s_barrier
	s_sub_u32 s10, s10, 1
	s_cbranch_scc1 .LatA_evs_h3
; #define LAS __attribute__((address_space(3)))
; __device__ __forceinline__ void attn_unit(LAS unsigned char* lds, const bf16_t* Z, bf16_t* A2, const float* tabg, int seq_base, int S, int h, int qb, float lam) {
;     ...
;             for (int ds = 0; ds < 4; ++ds) { kf[2 * ds] = *(const LAS bf16x8*)(Kt + (kfo ^ (unsigned)(ds << 5))); kf[2 * ds + 1] = *(const LAS bf16x8*)(Kt + 32 * 256 + (kfo ^ (unsigned)(ds << 5))); }
;             __builtin_amdgcn_sched_barrier(0);
;             p0 = __builtin_amdgcn_mfma_f32_32x32x16_bf16(kf[0], qf[0], cblk, 0, 0, 0);
;             p1 = __builtin_amdgcn_mfma_f32_32x32x16_bf16(kf[1], qf[0], cblk, 0, 0, 0);
; #pragma unroll
;             for (int ds = 1; ds < 4; ++ds) {
;                 p0 = __builtin_amdgcn_mfma_f32_32x32x16_bf16(kf[2 * ds], qf[ds], p0, 0, 0, 0);
;                 p1 = __builtin_amdgcn_mfma_f32_32x32x16_bf16(kf[2 * ds + 1], qf[ds], p1, 0, 0, 0);
;             }
;         }
;     ...
;         const unsigned vbase = (unsigned)(size_t)Vt + vfo;
;         s16x4 va[8], vb[8];
;         VREADS1(va, 0);
;         if (near) {
;             const LAS float* tp = tab + (kv0 + 4 * hi - (qlo + r32) + 224);
; #pragma unroll
;             for (int r = 0; r < 16; ++r) { p0[r] += tp[(r & 3) + 8 * (r >> 2)]; p1[r] += tp[32 + (r & 3) + 8 * (r >> 2)]; }
;         }
;         float mx = max2f(max16f(p0), max16f(p1));
;         const bool first = (t == 0);
;         if (first || __any(mx > THR)) {
;             { auto rr = __builtin_amdgcn_permlane32_swap(__float_as_uint(mx), __float_as_uint(mx), false, false); mx = max2f(__uint_as_float(rr[0]), __uint_as_float(rr[1])); }
;             const float delta = first ? mx : fmaxf(mx, 0.f);
;             const float alpha = first ? 1.0f : __builtin_amdgcn_exp2f(-delta);
;             mu += delta; ls2 *= alpha;
;             if (!first) {
;                 asm volatile("" ::: "memory");
;                 scr[r32] = alpha;
;                 asm volatile("s_waitcnt lgkmcnt(0)" ::: "memory");
; #pragma unroll
;                 for (int g = 0; g < 4; ++g) { const f32x4 a4 = *(const LAS f32x4*)(scr + 8 * g + 4 * hi);
; #pragma unroll
;                     for (int d = 0; d < 4; ++d) { O[d][4 * g + 0] *= a4[0]; O[d][4 * g + 1] *= a4[1]; O[d][4 * g + 2] *= a4[2]; O[d][4 * g + 3] *= a4[3]; } }
;                 asm volatile("s_waitcnt lgkmcnt(0)" ::: "memory");
;             }
; #pragma unroll
.LatA_evret_h3:
	ds_read_b64_tr_b16 v[132:133], v228 offset:32768
	ds_read_b64_tr_b16 v[134:135], v228 offset:34816
	ds_read_b64_tr_b16 v[136:137], v229 offset:32768
	ds_read_b64_tr_b16 v[138:139], v229 offset:34816
	ds_read_b64_tr_b16 v[140:141], v230 offset:32768
	ds_read_b64_tr_b16 v[142:143], v230 offset:34816
	ds_read_b64_tr_b16 v[144:145], v231 offset:32768
	ds_read_b64_tr_b16 v[146:147], v231 offset:34816
	ds_read_b64_tr_b16 v[220:221], v228 offset:36864
	ds_read_b64_tr_b16 v[222:223], v228 offset:38912
	ds_read_b64_tr_b16 v[224:225], v229 offset:36864
	ds_read_b64_tr_b16 v[226:227], v229 offset:38912
	ds_read_b64_tr_b16 v[232:233], v230 offset:36864
	ds_read_b64_tr_b16 v[234:235], v230 offset:38912
	v_max3_f32 v251, v188, v189, v190
	v_max3_f32 v252, v191, v192, v193
	v_max3_f32 v251, v251, v194, v195
	v_max3_f32 v252, v252, v196, v197
	v_max3_f32 v251, v251, v198, v199
	v_max3_f32 v252, v252, v200, v201
	v_max3_f32 v251, v251, v202, v203
	v_max3_f32 v252, v252, v204, v205
	v_max3_f32 v251, v251, v206, v207
	v_max3_f32 v252, v252, v208, v209
	v_max3_f32 v251, v251, v210, v211
	v_max3_f32 v252, v252, v212, v213
	v_max3_f32 v251, v251, v214, v215
	v_max3_f32 v252, v252, v216, v217
	v_max3_f32 v251, v251, v218, v219
	v_max_f32_e32 v251, v251, v252
	v_cmp_lt_f32_e32 vcc, 0x41000000, v251
	s_cbranch_vccnz .LatA_rs_h3
.LatA_rareret_h3:
	s_waitcnt lgkmcnt(10)
	v_mfma_f32_32x32x16_bf16 v[20:35], v[84:87], v[132:135], v[20:35]
	ds_read_b64_tr_b16 v[132:133], v231 offset:36864
	ds_read_b64_tr_b16 v[134:135], v231 offset:38912
	v_exp_f32_e32 v188, v188
	v_exp_f32_e32 v189, v189
	v_mfma_f32_32x32x16_bf16 v[36:51], v[84:87], v[136:139], v[36:51]
	ds_read_b64_tr_b16 v[136:137], v228 offset:40960
	ds_read_b64_tr_b16 v[138:139], v228 offset:43008
	v_exp_f32_e32 v190, v190
	v_exp_f32_e32 v191, v191
	s_waitcnt lgkmcnt(10)
	v_mfma_f32_32x32x16_bf16 v[52:67], v[84:87], v[140:143], v[52:67]
	ds_read_b64_tr_b16 v[140:141], v229 offset:40960
	ds_read_b64_tr_b16 v[142:143], v229 offset:43008
	v_pk_add_f32 v[150:151], v[150:151], v[188:189]
	v_pk_add_f32 v[150:151], v[150:151], v[190:191]
	v_exp_f32_e32 v192, v192
	s_mov_b32 m0, s28
	v_mfma_f32_32x32x16_bf16 v[68:83], v[84:87], v[144:147], v[68:83]
	global_load_lds_dwordx4 v236, s[8:9]
	ds_read_b64_tr_b16 v[144:145], v230 offset:40960
	ds_read_b64_tr_b16 v[146:147], v230 offset:43008
	v_exp_f32_e32 v193, v193
	v_cvt_pk_bf16_f32 v188, v188, v189
	v_cvt_pk_bf16_f32 v189, v190, v191
	s_waitcnt lgkmcnt(10)
	v_mfma_f32_32x32x16_bf16 v[20:35], v[88:91], v[220:223], v[20:35]
	ds_read_b64_tr_b16 v[220:221], v231 offset:40960
	ds_read_b64_tr_b16 v[222:223], v231 offset:43008
	v_exp_f32_e32 v194, v194
	v_exp_f32_e32 v195, v195
	v_mfma_f32_32x32x16_bf16 v[36:51], v[88:91], v[224:227], v[36:51]
	ds_read_b64_tr_b16 v[224:225], v228 offset:45056
	ds_read_b64_tr_b16 v[226:227], v228 offset:47104
	v_pk_add_f32 v[150:151], v[150:151], v[192:193]
	v_pk_add_f32 v[150:151], v[150:151], v[194:195]
	v_cvt_pk_bf16_f32 v190, v192, v193
	v_cvt_pk_bf16_f32 v191, v194, v195
	s_waitcnt lgkmcnt(10)
	v_mfma_f32_32x32x16_bf16 v[52:67], v[88:91], v[232:235], v[52:67]
	ds_read_b64_tr_b16 v[232:233], v229 offset:45056
	ds_read_b64_tr_b16 v[234:235], v229 offset:47104
	v_exp_f32_e32 v196, v196
	v_exp_f32_e32 v197, v197
	s_add_u32 m0, s29, 0x4000
	v_mfma_f32_32x32x16_bf16 v[68:83], v[88:91], v[132:135], v[68:83]
	global_load_lds_dwordx4 v160, s[8:9]
	ds_read_b64_tr_b16 v[132:133], v230 offset:45056
	ds_read_b64_tr_b16 v[134:135], v230 offset:47104
	v_exp_f32_e32 v198, v198
	v_exp_f32_e32 v199, v199
	s_waitcnt lgkmcnt(10)
	v_mfma_f32_32x32x16_bf16 v[20:35], v[100:103], v[136:139], v[20:35]
	ds_read_b64_tr_b16 v[136:137], v231 offset:45056
	ds_read_b64_tr_b16 v[138:139], v231 offset:47104
	v_pk_add_f32 v[150:151], v[150:151], v[196:197]
	v_pk_add_f32 v[150:151], v[150:151], v[198:199]
	v_exp_f32_e32 v200, v200
	v_mfma_f32_32x32x16_bf16 v[36:51], v[100:103], v[140:143], v[36:51]
	ds_read_b128 v[140:143], v19 offset:16384
	v_exp_f32_e32 v201, v201
	v_cvt_pk_bf16_f32 v192, v196, v197
	v_cvt_pk_bf16_f32 v193, v198, v199
	s_waitcnt lgkmcnt(9)
	v_mfma_f32_32x32x16_bf16 v[52:67], v[100:103], v[144:147], v[52:67]
	ds_read_b128 v[144:147], v19 offset:24576
	v_exp_f32_e32 v202, v202
	v_exp_f32_e32 v203, v203
	s_add_u32 m0, s28, 0x2000
	v_mfma_f32_32x32x16_bf16 v[68:83], v[100:103], v[220:223], v[68:83]
	global_load_lds_dwordx4 v237, s[8:9]
	ds_read_b128 v[220:223], v180 offset:16384
	v_pk_add_f32 v[150:151], v[150:151], v[200:201]
	v_pk_add_f32 v[150:151], v[150:151], v[202:203]
	v_cvt_pk_bf16_f32 v194, v200, v201
	v_cvt_pk_bf16_f32 v195, v202, v203
	s_waitcnt lgkmcnt(7)
	v_mfma_f32_32x32x16_bf16 v[20:35], v[104:107], v[224:227], v[20:35]
	ds_read_b128 v[224:227], v180 offset:24576
	v_exp_f32_e32 v204, v204
	v_exp_f32_e32 v205, v205
	v_mfma_f32_32x32x16_bf16 v[36:51], v[104:107], v[232:235], v[36:51]
	ds_read_b128 v[232:235], v181 offset:16384
	v_exp_f32_e32 v206, v206
	v_exp_f32_e32 v207, v207
	s_waitcnt lgkmcnt(5)
	v_mfma_f32_32x32x16_bf16 v[52:67], v[104:107], v[132:135], v[52:67]
	ds_read_b128 v[132:135], v181 offset:24576
	v_pk_add_f32 v[150:151], v[150:151], v[204:205]
	v_pk_add_f32 v[150:151], v[150:151], v[206:207]
	v_exp_f32_e32 v208, v208
	s_add_u32 m0, s29, 0x6000
	v_mfma_f32_32x32x16_bf16 v[68:83], v[104:107], v[136:139], v[68:83]
	global_load_lds_dwordx4 v176, s[8:9]
	ds_read_b128 v[136:139], v182 offset:16384
	v_exp_f32_e32 v209, v209
	v_cvt_pk_bf16_f32 v204, v204, v205
	v_cvt_pk_bf16_f32 v205, v206, v207
	s_waitcnt lgkmcnt(5)
; #define LAS __attribute__((address_space(3)))
; __device__ __forceinline__ void attn_unit(LAS unsigned char* lds, const bf16_t* Z, bf16_t* A2, const float* tabg, int seq_base, int S, int h, int qb, float lam) {
;     ...
;             for (int ds = 0; ds < 4; ++ds) { kf[2 * ds] = *(const LAS bf16x8*)(Kt + (kfo ^ (unsigned)(ds << 5))); kf[2 * ds + 1] = *(const LAS bf16x8*)(Kt + 32 * 256 + (kfo ^ (unsigned)(ds << 5))); }
;             __builtin_amdgcn_sched_barrier(0);
;             p0 = __builtin_amdgcn_mfma_f32_32x32x16_bf16(kf[0], qf[0], cblk, 0, 0, 0);
;             p1 = __builtin_amdgcn_mfma_f32_32x32x16_bf16(kf[1], qf[0], cblk, 0, 0, 0);
; #pragma unroll
;             for (int ds = 1; ds < 4; ++ds) {
;                 p0 = __builtin_amdgcn_mfma_f32_32x32x16_bf16(kf[2 * ds], qf[ds], p0, 0, 0, 0);
;                 p1 = __builtin_amdgcn_mfma_f32_32x32x16_bf16(kf[2 * ds + 1], qf[ds], p1, 0, 0, 0);
;             }
;         }
;     ...
;         const unsigned vbase = (unsigned)(size_t)Vt + vfo;
;         s16x4 va[8], vb[8];
;         VREADS1(va, 0);
;         if (near) {
;             const LAS float* tp = tab + (kv0 + 4 * hi - (qlo + r32) + 224);
; #pragma unroll
;             for (int r = 0; r < 16; ++r) { p0[r] += tp[(r & 3) + 8 * (r >> 2)]; p1[r] += tp[32 + (r & 3) + 8 * (r >> 2)]; }
;         }
;         float mx = max2f(max16f(p0), max16f(p1));
;         const bool first = (t == 0);
;         if (first || __any(mx > THR)) {
;             { auto rr = __builtin_amdgcn_permlane32_swap(__float_as_uint(mx), __float_as_uint(mx), false, false); mx = max2f(__uint_as_float(rr[0]), __uint_as_float(rr[1])); }
;             const float delta = first ? mx : fmaxf(mx, 0.f);
;             const float alpha = first ? 1.0f : __builtin_amdgcn_exp2f(-delta);
;             mu += delta; ls2 *= alpha;
;             if (!first) {
;                 asm volatile("" ::: "memory");
;                 scr[r32] = alpha;
;                 asm volatile("s_waitcnt lgkmcnt(0)" ::: "memory");
; #pragma unroll
;                 for (int g = 0; g < 4; ++g) { const f32x4 a4 = *(const LAS f32x4*)(scr + 8 * g + 4 * hi);
; #pragma unroll
;                     for (int d = 0; d < 4; ++d) { O[d][4 * g + 0] *= a4[0]; O[d][4 * g + 1] *= a4[1]; O[d][4 * g + 2] *= a4[2]; O[d][4 * g + 3] *= a4[3]; } }
;                 asm volatile("s_waitcnt lgkmcnt(0)" ::: "memory");
;             }
; #pragma unroll
	v_mfma_f32_32x32x16_bf16 v[84:99], v[140:143], v[116:119], v[2:17]
	ds_read_b128 v[140:143], v182 offset:24576
	v_exp_f32_e32 v210, v210
	v_exp_f32_e32 v211, v211
	v_mfma_f32_32x32x16_bf16 v[100:115], v[144:147], v[116:119], v[2:17]
	v_pk_add_f32 v[150:151], v[150:151], v[208:209]
	v_pk_add_f32 v[150:151], v[150:151], v[210:211]
	v_cvt_pk_bf16_f32 v206, v208, v209
	v_cvt_pk_bf16_f32 v207, v210, v211
	s_waitcnt lgkmcnt(4)
	v_mfma_f32_32x32x16_bf16 v[84:99], v[220:223], v[120:123], v[84:99]
	v_exp_f32_e32 v212, v212
	v_exp_f32_e32 v213, v213
	v_mfma_f32_32x32x16_bf16 v[100:115], v[224:227], v[120:123], v[100:115]
	v_exp_f32_e32 v214, v214
	v_exp_f32_e32 v215, v215
	s_waitcnt lgkmcnt(2)
	v_mfma_f32_32x32x16_bf16 v[84:99], v[232:235], v[124:127], v[84:99]
	v_pk_add_f32 v[150:151], v[150:151], v[212:213]
	v_pk_add_f32 v[150:151], v[150:151], v[214:215]
	v_exp_f32_e32 v216, v216
	v_mfma_f32_32x32x16_bf16 v[100:115], v[132:135], v[124:127], v[100:115]
	v_exp_f32_e32 v217, v217
	v_cvt_pk_bf16_f32 v208, v212, v213
	v_cvt_pk_bf16_f32 v209, v214, v215
	s_waitcnt lgkmcnt(0)
	v_mfma_f32_32x32x16_bf16 v[84:99], v[136:139], v[128:131], v[84:99]
	v_exp_f32_e32 v218, v218
	v_exp_f32_e32 v219, v219
	v_mfma_f32_32x32x16_bf16 v[100:115], v[140:143], v[128:131], v[100:115]
	v_pk_add_f32 v[150:151], v[150:151], v[216:217]
	v_pk_add_f32 v[150:151], v[150:151], v[218:219]
	v_cvt_pk_bf16_f32 v210, v216, v217
	v_cvt_pk_bf16_f32 v211, v218, v219
	s_add_u32 s8, s8, 0x40000
	s_addc_u32 s9, s9, 0
	s_waitcnt vmcnt(4) lgkmcnt(0)
	s_barrier
	s_movk_i32 s36, 20
.LatA_loop:
	s_sub_u32 s10, s10, 1
	s_cbranch_scc1 .LatA_evs_m0
.LatA_evret_m0:
	ds_read_b64_tr_b16 v[132:133], v228 offset:0
	ds_read_b64_tr_b16 v[134:135], v228 offset:2048
	ds_read_b64_tr_b16 v[136:137], v229 offset:0
	ds_read_b64_tr_b16 v[138:139], v229 offset:2048
	ds_read_b64_tr_b16 v[140:141], v230 offset:0
	ds_read_b64_tr_b16 v[142:143], v230 offset:2048
	ds_read_b64_tr_b16 v[144:145], v231 offset:0
	ds_read_b64_tr_b16 v[146:147], v231 offset:2048
	ds_read_b64_tr_b16 v[220:221], v228 offset:4096
	ds_read_b64_tr_b16 v[222:223], v228 offset:6144
	ds_read_b64_tr_b16 v[224:225], v229 offset:4096
	ds_read_b64_tr_b16 v[226:227], v229 offset:6144
	ds_read_b64_tr_b16 v[232:233], v230 offset:4096
	ds_read_b64_tr_b16 v[234:235], v230 offset:6144
	v_max3_f32 v251, v84, v85, v86
	v_max3_f32 v252, v87, v88, v89
	v_max3_f32 v251, v251, v90, v91
	v_max3_f32 v252, v252, v92, v93
	v_max3_f32 v251, v251, v94, v95
	v_max3_f32 v252, v252, v96, v97
	v_max3_f32 v251, v251, v98, v99
	v_max3_f32 v252, v252, v100, v101
	v_max3_f32 v251, v251, v102, v103
	v_max3_f32 v252, v252, v104, v105
	v_max3_f32 v251, v251, v106, v107
	v_max3_f32 v252, v252, v108, v109
	v_max3_f32 v251, v251, v110, v111
	v_max3_f32 v252, v252, v112, v113
	v_max3_f32 v251, v251, v114, v115
	v_max_f32_e32 v251, v251, v252
	v_cmp_lt_f32_e32 vcc, 0x41000000, v251
	s_cbranch_vccnz .LatA_rs_m0
.LatA_rareret_m0:
	s_waitcnt lgkmcnt(10)
	v_mfma_f32_32x32x16_bf16 v[20:35], v[188:191], v[132:135], v[20:35]
	ds_read_b64_tr_b16 v[132:133], v231 offset:4096
	ds_read_b64_tr_b16 v[134:135], v231 offset:6144
	v_exp_f32_e32 v84, v84
	v_exp_f32_e32 v85, v85
	v_mfma_f32_32x32x16_bf16 v[36:51], v[188:191], v[136:139], v[36:51]
	ds_read_b64_tr_b16 v[136:137], v228 offset:8192
	ds_read_b64_tr_b16 v[138:139], v228 offset:10240
	v_exp_f32_e32 v86, v86
	v_exp_f32_e32 v87, v87
	s_waitcnt lgkmcnt(10)
	v_mfma_f32_32x32x16_bf16 v[52:67], v[188:191], v[140:143], v[52:67]
	ds_read_b64_tr_b16 v[140:141], v229 offset:8192
	ds_read_b64_tr_b16 v[142:143], v229 offset:10240
	v_pk_add_f32 v[150:151], v[150:151], v[84:85]
	v_pk_add_f32 v[150:151], v[150:151], v[86:87]
	v_exp_f32_e32 v88, v88
	s_add_u32 m0, s28, 0x4000
	v_mfma_f32_32x32x16_bf16 v[68:83], v[188:191], v[144:147], v[68:83]
	global_load_lds_dwordx4 v236, s[8:9]
	ds_read_b64_tr_b16 v[144:145], v230 offset:8192
	ds_read_b64_tr_b16 v[146:147], v230 offset:10240
	v_exp_f32_e32 v89, v89
	v_cvt_pk_bf16_f32 v84, v84, v85
	v_cvt_pk_bf16_f32 v85, v86, v87
	s_waitcnt lgkmcnt(10)
	v_mfma_f32_32x32x16_bf16 v[20:35], v[192:195], v[220:223], v[20:35]
	ds_read_b64_tr_b16 v[220:221], v231 offset:8192
	ds_read_b64_tr_b16 v[222:223], v231 offset:10240
	v_exp_f32_e32 v90, v90
	v_exp_f32_e32 v91, v91
	v_mfma_f32_32x32x16_bf16 v[36:51], v[192:195], v[224:227], v[36:51]
	ds_read_b64_tr_b16 v[224:225], v228 offset:12288
	ds_read_b64_tr_b16 v[226:227], v228 offset:14336
	v_pk_add_f32 v[150:151], v[150:151], v[88:89]
	v_pk_add_f32 v[150:151], v[150:151], v[90:91]
	v_cvt_pk_bf16_f32 v86, v88, v89
	v_cvt_pk_bf16_f32 v87, v90, v91
	s_waitcnt lgkmcnt(10)
	v_mfma_f32_32x32x16_bf16 v[52:67], v[192:195], v[232:235], v[52:67]
	ds_read_b64_tr_b16 v[232:233], v229 offset:12288
	ds_read_b64_tr_b16 v[234:235], v229 offset:14336
	v_exp_f32_e32 v92, v92
	v_exp_f32_e32 v93, v93
	s_add_u32 m0, s29, 0x8000
	v_mfma_f32_32x32x16_bf16 v[68:83], v[192:195], v[132:135], v[68:83]
	global_load_lds_dwordx4 v160, s[8:9]
	ds_read_b64_tr_b16 v[132:133], v230 offset:12288
	ds_read_b64_tr_b16 v[134:135], v230 offset:14336
	v_exp_f32_e32 v94, v94
	v_exp_f32_e32 v95, v95
	s_waitcnt lgkmcnt(10)
	v_mfma_f32_32x32x16_bf16 v[20:35], v[204:207], v[136:139], v[20:35]
	ds_read_b64_tr_b16 v[136:137], v231 offset:12288
	ds_read_b64_tr_b16 v[138:139], v231 offset:14336
	v_pk_add_f32 v[150:151], v[150:151], v[92:93]
	v_pk_add_f32 v[150:151], v[150:151], v[94:95]
	v_exp_f32_e32 v96, v96
	v_mfma_f32_32x32x16_bf16 v[36:51], v[204:207], v[140:143], v[36:51]
	ds_read_b128 v[140:143], v19 offset:32768
	v_exp_f32_e32 v97, v97
	v_cvt_pk_bf16_f32 v88, v92, v93
	v_cvt_pk_bf16_f32 v89, v94, v95
	s_waitcnt lgkmcnt(9)
; #define LAS __attribute__((address_space(3)))
; __device__ __forceinline__ void attn_unit(LAS unsigned char* lds, const bf16_t* Z, bf16_t* A2, const float* tabg, int seq_base, int S, int h, int qb, float lam) {
;     ...
;             for (int ds = 0; ds < 4; ++ds) { kf[2 * ds] = *(const LAS bf16x8*)(Kt + (kfo ^ (unsigned)(ds << 5))); kf[2 * ds + 1] = *(const LAS bf16x8*)(Kt + 32 * 256 + (kfo ^ (unsigned)(ds << 5))); }
;             __builtin_amdgcn_sched_barrier(0);
;             p0 = __builtin_amdgcn_mfma_f32_32x32x16_bf16(kf[0], qf[0], cblk, 0, 0, 0);
;             p1 = __builtin_amdgcn_mfma_f32_32x32x16_bf16(kf[1], qf[0], cblk, 0, 0, 0);
; #pragma unroll
;             for (int ds = 1; ds < 4; ++ds) {
;                 p0 = __builtin_amdgcn_mfma_f32_32x32x16_bf16(kf[2 * ds], qf[ds], p0, 0, 0, 0);
;                 p1 = __builtin_amdgcn_mfma_f32_32x32x16_bf16(kf[2 * ds + 1], qf[ds], p1, 0, 0, 0);
;             }
;         }
;     ...
;         const unsigned vbase = (unsigned)(size_t)Vt + vfo;
;         s16x4 va[8], vb[8];
;         VREADS1(va, 0);
;         if (near) {
;             const LAS float* tp = tab + (kv0 + 4 * hi - (qlo + r32) + 224);
; #pragma unroll
;             for (int r = 0; r < 16; ++r) { p0[r] += tp[(r & 3) + 8 * (r >> 2)]; p1[r] += tp[32 + (r & 3) + 8 * (r >> 2)]; }
;         }
;         float mx = max2f(max16f(p0), max16f(p1));
;         const bool first = (t == 0);
;         if (first || __any(mx > THR)) {
;             { auto rr = __builtin_amdgcn_permlane32_swap(__float_as_uint(mx), __float_as_uint(mx), false, false); mx = max2f(__uint_as_float(rr[0]), __uint_as_float(rr[1])); }
;             const float delta = first ? mx : fmaxf(mx, 0.f);
;             const float alpha = first ? 1.0f : __builtin_amdgcn_exp2f(-delta);
;             mu += delta; ls2 *= alpha;
;             if (!first) {
;                 asm volatile("" ::: "memory");
;                 scr[r32] = alpha;
;                 asm volatile("s_waitcnt lgkmcnt(0)" ::: "memory");
; #pragma unroll
;                 for (int g = 0; g < 4; ++g) { const f32x4 a4 = *(const LAS f32x4*)(scr + 8 * g + 4 * hi);
; #pragma unroll
;                     for (int d = 0; d < 4; ++d) { O[d][4 * g + 0] *= a4[0]; O[d][4 * g + 1] *= a4[1]; O[d][4 * g + 2] *= a4[2]; O[d][4 * g + 3] *= a4[3]; } }
;                 asm volatile("s_waitcnt lgkmcnt(0)" ::: "memory");
;             }
; #pragma unroll
	v_mfma_f32_32x32x16_bf16 v[52:67], v[204:207], v[144:147], v[52:67]
	ds_read_b128 v[144:147], v19 offset:40960
	v_exp_f32_e32 v98, v98
	v_exp_f32_e32 v99, v99
	s_add_u32 m0, s28, 0x6000
	v_mfma_f32_32x32x16_bf16 v[68:83], v[204:207], v[220:223], v[68:83]
	global_load_lds_dwordx4 v237, s[8:9]
	ds_read_b128 v[220:223], v180 offset:32768
	v_pk_add_f32 v[150:151], v[150:151], v[96:97]
	v_pk_add_f32 v[150:151], v[150:151], v[98:99]
	v_cvt_pk_bf16_f32 v90, v96, v97
	v_cvt_pk_bf16_f32 v91, v98, v99
	s_waitcnt lgkmcnt(7)
	v_mfma_f32_32x32x16_bf16 v[20:35], v[208:211], v[224:227], v[20:35]
	ds_read_b128 v[224:227], v180 offset:40960
	v_exp_f32_e32 v100, v100
	v_exp_f32_e32 v101, v101
	v_mfma_f32_32x32x16_bf16 v[36:51], v[208:211], v[232:235], v[36:51]
	ds_read_b128 v[232:235], v181 offset:32768
	v_exp_f32_e32 v102, v102
	v_exp_f32_e32 v103, v103
	s_waitcnt lgkmcnt(5)
	v_mfma_f32_32x32x16_bf16 v[52:67], v[208:211], v[132:135], v[52:67]
	ds_read_b128 v[132:135], v181 offset:40960
	v_pk_add_f32 v[150:151], v[150:151], v[100:101]
	v_pk_add_f32 v[150:151], v[150:151], v[102:103]
	v_exp_f32_e32 v104, v104
	s_add_u32 m0, s29, 0xa000
	v_mfma_f32_32x32x16_bf16 v[68:83], v[208:211], v[136:139], v[68:83]
	global_load_lds_dwordx4 v176, s[8:9]
	ds_read_b128 v[136:139], v182 offset:32768
	v_exp_f32_e32 v105, v105
	v_cvt_pk_bf16_f32 v100, v100, v101
	v_cvt_pk_bf16_f32 v101, v102, v103
	s_waitcnt lgkmcnt(5)
	v_mfma_f32_32x32x16_bf16 v[188:203], v[140:143], v[116:119], v[2:17]
	ds_read_b128 v[140:143], v182 offset:40960
	v_exp_f32_e32 v106, v106
	v_exp_f32_e32 v107, v107
	v_mfma_f32_32x32x16_bf16 v[204:219], v[144:147], v[116:119], v[2:17]
	v_pk_add_f32 v[150:151], v[150:151], v[104:105]
	v_pk_add_f32 v[150:151], v[150:151], v[106:107]
	v_cvt_pk_bf16_f32 v102, v104, v105
	v_cvt_pk_bf16_f32 v103, v106, v107
	s_waitcnt lgkmcnt(4)
	v_mfma_f32_32x32x16_bf16 v[188:203], v[220:223], v[120:123], v[188:203]
	v_exp_f32_e32 v108, v108
	v_exp_f32_e32 v109, v109
	v_mfma_f32_32x32x16_bf16 v[204:219], v[224:227], v[120:123], v[204:219]
	v_exp_f32_e32 v110, v110
	v_exp_f32_e32 v111, v111
	s_waitcnt lgkmcnt(2)
	v_mfma_f32_32x32x16_bf16 v[188:203], v[232:235], v[124:127], v[188:203]
	v_pk_add_f32 v[150:151], v[150:151], v[108:109]
	v_pk_add_f32 v[150:151], v[150:151], v[110:111]
	v_exp_f32_e32 v112, v112
	v_mfma_f32_32x32x16_bf16 v[204:219], v[132:135], v[124:127], v[204:219]
	v_exp_f32_e32 v113, v113
	v_cvt_pk_bf16_f32 v104, v108, v109
	v_cvt_pk_bf16_f32 v105, v110, v111
	s_waitcnt lgkmcnt(0)
	v_mfma_f32_32x32x16_bf16 v[188:203], v[136:139], v[128:131], v[188:203]
	v_exp_f32_e32 v114, v114
	v_exp_f32_e32 v115, v115
	v_mfma_f32_32x32x16_bf16 v[204:219], v[140:143], v[128:131], v[204:219]
	v_pk_add_f32 v[150:151], v[150:151], v[112:113]
	v_pk_add_f32 v[150:151], v[150:151], v[114:115]
	v_cvt_pk_bf16_f32 v106, v112, v113
	v_cvt_pk_bf16_f32 v107, v114, v115
	s_add_u32 s8, s8, 0x40000
	s_addc_u32 s9, s9, 0
	s_waitcnt vmcnt(4) lgkmcnt(0)
	s_barrier
	s_sub_u32 s10, s10, 1
	s_cbranch_scc1 .LatA_evs_m1
.LatA_evret_m1:
	ds_read_b64_tr_b16 v[132:133], v228 offset:16384
	ds_read_b64_tr_b16 v[134:135], v228 offset:18432
	ds_read_b64_tr_b16 v[136:137], v229 offset:16384
	ds_read_b64_tr_b16 v[138:139], v229 offset:18432
	ds_read_b64_tr_b16 v[140:141], v230 offset:16384
	ds_read_b64_tr_b16 v[142:143], v230 offset:18432
	ds_read_b64_tr_b16 v[144:145], v231 offset:16384
	ds_read_b64_tr_b16 v[146:147], v231 offset:18432
	ds_read_b64_tr_b16 v[220:221], v228 offset:20480
	ds_read_b64_tr_b16 v[222:223], v228 offset:22528
	ds_read_b64_tr_b16 v[224:225], v229 offset:20480
	ds_read_b64_tr_b16 v[226:227], v229 offset:22528
	ds_read_b64_tr_b16 v[232:233], v230 offset:20480
	ds_read_b64_tr_b16 v[234:235], v230 offset:22528
	v_max3_f32 v251, v188, v189, v190
	v_max3_f32 v252, v191, v192, v193
	v_max3_f32 v251, v251, v194, v195
	v_max3_f32 v252, v252, v196, v197
	v_max3_f32 v251, v251, v198, v199
	v_max3_f32 v252, v252, v200, v201
	v_max3_f32 v251, v251, v202, v203
	v_max3_f32 v252, v252, v204, v205
	v_max3_f32 v251, v251, v206, v207
	v_max3_f32 v252, v252, v208, v209
	v_max3_f32 v251, v251, v210, v211
	v_max3_f32 v252, v252, v212, v213
	v_max3_f32 v251, v251, v214, v215
	v_max3_f32 v252, v252, v216, v217
	v_max3_f32 v251, v251, v218, v219
	v_max_f32_e32 v251, v251, v252
	v_cmp_lt_f32_e32 vcc, 0x41000000, v251
	s_cbranch_vccnz .LatA_rs_m1
; #define LAS __attribute__((address_space(3)))
; __device__ __forceinline__ void attn_unit(LAS unsigned char* lds, const bf16_t* Z, bf16_t* A2, const float* tabg, int seq_base, int S, int h, int qb, float lam) {
;     ...
;             for (int ds = 0; ds < 4; ++ds) { kf[2 * ds] = *(const LAS bf16x8*)(Kt + (kfo ^ (unsigned)(ds << 5))); kf[2 * ds + 1] = *(const LAS bf16x8*)(Kt + 32 * 256 + (kfo ^ (unsigned)(ds << 5))); }
;             __builtin_amdgcn_sched_barrier(0);
;             p0 = __builtin_amdgcn_mfma_f32_32x32x16_bf16(kf[0], qf[0], cblk, 0, 0, 0);
;             p1 = __builtin_amdgcn_mfma_f32_32x32x16_bf16(kf[1], qf[0], cblk, 0, 0, 0);
; #pragma unroll
;             for (int ds = 1; ds < 4; ++ds) {
;                 p0 = __builtin_amdgcn_mfma_f32_32x32x16_bf16(kf[2 * ds], qf[ds], p0, 0, 0, 0);
;                 p1 = __builtin_amdgcn_mfma_f32_32x32x16_bf16(kf[2 * ds + 1], qf[ds], p1, 0, 0, 0);
;             }
;         }
;     ...
;         const unsigned vbase = (unsigned)(size_t)Vt + vfo;
;         s16x4 va[8], vb[8];
;         VREADS1(va, 0);
;         if (near) {
;             const LAS float* tp = tab + (kv0 + 4 * hi - (qlo + r32) + 224);
; #pragma unroll
;             for (int r = 0; r < 16; ++r) { p0[r] += tp[(r & 3) + 8 * (r >> 2)]; p1[r] += tp[32 + (r & 3) + 8 * (r >> 2)]; }
;         }
;         float mx = max2f(max16f(p0), max16f(p1));
;         const bool first = (t == 0);
;         if (first || __any(mx > THR)) {
;             { auto rr = __builtin_amdgcn_permlane32_swap(__float_as_uint(mx), __float_as_uint(mx), false, false); mx = max2f(__uint_as_float(rr[0]), __uint_as_float(rr[1])); }
;             const float delta = first ? mx : fmaxf(mx, 0.f);
;             const float alpha = first ? 1.0f : __builtin_amdgcn_exp2f(-delta);
;             mu += delta; ls2 *= alpha;
;             if (!first) {
;                 asm volatile("" ::: "memory");
;                 scr[r32] = alpha;
;                 asm volatile("s_waitcnt lgkmcnt(0)" ::: "memory");
; #pragma unroll
;                 for (int g = 0; g < 4; ++g) { const f32x4 a4 = *(const LAS f32x4*)(scr + 8 * g + 4 * hi);
; #pragma unroll
;                     for (int d = 0; d < 4; ++d) { O[d][4 * g + 0] *= a4[0]; O[d][4 * g + 1] *= a4[1]; O[d][4 * g + 2] *= a4[2]; O[d][4 * g + 3] *= a4[3]; } }
;                 asm volatile("s_waitcnt lgkmcnt(0)" ::: "memory");
;             }
; #pragma unroll
.LatA_rareret_m1:
	s_waitcnt lgkmcnt(10)
	v_mfma_f32_32x32x16_bf16 v[20:35], v[84:87], v[132:135], v[20:35]
	ds_read_b64_tr_b16 v[132:133], v231 offset:20480
	ds_read_b64_tr_b16 v[134:135], v231 offset:22528
	v_exp_f32_e32 v188, v188
	v_exp_f32_e32 v189, v189
	v_mfma_f32_32x32x16_bf16 v[36:51], v[84:87], v[136:139], v[36:51]
	ds_read_b64_tr_b16 v[136:137], v228 offset:24576
	ds_read_b64_tr_b16 v[138:139], v228 offset:26624
	v_exp_f32_e32 v190, v190
	v_exp_f32_e32 v191, v191
	s_waitcnt lgkmcnt(10)
	v_mfma_f32_32x32x16_bf16 v[52:67], v[84:87], v[140:143], v[52:67]
	ds_read_b64_tr_b16 v[140:141], v229 offset:24576
	ds_read_b64_tr_b16 v[142:143], v229 offset:26624
	v_pk_add_f32 v[150:151], v[150:151], v[188:189]
	v_pk_add_f32 v[150:151], v[150:151], v[190:191]
	v_exp_f32_e32 v192, v192
	s_add_u32 m0, s28, 0x8000
	v_mfma_f32_32x32x16_bf16 v[68:83], v[84:87], v[144:147], v[68:83]
	global_load_lds_dwordx4 v236, s[8:9]
	ds_read_b64_tr_b16 v[144:145], v230 offset:24576
	ds_read_b64_tr_b16 v[146:147], v230 offset:26624
	v_exp_f32_e32 v193, v193
	v_cvt_pk_bf16_f32 v188, v188, v189
	v_cvt_pk_bf16_f32 v189, v190, v191
	s_waitcnt lgkmcnt(10)
	v_mfma_f32_32x32x16_bf16 v[20:35], v[88:91], v[220:223], v[20:35]
	ds_read_b64_tr_b16 v[220:221], v231 offset:24576
	ds_read_b64_tr_b16 v[222:223], v231 offset:26624
	v_exp_f32_e32 v194, v194
	v_exp_f32_e32 v195, v195
	v_mfma_f32_32x32x16_bf16 v[36:51], v[88:91], v[224:227], v[36:51]
	ds_read_b64_tr_b16 v[224:225], v228 offset:28672
	ds_read_b64_tr_b16 v[226:227], v228 offset:30720
	v_pk_add_f32 v[150:151], v[150:151], v[192:193]
	v_pk_add_f32 v[150:151], v[150:151], v[194:195]
	v_cvt_pk_bf16_f32 v190, v192, v193
	v_cvt_pk_bf16_f32 v191, v194, v195
	s_waitcnt lgkmcnt(10)
	v_mfma_f32_32x32x16_bf16 v[52:67], v[88:91], v[232:235], v[52:67]
	ds_read_b64_tr_b16 v[232:233], v229 offset:28672
	ds_read_b64_tr_b16 v[234:235], v229 offset:30720
	v_exp_f32_e32 v196, v196
	v_exp_f32_e32 v197, v197
	s_mov_b32 m0, s29
	v_mfma_f32_32x32x16_bf16 v[68:83], v[88:91], v[132:135], v[68:83]
	global_load_lds_dwordx4 v160, s[8:9]
	ds_read_b64_tr_b16 v[132:133], v230 offset:28672
	ds_read_b64_tr_b16 v[134:135], v230 offset:30720
	v_exp_f32_e32 v198, v198
	v_exp_f32_e32 v199, v199
	s_waitcnt lgkmcnt(10)
	v_mfma_f32_32x32x16_bf16 v[20:35], v[100:103], v[136:139], v[20:35]
	ds_read_b64_tr_b16 v[136:137], v231 offset:28672
	ds_read_b64_tr_b16 v[138:139], v231 offset:30720
	v_pk_add_f32 v[150:151], v[150:151], v[196:197]
	v_pk_add_f32 v[150:151], v[150:151], v[198:199]
	v_exp_f32_e32 v200, v200
	v_mfma_f32_32x32x16_bf16 v[36:51], v[100:103], v[140:143], v[36:51]
	ds_read_b128 v[140:143], v19
	v_exp_f32_e32 v201, v201
	v_cvt_pk_bf16_f32 v192, v196, v197
	v_cvt_pk_bf16_f32 v193, v198, v199
	s_waitcnt lgkmcnt(9)
	v_mfma_f32_32x32x16_bf16 v[52:67], v[100:103], v[144:147], v[52:67]
	ds_read_b128 v[144:147], v19 offset:8192
	v_exp_f32_e32 v202, v202
	v_exp_f32_e32 v203, v203
	s_add_u32 m0, s28, 0xa000
	v_mfma_f32_32x32x16_bf16 v[68:83], v[100:103], v[220:223], v[68:83]
	global_load_lds_dwordx4 v237, s[8:9]
	ds_read_b128 v[220:223], v180
	v_pk_add_f32 v[150:151], v[150:151], v[200:201]
	v_pk_add_f32 v[150:151], v[150:151], v[202:203]
	v_cvt_pk_bf16_f32 v194, v200, v201
	v_cvt_pk_bf16_f32 v195, v202, v203
	s_waitcnt lgkmcnt(7)
	v_mfma_f32_32x32x16_bf16 v[20:35], v[104:107], v[224:227], v[20:35]
	ds_read_b128 v[224:227], v180 offset:8192
	v_exp_f32_e32 v204, v204
	v_exp_f32_e32 v205, v205
	v_mfma_f32_32x32x16_bf16 v[36:51], v[104:107], v[232:235], v[36:51]
	ds_read_b128 v[232:235], v181
	v_exp_f32_e32 v206, v206
	v_exp_f32_e32 v207, v207
	s_waitcnt lgkmcnt(5)
	v_mfma_f32_32x32x16_bf16 v[52:67], v[104:107], v[132:135], v[52:67]
	ds_read_b128 v[132:135], v181 offset:8192
	v_pk_add_f32 v[150:151], v[150:151], v[204:205]
	v_pk_add_f32 v[150:151], v[150:151], v[206:207]
	v_exp_f32_e32 v208, v208
	s_add_u32 m0, s29, 0x2000
	v_mfma_f32_32x32x16_bf16 v[68:83], v[104:107], v[136:139], v[68:83]
	global_load_lds_dwordx4 v176, s[8:9]
	ds_read_b128 v[136:139], v182
	v_exp_f32_e32 v209, v209
	v_cvt_pk_bf16_f32 v204, v204, v205
	v_cvt_pk_bf16_f32 v205, v206, v207
	s_waitcnt lgkmcnt(5)
	v_mfma_f32_32x32x16_bf16 v[84:99], v[140:143], v[116:119], v[2:17]
	ds_read_b128 v[140:143], v182 offset:8192
	v_exp_f32_e32 v210, v210
	v_exp_f32_e32 v211, v211
	v_mfma_f32_32x32x16_bf16 v[100:115], v[144:147], v[116:119], v[2:17]
	v_pk_add_f32 v[150:151], v[150:151], v[208:209]
	v_pk_add_f32 v[150:151], v[150:151], v[210:211]
	v_cvt_pk_bf16_f32 v206, v208, v209
	v_cvt_pk_bf16_f32 v207, v210, v211
	s_waitcnt lgkmcnt(4)
	v_mfma_f32_32x32x16_bf16 v[84:99], v[220:223], v[120:123], v[84:99]
	v_exp_f32_e32 v212, v212
	v_exp_f32_e32 v213, v213
	v_mfma_f32_32x32x16_bf16 v[100:115], v[224:227], v[120:123], v[100:115]
	v_exp_f32_e32 v214, v214
	v_exp_f32_e32 v215, v215
	s_waitcnt lgkmcnt(2)
	v_mfma_f32_32x32x16_bf16 v[84:99], v[232:235], v[124:127], v[84:99]
	v_pk_add_f32 v[150:151], v[150:151], v[212:213]
	v_pk_add_f32 v[150:151], v[150:151], v[214:215]
	v_exp_f32_e32 v216, v216
	v_mfma_f32_32x32x16_bf16 v[100:115], v[132:135], v[124:127], v[100:115]
	v_exp_f32_e32 v217, v217
	v_cvt_pk_bf16_f32 v208, v212, v213
	v_cvt_pk_bf16_f32 v209, v214, v215
	s_waitcnt lgkmcnt(0)
	v_mfma_f32_32x32x16_bf16 v[84:99], v[136:139], v[128:131], v[84:99]
	v_exp_f32_e32 v218, v218
	v_exp_f32_e32 v219, v219
	v_mfma_f32_32x32x16_bf16 v[100:115], v[140:143], v[128:131], v[100:115]
	v_pk_add_f32 v[150:151], v[150:151], v[216:217]
	v_pk_add_f32 v[150:151], v[150:151], v[218:219]
	v_cvt_pk_bf16_f32 v210, v216, v217
	v_cvt_pk_bf16_f32 v211, v218, v219
	s_add_u32 s8, s8, 0x40000
	s_addc_u32 s9, s9, 0
	s_waitcnt vmcnt(4) lgkmcnt(0)
	s_barrier
	s_sub_u32 s10, s10, 1
	s_cbranch_scc1 .LatA_evs_m2
; #define LAS __attribute__((address_space(3)))
; __device__ __forceinline__ float max2f(float a, float b) { float r; asm("v_max_f32_e32 %0, %1, %2" : "=v"(r) : "v"(a), "v"(b)); return r; }
; #define VREADS1(arr, d_) do { const unsigned ad_ = vbase ^ (unsigned)((d_) << 6); __builtin_amdgcn_sched_barrier(0); \
;         _Pragma("unroll") for (int ks_ = 0; ks_ < 4; ++ks_) { VTR(arr[ks_ * 2], ad_, ks_ * 4096); VTR(arr[ks_ * 2 + 1], ad_, ks_ * 4096 + 2048); } __builtin_amdgcn_sched_barrier(0); } while (0)
; __device__ __forceinline__ void attn_unit(LAS unsigned char* lds, const bf16_t* Z, bf16_t* A2, const float* tabg, int seq_base, int S, int h, int qb, float lam) {
;     ...
;         const unsigned vbase = (unsigned)(size_t)Vt + vfo;
;         s16x4 va[8], vb[8];
;         VREADS1(va, 0);
;         if (near) {
;             const LAS float* tp = tab + (kv0 + 4 * hi - (qlo + r32) + 224);
; #pragma unroll
;             for (int r = 0; r < 16; ++r) { p0[r] += tp[(r & 3) + 8 * (r >> 2)]; p1[r] += tp[32 + (r & 3) + 8 * (r >> 2)]; }
;         }
;         float mx = max2f(max16f(p0), max16f(p1));
;         const bool first = (t == 0);
;         if (first || __any(mx > THR)) {
.LatA_evret_m2:
	ds_read_b64_tr_b16 v[132:133], v228 offset:32768
	ds_read_b64_tr_b16 v[134:135], v228 offset:34816
	ds_read_b64_tr_b16 v[136:137], v229 offset:32768
	ds_read_b64_tr_b16 v[138:139], v229 offset:34816
	ds_read_b64_tr_b16 v[140:141], v230 offset:32768
	ds_read_b64_tr_b16 v[142:143], v230 offset:34816
	ds_read_b64_tr_b16 v[144:145], v231 offset:32768
	ds_read_b64_tr_b16 v[146:147], v231 offset:34816
	ds_read_b64_tr_b16 v[220:221], v228 offset:36864
	ds_read_b64_tr_b16 v[222:223], v228 offset:38912
	ds_read_b64_tr_b16 v[224:225], v229 offset:36864
	ds_read_b64_tr_b16 v[226:227], v229 offset:38912
	ds_read_b64_tr_b16 v[232:233], v230 offset:36864
	ds_read_b64_tr_b16 v[234:235], v230 offset:38912
	v_max3_f32 v251, v84, v85, v86
	v_max3_f32 v252, v87, v88, v89
	v_max3_f32 v251, v251, v90, v91
	v_max3_f32 v252, v252, v92, v93
	v_max3_f32 v251, v251, v94, v95
	v_max3_f32 v252, v252, v96, v97
	v_max3_f32 v251, v251, v98, v99
	v_max3_f32 v252, v252, v100, v101
	v_max3_f32 v251, v251, v102, v103
	v_max3_f32 v252, v252, v104, v105
	v_max3_f32 v251, v251, v106, v107
	v_max3_f32 v252, v252, v108, v109
	v_max3_f32 v251, v251, v110, v111
	v_max3_f32 v252, v252, v112, v113
	v_max3_f32 v251, v251, v114, v115
	v_max_f32_e32 v251, v251, v252
	v_cmp_lt_f32_e32 vcc, 0x41000000, v251
	s_cbranch_vccnz .LatA_rs_m2
; #define LAS __attribute__((address_space(3)))
; __device__ __forceinline__ void attn_unit(LAS unsigned char* lds, const bf16_t* Z, bf16_t* A2, const float* tabg, int seq_base, int S, int h, int qb, float lam) {
;     ...
;             for (int ds = 0; ds < 4; ++ds) { kf[2 * ds] = *(const LAS bf16x8*)(Kt + (kfo ^ (unsigned)(ds << 5))); kf[2 * ds + 1] = *(const LAS bf16x8*)(Kt + 32 * 256 + (kfo ^ (unsigned)(ds << 5))); }
;             __builtin_amdgcn_sched_barrier(0);
;             p0 = __builtin_amdgcn_mfma_f32_32x32x16_bf16(kf[0], qf[0], cblk, 0, 0, 0);
;             p1 = __builtin_amdgcn_mfma_f32_32x32x16_bf16(kf[1], qf[0], cblk, 0, 0, 0);
; #pragma unroll
;             for (int ds = 1; ds < 4; ++ds) {
;                 p0 = __builtin_amdgcn_mfma_f32_32x32x16_bf16(kf[2 * ds], qf[ds], p0, 0, 0, 0);
;                 p1 = __builtin_amdgcn_mfma_f32_32x32x16_bf16(kf[2 * ds + 1], qf[ds], p1, 0, 0, 0);
;             }
;         }
;     ...
;         const unsigned vbase = (unsigned)(size_t)Vt + vfo;
;         s16x4 va[8], vb[8];
;         VREADS1(va, 0);
;         if (near) {
;             const LAS float* tp = tab + (kv0 + 4 * hi - (qlo + r32) + 224);
; #pragma unroll
;             for (int r = 0; r < 16; ++r) { p0[r] += tp[(r & 3) + 8 * (r >> 2)]; p1[r] += tp[32 + (r & 3) + 8 * (r >> 2)]; }
;         }
;         float mx = max2f(max16f(p0), max16f(p1));
;         const bool first = (t == 0);
;         if (first || __any(mx > THR)) {
;             { auto rr = __builtin_amdgcn_permlane32_swap(__float_as_uint(mx), __float_as_uint(mx), false, false); mx = max2f(__uint_as_float(rr[0]), __uint_as_float(rr[1])); }
;             const float delta = first ? mx : fmaxf(mx, 0.f);
;             const float alpha = first ? 1.0f : __builtin_amdgcn_exp2f(-delta);
;             mu += delta; ls2 *= alpha;
;             if (!first) {
;                 asm volatile("" ::: "memory");
;                 scr[r32] = alpha;
;                 asm volatile("s_waitcnt lgkmcnt(0)" ::: "memory");
; #pragma unroll
;                 for (int g = 0; g < 4; ++g) { const f32x4 a4 = *(const LAS f32x4*)(scr + 8 * g + 4 * hi);
; #pragma unroll
;                     for (int d = 0; d < 4; ++d) { O[d][4 * g + 0] *= a4[0]; O[d][4 * g + 1] *= a4[1]; O[d][4 * g + 2] *= a4[2]; O[d][4 * g + 3] *= a4[3]; } }
;                 asm volatile("s_waitcnt lgkmcnt(0)" ::: "memory");
;             }
; #pragma unroll
.LatA_rareret_m2:
	s_waitcnt lgkmcnt(10)
	v_mfma_f32_32x32x16_bf16 v[20:35], v[188:191], v[132:135], v[20:35]
	ds_read_b64_tr_b16 v[132:133], v231 offset:36864
	ds_read_b64_tr_b16 v[134:135], v231 offset:38912
	v_exp_f32_e32 v84, v84
	v_exp_f32_e32 v85, v85
	v_mfma_f32_32x32x16_bf16 v[36:51], v[188:191], v[136:139], v[36:51]
	ds_read_b64_tr_b16 v[136:137], v228 offset:40960
	ds_read_b64_tr_b16 v[138:139], v228 offset:43008
	v_exp_f32_e32 v86, v86
	v_exp_f32_e32 v87, v87
	s_waitcnt lgkmcnt(10)
	v_mfma_f32_32x32x16_bf16 v[52:67], v[188:191], v[140:143], v[52:67]
	ds_read_b64_tr_b16 v[140:141], v229 offset:40960
	ds_read_b64_tr_b16 v[142:143], v229 offset:43008
	v_pk_add_f32 v[150:151], v[150:151], v[84:85]
	v_pk_add_f32 v[150:151], v[150:151], v[86:87]
	v_exp_f32_e32 v88, v88
	s_mov_b32 m0, s28
	v_mfma_f32_32x32x16_bf16 v[68:83], v[188:191], v[144:147], v[68:83]
	global_load_lds_dwordx4 v236, s[8:9]
	ds_read_b64_tr_b16 v[144:145], v230 offset:40960
	ds_read_b64_tr_b16 v[146:147], v230 offset:43008
	v_exp_f32_e32 v89, v89
	v_cvt_pk_bf16_f32 v84, v84, v85
	v_cvt_pk_bf16_f32 v85, v86, v87
	s_waitcnt lgkmcnt(10)
	v_mfma_f32_32x32x16_bf16 v[20:35], v[192:195], v[220:223], v[20:35]
	ds_read_b64_tr_b16 v[220:221], v231 offset:40960
	ds_read_b64_tr_b16 v[222:223], v231 offset:43008
	v_exp_f32_e32 v90, v90
	v_exp_f32_e32 v91, v91
	v_mfma_f32_32x32x16_bf16 v[36:51], v[192:195], v[224:227], v[36:51]
	ds_read_b64_tr_b16 v[224:225], v228 offset:45056
	ds_read_b64_tr_b16 v[226:227], v228 offset:47104
	v_pk_add_f32 v[150:151], v[150:151], v[88:89]
	v_pk_add_f32 v[150:151], v[150:151], v[90:91]
	v_cvt_pk_bf16_f32 v86, v88, v89
	v_cvt_pk_bf16_f32 v87, v90, v91
	s_waitcnt lgkmcnt(10)
	v_mfma_f32_32x32x16_bf16 v[52:67], v[192:195], v[232:235], v[52:67]
	ds_read_b64_tr_b16 v[232:233], v229 offset:45056
	ds_read_b64_tr_b16 v[234:235], v229 offset:47104
	v_exp_f32_e32 v92, v92
	v_exp_f32_e32 v93, v93
	s_add_u32 m0, s29, 0x4000
	v_mfma_f32_32x32x16_bf16 v[68:83], v[192:195], v[132:135], v[68:83]
	global_load_lds_dwordx4 v160, s[8:9]
	ds_read_b64_tr_b16 v[132:133], v230 offset:45056
	ds_read_b64_tr_b16 v[134:135], v230 offset:47104
	v_exp_f32_e32 v94, v94
	v_exp_f32_e32 v95, v95
	s_waitcnt lgkmcnt(10)
	v_mfma_f32_32x32x16_bf16 v[20:35], v[204:207], v[136:139], v[20:35]
	ds_read_b64_tr_b16 v[136:137], v231 offset:45056
	ds_read_b64_tr_b16 v[138:139], v231 offset:47104
	v_pk_add_f32 v[150:151], v[150:151], v[92:93]
	v_pk_add_f32 v[150:151], v[150:151], v[94:95]
	v_exp_f32_e32 v96, v96
	v_mfma_f32_32x32x16_bf16 v[36:51], v[204:207], v[140:143], v[36:51]
	ds_read_b128 v[140:143], v19 offset:16384
	v_exp_f32_e32 v97, v97
	v_cvt_pk_bf16_f32 v88, v92, v93
	v_cvt_pk_bf16_f32 v89, v94, v95
	s_waitcnt lgkmcnt(9)
	v_mfma_f32_32x32x16_bf16 v[52:67], v[204:207], v[144:147], v[52:67]
	ds_read_b128 v[144:147], v19 offset:24576
	v_exp_f32_e32 v98, v98
	v_exp_f32_e32 v99, v99
	s_add_u32 m0, s28, 0x2000
	v_mfma_f32_32x32x16_bf16 v[68:83], v[204:207], v[220:223], v[68:83]
	global_load_lds_dwordx4 v237, s[8:9]
	ds_read_b128 v[220:223], v180 offset:16384
	v_pk_add_f32 v[150:151], v[150:151], v[96:97]
	v_pk_add_f32 v[150:151], v[150:151], v[98:99]
	v_cvt_pk_bf16_f32 v90, v96, v97
	v_cvt_pk_bf16_f32 v91, v98, v99
	s_waitcnt lgkmcnt(7)
	v_mfma_f32_32x32x16_bf16 v[20:35], v[208:211], v[224:227], v[20:35]
	ds_read_b128 v[224:227], v180 offset:24576
	v_exp_f32_e32 v100, v100
	v_exp_f32_e32 v101, v101
	v_mfma_f32_32x32x16_bf16 v[36:51], v[208:211], v[232:235], v[36:51]
	ds_read_b128 v[232:235], v181 offset:16384
	v_exp_f32_e32 v102, v102
	v_exp_f32_e32 v103, v103
	s_waitcnt lgkmcnt(5)
	v_mfma_f32_32x32x16_bf16 v[52:67], v[208:211], v[132:135], v[52:67]
	ds_read_b128 v[132:135], v181 offset:24576
	v_pk_add_f32 v[150:151], v[150:151], v[100:101]
	v_pk_add_f32 v[150:151], v[150:151], v[102:103]
	v_exp_f32_e32 v104, v104
	s_add_u32 m0, s29, 0x6000
	v_mfma_f32_32x32x16_bf16 v[68:83], v[208:211], v[136:139], v[68:83]
	global_load_lds_dwordx4 v176, s[8:9]
	ds_read_b128 v[136:139], v182 offset:16384
	v_exp_f32_e32 v105, v105
	v_cvt_pk_bf16_f32 v100, v100, v101
	v_cvt_pk_bf16_f32 v101, v102, v103
	s_waitcnt lgkmcnt(5)
	v_mfma_f32_32x32x16_bf16 v[188:203], v[140:143], v[116:119], v[2:17]
	ds_read_b128 v[140:143], v182 offset:24576
	v_exp_f32_e32 v106, v106
	v_exp_f32_e32 v107, v107
	v_mfma_f32_32x32x16_bf16 v[204:219], v[144:147], v[116:119], v[2:17]
	v_pk_add_f32 v[150:151], v[150:151], v[104:105]
	v_pk_add_f32 v[150:151], v[150:151], v[106:107]
	v_cvt_pk_bf16_f32 v102, v104, v105
	v_cvt_pk_bf16_f32 v103, v106, v107
	s_waitcnt lgkmcnt(4)
	v_mfma_f32_32x32x16_bf16 v[188:203], v[220:223], v[120:123], v[188:203]
	v_exp_f32_e32 v108, v108
	v_exp_f32_e32 v109, v109
	v_mfma_f32_32x32x16_bf16 v[204:219], v[224:227], v[120:123], v[204:219]
	v_exp_f32_e32 v110, v110
	v_exp_f32_e32 v111, v111
	s_waitcnt lgkmcnt(2)
	v_mfma_f32_32x32x16_bf16 v[188:203], v[232:235], v[124:127], v[188:203]
	v_pk_add_f32 v[150:151], v[150:151], v[108:109]
	v_pk_add_f32 v[150:151], v[150:151], v[110:111]
	v_exp_f32_e32 v112, v112
	v_mfma_f32_32x32x16_bf16 v[204:219], v[132:135], v[124:127], v[204:219]
	v_exp_f32_e32 v113, v113
	v_cvt_pk_bf16_f32 v104, v108, v109
	v_cvt_pk_bf16_f32 v105, v110, v111
	s_waitcnt lgkmcnt(0)
	v_mfma_f32_32x32x16_bf16 v[188:203], v[136:139], v[128:131], v[188:203]
	v_exp_f32_e32 v114, v114
	v_exp_f32_e32 v115, v115
	v_mfma_f32_32x32x16_bf16 v[204:219], v[140:143], v[128:131], v[204:219]
	v_pk_add_f32 v[150:151], v[150:151], v[112:113]
	v_pk_add_f32 v[150:151], v[150:151], v[114:115]
	v_cvt_pk_bf16_f32 v106, v112, v113
	v_cvt_pk_bf16_f32 v107, v114, v115
	s_add_u32 s8, s8, 0x40000
	s_addc_u32 s9, s9, 0
	s_waitcnt vmcnt(4) lgkmcnt(0)
	s_barrier
	s_sub_u32 s10, s10, 1
	s_cbranch_scc1 .LatA_evs_m3

; #define LAS __attribute__((address_space(3)))
; __device__ __forceinline__ void attn_unit(LAS unsigned char* lds, const bf16_t* Z, bf16_t* A2, const float* tabg, int seq_base, int S, int h, int qb, float lam) {
;     ...
;             for (int ds = 0; ds < 4; ++ds) { kf[2 * ds] = *(const LAS bf16x8*)(Kt + (kfo ^ (unsigned)(ds << 5))); kf[2 * ds + 1] = *(const LAS bf16x8*)(Kt + 32 * 256 + (kfo ^ (unsigned)(ds << 5))); }
;             __builtin_amdgcn_sched_barrier(0);
;             p0 = __builtin_amdgcn_mfma_f32_32x32x16_bf16(kf[0], qf[0], cblk, 0, 0, 0);
;             p1 = __builtin_amdgcn_mfma_f32_32x32x16_bf16(kf[1], qf[0], cblk, 0, 0, 0);
; #pragma unroll
;             for (int ds = 1; ds < 4; ++ds) {
;                 p0 = __builtin_amdgcn_mfma_f32_32x32x16_bf16(kf[2 * ds], qf[ds], p0, 0, 0, 0);
;                 p1 = __builtin_amdgcn_mfma_f32_32x32x16_bf16(kf[2 * ds + 1], qf[ds], p1, 0, 0, 0);
;             }
;         }
;     ...
;         const unsigned vbase = (unsigned)(size_t)Vt + vfo;
;         s16x4 va[8], vb[8];
;         VREADS1(va, 0);
;         if (near) {
;             const LAS float* tp = tab + (kv0 + 4 * hi - (qlo + r32) + 224);
; #pragma unroll
;             for (int r = 0; r < 16; ++r) { p0[r] += tp[(r & 3) + 8 * (r >> 2)]; p1[r] += tp[32 + (r & 3) + 8 * (r >> 2)]; }
;         }
;         float mx = max2f(max16f(p0), max16f(p1));
;         const bool first = (t == 0);
;         if (first || __any(mx > THR)) {
;             { auto rr = __builtin_amdgcn_permlane32_swap(__float_as_uint(mx), __float_as_uint(mx), false, false); mx = max2f(__uint_as_float(rr[0]), __uint_as_float(rr[1])); }
;             const float delta = first ? mx : fmaxf(mx, 0.f);
;             const float alpha = first ? 1.0f : __builtin_amdgcn_exp2f(-delta);
;             mu += delta; ls2 *= alpha;
;             if (!first) {
;                 asm volatile("" ::: "memory");
;                 scr[r32] = alpha;
;                 asm volatile("s_waitcnt lgkmcnt(0)" ::: "memory");
; #pragma unroll
;                 for (int g = 0; g < 4; ++g) { const f32x4 a4 = *(const LAS f32x4*)(scr + 8 * g + 4 * hi);
; #pragma unroll
;                     for (int d = 0; d < 4; ++d) { O[d][4 * g + 0] *= a4[0]; O[d][4 * g + 1] *= a4[1]; O[d][4 * g + 2] *= a4[2]; O[d][4 * g + 3] *= a4[3]; } }
;                 asm volatile("s_waitcnt lgkmcnt(0)" ::: "memory");
;             }
; #pragma unroll
.LatA_rareret_m5:
	s_waitcnt lgkmcnt(10)
	v_mfma_f32_32x32x16_bf16 v[20:35], v[84:87], v[132:135], v[20:35]
	ds_read_b64_tr_b16 v[132:133], v231 offset:36864
	ds_read_b64_tr_b16 v[134:135], v231 offset:38912
	v_exp_f32_e32 v188, v188
	v_exp_f32_e32 v189, v189
	v_mfma_f32_32x32x16_bf16 v[36:51], v[84:87], v[136:139], v[36:51]
	ds_read_b64_tr_b16 v[136:137], v228 offset:40960
	ds_read_b64_tr_b16 v[138:139], v228 offset:43008
	v_exp_f32_e32 v190, v190
	v_exp_f32_e32 v191, v191
	s_waitcnt lgkmcnt(10)
	v_mfma_f32_32x32x16_bf16 v[52:67], v[84:87], v[140:143], v[52:67]
	ds_read_b64_tr_b16 v[140:141], v229 offset:40960
	ds_read_b64_tr_b16 v[142:143], v229 offset:43008
	v_pk_add_f32 v[150:151], v[150:151], v[188:189]
	v_pk_add_f32 v[150:151], v[150:151], v[190:191]
	v_exp_f32_e32 v192, v192
	s_mov_b32 m0, s28
	v_mfma_f32_32x32x16_bf16 v[68:83], v[84:87], v[144:147], v[68:83]
	global_load_lds_dwordx4 v236, s[8:9]
	ds_read_b64_tr_b16 v[144:145], v230 offset:40960
	ds_read_b64_tr_b16 v[146:147], v230 offset:43008
	v_exp_f32_e32 v193, v193
	v_cvt_pk_bf16_f32 v188, v188, v189
	v_cvt_pk_bf16_f32 v189, v190, v191
	s_waitcnt lgkmcnt(10)
	v_mfma_f32_32x32x16_bf16 v[20:35], v[88:91], v[220:223], v[20:35]
	ds_read_b64_tr_b16 v[220:221], v231 offset:40960
	ds_read_b64_tr_b16 v[222:223], v231 offset:43008
	v_exp_f32_e32 v194, v194
	v_exp_f32_e32 v195, v195
	v_mfma_f32_32x32x16_bf16 v[36:51], v[88:91], v[224:227], v[36:51]
	ds_read_b64_tr_b16 v[224:225], v228 offset:45056
	ds_read_b64_tr_b16 v[226:227], v228 offset:47104
	v_pk_add_f32 v[150:151], v[150:151], v[192:193]
	v_pk_add_f32 v[150:151], v[150:151], v[194:195]
	v_cvt_pk_bf16_f32 v190, v192, v193
	v_cvt_pk_bf16_f32 v191, v194, v195
	s_waitcnt lgkmcnt(10)
	v_mfma_f32_32x32x16_bf16 v[52:67], v[88:91], v[232:235], v[52:67]
	ds_read_b64_tr_b16 v[232:233], v229 offset:45056
	ds_read_b64_tr_b16 v[234:235], v229 offset:47104
	v_exp_f32_e32 v196, v196
	v_exp_f32_e32 v197, v197
	s_add_u32 m0, s29, 0x4000
	v_mfma_f32_32x32x16_bf16 v[68:83], v[88:91], v[132:135], v[68:83]
	global_load_lds_dwordx4 v160, s[8:9]
	ds_read_b64_tr_b16 v[132:133], v230 offset:45056
	ds_read_b64_tr_b16 v[134:135], v230 offset:47104
	v_exp_f32_e32 v198, v198
	v_exp_f32_e32 v199, v199
	s_waitcnt lgkmcnt(10)
	v_mfma_f32_32x32x16_bf16 v[20:35], v[100:103], v[136:139], v[20:35]
	ds_read_b64_tr_b16 v[136:137], v231 offset:45056
	ds_read_b64_tr_b16 v[138:139], v231 offset:47104
	v_pk_add_f32 v[150:151], v[150:151], v[196:197]
	v_pk_add_f32 v[150:151], v[150:151], v[198:199]
	v_exp_f32_e32 v200, v200
	v_mfma_f32_32x32x16_bf16 v[36:51], v[100:103], v[140:143], v[36:51]
	ds_read_b128 v[140:143], v19 offset:16384
	v_exp_f32_e32 v201, v201
	v_cvt_pk_bf16_f32 v192, v196, v197
	v_cvt_pk_bf16_f32 v193, v198, v199
	s_waitcnt lgkmcnt(9)
	v_mfma_f32_32x32x16_bf16 v[52:67], v[100:103], v[144:147], v[52:67]
	ds_read_b128 v[144:147], v19 offset:24576
	v_exp_f32_e32 v202, v202
	v_exp_f32_e32 v203, v203
	s_add_u32 m0, s28, 0x2000
	v_mfma_f32_32x32x16_bf16 v[68:83], v[100:103], v[220:223], v[68:83]
	global_load_lds_dwordx4 v237, s[8:9]
	ds_read_b128 v[220:223], v180 offset:16384
	v_pk_add_f32 v[150:151], v[150:151], v[200:201]
	v_pk_add_f32 v[150:151], v[150:151], v[202:203]
	v_cvt_pk_bf16_f32 v194, v200, v201
	v_cvt_pk_bf16_f32 v195, v202, v203
	s_waitcnt lgkmcnt(7)
	v_mfma_f32_32x32x16_bf16 v[20:35], v[104:107], v[224:227], v[20:35]
	ds_read_b128 v[224:227], v180 offset:24576
	v_exp_f32_e32 v204, v204
	v_exp_f32_e32 v205, v205
	v_mfma_f32_32x32x16_bf16 v[36:51], v[104:107], v[232:235], v[36:51]
	ds_read_b128 v[232:235], v181 offset:16384
	v_exp_f32_e32 v206, v206
	v_exp_f32_e32 v207, v207
	s_waitcnt lgkmcnt(5)
	v_mfma_f32_32x32x16_bf16 v[52:67], v[104:107], v[132:135], v[52:67]
	ds_read_b128 v[132:135], v181 offset:24576
	v_pk_add_f32 v[150:151], v[150:151], v[204:205]
	v_pk_add_f32 v[150:151], v[150:151], v[206:207]
	v_exp_f32_e32 v208, v208
	s_add_u32 m0, s29, 0x6000
	v_mfma_f32_32x32x16_bf16 v[68:83], v[104:107], v[136:139], v[68:83]
	global_load_lds_dwordx4 v176, s[8:9]
	ds_read_b128 v[136:139], v182 offset:16384
	v_exp_f32_e32 v209, v209
	v_cvt_pk_bf16_f32 v204, v204, v205
	v_cvt_pk_bf16_f32 v205, v206, v207
	s_waitcnt lgkmcnt(5)
	v_mfma_f32_32x32x16_bf16 v[84:99], v[140:143], v[116:119], v[2:17]
	ds_read_b128 v[140:143], v182 offset:24576
	v_exp_f32_e32 v210, v210
	v_exp_f32_e32 v211, v211
	v_mfma_f32_32x32x16_bf16 v[100:115], v[144:147], v[116:119], v[2:17]
	v_pk_add_f32 v[150:151], v[150:151], v[208:209]
	v_pk_add_f32 v[150:151], v[150:151], v[210:211]
	v_cvt_pk_bf16_f32 v206, v208, v209
	v_cvt_pk_bf16_f32 v207, v210, v211
	s_waitcnt lgkmcnt(4)
	v_mfma_f32_32x32x16_bf16 v[84:99], v[220:223], v[120:123], v[84:99]
	v_exp_f32_e32 v212, v212
	v_exp_f32_e32 v213, v213
	v_mfma_f32_32x32x16_bf16 v[100:115], v[224:227], v[120:123], v[100:115]
	v_exp_f32_e32 v214, v214
	v_exp_f32_e32 v215, v215
	s_waitcnt lgkmcnt(2)
	v_mfma_f32_32x32x16_bf16 v[84:99], v[232:235], v[124:127], v[84:99]
	v_pk_add_f32 v[150:151], v[150:151], v[212:213]
	v_pk_add_f32 v[150:151], v[150:151], v[214:215]
	v_exp_f32_e32 v216, v216
	v_mfma_f32_32x32x16_bf16 v[100:115], v[132:135], v[124:127], v[100:115]
	v_exp_f32_e32 v217, v217
	v_cvt_pk_bf16_f32 v208, v212, v213
	v_cvt_pk_bf16_f32 v209, v214, v215
	s_waitcnt lgkmcnt(0)
	v_mfma_f32_32x32x16_bf16 v[84:99], v[136:139], v[128:131], v[84:99]
	v_exp_f32_e32 v218, v218
	v_exp_f32_e32 v219, v219
	v_mfma_f32_32x32x16_bf16 v[100:115], v[140:143], v[128:131], v[100:115]
	v_pk_add_f32 v[150:151], v[150:151], v[216:217]
	v_pk_add_f32 v[150:151], v[150:151], v[218:219]
	v_cvt_pk_bf16_f32 v210, v216, v217
	v_cvt_pk_bf16_f32 v211, v218, v219
	s_add_u32 s8, s8, 0x40000
	s_addc_u32 s9, s9, 0
	s_waitcnt vmcnt(4) lgkmcnt(0)
	s_barrier
	s_sub_u32 s36, s36, 1
	s_cmp_lg_u32 s36, 0
	s_cbranch_scc1 .LatA_loop
	s_sub_u32 s10, s10, 1
	s_cbranch_scc1 .LatA_evs_x4

; #define LAS __attribute__((address_space(3)))
; __device__ __forceinline__ void attn_unit(LAS unsigned char* lds, const bf16_t* Z, bf16_t* A2, const float* tabg, int seq_base, int S, int h, int qb, float lam) {
;     ...
;             for (int ds = 0; ds < 4; ++ds) { kf[2 * ds] = *(const LAS bf16x8*)(Kt + (kfo ^ (unsigned)(ds << 5))); kf[2 * ds + 1] = *(const LAS bf16x8*)(Kt + 32 * 256 + (kfo ^ (unsigned)(ds << 5))); }
;             __builtin_amdgcn_sched_barrier(0);
;             p0 = __builtin_amdgcn_mfma_f32_32x32x16_bf16(kf[0], qf[0], cblk, 0, 0, 0);
;             p1 = __builtin_amdgcn_mfma_f32_32x32x16_bf16(kf[1], qf[0], cblk, 0, 0, 0);
; #pragma unroll
;             for (int ds = 1; ds < 4; ++ds) {
;                 p0 = __builtin_amdgcn_mfma_f32_32x32x16_bf16(kf[2 * ds], qf[ds], p0, 0, 0, 0);
;                 p1 = __builtin_amdgcn_mfma_f32_32x32x16_bf16(kf[2 * ds + 1], qf[ds], p1, 0, 0, 0);
;             }
;         }
;     ...
;         const unsigned vbase = (unsigned)(size_t)Vt + vfo;
;         s16x4 va[8], vb[8];
;         VREADS1(va, 0);
;         if (near) {
;             const LAS float* tp = tab + (kv0 + 4 * hi - (qlo + r32) + 224);
; #pragma unroll
;             for (int r = 0; r < 16; ++r) { p0[r] += tp[(r & 3) + 8 * (r >> 2)]; p1[r] += tp[32 + (r & 3) + 8 * (r >> 2)]; }
;         }
;         float mx = max2f(max16f(p0), max16f(p1));
;         const bool first = (t == 0);
;         if (first || __any(mx > THR)) {
;             { auto rr = __builtin_amdgcn_permlane32_swap(__float_as_uint(mx), __float_as_uint(mx), false, false); mx = max2f(__uint_as_float(rr[0]), __uint_as_float(rr[1])); }
;             const float delta = first ? mx : fmaxf(mx, 0.f);
;             const float alpha = first ? 1.0f : __builtin_amdgcn_exp2f(-delta);
;             mu += delta; ls2 *= alpha;
;             if (!first) {
;                 asm volatile("" ::: "memory");
;                 scr[r32] = alpha;
;                 asm volatile("s_waitcnt lgkmcnt(0)" ::: "memory");
; #pragma unroll
;                 for (int g = 0; g < 4; ++g) { const f32x4 a4 = *(const LAS f32x4*)(scr + 8 * g + 4 * hi);
; #pragma unroll
;                     for (int d = 0; d < 4; ++d) { O[d][4 * g + 0] *= a4[0]; O[d][4 * g + 1] *= a4[1]; O[d][4 * g + 2] *= a4[2]; O[d][4 * g + 3] *= a4[3]; } }
;                 asm volatile("s_waitcnt lgkmcnt(0)" ::: "memory");
;             }
; #pragma unroll
.LatA_rareret_x3:
	s_waitcnt lgkmcnt(10)
	v_mfma_f32_32x32x16_bf16 v[20:35], v[84:87], v[132:135], v[20:35]
	ds_read_b64_tr_b16 v[132:133], v231 offset:20480
	ds_read_b64_tr_b16 v[134:135], v231 offset:22528
	v_exp_f32_e32 v188, v188
	v_exp_f32_e32 v189, v189
	v_mfma_f32_32x32x16_bf16 v[36:51], v[84:87], v[136:139], v[36:51]
	ds_read_b64_tr_b16 v[136:137], v228 offset:24576
	ds_read_b64_tr_b16 v[138:139], v228 offset:26624
	v_exp_f32_e32 v190, v190
	v_exp_f32_e32 v191, v191
	s_waitcnt lgkmcnt(10)
	v_mfma_f32_32x32x16_bf16 v[52:67], v[84:87], v[140:143], v[52:67]
	ds_read_b64_tr_b16 v[140:141], v229 offset:24576
	ds_read_b64_tr_b16 v[142:143], v229 offset:26624
	v_pk_add_f32 v[150:151], v[150:151], v[188:189]
	v_pk_add_f32 v[150:151], v[150:151], v[190:191]
	v_exp_f32_e32 v192, v192
	v_mfma_f32_32x32x16_bf16 v[68:83], v[84:87], v[144:147], v[68:83]
	ds_read_b64_tr_b16 v[144:145], v230 offset:24576
	ds_read_b64_tr_b16 v[146:147], v230 offset:26624
	v_exp_f32_e32 v193, v193
	v_cvt_pk_bf16_f32 v188, v188, v189
	v_cvt_pk_bf16_f32 v189, v190, v191
	s_waitcnt lgkmcnt(10)
	v_mfma_f32_32x32x16_bf16 v[20:35], v[88:91], v[220:223], v[20:35]
	ds_read_b64_tr_b16 v[220:221], v231 offset:24576
	ds_read_b64_tr_b16 v[222:223], v231 offset:26624
	v_exp_f32_e32 v194, v194
	v_exp_f32_e32 v195, v195
	v_mfma_f32_32x32x16_bf16 v[36:51], v[88:91], v[224:227], v[36:51]
	ds_read_b64_tr_b16 v[224:225], v228 offset:28672
	ds_read_b64_tr_b16 v[226:227], v228 offset:30720
	v_pk_add_f32 v[150:151], v[150:151], v[192:193]
	v_pk_add_f32 v[150:151], v[150:151], v[194:195]
	v_cvt_pk_bf16_f32 v190, v192, v193
	v_cvt_pk_bf16_f32 v191, v194, v195
	s_waitcnt lgkmcnt(10)
	v_mfma_f32_32x32x16_bf16 v[52:67], v[88:91], v[232:235], v[52:67]
	ds_read_b64_tr_b16 v[232:233], v229 offset:28672
	ds_read_b64_tr_b16 v[234:235], v229 offset:30720
	v_exp_f32_e32 v196, v196
	v_exp_f32_e32 v197, v197
	s_mov_b32 m0, s29
	v_mfma_f32_32x32x16_bf16 v[68:83], v[88:91], v[132:135], v[68:83]
	global_load_lds_dwordx4 v160, s[8:9]
	ds_read_b64_tr_b16 v[132:133], v230 offset:28672
	ds_read_b64_tr_b16 v[134:135], v230 offset:30720
	v_exp_f32_e32 v198, v198
	v_exp_f32_e32 v199, v199
	s_waitcnt lgkmcnt(10)
	v_mfma_f32_32x32x16_bf16 v[20:35], v[100:103], v[136:139], v[20:35]
	ds_read_b64_tr_b16 v[136:137], v231 offset:28672
	ds_read_b64_tr_b16 v[138:139], v231 offset:30720
	v_pk_add_f32 v[150:151], v[150:151], v[196:197]
	v_pk_add_f32 v[150:151], v[150:151], v[198:199]
	v_exp_f32_e32 v200, v200
	v_mfma_f32_32x32x16_bf16 v[36:51], v[100:103], v[140:143], v[36:51]
	ds_read_b128 v[140:143], v19
	v_exp_f32_e32 v201, v201
	v_cvt_pk_bf16_f32 v192, v196, v197
	v_cvt_pk_bf16_f32 v193, v198, v199
	s_waitcnt lgkmcnt(9)
	v_mfma_f32_32x32x16_bf16 v[52:67], v[100:103], v[144:147], v[52:67]
	ds_read_b128 v[144:147], v19 offset:8192
	v_exp_f32_e32 v202, v202
	v_exp_f32_e32 v203, v203
	v_mfma_f32_32x32x16_bf16 v[68:83], v[100:103], v[220:223], v[68:83]
	ds_read_b128 v[220:223], v180
	v_pk_add_f32 v[150:151], v[150:151], v[200:201]
	v_pk_add_f32 v[150:151], v[150:151], v[202:203]
	v_cvt_pk_bf16_f32 v194, v200, v201
	v_cvt_pk_bf16_f32 v195, v202, v203
	s_waitcnt lgkmcnt(7)
	v_mfma_f32_32x32x16_bf16 v[20:35], v[104:107], v[224:227], v[20:35]
	ds_read_b128 v[224:227], v180 offset:8192
	v_exp_f32_e32 v204, v204
	v_exp_f32_e32 v205, v205
	v_mfma_f32_32x32x16_bf16 v[36:51], v[104:107], v[232:235], v[36:51]
	ds_read_b128 v[232:235], v181
	v_exp_f32_e32 v206, v206
	v_exp_f32_e32 v207, v207
	s_waitcnt lgkmcnt(5)
	v_mfma_f32_32x32x16_bf16 v[52:67], v[104:107], v[132:135], v[52:67]
	ds_read_b128 v[132:135], v181 offset:8192
	v_pk_add_f32 v[150:151], v[150:151], v[204:205]
	v_pk_add_f32 v[150:151], v[150:151], v[206:207]
	v_exp_f32_e32 v208, v208
	s_add_u32 m0, s29, 0x2000
	v_mfma_f32_32x32x16_bf16 v[68:83], v[104:107], v[136:139], v[68:83]
	global_load_lds_dwordx4 v176, s[8:9]
	ds_read_b128 v[136:139], v182
	v_exp_f32_e32 v209, v209
	v_cvt_pk_bf16_f32 v204, v204, v205
	v_cvt_pk_bf16_f32 v205, v206, v207
	s_waitcnt lgkmcnt(5)
	v_mfma_f32_32x32x16_bf16 v[84:99], v[140:143], v[116:119], v[2:17]
	ds_read_b128 v[140:143], v182 offset:8192
	v_exp_f32_e32 v210, v210
	v_exp_f32_e32 v211, v211
	v_mfma_f32_32x32x16_bf16 v[100:115], v[144:147], v[116:119], v[2:17]
	v_pk_add_f32 v[150:151], v[150:151], v[208:209]
	v_pk_add_f32 v[150:151], v[150:151], v[210:211]
	v_cvt_pk_bf16_f32 v206, v208, v209
	v_cvt_pk_bf16_f32 v207, v210, v211
	s_waitcnt lgkmcnt(4)
	v_mfma_f32_32x32x16_bf16 v[84:99], v[220:223], v[120:123], v[84:99]
	v_exp_f32_e32 v212, v212
	v_exp_f32_e32 v213, v213
	v_mfma_f32_32x32x16_bf16 v[100:115], v[224:227], v[120:123], v[100:115]
	v_exp_f32_e32 v214, v214
	v_exp_f32_e32 v215, v215
	s_waitcnt lgkmcnt(2)
	v_mfma_f32_32x32x16_bf16 v[84:99], v[232:235], v[124:127], v[84:99]
	v_pk_add_f32 v[150:151], v[150:151], v[212:213]
	v_pk_add_f32 v[150:151], v[150:151], v[214:215]
	v_exp_f32_e32 v216, v216
	v_mfma_f32_32x32x16_bf16 v[100:115], v[132:135], v[124:127], v[100:115]
	v_exp_f32_e32 v217, v217
	v_cvt_pk_bf16_f32 v208, v212, v213
	v_cvt_pk_bf16_f32 v209, v214, v215
	s_waitcnt lgkmcnt(0)
	v_mfma_f32_32x32x16_bf16 v[84:99], v[136:139], v[128:131], v[84:99]
	v_exp_f32_e32 v218, v218
	v_exp_f32_e32 v219, v219
	v_mfma_f32_32x32x16_bf16 v[100:115], v[140:143], v[128:131], v[100:115]
	v_pk_add_f32 v[150:151], v[150:151], v[216:217]
	v_pk_add_f32 v[150:151], v[150:151], v[218:219]
	v_cvt_pk_bf16_f32 v210, v216, v217
	v_cvt_pk_bf16_f32 v211, v218, v219
	s_add_u32 s8, s8, 0x40000
	s_addc_u32 s9, s9, 0
	s_waitcnt vmcnt(2) lgkmcnt(0)
	s_barrier
	s_sub_u32 s10, s10, 1
	s_cbranch_scc1 .LatA_evs_x2

; #define LAS __attribute__((address_space(3)))
; __device__ __forceinline__ void attn_unit(LAS unsigned char* lds, const bf16_t* Z, bf16_t* A2, const float* tabg, int seq_base, int S, int h, int qb, float lam) {
;     ...
;             for (int ds = 0; ds < 4; ++ds) { kf[2 * ds] = *(const LAS bf16x8*)(Kt + (kfo ^ (unsigned)(ds << 5))); kf[2 * ds + 1] = *(const LAS bf16x8*)(Kt + 32 * 256 + (kfo ^ (unsigned)(ds << 5))); }
;             __builtin_amdgcn_sched_barrier(0);
;             p0 = __builtin_amdgcn_mfma_f32_32x32x16_bf16(kf[0], qf[0], cblk, 0, 0, 0);
;             p1 = __builtin_amdgcn_mfma_f32_32x32x16_bf16(kf[1], qf[0], cblk, 0, 0, 0);
; #pragma unroll
;             for (int ds = 1; ds < 4; ++ds) {
;                 p0 = __builtin_amdgcn_mfma_f32_32x32x16_bf16(kf[2 * ds], qf[ds], p0, 0, 0, 0);
;                 p1 = __builtin_amdgcn_mfma_f32_32x32x16_bf16(kf[2 * ds + 1], qf[ds], p1, 0, 0, 0);
;             }
;         }
;     ...
;         const unsigned vbase = (unsigned)(size_t)Vt + vfo;
;         s16x4 va[8], vb[8];
;         VREADS1(va, 0);
;         if (near) {
;             const LAS float* tp = tab + (kv0 + 4 * hi - (qlo + r32) + 224);
; #pragma unroll
;             for (int r = 0; r < 16; ++r) { p0[r] += tp[(r & 3) + 8 * (r >> 2)]; p1[r] += tp[32 + (r & 3) + 8 * (r >> 2)]; }
;         }
;         float mx = max2f(max16f(p0), max16f(p1));
;         const bool first = (t == 0);
;         if (first || __any(mx > THR)) {
;             { auto rr = __builtin_amdgcn_permlane32_swap(__float_as_uint(mx), __float_as_uint(mx), false, false); mx = max2f(__uint_as_float(rr[0]), __uint_as_float(rr[1])); }
;             const float delta = first ? mx : fmaxf(mx, 0.f);
;             const float alpha = first ? 1.0f : __builtin_amdgcn_exp2f(-delta);
;             mu += delta; ls2 *= alpha;
;             if (!first) {
;                 asm volatile("" ::: "memory");
;                 scr[r32] = alpha;
;                 asm volatile("s_waitcnt lgkmcnt(0)" ::: "memory");
; #pragma unroll
;                 for (int g = 0; g < 4; ++g) { const f32x4 a4 = *(const LAS f32x4*)(scr + 8 * g + 4 * hi);
; #pragma unroll
;                     for (int d = 0; d < 4; ++d) { O[d][4 * g + 0] *= a4[0]; O[d][4 * g + 1] *= a4[1]; O[d][4 * g + 2] *= a4[2]; O[d][4 * g + 3] *= a4[3]; } }
;                 asm volatile("s_waitcnt lgkmcnt(0)" ::: "memory");
;             }
; #pragma unroll
.LatA_rareret_x2:
	s_waitcnt lgkmcnt(10)
	v_mfma_f32_32x32x16_bf16 v[20:35], v[188:191], v[132:135], v[20:35]
	ds_read_b64_tr_b16 v[132:133], v231 offset:36864
	ds_read_b64_tr_b16 v[134:135], v231 offset:38912
	v_exp_f32_e32 v84, v84
	v_exp_f32_e32 v85, v85
	v_mfma_f32_32x32x16_bf16 v[36:51], v[188:191], v[136:139], v[36:51]
	ds_read_b64_tr_b16 v[136:137], v228 offset:40960
	ds_read_b64_tr_b16 v[138:139], v228 offset:43008
	v_exp_f32_e32 v86, v86
	v_exp_f32_e32 v87, v87
	s_waitcnt lgkmcnt(10)
	v_mfma_f32_32x32x16_bf16 v[52:67], v[188:191], v[140:143], v[52:67]
	ds_read_b64_tr_b16 v[140:141], v229 offset:40960
	ds_read_b64_tr_b16 v[142:143], v229 offset:43008
	v_pk_add_f32 v[150:151], v[150:151], v[84:85]
	v_pk_add_f32 v[150:151], v[150:151], v[86:87]
	v_exp_f32_e32 v88, v88
	v_mfma_f32_32x32x16_bf16 v[68:83], v[188:191], v[144:147], v[68:83]
	ds_read_b64_tr_b16 v[144:145], v230 offset:40960
	ds_read_b64_tr_b16 v[146:147], v230 offset:43008
	v_exp_f32_e32 v89, v89
	v_cvt_pk_bf16_f32 v84, v84, v85
	v_cvt_pk_bf16_f32 v85, v86, v87
	s_waitcnt lgkmcnt(10)
	v_mfma_f32_32x32x16_bf16 v[20:35], v[192:195], v[220:223], v[20:35]
	ds_read_b64_tr_b16 v[220:221], v231 offset:40960
	ds_read_b64_tr_b16 v[222:223], v231 offset:43008
	v_exp_f32_e32 v90, v90
	v_exp_f32_e32 v91, v91
	v_mfma_f32_32x32x16_bf16 v[36:51], v[192:195], v[224:227], v[36:51]
	ds_read_b64_tr_b16 v[224:225], v228 offset:45056
	ds_read_b64_tr_b16 v[226:227], v228 offset:47104
	v_pk_add_f32 v[150:151], v[150:151], v[88:89]
	v_pk_add_f32 v[150:151], v[150:151], v[90:91]
	v_cvt_pk_bf16_f32 v86, v88, v89
	v_cvt_pk_bf16_f32 v87, v90, v91
	s_waitcnt lgkmcnt(10)
	v_mfma_f32_32x32x16_bf16 v[52:67], v[192:195], v[232:235], v[52:67]
	ds_read_b64_tr_b16 v[232:233], v229 offset:45056
	ds_read_b64_tr_b16 v[234:235], v229 offset:47104
	v_exp_f32_e32 v92, v92
	v_exp_f32_e32 v93, v93
	s_add_u32 m0, s29, 0x4000
	v_mfma_f32_32x32x16_bf16 v[68:83], v[192:195], v[132:135], v[68:83]
	global_load_lds_dwordx4 v160, s[8:9]
	ds_read_b64_tr_b16 v[132:133], v230 offset:45056
	ds_read_b64_tr_b16 v[134:135], v230 offset:47104
	v_exp_f32_e32 v94, v94
	v_exp_f32_e32 v95, v95
	s_waitcnt lgkmcnt(10)
	v_mfma_f32_32x32x16_bf16 v[20:35], v[204:207], v[136:139], v[20:35]
	ds_read_b64_tr_b16 v[136:137], v231 offset:45056
	ds_read_b64_tr_b16 v[138:139], v231 offset:47104
	v_pk_add_f32 v[150:151], v[150:151], v[92:93]
	v_pk_add_f32 v[150:151], v[150:151], v[94:95]
	v_exp_f32_e32 v96, v96
	v_mfma_f32_32x32x16_bf16 v[36:51], v[204:207], v[140:143], v[36:51]
	ds_read_b128 v[140:143], v19 offset:16384
	v_exp_f32_e32 v97, v97
	v_cvt_pk_bf16_f32 v88, v92, v93
	v_cvt_pk_bf16_f32 v89, v94, v95
	s_waitcnt lgkmcnt(9)
	v_mfma_f32_32x32x16_bf16 v[52:67], v[204:207], v[144:147], v[52:67]
	ds_read_b128 v[144:147], v19 offset:24576
	v_exp_f32_e32 v98, v98
	v_exp_f32_e32 v99, v99
	v_mfma_f32_32x32x16_bf16 v[68:83], v[204:207], v[220:223], v[68:83]
	ds_read_b128 v[220:223], v180 offset:16384
	v_pk_add_f32 v[150:151], v[150:151], v[96:97]
	v_pk_add_f32 v[150:151], v[150:151], v[98:99]
	v_cvt_pk_bf16_f32 v90, v96, v97
	v_cvt_pk_bf16_f32 v91, v98, v99
	s_waitcnt lgkmcnt(7)
	v_mfma_f32_32x32x16_bf16 v[20:35], v[208:211], v[224:227], v[20:35]
	ds_read_b128 v[224:227], v180 offset:24576
	v_exp_f32_e32 v100, v100
	v_exp_f32_e32 v101, v101
	v_mfma_f32_32x32x16_bf16 v[36:51], v[208:211], v[232:235], v[36:51]
	ds_read_b128 v[232:235], v181 offset:16384
	v_exp_f32_e32 v102, v102
	v_exp_f32_e32 v103, v103
	s_waitcnt lgkmcnt(5)
	v_mfma_f32_32x32x16_bf16 v[52:67], v[208:211], v[132:135], v[52:67]
	ds_read_b128 v[132:135], v181 offset:24576
	v_pk_add_f32 v[150:151], v[150:151], v[100:101]
	v_pk_add_f32 v[150:151], v[150:151], v[102:103]
	v_exp_f32_e32 v104, v104
	s_add_u32 m0, s29, 0x6000
	v_mfma_f32_32x32x16_bf16 v[68:83], v[208:211], v[136:139], v[68:83]
	global_load_lds_dwordx4 v176, s[8:9]
	ds_read_b128 v[136:139], v182 offset:16384
	v_exp_f32_e32 v105, v105
	v_cvt_pk_bf16_f32 v100, v100, v101
	v_cvt_pk_bf16_f32 v101, v102, v103
	s_waitcnt lgkmcnt(5)
	v_mfma_f32_32x32x16_bf16 v[188:203], v[140:143], v[116:119], v[2:17]
	ds_read_b128 v[140:143], v182 offset:24576
	v_exp_f32_e32 v106, v106
	v_exp_f32_e32 v107, v107
	v_mfma_f32_32x32x16_bf16 v[204:219], v[144:147], v[116:119], v[2:17]
	v_pk_add_f32 v[150:151], v[150:151], v[104:105]
	v_pk_add_f32 v[150:151], v[150:151], v[106:107]
	v_cvt_pk_bf16_f32 v102, v104, v105
	v_cvt_pk_bf16_f32 v103, v106, v107
	s_waitcnt lgkmcnt(4)
	v_mfma_f32_32x32x16_bf16 v[188:203], v[220:223], v[120:123], v[188:203]
	v_exp_f32_e32 v108, v108
	v_exp_f32_e32 v109, v109
	v_mfma_f32_32x32x16_bf16 v[204:219], v[224:227], v[120:123], v[204:219]
	v_exp_f32_e32 v110, v110
	v_exp_f32_e32 v111, v111
	s_waitcnt lgkmcnt(2)
	v_mfma_f32_32x32x16_bf16 v[188:203], v[232:235], v[124:127], v[188:203]
	v_pk_add_f32 v[150:151], v[150:151], v[108:109]
	v_pk_add_f32 v[150:151], v[150:151], v[110:111]
	v_exp_f32_e32 v112, v112
	v_mfma_f32_32x32x16_bf16 v[204:219], v[132:135], v[124:127], v[204:219]
	v_exp_f32_e32 v113, v113
	v_cvt_pk_bf16_f32 v104, v108, v109
	v_cvt_pk_bf16_f32 v105, v110, v111
	s_waitcnt lgkmcnt(0)
	v_mfma_f32_32x32x16_bf16 v[188:203], v[136:139], v[128:131], v[188:203]
	v_exp_f32_e32 v114, v114
	v_exp_f32_e32 v115, v115
	v_mfma_f32_32x32x16_bf16 v[204:219], v[140:143], v[128:131], v[204:219]
	v_pk_add_f32 v[150:151], v[150:151], v[112:113]
	v_pk_add_f32 v[150:151], v[150:151], v[114:115]
	v_cvt_pk_bf16_f32 v106, v112, v113
	v_cvt_pk_bf16_f32 v107, v114, v115
	s_add_u32 s8, s8, 0x40000
	s_addc_u32 s9, s9, 0
	s_waitcnt vmcnt(2) lgkmcnt(0)
	s_barrier
	s_sub_u32 s10, s10, 1
	s_cbranch_scc1 .LatA_evs_x1

; #define LAS __attribute__((address_space(3)))
; __device__ __forceinline__ void attn_unit(LAS unsigned char* lds, const bf16_t* Z, bf16_t* A2, const float* tabg, int seq_base, int S, int h, int qb, float lam) {
;     ...
;         const unsigned vbase = (unsigned)(size_t)Vt + vfo;
;         s16x4 va[8], vb[8];
;         VREADS1(va, 0);
;         if (near) {
;             const LAS float* tp = tab + (kv0 + 4 * hi - (qlo + r32) + 224);
; #pragma unroll
;             for (int r = 0; r < 16; ++r) { p0[r] += tp[(r & 3) + 8 * (r >> 2)]; p1[r] += tp[32 + (r & 3) + 8 * (r >> 2)]; }
;         }
;         float mx = max2f(max16f(p0), max16f(p1));
;         const bool first = (t == 0);
;         if (first || __any(mx > THR)) {
;             { auto rr = __builtin_amdgcn_permlane32_swap(__float_as_uint(mx), __float_as_uint(mx), false, false); mx = max2f(__uint_as_float(rr[0]), __uint_as_float(rr[1])); }
;             const float delta = first ? mx : fmaxf(mx, 0.f);
;             const float alpha = first ? 1.0f : __builtin_amdgcn_exp2f(-delta);
;             mu += delta; ls2 *= alpha;
;             if (!first) {
;                 asm volatile("" ::: "memory");
;                 scr[r32] = alpha;
;                 asm volatile("s_waitcnt lgkmcnt(0)" ::: "memory");
; #pragma unroll
;                 for (int g = 0; g < 4; ++g) { const f32x4 a4 = *(const LAS f32x4*)(scr + 8 * g + 4 * hi);
; #pragma unroll
;                     for (int d = 0; d < 4; ++d) { O[d][4 * g + 0] *= a4[0]; O[d][4 * g + 1] *= a4[1]; O[d][4 * g + 2] *= a4[2]; O[d][4 * g + 3] *= a4[3]; } }
;                 asm volatile("s_waitcnt lgkmcnt(0)" ::: "memory");
;             }
; #pragma unroll
;             for (int r = 0; r < 16; ++r) { p0[r] -= delta; p1[r] -= delta; }
;             asm volatile("" : "+v"(p0), "+v"(p1));
;         }
; #pragma unroll
;         for (int r = 0; r < 16; ++r) { p0[r] = __builtin_amdgcn_exp2f(p0[r]); p1[r] = __builtin_amdgcn_exp2f(p1[r]); }
; #pragma unroll
;         for (int r = 0; r < 16; r += 2) { ls2 += (f32x2){p0[r], p0[r + 1]}; ls2 += (f32x2){p1[r], p1[r + 1]}; }
;         bf16x8 pa[4]; pa[0] = pack8(p0, 0); pa[1] = pack8(p0, 8); pa[2] = pack8(p1, 0); pa[3] = pack8(p1, 8);
;         LGKM0(); VREADS1(vb, 1); PV1(va, 0); LGKM0(); VREADS1(va, 2); PV1(vb, 1); LGKM0(); VREADS1(vb, 3); PV1(va, 2); LGKM0(); PV1(vb, 3);
.LatA_rareret_x1:
	s_waitcnt lgkmcnt(10)
	v_mfma_f32_32x32x16_bf16 v[20:35], v[84:87], v[132:135], v[20:35]
	ds_read_b64_tr_b16 v[132:133], v231 offset:4096
	ds_read_b64_tr_b16 v[134:135], v231 offset:6144
	v_exp_f32_e32 v188, v188
	v_exp_f32_e32 v189, v189
	v_exp_f32_e32 v190, v190
	v_mfma_f32_32x32x16_bf16 v[36:51], v[84:87], v[136:139], v[36:51]
	ds_read_b64_tr_b16 v[136:137], v228 offset:8192
	ds_read_b64_tr_b16 v[138:139], v228 offset:10240
	v_exp_f32_e32 v191, v191
	v_pk_add_f32 v[150:151], v[150:151], v[188:189]
	v_pk_add_f32 v[150:151], v[150:151], v[190:191]
	v_exp_f32_e32 v192, v192
	s_waitcnt lgkmcnt(10)
	v_mfma_f32_32x32x16_bf16 v[52:67], v[84:87], v[140:143], v[52:67]
	ds_read_b64_tr_b16 v[140:141], v229 offset:8192
	ds_read_b64_tr_b16 v[142:143], v229 offset:10240
	v_exp_f32_e32 v193, v193
	v_cvt_pk_bf16_f32 v188, v188, v189
	v_cvt_pk_bf16_f32 v189, v190, v191
	v_exp_f32_e32 v194, v194
	v_mfma_f32_32x32x16_bf16 v[68:83], v[84:87], v[144:147], v[68:83]
	ds_read_b64_tr_b16 v[144:145], v230 offset:8192
	ds_read_b64_tr_b16 v[146:147], v230 offset:10240
	v_exp_f32_e32 v195, v195
	v_pk_add_f32 v[150:151], v[150:151], v[192:193]
	v_pk_add_f32 v[150:151], v[150:151], v[194:195]
	v_cvt_pk_bf16_f32 v190, v192, v193
	v_cvt_pk_bf16_f32 v191, v194, v195
	s_waitcnt lgkmcnt(10)
	v_mfma_f32_32x32x16_bf16 v[20:35], v[88:91], v[220:223], v[20:35]
	ds_read_b64_tr_b16 v[220:221], v231 offset:8192
	ds_read_b64_tr_b16 v[222:223], v231 offset:10240
	v_exp_f32_e32 v196, v196
	v_exp_f32_e32 v197, v197
	v_exp_f32_e32 v198, v198
	v_mfma_f32_32x32x16_bf16 v[36:51], v[88:91], v[224:227], v[36:51]
	ds_read_b64_tr_b16 v[224:225], v228 offset:12288
	ds_read_b64_tr_b16 v[226:227], v228 offset:14336
	v_exp_f32_e32 v199, v199
	v_pk_add_f32 v[150:151], v[150:151], v[196:197]
	v_pk_add_f32 v[150:151], v[150:151], v[198:199]
	v_exp_f32_e32 v200, v200
	s_waitcnt lgkmcnt(10)
	v_mfma_f32_32x32x16_bf16 v[52:67], v[88:91], v[232:235], v[52:67]
	ds_read_b64_tr_b16 v[232:233], v229 offset:12288
	ds_read_b64_tr_b16 v[234:235], v229 offset:14336
	v_exp_f32_e32 v201, v201
	v_cvt_pk_bf16_f32 v192, v196, v197
	v_cvt_pk_bf16_f32 v193, v198, v199
	v_exp_f32_e32 v202, v202
	v_mfma_f32_32x32x16_bf16 v[68:83], v[88:91], v[132:135], v[68:83]
	ds_read_b64_tr_b16 v[132:133], v230 offset:12288
	ds_read_b64_tr_b16 v[134:135], v230 offset:14336
	v_exp_f32_e32 v203, v203
	v_pk_add_f32 v[150:151], v[150:151], v[200:201]
	v_pk_add_f32 v[150:151], v[150:151], v[202:203]
	v_cvt_pk_bf16_f32 v194, v200, v201
	v_cvt_pk_bf16_f32 v195, v202, v203
	s_waitcnt lgkmcnt(10)
	v_mfma_f32_32x32x16_bf16 v[20:35], v[100:103], v[136:139], v[20:35]
	ds_read_b64_tr_b16 v[136:137], v231 offset:12288
	ds_read_b64_tr_b16 v[138:139], v231 offset:14336
	v_exp_f32_e32 v204, v204
	v_exp_f32_e32 v205, v205
	v_exp_f32_e32 v206, v206
	v_mfma_f32_32x32x16_bf16 v[36:51], v[100:103], v[140:143], v[36:51]
	v_exp_f32_e32 v207, v207
	v_pk_add_f32 v[150:151], v[150:151], v[204:205]
	v_pk_add_f32 v[150:151], v[150:151], v[206:207]
	v_exp_f32_e32 v208, v208
	s_waitcnt lgkmcnt(8)
	v_mfma_f32_32x32x16_bf16 v[52:67], v[100:103], v[144:147], v[52:67]
	v_exp_f32_e32 v209, v209
	v_cvt_pk_bf16_f32 v204, v204, v205
	v_cvt_pk_bf16_f32 v205, v206, v207
	v_exp_f32_e32 v210, v210
	v_mfma_f32_32x32x16_bf16 v[68:83], v[100:103], v[220:223], v[68:83]
	v_exp_f32_e32 v211, v211
	v_pk_add_f32 v[150:151], v[150:151], v[208:209]
	v_pk_add_f32 v[150:151], v[150:151], v[210:211]
	v_cvt_pk_bf16_f32 v206, v208, v209
	v_cvt_pk_bf16_f32 v207, v210, v211
	s_waitcnt lgkmcnt(4)
	v_mfma_f32_32x32x16_bf16 v[20:35], v[104:107], v[224:227], v[20:35]
	v_exp_f32_e32 v212, v212
	v_exp_f32_e32 v213, v213
	v_exp_f32_e32 v214, v214
	v_mfma_f32_32x32x16_bf16 v[36:51], v[104:107], v[232:235], v[36:51]
	v_exp_f32_e32 v215, v215
	v_pk_add_f32 v[150:151], v[150:151], v[212:213]
	v_pk_add_f32 v[150:151], v[150:151], v[214:215]
	v_exp_f32_e32 v216, v216
	s_waitcnt lgkmcnt(0)
	v_mfma_f32_32x32x16_bf16 v[52:67], v[104:107], v[132:135], v[52:67]
	v_exp_f32_e32 v217, v217
	v_cvt_pk_bf16_f32 v208, v212, v213
	v_cvt_pk_bf16_f32 v209, v214, v215
	v_exp_f32_e32 v218, v218
	v_mfma_f32_32x32x16_bf16 v[68:83], v[104:107], v[136:139], v[68:83]
	v_exp_f32_e32 v219, v219
	v_pk_add_f32 v[150:151], v[150:151], v[216:217]
	v_pk_add_f32 v[150:151], v[150:151], v[218:219]
	v_cvt_pk_bf16_f32 v210, v216, v217
	v_cvt_pk_bf16_f32 v211, v218, v219
	s_add_u32 s8, s8, 0x40000
	s_addc_u32 s9, s9, 0
	s_waitcnt vmcnt(0) lgkmcnt(0)
	s_barrier
; #define LAS __attribute__((address_space(3)))
; __device__ __forceinline__ void attn_unit(LAS unsigned char* lds, const bf16_t* Z, bf16_t* A2, const float* tabg, int seq_base, int S, int h, int qb, float lam) {
;     ...
;         const unsigned vbase = (unsigned)(size_t)Vt + vfo;
;         s16x4 va[8], vb[8];
;         VREADS1(va, 0);
;         if (near) {
;             const LAS float* tp = tab + (kv0 + 4 * hi - (qlo + r32) + 224);
; #pragma unroll
;             for (int r = 0; r < 16; ++r) { p0[r] += tp[(r & 3) + 8 * (r >> 2)]; p1[r] += tp[32 + (r & 3) + 8 * (r >> 2)]; }
;         }
;         float mx = max2f(max16f(p0), max16f(p1));
;         const bool first = (t == 0);
;         if (first || __any(mx > THR)) {
;             { auto rr = __builtin_amdgcn_permlane32_swap(__float_as_uint(mx), __float_as_uint(mx), false, false); mx = max2f(__uint_as_float(rr[0]), __uint_as_float(rr[1])); }
;             const float delta = first ? mx : fmaxf(mx, 0.f);
;             const float alpha = first ? 1.0f : __builtin_amdgcn_exp2f(-delta);
;             mu += delta; ls2 *= alpha;
;             if (!first) {
;                 asm volatile("" ::: "memory");
;                 scr[r32] = alpha;
;                 asm volatile("s_waitcnt lgkmcnt(0)" ::: "memory");
; #pragma unroll
;                 for (int g = 0; g < 4; ++g) { const f32x4 a4 = *(const LAS f32x4*)(scr + 8 * g + 4 * hi);
; #pragma unroll
;                     for (int d = 0; d < 4; ++d) { O[d][4 * g + 0] *= a4[0]; O[d][4 * g + 1] *= a4[1]; O[d][4 * g + 2] *= a4[2]; O[d][4 * g + 3] *= a4[3]; } }
;                 asm volatile("s_waitcnt lgkmcnt(0)" ::: "memory");
;             }
; #pragma unroll
;             for (int r = 0; r < 16; ++r) { p0[r] -= delta; p1[r] -= delta; }
;             asm volatile("" : "+v"(p0), "+v"(p1));
;         }
; #pragma unroll
;         for (int r = 0; r < 16; ++r) { p0[r] = __builtin_amdgcn_exp2f(p0[r]); p1[r] = __builtin_amdgcn_exp2f(p1[r]); }
; #pragma unroll
;         for (int r = 0; r < 16; r += 2) { ls2 += (f32x2){p0[r], p0[r + 1]}; ls2 += (f32x2){p1[r], p1[r + 1]}; }
;         bf16x8 pa[4]; pa[0] = pack8(p0, 0); pa[1] = pack8(p0, 8); pa[2] = pack8(p1, 0); pa[3] = pack8(p1, 8);
;         LGKM0(); VREADS1(vb, 1); PV1(va, 0); LGKM0(); VREADS1(va, 2); PV1(vb, 1); LGKM0(); VREADS1(vb, 3); PV1(va, 2); LGKM0(); PV1(vb, 3);
	ds_read_b64_tr_b16 v[132:133], v228 offset:16384
	ds_read_b64_tr_b16 v[134:135], v228 offset:18432
	ds_read_b64_tr_b16 v[136:137], v229 offset:16384
	ds_read_b64_tr_b16 v[138:139], v229 offset:18432
	ds_read_b64_tr_b16 v[140:141], v230 offset:16384
	ds_read_b64_tr_b16 v[142:143], v230 offset:18432
	ds_read_b64_tr_b16 v[144:145], v231 offset:16384
	ds_read_b64_tr_b16 v[146:147], v231 offset:18432
	ds_read_b64_tr_b16 v[220:221], v228 offset:20480
	ds_read_b64_tr_b16 v[222:223], v228 offset:22528
	ds_read_b64_tr_b16 v[224:225], v229 offset:20480
	ds_read_b64_tr_b16 v[226:227], v229 offset:22528
	ds_read_b64_tr_b16 v[232:233], v230 offset:20480
	ds_read_b64_tr_b16 v[234:235], v230 offset:22528
	s_waitcnt lgkmcnt(10)
	v_mfma_f32_32x32x16_bf16 v[20:35], v[188:191], v[132:135], v[20:35]
	ds_read_b64_tr_b16 v[132:133], v231 offset:20480
	ds_read_b64_tr_b16 v[134:135], v231 offset:22528
	v_mfma_f32_32x32x16_bf16 v[36:51], v[188:191], v[136:139], v[36:51]
	ds_read_b64_tr_b16 v[136:137], v228 offset:24576
	ds_read_b64_tr_b16 v[138:139], v228 offset:26624
	s_waitcnt lgkmcnt(10)
	v_mfma_f32_32x32x16_bf16 v[52:67], v[188:191], v[140:143], v[52:67]
	ds_read_b64_tr_b16 v[140:141], v229 offset:24576
	ds_read_b64_tr_b16 v[142:143], v229 offset:26624
	v_mfma_f32_32x32x16_bf16 v[68:83], v[188:191], v[144:147], v[68:83]
	ds_read_b64_tr_b16 v[144:145], v230 offset:24576
	ds_read_b64_tr_b16 v[146:147], v230 offset:26624
	s_waitcnt lgkmcnt(10)
	v_mfma_f32_32x32x16_bf16 v[20:35], v[192:195], v[220:223], v[20:35]
	ds_read_b64_tr_b16 v[220:221], v231 offset:24576
	ds_read_b64_tr_b16 v[222:223], v231 offset:26624
	v_mfma_f32_32x32x16_bf16 v[36:51], v[192:195], v[224:227], v[36:51]
	ds_read_b64_tr_b16 v[224:225], v228 offset:28672
	ds_read_b64_tr_b16 v[226:227], v228 offset:30720
	s_waitcnt lgkmcnt(10)
	v_mfma_f32_32x32x16_bf16 v[52:67], v[192:195], v[232:235], v[52:67]
	ds_read_b64_tr_b16 v[232:233], v229 offset:28672
	ds_read_b64_tr_b16 v[234:235], v229 offset:30720
	v_mfma_f32_32x32x16_bf16 v[68:83], v[192:195], v[132:135], v[68:83]
	ds_read_b64_tr_b16 v[132:133], v230 offset:28672
	ds_read_b64_tr_b16 v[134:135], v230 offset:30720
	s_waitcnt lgkmcnt(10)
	v_mfma_f32_32x32x16_bf16 v[20:35], v[204:207], v[136:139], v[20:35]
	ds_read_b64_tr_b16 v[136:137], v231 offset:28672
	ds_read_b64_tr_b16 v[138:139], v231 offset:30720
	v_mfma_f32_32x32x16_bf16 v[36:51], v[204:207], v[140:143], v[36:51]
	s_waitcnt lgkmcnt(8)
	v_mfma_f32_32x32x16_bf16 v[52:67], v[204:207], v[144:147], v[52:67]
	v_mfma_f32_32x32x16_bf16 v[68:83], v[204:207], v[220:223], v[68:83]
	s_waitcnt lgkmcnt(4)
	v_mfma_f32_32x32x16_bf16 v[20:35], v[208:211], v[224:227], v[20:35]
	v_mfma_f32_32x32x16_bf16 v[36:51], v[208:211], v[232:235], v[36:51]
	s_waitcnt lgkmcnt(0)
	v_mfma_f32_32x32x16_bf16 v[52:67], v[208:211], v[132:135], v[52:67]
	v_mfma_f32_32x32x16_bf16 v[68:83], v[208:211], v[136:139], v[68:83]
	s_waitcnt lgkmcnt(0)
	s_barrier
	s_mov_b32 m0, s32
	s_nop 15
	s_branch .LatA_done
.LatA_rs_h0:
	s_mov_b32 s42, 0
	s_branch .LatA_rare_001

; __device__ __forceinline__ void attn_unit(LAS unsigned char* lds, const bf16_t* Z, bf16_t* A2, const float* tabg, int seq_base, int S, int h, int qb, float lam) {
;     ...
;         bool near = true; float cc = 0.f;
;         if (kv0 - (qlo + 31) >= 128) { near = false; cc = tabR; } else if (qlo - (kv0 + 63) >= 128) { near = false; cc = tabL; }
;         { const float coff = cc - mu;
;           if (__any(!(coff == coff_cur))) { coff_cur = coff;
; #pragma unroll
;               for (int r = 0; r < 16; ++r) cblk[r] = coff;
;               asm volatile("" : "+v"(cblk)); } }
.LatA_evs_h3:
	s_mov_b32 s42, 1
	s_branch .LatA_ev_11

; __device__ __forceinline__ void attn_unit(LAS unsigned char* lds, const bf16_t* Z, bf16_t* A2, const float* tabg, int seq_base, int S, int h, int qb, float lam) {
;     ...
;         bool near = true; float cc = 0.f;
;         if (kv0 - (qlo + 31) >= 128) { near = false; cc = tabR; } else if (qlo - (kv0 + 63) >= 128) { near = false; cc = tabL; }
;         { const float coff = cc - mu;
;           if (__any(!(coff == coff_cur))) { coff_cur = coff;
; #pragma unroll
;               for (int r = 0; r < 16; ++r) cblk[r] = coff;
;               asm volatile("" : "+v"(cblk)); } }
.LatA_evs_m1:
	s_mov_b32 s42, 2
	s_branch .LatA_ev_11

; __device__ __forceinline__ void attn_unit(LAS unsigned char* lds, const bf16_t* Z, bf16_t* A2, const float* tabg, int seq_base, int S, int h, int qb, float lam) {
;     ...
;         bool near = true; float cc = 0.f;
;         if (kv0 - (qlo + 31) >= 128) { near = false; cc = tabR; } else if (qlo - (kv0 + 63) >= 128) { near = false; cc = tabL; }
;         { const float coff = cc - mu;
;           if (__any(!(coff == coff_cur))) { coff_cur = coff;
; #pragma unroll
;               for (int r = 0; r < 16; ++r) cblk[r] = coff;
;               asm volatile("" : "+v"(cblk)); } }
.LatA_evs_m3:
	s_mov_b32 s42, 3
	s_branch .LatA_ev_11

; __device__ __forceinline__ void attn_unit(LAS unsigned char* lds, const bf16_t* Z, bf16_t* A2, const float* tabg, int seq_base, int S, int h, int qb, float lam) {
;     ...
;         bool near = true; float cc = 0.f;
;         if (kv0 - (qlo + 31) >= 128) { near = false; cc = tabR; } else if (qlo - (kv0 + 63) >= 128) { near = false; cc = tabL; }
;         { const float coff = cc - mu;
;           if (__any(!(coff == coff_cur))) { coff_cur = coff;
; #pragma unroll
;               for (int r = 0; r < 16; ++r) cblk[r] = coff;
;               asm volatile("" : "+v"(cblk)); } }
.LatA_evs_m5:
	s_mov_b32 s42, 4
	s_branch .LatA_ev_11

; __device__ __forceinline__ void attn_unit(LAS unsigned char* lds, const bf16_t* Z, bf16_t* A2, const float* tabg, int seq_base, int S, int h, int qb, float lam) {
;     ...
;         bool near = true; float cc = 0.f;
;         if (kv0 - (qlo + 31) >= 128) { near = false; cc = tabR; } else if (qlo - (kv0 + 63) >= 128) { near = false; cc = tabL; }
;         { const float coff = cc - mu;
;           if (__any(!(coff == coff_cur))) { coff_cur = coff;
; #pragma unroll
;               for (int r = 0; r < 16; ++r) cblk[r] = coff;
;               asm volatile("" : "+v"(cblk)); } }
.LatA_evs_x3:
	s_mov_b32 s42, 5
	s_branch .LatA_ev_11

; #define LAS __attribute__((address_space(3)))
; __device__ __forceinline__ void attn_unit(LAS unsigned char* lds, const bf16_t* Z, bf16_t* A2, const float* tabg, int seq_base, int S, int h, int qb, float lam) {
;     ...
;         bool near = true; float cc = 0.f;
;         if (kv0 - (qlo + 31) >= 128) { near = false; cc = tabR; } else if (qlo - (kv0 + 63) >= 128) { near = false; cc = tabL; }
;         { const float coff = cc - mu;
;           if (__any(!(coff == coff_cur))) { coff_cur = coff;
; #pragma unroll
;               for (int r = 0; r < 16; ++r) cblk[r] = coff;
;               asm volatile("" : "+v"(cblk)); } }
;     ...
;         if (near) {
;             const LAS float* tp = tab + (kv0 + 4 * hi - (qlo + r32) + 224);
; #pragma unroll
;             for (int r = 0; r < 16; ++r) { p0[r] += tp[(r & 3) + 8 * (r >> 2)]; p1[r] += tp[32 + (r & 3) + 8 * (r >> 2)]; }
;         }
.LatA_ev_11:
	s_sub_u32 s5, s8, s4
	s_lshr_b32 s5, s5, 12
	s_sub_u32 s5, s5, 64
	s_cmp_ge_u32 s5, s11
	s_cselect_b32 s37, 1, 0
	s_cmp_le_u32 s5, s31
	s_cselect_b32 s38, 1, 0
	s_and_b32 s37, s37, s38
	s_add_u32 s38, s5, 64
	s_cmp_le_u32 s38, s31
	s_cselect_b32 s10, 0, 0x7fffffff
	s_cmp_eq_u32 s37, 0
	s_cbranch_scc1 .LatA_evnn_11
	s_lshl_b32 s38, s5, 2
	s_add_i32 s38, s38, 0x18b80
	v_add_u32_e32 v187, s38, v162
	ds_read2_b32 v[132:133], v187 offset0:0 offset1:1
	ds_read2_b32 v[134:135], v187 offset0:2 offset1:3
	ds_read2_b32 v[136:137], v187 offset0:8 offset1:9
	ds_read2_b32 v[138:139], v187 offset0:10 offset1:11
	s_waitcnt lgkmcnt(0)
	v_pk_add_f32 v[188:189], v[188:189], v[132:133]
	v_pk_add_f32 v[190:191], v[190:191], v[134:135]
	v_pk_add_f32 v[192:193], v[192:193], v[136:137]
	v_pk_add_f32 v[194:195], v[194:195], v[138:139]
	ds_read2_b32 v[132:133], v187 offset0:16 offset1:17
	ds_read2_b32 v[134:135], v187 offset0:18 offset1:19
	ds_read2_b32 v[136:137], v187 offset0:24 offset1:25
	ds_read2_b32 v[138:139], v187 offset0:26 offset1:27
	s_waitcnt lgkmcnt(0)
	v_pk_add_f32 v[196:197], v[196:197], v[132:133]
	v_pk_add_f32 v[198:199], v[198:199], v[134:135]
	v_pk_add_f32 v[200:201], v[200:201], v[136:137]
	v_pk_add_f32 v[202:203], v[202:203], v[138:139]
	ds_read2_b32 v[132:133], v187 offset0:32 offset1:33
	ds_read2_b32 v[134:135], v187 offset0:34 offset1:35
	ds_read2_b32 v[136:137], v187 offset0:40 offset1:41
	ds_read2_b32 v[138:139], v187 offset0:42 offset1:43
	s_waitcnt lgkmcnt(0)
	v_pk_add_f32 v[204:205], v[204:205], v[132:133]
	v_pk_add_f32 v[206:207], v[206:207], v[134:135]
	v_pk_add_f32 v[208:209], v[208:209], v[136:137]
	v_pk_add_f32 v[210:211], v[210:211], v[138:139]
	ds_read2_b32 v[132:133], v187 offset0:48 offset1:49
	ds_read2_b32 v[134:135], v187 offset0:50 offset1:51
	ds_read2_b32 v[136:137], v187 offset0:56 offset1:57
	ds_read2_b32 v[138:139], v187 offset0:58 offset1:59
	s_waitcnt lgkmcnt(0)
	v_pk_add_f32 v[212:213], v[212:213], v[132:133]
	v_pk_add_f32 v[214:215], v[214:215], v[134:135]
	v_pk_add_f32 v[216:217], v[216:217], v[136:137]
	v_pk_add_f32 v[218:219], v[218:219], v[138:139]
.LatA_evnn_11:
	s_add_u32 s38, s5, 64
	s_cmp_lt_u32 s38, s11
	s_cselect_b32 s37, 1, 0
	s_cmp_gt_u32 s38, s31
	s_cselect_b32 s40, 2, 0
	s_or_b32 s37, s37, s40
	s_cmp_eq_u32 s37, s35
	s_cbranch_scc1 .LatA_evdisp_11
	s_mov_b32 s35, s37
	v_mov_b32_e32 v251, 0
	s_cmp_eq_u32 s37, 1
	s_cselect_b64 vcc, -1, 0
	v_cndmask_b32_e32 v251, v251, v177, vcc
	s_cmp_eq_u32 s37, 2
	s_cselect_b64 vcc, -1, 0
	v_cndmask_b32_e32 v251, v251, v178, vcc
	v_sub_f32_e32 v2, v251, v186
	v_mov_b32_e32 v3, v2
	v_mov_b64_e32 v[4:5], v[2:3]
	v_mov_b64_e32 v[6:7], v[2:3]
	v_mov_b64_e32 v[8:9], v[2:3]
	v_mov_b64_e32 v[10:11], v[2:3]
	v_mov_b64_e32 v[12:13], v[2:3]
	v_mov_b64_e32 v[14:15], v[2:3]
	v_mov_b64_e32 v[16:17], v[2:3]
.LatA_evdisp_11:
	s_cmp_eq_u32 s42, 0
	s_cbranch_scc1 .LatA_evret_h1
	s_cmp_eq_u32 s42, 1
	s_cbranch_scc1 .LatA_evret_h3
	s_cmp_eq_u32 s42, 2
	s_cbranch_scc1 .LatA_evret_m1
	s_cmp_eq_u32 s42, 3
	s_cbranch_scc1 .LatA_evret_m3
	s_cmp_eq_u32 s42, 4
	s_cbranch_scc1 .LatA_evret_m5
	s_branch .LatA_evret_x3
.LatA_ev_01:
	s_sub_u32 s5, s8, s4
	s_lshr_b32 s5, s5, 12
	s_sub_u32 s5, s5, 64
	s_cmp_ge_u32 s5, s11
	s_cselect_b32 s37, 1, 0
	s_cmp_le_u32 s5, s31
	s_cselect_b32 s38, 1, 0
	s_and_b32 s37, s37, s38
	s_add_u32 s38, s5, 64
	s_cmp_le_u32 s38, s31
	s_cselect_b32 s10, 0, 0x7fffffff
	s_cmp_eq_u32 s37, 0
	s_cbranch_scc1 .LatA_evnn_01
	s_lshl_b32 s38, s5, 2
	s_add_i32 s38, s38, 0x18b80
	v_add_u32_e32 v187, s38, v162
	ds_read2_b32 v[132:133], v187 offset0:0 offset1:1
	ds_read2_b32 v[134:135], v187 offset0:2 offset1:3
	ds_read2_b32 v[136:137], v187 offset0:8 offset1:9
	ds_read2_b32 v[138:139], v187 offset0:10 offset1:11
	s_waitcnt lgkmcnt(0)
	v_pk_add_f32 v[84:85], v[84:85], v[132:133]
	v_pk_add_f32 v[86:87], v[86:87], v[134:135]
	v_pk_add_f32 v[88:89], v[88:89], v[136:137]
	v_pk_add_f32 v[90:91], v[90:91], v[138:139]
	ds_read2_b32 v[132:133], v187 offset0:16 offset1:17
	ds_read2_b32 v[134:135], v187 offset0:18 offset1:19
	ds_read2_b32 v[136:137], v187 offset0:24 offset1:25
	ds_read2_b32 v[138:139], v187 offset0:26 offset1:27
	s_waitcnt lgkmcnt(0)
	v_pk_add_f32 v[92:93], v[92:93], v[132:133]
	v_pk_add_f32 v[94:95], v[94:95], v[134:135]
	v_pk_add_f32 v[96:97], v[96:97], v[136:137]
	v_pk_add_f32 v[98:99], v[98:99], v[138:139]
	ds_read2_b32 v[132:133], v187 offset0:32 offset1:33
	ds_read2_b32 v[134:135], v187 offset0:34 offset1:35
	ds_read2_b32 v[136:137], v187 offset0:40 offset1:41
	ds_read2_b32 v[138:139], v187 offset0:42 offset1:43
	s_waitcnt lgkmcnt(0)
	v_pk_add_f32 v[100:101], v[100:101], v[132:133]
	v_pk_add_f32 v[102:103], v[102:103], v[134:135]
	v_pk_add_f32 v[104:105], v[104:105], v[136:137]
	v_pk_add_f32 v[106:107], v[106:107], v[138:139]
	ds_read2_b32 v[132:133], v187 offset0:48 offset1:49
	ds_read2_b32 v[134:135], v187 offset0:50 offset1:51
	ds_read2_b32 v[136:137], v187 offset0:56 offset1:57
	ds_read2_b32 v[138:139], v187 offset0:58 offset1:59
	s_waitcnt lgkmcnt(0)
	v_pk_add_f32 v[108:109], v[108:109], v[132:133]
	v_pk_add_f32 v[110:111], v[110:111], v[134:135]
	v_pk_add_f32 v[112:113], v[112:113], v[136:137]
	v_pk_add_f32 v[114:115], v[114:115], v[138:139]

; #define LAS __attribute__((address_space(3)))
; __device__ __forceinline__ float max2f(float a, float b) { float r; asm("v_max_f32_e32 %0, %1, %2" : "=v"(r) : "v"(a), "v"(b)); return r; }
; __device__ __forceinline__ void attn_unit(LAS unsigned char* lds, const bf16_t* Z, bf16_t* A2, const float* tabg, int seq_base, int S, int h, int qb, float lam) {
;     ...
;         if (first || __any(mx > THR)) {
;             { auto rr = __builtin_amdgcn_permlane32_swap(__float_as_uint(mx), __float_as_uint(mx), false, false); mx = max2f(__uint_as_float(rr[0]), __uint_as_float(rr[1])); }
;             const float delta = first ? mx : fmaxf(mx, 0.f);
;             const float alpha = first ? 1.0f : __builtin_amdgcn_exp2f(-delta);
;             mu += delta; ls2 *= alpha;
;             if (!first) {
;                 asm volatile("" ::: "memory");
;                 scr[r32] = alpha;
;                 asm volatile("s_waitcnt lgkmcnt(0)" ::: "memory");
; #pragma unroll
;                 for (int g = 0; g < 4; ++g) { const f32x4 a4 = *(const LAS f32x4*)(scr + 8 * g + 4 * hi);
; #pragma unroll
;                     for (int d = 0; d < 4; ++d) { O[d][4 * g + 0] *= a4[0]; O[d][4 * g + 1] *= a4[1]; O[d][4 * g + 2] *= a4[2]; O[d][4 * g + 3] *= a4[3]; } }
;                 asm volatile("s_waitcnt lgkmcnt(0)" ::: "memory");
;             }
; #pragma unroll
;             for (int r = 0; r < 16; ++r) { p0[r] -= delta; p1[r] -= delta; }
;             asm volatile("" : "+v"(p0), "+v"(p1));
;         }
.LatA_evnn_10:
.LatA_evdisp_10:
	s_branch .LatA_evret_x1
.LatA_rare_001:
	v_mov_b32_e32 v252, v251
	s_nop 1
	v_permlane32_swap_b32_e32 v251, v252
	v_max_f32_e32 v251, v251, v252
	v_max_f32_e32 v253, 0, v251
	v_exp_f32_e64 v254, -v253
	v_add_f32_e32 v186, v186, v253
	s_nop 0
	v_mul_f32_e32 v150, v150, v254
	v_mul_f32_e32 v151, v151, v254
	ds_write_b32 v184, v254
	s_waitcnt lgkmcnt(0)
	ds_read_b128 v[196:199], v185
	ds_read_b128 v[200:203], v185 offset:32
	ds_read_b128 v[212:215], v185 offset:64
	ds_read_b128 v[216:219], v185 offset:96
	s_waitcnt lgkmcnt(0)
	s_nop 15
	s_nop 15
	v_pk_mul_f32 v[20:21], v[20:21], v[196:197]
	v_pk_mul_f32 v[22:23], v[22:23], v[198:199]
	v_pk_mul_f32 v[24:25], v[24:25], v[200:201]
	v_pk_mul_f32 v[26:27], v[26:27], v[202:203]
	v_pk_mul_f32 v[28:29], v[28:29], v[212:213]
	v_pk_mul_f32 v[30:31], v[30:31], v[214:215]
	v_pk_mul_f32 v[32:33], v[32:33], v[216:217]
	v_pk_mul_f32 v[34:35], v[34:35], v[218:219]
	v_pk_mul_f32 v[36:37], v[36:37], v[196:197]
	v_pk_mul_f32 v[38:39], v[38:39], v[198:199]
	v_pk_mul_f32 v[40:41], v[40:41], v[200:201]
	v_pk_mul_f32 v[42:43], v[42:43], v[202:203]
	v_pk_mul_f32 v[44:45], v[44:45], v[212:213]
	v_pk_mul_f32 v[46:47], v[46:47], v[214:215]
	v_pk_mul_f32 v[48:49], v[48:49], v[216:217]
	v_pk_mul_f32 v[50:51], v[50:51], v[218:219]
	v_pk_mul_f32 v[52:53], v[52:53], v[196:197]
	v_pk_mul_f32 v[54:55], v[54:55], v[198:199]
	v_pk_mul_f32 v[56:57], v[56:57], v[200:201]
	v_pk_mul_f32 v[58:59], v[58:59], v[202:203]
	v_pk_mul_f32 v[60:61], v[60:61], v[212:213]
	v_pk_mul_f32 v[62:63], v[62:63], v[214:215]
	v_pk_mul_f32 v[64:65], v[64:65], v[216:217]
	v_pk_mul_f32 v[66:67], v[66:67], v[218:219]
	v_pk_mul_f32 v[68:69], v[68:69], v[196:197]
	v_pk_mul_f32 v[70:71], v[70:71], v[198:199]
	v_pk_mul_f32 v[72:73], v[72:73], v[200:201]
	v_pk_mul_f32 v[74:75], v[74:75], v[202:203]
	v_pk_mul_f32 v[76:77], v[76:77], v[212:213]
	v_pk_mul_f32 v[78:79], v[78:79], v[214:215]
	v_pk_mul_f32 v[80:81], v[80:81], v[216:217]
	v_pk_mul_f32 v[82:83], v[82:83], v[218:219]
	v_mov_b32_e32 v252, v253
	v_pk_add_f32 v[84:85], v[84:85], v[252:253] neg_lo:[0,1] neg_hi:[0,1]
	v_pk_add_f32 v[86:87], v[86:87], v[252:253] neg_lo:[0,1] neg_hi:[0,1]
	v_pk_add_f32 v[88:89], v[88:89], v[252:253] neg_lo:[0,1] neg_hi:[0,1]
	v_pk_add_f32 v[90:91], v[90:91], v[252:253] neg_lo:[0,1] neg_hi:[0,1]
	v_pk_add_f32 v[92:93], v[92:93], v[252:253] neg_lo:[0,1] neg_hi:[0,1]
	v_pk_add_f32 v[94:95], v[94:95], v[252:253] neg_lo:[0,1] neg_hi:[0,1]
	v_pk_add_f32 v[96:97], v[96:97], v[252:253] neg_lo:[0,1] neg_hi:[0,1]
	v_pk_add_f32 v[98:99], v[98:99], v[252:253] neg_lo:[0,1] neg_hi:[0,1]
	v_pk_add_f32 v[100:101], v[100:101], v[252:253] neg_lo:[0,1] neg_hi:[0,1]
	v_pk_add_f32 v[102:103], v[102:103], v[252:253] neg_lo:[0,1] neg_hi:[0,1]
	v_pk_add_f32 v[104:105], v[104:105], v[252:253] neg_lo:[0,1] neg_hi:[0,1]
	v_pk_add_f32 v[106:107], v[106:107], v[252:253] neg_lo:[0,1] neg_hi:[0,1]
	v_pk_add_f32 v[108:109], v[108:109], v[252:253] neg_lo:[0,1] neg_hi:[0,1]
	v_pk_add_f32 v[110:111], v[110:111], v[252:253] neg_lo:[0,1] neg_hi:[0,1]
	v_pk_add_f32 v[112:113], v[112:113], v[252:253] neg_lo:[0,1] neg_hi:[0,1]
	v_pk_add_f32 v[114:115], v[114:115], v[252:253] neg_lo:[0,1] neg_hi:[0,1]
	s_sub_u32 s5, s8, s4
	s_lshr_b32 s5, s5, 12
	s_sub_u32 s5, s5, 64
	s_add_u32 s38, s5, 64
	s_cmp_lt_u32 s38, s11
	s_cselect_b32 s37, 1, 0
	s_cmp_gt_u32 s38, s31
	s_cselect_b32 s40, 2, 0
	s_or_b32 s37, s37, s40
	s_mov_b32 s35, s37
	v_mov_b32_e32 v251, 0
	s_cmp_eq_u32 s37, 1
	s_cselect_b64 vcc, -1, 0
	v_cndmask_b32_e32 v251, v251, v177, vcc
	s_cmp_eq_u32 s37, 2
	s_cselect_b64 vcc, -1, 0
	v_cndmask_b32_e32 v251, v251, v178, vcc
	v_sub_f32_e32 v2, v251, v186
	v_mov_b32_e32 v3, v2
	v_mov_b64_e32 v[4:5], v[2:3]
	v_mov_b64_e32 v[6:7], v[2:3]
	v_mov_b64_e32 v[8:9], v[2:3]
	v_mov_b64_e32 v[10:11], v[2:3]
	v_mov_b64_e32 v[12:13], v[2:3]
	v_mov_b64_e32 v[14:15], v[2:3]
	v_mov_b64_e32 v[16:17], v[2:3]
	s_nop 1
	s_branch .LatA_rareret_h0
.LatA_rare_111:
	v_mov_b32_e32 v252, v251
	s_nop 1
	v_permlane32_swap_b32_e32 v251, v252
	v_max_f32_e32 v251, v251, v252
	v_max_f32_e32 v253, 0, v251
	v_exp_f32_e64 v254, -v253
	v_add_f32_e32 v186, v186, v253
	s_nop 0
	v_mul_f32_e32 v150, v150, v254
	v_mul_f32_e32 v151, v151, v254
	ds_write_b32 v184, v254
	s_waitcnt lgkmcnt(0)
	v_mfma_f32_32x32x16_bf16 v[20:35], v[84:87], v[132:135], v[20:35]
	v_mfma_f32_32x32x16_bf16 v[36:51], v[84:87], v[136:139], v[36:51]
	v_mfma_f32_32x32x16_bf16 v[52:67], v[84:87], v[140:143], v[52:67]
	v_mfma_f32_32x32x16_bf16 v[68:83], v[84:87], v[144:147], v[68:83]
	v_mfma_f32_32x32x16_bf16 v[20:35], v[88:91], v[220:223], v[20:35]
	v_mfma_f32_32x32x16_bf16 v[36:51], v[88:91], v[224:227], v[36:51]
	v_mfma_f32_32x32x16_bf16 v[52:67], v[88:91], v[232:235], v[52:67]
	ds_read_b64_tr_b16 v[132:133], v231 offset:4096
	ds_read_b64_tr_b16 v[134:135], v231 offset:6144
	ds_read_b64_tr_b16 v[136:137], v228 offset:8192
	ds_read_b64_tr_b16 v[138:139], v228 offset:10240
	ds_read_b64_tr_b16 v[140:141], v229 offset:8192
	ds_read_b64_tr_b16 v[142:143], v229 offset:10240
	ds_read_b64_tr_b16 v[144:145], v230 offset:8192
	ds_read_b64_tr_b16 v[146:147], v230 offset:10240
	ds_read_b64_tr_b16 v[220:221], v231 offset:8192
	ds_read_b64_tr_b16 v[222:223], v231 offset:10240
	ds_read_b64_tr_b16 v[224:225], v228 offset:12288
	ds_read_b64_tr_b16 v[226:227], v228 offset:14336
	ds_read_b64_tr_b16 v[232:233], v229 offset:12288
	ds_read_b64_tr_b16 v[234:235], v229 offset:14336
	s_waitcnt lgkmcnt(0)
; #define LAS __attribute__((address_space(3)))
; __device__ __forceinline__ float max2f(float a, float b) { float r; asm("v_max_f32_e32 %0, %1, %2" : "=v"(r) : "v"(a), "v"(b)); return r; }
; __device__ __forceinline__ void attn_unit(LAS unsigned char* lds, const bf16_t* Z, bf16_t* A2, const float* tabg, int seq_base, int S, int h, int qb, float lam) {
;     ...
;         bool near = true; float cc = 0.f;
;         if (kv0 - (qlo + 31) >= 128) { near = false; cc = tabR; } else if (qlo - (kv0 + 63) >= 128) { near = false; cc = tabL; }
;         { const float coff = cc - mu;
;           if (__any(!(coff == coff_cur))) { coff_cur = coff;
; #pragma unroll
;               for (int r = 0; r < 16; ++r) cblk[r] = coff;
;               asm volatile("" : "+v"(cblk)); } }
;     ...
;         if (first || __any(mx > THR)) {
;             { auto rr = __builtin_amdgcn_permlane32_swap(__float_as_uint(mx), __float_as_uint(mx), false, false); mx = max2f(__uint_as_float(rr[0]), __uint_as_float(rr[1])); }
;             const float delta = first ? mx : fmaxf(mx, 0.f);
;             const float alpha = first ? 1.0f : __builtin_amdgcn_exp2f(-delta);
;             mu += delta; ls2 *= alpha;
;             if (!first) {
;                 asm volatile("" ::: "memory");
;                 scr[r32] = alpha;
;                 asm volatile("s_waitcnt lgkmcnt(0)" ::: "memory");
; #pragma unroll
;                 for (int g = 0; g < 4; ++g) { const f32x4 a4 = *(const LAS f32x4*)(scr + 8 * g + 4 * hi);
; #pragma unroll
;                     for (int d = 0; d < 4; ++d) { O[d][4 * g + 0] *= a4[0]; O[d][4 * g + 1] *= a4[1]; O[d][4 * g + 2] *= a4[2]; O[d][4 * g + 3] *= a4[3]; } }
;                 asm volatile("s_waitcnt lgkmcnt(0)" ::: "memory");
;             }
; #pragma unroll
;             for (int r = 0; r < 16; ++r) { p0[r] -= delta; p1[r] -= delta; }
;             asm volatile("" : "+v"(p0), "+v"(p1));
;         }
	v_mfma_f32_32x32x16_bf16 v[68:83], v[88:91], v[132:135], v[68:83]
	v_mfma_f32_32x32x16_bf16 v[20:35], v[100:103], v[136:139], v[20:35]
	v_mfma_f32_32x32x16_bf16 v[36:51], v[100:103], v[140:143], v[36:51]
	v_mfma_f32_32x32x16_bf16 v[52:67], v[100:103], v[144:147], v[52:67]
	v_mfma_f32_32x32x16_bf16 v[68:83], v[100:103], v[220:223], v[68:83]
	v_mfma_f32_32x32x16_bf16 v[20:35], v[104:107], v[224:227], v[20:35]
	v_mfma_f32_32x32x16_bf16 v[36:51], v[104:107], v[232:235], v[36:51]
	ds_read_b64_tr_b16 v[132:133], v230 offset:12288
	ds_read_b64_tr_b16 v[134:135], v230 offset:14336
	ds_read_b64_tr_b16 v[136:137], v231 offset:12288
	ds_read_b64_tr_b16 v[138:139], v231 offset:14336
	s_waitcnt lgkmcnt(0)
	v_mfma_f32_32x32x16_bf16 v[52:67], v[104:107], v[132:135], v[52:67]
	v_mfma_f32_32x32x16_bf16 v[68:83], v[104:107], v[136:139], v[68:83]
	ds_read_b128 v[92:95], v185
	ds_read_b128 v[96:99], v185 offset:32
	ds_read_b128 v[108:111], v185 offset:64
	ds_read_b128 v[112:115], v185 offset:96
	s_waitcnt lgkmcnt(0)
	s_nop 15
	s_nop 15
	v_pk_mul_f32 v[20:21], v[20:21], v[92:93]
	v_pk_mul_f32 v[22:23], v[22:23], v[94:95]
	v_pk_mul_f32 v[24:25], v[24:25], v[96:97]
	v_pk_mul_f32 v[26:27], v[26:27], v[98:99]
	v_pk_mul_f32 v[28:29], v[28:29], v[108:109]
	v_pk_mul_f32 v[30:31], v[30:31], v[110:111]
	v_pk_mul_f32 v[32:33], v[32:33], v[112:113]
	v_pk_mul_f32 v[34:35], v[34:35], v[114:115]
	v_pk_mul_f32 v[36:37], v[36:37], v[92:93]
	v_pk_mul_f32 v[38:39], v[38:39], v[94:95]
	v_pk_mul_f32 v[40:41], v[40:41], v[96:97]
	v_pk_mul_f32 v[42:43], v[42:43], v[98:99]
	v_pk_mul_f32 v[44:45], v[44:45], v[108:109]
	v_pk_mul_f32 v[46:47], v[46:47], v[110:111]
	v_pk_mul_f32 v[48:49], v[48:49], v[112:113]
	v_pk_mul_f32 v[50:51], v[50:51], v[114:115]
	v_pk_mul_f32 v[52:53], v[52:53], v[92:93]
	v_pk_mul_f32 v[54:55], v[54:55], v[94:95]
	v_pk_mul_f32 v[56:57], v[56:57], v[96:97]
	v_pk_mul_f32 v[58:59], v[58:59], v[98:99]
	v_pk_mul_f32 v[60:61], v[60:61], v[108:109]
	v_pk_mul_f32 v[62:63], v[62:63], v[110:111]
	v_pk_mul_f32 v[64:65], v[64:65], v[112:113]
	v_pk_mul_f32 v[66:67], v[66:67], v[114:115]
	v_pk_mul_f32 v[68:69], v[68:69], v[92:93]
	v_pk_mul_f32 v[70:71], v[70:71], v[94:95]
	v_pk_mul_f32 v[72:73], v[72:73], v[96:97]
	v_pk_mul_f32 v[74:75], v[74:75], v[98:99]
	v_pk_mul_f32 v[76:77], v[76:77], v[108:109]
	v_pk_mul_f32 v[78:79], v[78:79], v[110:111]
	v_pk_mul_f32 v[80:81], v[80:81], v[112:113]
	v_pk_mul_f32 v[82:83], v[82:83], v[114:115]
	v_mov_b32_e32 v252, v253
	v_pk_add_f32 v[188:189], v[188:189], v[252:253] neg_lo:[0,1] neg_hi:[0,1]
	v_pk_add_f32 v[190:191], v[190:191], v[252:253] neg_lo:[0,1] neg_hi:[0,1]
	v_pk_add_f32 v[192:193], v[192:193], v[252:253] neg_lo:[0,1] neg_hi:[0,1]
	v_pk_add_f32 v[194:195], v[194:195], v[252:253] neg_lo:[0,1] neg_hi:[0,1]
	v_pk_add_f32 v[196:197], v[196:197], v[252:253] neg_lo:[0,1] neg_hi:[0,1]
	v_pk_add_f32 v[198:199], v[198:199], v[252:253] neg_lo:[0,1] neg_hi:[0,1]
	v_pk_add_f32 v[200:201], v[200:201], v[252:253] neg_lo:[0,1] neg_hi:[0,1]
	v_pk_add_f32 v[202:203], v[202:203], v[252:253] neg_lo:[0,1] neg_hi:[0,1]
	v_pk_add_f32 v[204:205], v[204:205], v[252:253] neg_lo:[0,1] neg_hi:[0,1]
	v_pk_add_f32 v[206:207], v[206:207], v[252:253] neg_lo:[0,1] neg_hi:[0,1]
	v_pk_add_f32 v[208:209], v[208:209], v[252:253] neg_lo:[0,1] neg_hi:[0,1]
	v_pk_add_f32 v[210:211], v[210:211], v[252:253] neg_lo:[0,1] neg_hi:[0,1]
	v_pk_add_f32 v[212:213], v[212:213], v[252:253] neg_lo:[0,1] neg_hi:[0,1]
	v_pk_add_f32 v[214:215], v[214:215], v[252:253] neg_lo:[0,1] neg_hi:[0,1]
	v_pk_add_f32 v[216:217], v[216:217], v[252:253] neg_lo:[0,1] neg_hi:[0,1]
	v_pk_add_f32 v[218:219], v[218:219], v[252:253] neg_lo:[0,1] neg_hi:[0,1]
	v_mov_b64_e32 v[84:85], 0
	v_mov_b64_e32 v[86:87], 0
	v_mov_b64_e32 v[88:89], 0
	v_mov_b64_e32 v[90:91], 0
	v_mov_b64_e32 v[100:101], 0
	v_mov_b64_e32 v[102:103], 0
	v_mov_b64_e32 v[104:105], 0
	v_mov_b64_e32 v[106:107], 0
	s_sub_u32 s5, s8, s4
	s_lshr_b32 s5, s5, 12
	s_sub_u32 s5, s5, 64
	s_add_u32 s38, s5, 64
	s_cmp_lt_u32 s38, s11
	s_cselect_b32 s37, 1, 0
	s_cmp_gt_u32 s38, s31
	s_cselect_b32 s40, 2, 0
	s_or_b32 s37, s37, s40
	s_mov_b32 s35, s37
	v_mov_b32_e32 v251, 0
	s_cmp_eq_u32 s37, 1
	s_cselect_b64 vcc, -1, 0
	v_cndmask_b32_e32 v251, v251, v177, vcc
	s_cmp_eq_u32 s37, 2
	s_cselect_b64 vcc, -1, 0
	v_cndmask_b32_e32 v251, v251, v178, vcc
	v_sub_f32_e32 v2, v251, v186
	v_mov_b32_e32 v3, v2
	v_mov_b64_e32 v[4:5], v[2:3]
	v_mov_b64_e32 v[6:7], v[2:3]
	v_mov_b64_e32 v[8:9], v[2:3]
	v_mov_b64_e32 v[10:11], v[2:3]
	v_mov_b64_e32 v[12:13], v[2:3]
	v_mov_b64_e32 v[14:15], v[2:3]
	v_mov_b64_e32 v[16:17], v[2:3]
	s_nop 1
	s_cmp_eq_u32 s42, 0
	s_cbranch_scc1 .LatA_rareret_h1
	s_branch .LatA_rareret_m3
; #define LAS __attribute__((address_space(3)))
; __device__ __forceinline__ float max2f(float a, float b) { float r; asm("v_max_f32_e32 %0, %1, %2" : "=v"(r) : "v"(a), "v"(b)); return r; }
; __device__ __forceinline__ void attn_unit(LAS unsigned char* lds, const bf16_t* Z, bf16_t* A2, const float* tabg, int seq_base, int S, int h, int qb, float lam) {
;     ...
;         bool near = true; float cc = 0.f;
;         if (kv0 - (qlo + 31) >= 128) { near = false; cc = tabR; } else if (qlo - (kv0 + 63) >= 128) { near = false; cc = tabL; }
;         { const float coff = cc - mu;
;           if (__any(!(coff == coff_cur))) { coff_cur = coff;
; #pragma unroll
;               for (int r = 0; r < 16; ++r) cblk[r] = coff;
;               asm volatile("" : "+v"(cblk)); } }
;     ...
;         if (first || __any(mx > THR)) {
;             { auto rr = __builtin_amdgcn_permlane32_swap(__float_as_uint(mx), __float_as_uint(mx), false, false); mx = max2f(__uint_as_float(rr[0]), __uint_as_float(rr[1])); }
;             const float delta = first ? mx : fmaxf(mx, 0.f);
;             const float alpha = first ? 1.0f : __builtin_amdgcn_exp2f(-delta);
;             mu += delta; ls2 *= alpha;
;             if (!first) {
;                 asm volatile("" ::: "memory");
;                 scr[r32] = alpha;
;                 asm volatile("s_waitcnt lgkmcnt(0)" ::: "memory");
; #pragma unroll
;                 for (int g = 0; g < 4; ++g) { const f32x4 a4 = *(const LAS f32x4*)(scr + 8 * g + 4 * hi);
; #pragma unroll
;                     for (int d = 0; d < 4; ++d) { O[d][4 * g + 0] *= a4[0]; O[d][4 * g + 1] *= a4[1]; O[d][4 * g + 2] *= a4[2]; O[d][4 * g + 3] *= a4[3]; } }
;                 asm volatile("s_waitcnt lgkmcnt(0)" ::: "memory");
;             }
; #pragma unroll
;             for (int r = 0; r < 16; ++r) { p0[r] -= delta; p1[r] -= delta; }
;             asm volatile("" : "+v"(p0), "+v"(p1));
;         }
.LatA_rare_211:
	v_mov_b32_e32 v252, v251
	s_nop 1
	v_permlane32_swap_b32_e32 v251, v252
	v_max_f32_e32 v251, v251, v252
	v_max_f32_e32 v253, 0, v251
	v_exp_f32_e64 v254, -v253
	v_add_f32_e32 v186, v186, v253
	s_nop 0
	v_mul_f32_e32 v150, v150, v254
	v_mul_f32_e32 v151, v151, v254
	ds_write_b32 v184, v254
	s_waitcnt lgkmcnt(0)
	v_mfma_f32_32x32x16_bf16 v[20:35], v[188:191], v[132:135], v[20:35]
	v_mfma_f32_32x32x16_bf16 v[36:51], v[188:191], v[136:139], v[36:51]
	v_mfma_f32_32x32x16_bf16 v[52:67], v[188:191], v[140:143], v[52:67]
	v_mfma_f32_32x32x16_bf16 v[68:83], v[188:191], v[144:147], v[68:83]
	v_mfma_f32_32x32x16_bf16 v[20:35], v[192:195], v[220:223], v[20:35]
	v_mfma_f32_32x32x16_bf16 v[36:51], v[192:195], v[224:227], v[36:51]
	v_mfma_f32_32x32x16_bf16 v[52:67], v[192:195], v[232:235], v[52:67]
	ds_read_b64_tr_b16 v[132:133], v231 offset:20480
	ds_read_b64_tr_b16 v[134:135], v231 offset:22528
	ds_read_b64_tr_b16 v[136:137], v228 offset:24576
	ds_read_b64_tr_b16 v[138:139], v228 offset:26624
	ds_read_b64_tr_b16 v[140:141], v229 offset:24576
	ds_read_b64_tr_b16 v[142:143], v229 offset:26624
	ds_read_b64_tr_b16 v[144:145], v230 offset:24576
	ds_read_b64_tr_b16 v[146:147], v230 offset:26624
	ds_read_b64_tr_b16 v[220:221], v231 offset:24576
	ds_read_b64_tr_b16 v[222:223], v231 offset:26624
	ds_read_b64_tr_b16 v[224:225], v228 offset:28672
	ds_read_b64_tr_b16 v[226:227], v228 offset:30720
	ds_read_b64_tr_b16 v[232:233], v229 offset:28672
	ds_read_b64_tr_b16 v[234:235], v229 offset:30720
	s_waitcnt lgkmcnt(0)
	v_mfma_f32_32x32x16_bf16 v[68:83], v[192:195], v[132:135], v[68:83]
	v_mfma_f32_32x32x16_bf16 v[20:35], v[204:207], v[136:139], v[20:35]
	v_mfma_f32_32x32x16_bf16 v[36:51], v[204:207], v[140:143], v[36:51]
	v_mfma_f32_32x32x16_bf16 v[52:67], v[204:207], v[144:147], v[52:67]
	v_mfma_f32_32x32x16_bf16 v[68:83], v[204:207], v[220:223], v[68:83]
	v_mfma_f32_32x32x16_bf16 v[20:35], v[208:211], v[224:227], v[20:35]
	v_mfma_f32_32x32x16_bf16 v[36:51], v[208:211], v[232:235], v[36:51]
	ds_read_b64_tr_b16 v[132:133], v230 offset:28672
	ds_read_b64_tr_b16 v[134:135], v230 offset:30720
	ds_read_b64_tr_b16 v[136:137], v231 offset:28672
	ds_read_b64_tr_b16 v[138:139], v231 offset:30720
	s_waitcnt lgkmcnt(0)
	v_mfma_f32_32x32x16_bf16 v[52:67], v[208:211], v[132:135], v[52:67]
	v_mfma_f32_32x32x16_bf16 v[68:83], v[208:211], v[136:139], v[68:83]
	ds_read_b128 v[196:199], v185
	ds_read_b128 v[200:203], v185 offset:32
	ds_read_b128 v[212:215], v185 offset:64
	ds_read_b128 v[216:219], v185 offset:96
	s_waitcnt lgkmcnt(0)
	s_nop 15
	s_nop 15
	v_pk_mul_f32 v[20:21], v[20:21], v[196:197]
	v_pk_mul_f32 v[22:23], v[22:23], v[198:199]
	v_pk_mul_f32 v[24:25], v[24:25], v[200:201]
	v_pk_mul_f32 v[26:27], v[26:27], v[202:203]
	v_pk_mul_f32 v[28:29], v[28:29], v[212:213]
	v_pk_mul_f32 v[30:31], v[30:31], v[214:215]
	v_pk_mul_f32 v[32:33], v[32:33], v[216:217]
	v_pk_mul_f32 v[34:35], v[34:35], v[218:219]
	v_pk_mul_f32 v[36:37], v[36:37], v[196:197]
	v_pk_mul_f32 v[38:39], v[38:39], v[198:199]
	v_pk_mul_f32 v[40:41], v[40:41], v[200:201]
	v_pk_mul_f32 v[42:43], v[42:43], v[202:203]
	v_pk_mul_f32 v[44:45], v[44:45], v[212:213]
	v_pk_mul_f32 v[46:47], v[46:47], v[214:215]
	v_pk_mul_f32 v[48:49], v[48:49], v[216:217]
	v_pk_mul_f32 v[50:51], v[50:51], v[218:219]
	v_pk_mul_f32 v[52:53], v[52:53], v[196:197]
	v_pk_mul_f32 v[54:55], v[54:55], v[198:199]
	v_pk_mul_f32 v[56:57], v[56:57], v[200:201]
	v_pk_mul_f32 v[58:59], v[58:59], v[202:203]
	v_pk_mul_f32 v[60:61], v[60:61], v[212:213]
	v_pk_mul_f32 v[62:63], v[62:63], v[214:215]
	v_pk_mul_f32 v[64:65], v[64:65], v[216:217]
	v_pk_mul_f32 v[66:67], v[66:67], v[218:219]
	v_pk_mul_f32 v[68:69], v[68:69], v[196:197]
	v_pk_mul_f32 v[70:71], v[70:71], v[198:199]
	v_pk_mul_f32 v[72:73], v[72:73], v[200:201]
	v_pk_mul_f32 v[74:75], v[74:75], v[202:203]
	v_pk_mul_f32 v[76:77], v[76:77], v[212:213]
	v_pk_mul_f32 v[78:79], v[78:79], v[214:215]
	v_pk_mul_f32 v[80:81], v[80:81], v[216:217]
	v_pk_mul_f32 v[82:83], v[82:83], v[218:219]
	v_mov_b32_e32 v252, v253
	v_pk_add_f32 v[84:85], v[84:85], v[252:253] neg_lo:[0,1] neg_hi:[0,1]
	v_pk_add_f32 v[86:87], v[86:87], v[252:253] neg_lo:[0,1] neg_hi:[0,1]
	v_pk_add_f32 v[88:89], v[88:89], v[252:253] neg_lo:[0,1] neg_hi:[0,1]
	v_pk_add_f32 v[90:91], v[90:91], v[252:253] neg_lo:[0,1] neg_hi:[0,1]
	v_pk_add_f32 v[92:93], v[92:93], v[252:253] neg_lo:[0,1] neg_hi:[0,1]
	v_pk_add_f32 v[94:95], v[94:95], v[252:253] neg_lo:[0,1] neg_hi:[0,1]
	v_pk_add_f32 v[96:97], v[96:97], v[252:253] neg_lo:[0,1] neg_hi:[0,1]
	v_pk_add_f32 v[98:99], v[98:99], v[252:253] neg_lo:[0,1] neg_hi:[0,1]
	v_pk_add_f32 v[100:101], v[100:101], v[252:253] neg_lo:[0,1] neg_hi:[0,1]
	v_pk_add_f32 v[102:103], v[102:103], v[252:253] neg_lo:[0,1] neg_hi:[0,1]
	v_pk_add_f32 v[104:105], v[104:105], v[252:253] neg_lo:[0,1] neg_hi:[0,1]
	v_pk_add_f32 v[106:107], v[106:107], v[252:253] neg_lo:[0,1] neg_hi:[0,1]
	v_pk_add_f32 v[108:109], v[108:109], v[252:253] neg_lo:[0,1] neg_hi:[0,1]
	v_pk_add_f32 v[110:111], v[110:111], v[252:253] neg_lo:[0,1] neg_hi:[0,1]
	v_pk_add_f32 v[112:113], v[112:113], v[252:253] neg_lo:[0,1] neg_hi:[0,1]
	v_pk_add_f32 v[114:115], v[114:115], v[252:253] neg_lo:[0,1] neg_hi:[0,1]
	v_mov_b64_e32 v[188:189], 0
	v_mov_b64_e32 v[190:191], 0
	v_mov_b64_e32 v[192:193], 0
	v_mov_b64_e32 v[194:195], 0
	v_mov_b64_e32 v[204:205], 0
	v_mov_b64_e32 v[206:207], 0
	v_mov_b64_e32 v[208:209], 0
	v_mov_b64_e32 v[210:211], 0
	s_sub_u32 s5, s8, s4
	s_lshr_b32 s5, s5, 12
	s_sub_u32 s5, s5, 64
	s_add_u32 s38, s5, 64
	s_cmp_lt_u32 s38, s11
	s_cselect_b32 s37, 1, 0
	s_cmp_gt_u32 s38, s31
	s_cselect_b32 s40, 2, 0
	s_or_b32 s37, s37, s40
	s_mov_b32 s35, s37
	v_mov_b32_e32 v251, 0
	s_cmp_eq_u32 s37, 1
	s_cselect_b64 vcc, -1, 0
	v_cndmask_b32_e32 v251, v251, v177, vcc
	s_cmp_eq_u32 s37, 2
	s_cselect_b64 vcc, -1, 0
	v_cndmask_b32_e32 v251, v251, v178, vcc
	v_sub_f32_e32 v2, v251, v186
	v_mov_b32_e32 v3, v2
	v_mov_b64_e32 v[4:5], v[2:3]
	v_mov_b64_e32 v[6:7], v[2:3]
	v_mov_b64_e32 v[8:9], v[2:3]
	v_mov_b64_e32 v[10:11], v[2:3]
	v_mov_b64_e32 v[12:13], v[2:3]
	v_mov_b64_e32 v[14:15], v[2:3]
	v_mov_b64_e32 v[16:17], v[2:3]
	s_nop 1
	s_cmp_eq_u32 s42, 0
	s_cbranch_scc1 .LatA_rareret_h2
	s_branch .LatA_rareret_m4
; #define LAS __attribute__((address_space(3)))
; __device__ __forceinline__ float max2f(float a, float b) { float r; asm("v_max_f32_e32 %0, %1, %2" : "=v"(r) : "v"(a), "v"(b)); return r; }
; __device__ __forceinline__ void attn_unit(LAS unsigned char* lds, const bf16_t* Z, bf16_t* A2, const float* tabg, int seq_base, int S, int h, int qb, float lam) {
;     ...
;         bool near = true; float cc = 0.f;
;         if (kv0 - (qlo + 31) >= 128) { near = false; cc = tabR; } else if (qlo - (kv0 + 63) >= 128) { near = false; cc = tabL; }
;         { const float coff = cc - mu;
;           if (__any(!(coff == coff_cur))) { coff_cur = coff;
; #pragma unroll
;               for (int r = 0; r < 16; ++r) cblk[r] = coff;
;               asm volatile("" : "+v"(cblk)); } }
;     ...
;         if (first || __any(mx > THR)) {
;             { auto rr = __builtin_amdgcn_permlane32_swap(__float_as_uint(mx), __float_as_uint(mx), false, false); mx = max2f(__uint_as_float(rr[0]), __uint_as_float(rr[1])); }
;             const float delta = first ? mx : fmaxf(mx, 0.f);
;             const float alpha = first ? 1.0f : __builtin_amdgcn_exp2f(-delta);
;             mu += delta; ls2 *= alpha;
;             if (!first) {
;                 asm volatile("" ::: "memory");
;                 scr[r32] = alpha;
;                 asm volatile("s_waitcnt lgkmcnt(0)" ::: "memory");
; #pragma unroll
;                 for (int g = 0; g < 4; ++g) { const f32x4 a4 = *(const LAS f32x4*)(scr + 8 * g + 4 * hi);
; #pragma unroll
;                     for (int d = 0; d < 4; ++d) { O[d][4 * g + 0] *= a4[0]; O[d][4 * g + 1] *= a4[1]; O[d][4 * g + 2] *= a4[2]; O[d][4 * g + 3] *= a4[3]; } }
;                 asm volatile("s_waitcnt lgkmcnt(0)" ::: "memory");
;             }
; #pragma unroll
;             for (int r = 0; r < 16; ++r) { p0[r] -= delta; p1[r] -= delta; }
;             asm volatile("" : "+v"(p0), "+v"(p1));
;         }
.LatA_rare_311:
	v_mov_b32_e32 v252, v251
	s_nop 1
	v_permlane32_swap_b32_e32 v251, v252
	v_max_f32_e32 v251, v251, v252
	v_max_f32_e32 v253, 0, v251
	v_exp_f32_e64 v254, -v253
	v_add_f32_e32 v186, v186, v253
	s_nop 0
	v_mul_f32_e32 v150, v150, v254
	v_mul_f32_e32 v151, v151, v254
	ds_write_b32 v184, v254
	s_waitcnt lgkmcnt(0)
	v_mfma_f32_32x32x16_bf16 v[20:35], v[84:87], v[132:135], v[20:35]
	v_mfma_f32_32x32x16_bf16 v[36:51], v[84:87], v[136:139], v[36:51]
	v_mfma_f32_32x32x16_bf16 v[52:67], v[84:87], v[140:143], v[52:67]
	v_mfma_f32_32x32x16_bf16 v[68:83], v[84:87], v[144:147], v[68:83]
	v_mfma_f32_32x32x16_bf16 v[20:35], v[88:91], v[220:223], v[20:35]
	v_mfma_f32_32x32x16_bf16 v[36:51], v[88:91], v[224:227], v[36:51]
	v_mfma_f32_32x32x16_bf16 v[52:67], v[88:91], v[232:235], v[52:67]
	ds_read_b64_tr_b16 v[132:133], v231 offset:36864
	ds_read_b64_tr_b16 v[134:135], v231 offset:38912
	ds_read_b64_tr_b16 v[136:137], v228 offset:40960
	ds_read_b64_tr_b16 v[138:139], v228 offset:43008
	ds_read_b64_tr_b16 v[140:141], v229 offset:40960
	ds_read_b64_tr_b16 v[142:143], v229 offset:43008
	ds_read_b64_tr_b16 v[144:145], v230 offset:40960
	ds_read_b64_tr_b16 v[146:147], v230 offset:43008
	ds_read_b64_tr_b16 v[220:221], v231 offset:40960
	ds_read_b64_tr_b16 v[222:223], v231 offset:43008
	ds_read_b64_tr_b16 v[224:225], v228 offset:45056
	ds_read_b64_tr_b16 v[226:227], v228 offset:47104
	ds_read_b64_tr_b16 v[232:233], v229 offset:45056
	ds_read_b64_tr_b16 v[234:235], v229 offset:47104
	s_waitcnt lgkmcnt(0)
	v_mfma_f32_32x32x16_bf16 v[68:83], v[88:91], v[132:135], v[68:83]
	v_mfma_f32_32x32x16_bf16 v[20:35], v[100:103], v[136:139], v[20:35]
	v_mfma_f32_32x32x16_bf16 v[36:51], v[100:103], v[140:143], v[36:51]
	v_mfma_f32_32x32x16_bf16 v[52:67], v[100:103], v[144:147], v[52:67]
	v_mfma_f32_32x32x16_bf16 v[68:83], v[100:103], v[220:223], v[68:83]
	v_mfma_f32_32x32x16_bf16 v[20:35], v[104:107], v[224:227], v[20:35]
	v_mfma_f32_32x32x16_bf16 v[36:51], v[104:107], v[232:235], v[36:51]
	ds_read_b64_tr_b16 v[132:133], v230 offset:45056
	ds_read_b64_tr_b16 v[134:135], v230 offset:47104
	ds_read_b64_tr_b16 v[136:137], v231 offset:45056
	ds_read_b64_tr_b16 v[138:139], v231 offset:47104
	s_waitcnt lgkmcnt(0)
	v_mfma_f32_32x32x16_bf16 v[52:67], v[104:107], v[132:135], v[52:67]
	v_mfma_f32_32x32x16_bf16 v[68:83], v[104:107], v[136:139], v[68:83]
	ds_read_b128 v[92:95], v185
	ds_read_b128 v[96:99], v185 offset:32
	ds_read_b128 v[108:111], v185 offset:64
	ds_read_b128 v[112:115], v185 offset:96
	s_waitcnt lgkmcnt(0)
	s_nop 15
	s_nop 15
	v_pk_mul_f32 v[20:21], v[20:21], v[92:93]
	v_pk_mul_f32 v[22:23], v[22:23], v[94:95]
	v_pk_mul_f32 v[24:25], v[24:25], v[96:97]
	v_pk_mul_f32 v[26:27], v[26:27], v[98:99]
	v_pk_mul_f32 v[28:29], v[28:29], v[108:109]
	v_pk_mul_f32 v[30:31], v[30:31], v[110:111]
	v_pk_mul_f32 v[32:33], v[32:33], v[112:113]
	v_pk_mul_f32 v[34:35], v[34:35], v[114:115]
	v_pk_mul_f32 v[36:37], v[36:37], v[92:93]
	v_pk_mul_f32 v[38:39], v[38:39], v[94:95]
	v_pk_mul_f32 v[40:41], v[40:41], v[96:97]
	v_pk_mul_f32 v[42:43], v[42:43], v[98:99]
	v_pk_mul_f32 v[44:45], v[44:45], v[108:109]
	v_pk_mul_f32 v[46:47], v[46:47], v[110:111]
	v_pk_mul_f32 v[48:49], v[48:49], v[112:113]
	v_pk_mul_f32 v[50:51], v[50:51], v[114:115]
	v_pk_mul_f32 v[52:53], v[52:53], v[92:93]
	v_pk_mul_f32 v[54:55], v[54:55], v[94:95]
	v_pk_mul_f32 v[56:57], v[56:57], v[96:97]
	v_pk_mul_f32 v[58:59], v[58:59], v[98:99]
	v_pk_mul_f32 v[60:61], v[60:61], v[108:109]
	v_pk_mul_f32 v[62:63], v[62:63], v[110:111]
	v_pk_mul_f32 v[64:65], v[64:65], v[112:113]
	v_pk_mul_f32 v[66:67], v[66:67], v[114:115]
	v_pk_mul_f32 v[68:69], v[68:69], v[92:93]
	v_pk_mul_f32 v[70:71], v[70:71], v[94:95]
	v_pk_mul_f32 v[72:73], v[72:73], v[96:97]
	v_pk_mul_f32 v[74:75], v[74:75], v[98:99]
	v_pk_mul_f32 v[76:77], v[76:77], v[108:109]
	v_pk_mul_f32 v[78:79], v[78:79], v[110:111]
	v_pk_mul_f32 v[80:81], v[80:81], v[112:113]
	v_pk_mul_f32 v[82:83], v[82:83], v[114:115]
	v_mov_b32_e32 v252, v253
	v_pk_add_f32 v[188:189], v[188:189], v[252:253] neg_lo:[0,1] neg_hi:[0,1]
	v_pk_add_f32 v[190:191], v[190:191], v[252:253] neg_lo:[0,1] neg_hi:[0,1]
	v_pk_add_f32 v[192:193], v[192:193], v[252:253] neg_lo:[0,1] neg_hi:[0,1]
	v_pk_add_f32 v[194:195], v[194:195], v[252:253] neg_lo:[0,1] neg_hi:[0,1]
	v_pk_add_f32 v[196:197], v[196:197], v[252:253] neg_lo:[0,1] neg_hi:[0,1]
	v_pk_add_f32 v[198:199], v[198:199], v[252:253] neg_lo:[0,1] neg_hi:[0,1]
	v_pk_add_f32 v[200:201], v[200:201], v[252:253] neg_lo:[0,1] neg_hi:[0,1]
	v_pk_add_f32 v[202:203], v[202:203], v[252:253] neg_lo:[0,1] neg_hi:[0,1]
	v_pk_add_f32 v[204:205], v[204:205], v[252:253] neg_lo:[0,1] neg_hi:[0,1]
	v_pk_add_f32 v[206:207], v[206:207], v[252:253] neg_lo:[0,1] neg_hi:[0,1]
	v_pk_add_f32 v[208:209], v[208:209], v[252:253] neg_lo:[0,1] neg_hi:[0,1]
	v_pk_add_f32 v[210:211], v[210:211], v[252:253] neg_lo:[0,1] neg_hi:[0,1]
	v_pk_add_f32 v[212:213], v[212:213], v[252:253] neg_lo:[0,1] neg_hi:[0,1]
	v_pk_add_f32 v[214:215], v[214:215], v[252:253] neg_lo:[0,1] neg_hi:[0,1]
	v_pk_add_f32 v[216:217], v[216:217], v[252:253] neg_lo:[0,1] neg_hi:[0,1]
	v_pk_add_f32 v[218:219], v[218:219], v[252:253] neg_lo:[0,1] neg_hi:[0,1]
	v_mov_b64_e32 v[84:85], 0
	v_mov_b64_e32 v[86:87], 0
	v_mov_b64_e32 v[88:89], 0
	v_mov_b64_e32 v[90:91], 0
	v_mov_b64_e32 v[100:101], 0
	v_mov_b64_e32 v[102:103], 0
	v_mov_b64_e32 v[104:105], 0
	v_mov_b64_e32 v[106:107], 0
	s_sub_u32 s5, s8, s4
	s_lshr_b32 s5, s5, 12
	s_sub_u32 s5, s5, 64
	s_add_u32 s38, s5, 64
	s_cmp_lt_u32 s38, s11
	s_cselect_b32 s37, 1, 0
	s_cmp_gt_u32 s38, s31
	s_cselect_b32 s40, 2, 0
	s_or_b32 s37, s37, s40
	s_mov_b32 s35, s37
	v_mov_b32_e32 v251, 0
	s_cmp_eq_u32 s37, 1
	s_cselect_b64 vcc, -1, 0
	v_cndmask_b32_e32 v251, v251, v177, vcc
	s_cmp_eq_u32 s37, 2
	s_cselect_b64 vcc, -1, 0
	v_cndmask_b32_e32 v251, v251, v178, vcc
	v_sub_f32_e32 v2, v251, v186
	v_mov_b32_e32 v3, v2
	v_mov_b64_e32 v[4:5], v[2:3]
	v_mov_b64_e32 v[6:7], v[2:3]
	v_mov_b64_e32 v[8:9], v[2:3]
	v_mov_b64_e32 v[10:11], v[2:3]
	v_mov_b64_e32 v[12:13], v[2:3]
	v_mov_b64_e32 v[14:15], v[2:3]
	v_mov_b64_e32 v[16:17], v[2:3]
	s_nop 1
	s_cmp_eq_u32 s42, 0
	s_cbranch_scc1 .LatA_rareret_h3
	s_branch .LatA_rareret_m5
; #define LAS __attribute__((address_space(3)))
; __device__ __forceinline__ float max2f(float a, float b) { float r; asm("v_max_f32_e32 %0, %1, %2" : "=v"(r) : "v"(a), "v"(b)); return r; }
; __device__ __forceinline__ void attn_unit(LAS unsigned char* lds, const bf16_t* Z, bf16_t* A2, const float* tabg, int seq_base, int S, int h, int qb, float lam) {
;     ...
;         bool near = true; float cc = 0.f;
;         if (kv0 - (qlo + 31) >= 128) { near = false; cc = tabR; } else if (qlo - (kv0 + 63) >= 128) { near = false; cc = tabL; }
;         { const float coff = cc - mu;
;           if (__any(!(coff == coff_cur))) { coff_cur = coff;
; #pragma unroll
;               for (int r = 0; r < 16; ++r) cblk[r] = coff;
;               asm volatile("" : "+v"(cblk)); } }
;     ...
;         if (first || __any(mx > THR)) {
;             { auto rr = __builtin_amdgcn_permlane32_swap(__float_as_uint(mx), __float_as_uint(mx), false, false); mx = max2f(__uint_as_float(rr[0]), __uint_as_float(rr[1])); }
;             const float delta = first ? mx : fmaxf(mx, 0.f);
;             const float alpha = first ? 1.0f : __builtin_amdgcn_exp2f(-delta);
;             mu += delta; ls2 *= alpha;
;             if (!first) {
;                 asm volatile("" ::: "memory");
;                 scr[r32] = alpha;
;                 asm volatile("s_waitcnt lgkmcnt(0)" ::: "memory");
; #pragma unroll
;                 for (int g = 0; g < 4; ++g) { const f32x4 a4 = *(const LAS f32x4*)(scr + 8 * g + 4 * hi);
; #pragma unroll
;                     for (int d = 0; d < 4; ++d) { O[d][4 * g + 0] *= a4[0]; O[d][4 * g + 1] *= a4[1]; O[d][4 * g + 2] *= a4[2]; O[d][4 * g + 3] *= a4[3]; } }
;                 asm volatile("s_waitcnt lgkmcnt(0)" ::: "memory");
;             }
; #pragma unroll
;             for (int r = 0; r < 16; ++r) { p0[r] -= delta; p1[r] -= delta; }
;             asm volatile("" : "+v"(p0), "+v"(p1));
;         }
.LatA_rare_411:
	v_mov_b32_e32 v252, v251
	s_nop 1
	v_permlane32_swap_b32_e32 v251, v252
	v_max_f32_e32 v251, v251, v252
	v_max_f32_e32 v253, 0, v251
	v_exp_f32_e64 v254, -v253
	v_add_f32_e32 v186, v186, v253
	s_nop 0
	v_mul_f32_e32 v150, v150, v254
	v_mul_f32_e32 v151, v151, v254
	ds_write_b32 v184, v254
	s_waitcnt lgkmcnt(0)
	v_mfma_f32_32x32x16_bf16 v[20:35], v[188:191], v[132:135], v[20:35]
	v_mfma_f32_32x32x16_bf16 v[36:51], v[188:191], v[136:139], v[36:51]
	v_mfma_f32_32x32x16_bf16 v[52:67], v[188:191], v[140:143], v[52:67]
	v_mfma_f32_32x32x16_bf16 v[68:83], v[188:191], v[144:147], v[68:83]
	v_mfma_f32_32x32x16_bf16 v[20:35], v[192:195], v[220:223], v[20:35]
	v_mfma_f32_32x32x16_bf16 v[36:51], v[192:195], v[224:227], v[36:51]
	v_mfma_f32_32x32x16_bf16 v[52:67], v[192:195], v[232:235], v[52:67]
	ds_read_b64_tr_b16 v[132:133], v231 offset:4096
	ds_read_b64_tr_b16 v[134:135], v231 offset:6144
	ds_read_b64_tr_b16 v[136:137], v228 offset:8192
	ds_read_b64_tr_b16 v[138:139], v228 offset:10240
	ds_read_b64_tr_b16 v[140:141], v229 offset:8192
	ds_read_b64_tr_b16 v[142:143], v229 offset:10240
	ds_read_b64_tr_b16 v[144:145], v230 offset:8192
	ds_read_b64_tr_b16 v[146:147], v230 offset:10240
	ds_read_b64_tr_b16 v[220:221], v231 offset:8192
	ds_read_b64_tr_b16 v[222:223], v231 offset:10240
	ds_read_b64_tr_b16 v[224:225], v228 offset:12288
	ds_read_b64_tr_b16 v[226:227], v228 offset:14336
	ds_read_b64_tr_b16 v[232:233], v229 offset:12288
	ds_read_b64_tr_b16 v[234:235], v229 offset:14336
	s_waitcnt lgkmcnt(0)
	v_mfma_f32_32x32x16_bf16 v[68:83], v[192:195], v[132:135], v[68:83]
	v_mfma_f32_32x32x16_bf16 v[20:35], v[204:207], v[136:139], v[20:35]
	v_mfma_f32_32x32x16_bf16 v[36:51], v[204:207], v[140:143], v[36:51]
	v_mfma_f32_32x32x16_bf16 v[52:67], v[204:207], v[144:147], v[52:67]
	v_mfma_f32_32x32x16_bf16 v[68:83], v[204:207], v[220:223], v[68:83]
	v_mfma_f32_32x32x16_bf16 v[20:35], v[208:211], v[224:227], v[20:35]
	v_mfma_f32_32x32x16_bf16 v[36:51], v[208:211], v[232:235], v[36:51]
	ds_read_b64_tr_b16 v[132:133], v230 offset:12288
	ds_read_b64_tr_b16 v[134:135], v230 offset:14336
	ds_read_b64_tr_b16 v[136:137], v231 offset:12288
	ds_read_b64_tr_b16 v[138:139], v231 offset:14336
	s_waitcnt lgkmcnt(0)
	v_mfma_f32_32x32x16_bf16 v[52:67], v[208:211], v[132:135], v[52:67]
	v_mfma_f32_32x32x16_bf16 v[68:83], v[208:211], v[136:139], v[68:83]
	ds_read_b128 v[196:199], v185
	ds_read_b128 v[200:203], v185 offset:32
	ds_read_b128 v[212:215], v185 offset:64
	ds_read_b128 v[216:219], v185 offset:96
	s_waitcnt lgkmcnt(0)
	s_nop 15
	s_nop 15
	v_pk_mul_f32 v[20:21], v[20:21], v[196:197]
	v_pk_mul_f32 v[22:23], v[22:23], v[198:199]
	v_pk_mul_f32 v[24:25], v[24:25], v[200:201]
	v_pk_mul_f32 v[26:27], v[26:27], v[202:203]
	v_pk_mul_f32 v[28:29], v[28:29], v[212:213]
	v_pk_mul_f32 v[30:31], v[30:31], v[214:215]
	v_pk_mul_f32 v[32:33], v[32:33], v[216:217]
	v_pk_mul_f32 v[34:35], v[34:35], v[218:219]
	v_pk_mul_f32 v[36:37], v[36:37], v[196:197]
	v_pk_mul_f32 v[38:39], v[38:39], v[198:199]
	v_pk_mul_f32 v[40:41], v[40:41], v[200:201]
	v_pk_mul_f32 v[42:43], v[42:43], v[202:203]
	v_pk_mul_f32 v[44:45], v[44:45], v[212:213]
	v_pk_mul_f32 v[46:47], v[46:47], v[214:215]
	v_pk_mul_f32 v[48:49], v[48:49], v[216:217]
	v_pk_mul_f32 v[50:51], v[50:51], v[218:219]
	v_pk_mul_f32 v[52:53], v[52:53], v[196:197]
	v_pk_mul_f32 v[54:55], v[54:55], v[198:199]
	v_pk_mul_f32 v[56:57], v[56:57], v[200:201]
	v_pk_mul_f32 v[58:59], v[58:59], v[202:203]
	v_pk_mul_f32 v[60:61], v[60:61], v[212:213]
	v_pk_mul_f32 v[62:63], v[62:63], v[214:215]
	v_pk_mul_f32 v[64:65], v[64:65], v[216:217]
	v_pk_mul_f32 v[66:67], v[66:67], v[218:219]
	v_pk_mul_f32 v[68:69], v[68:69], v[196:197]
	v_pk_mul_f32 v[70:71], v[70:71], v[198:199]
	v_pk_mul_f32 v[72:73], v[72:73], v[200:201]
	v_pk_mul_f32 v[74:75], v[74:75], v[202:203]
	v_pk_mul_f32 v[76:77], v[76:77], v[212:213]
	v_pk_mul_f32 v[78:79], v[78:79], v[214:215]
	v_pk_mul_f32 v[80:81], v[80:81], v[216:217]
	v_pk_mul_f32 v[82:83], v[82:83], v[218:219]
	v_mov_b32_e32 v252, v253
	v_pk_add_f32 v[84:85], v[84:85], v[252:253] neg_lo:[0,1] neg_hi:[0,1]
	v_pk_add_f32 v[86:87], v[86:87], v[252:253] neg_lo:[0,1] neg_hi:[0,1]
	v_pk_add_f32 v[88:89], v[88:89], v[252:253] neg_lo:[0,1] neg_hi:[0,1]
	v_pk_add_f32 v[90:91], v[90:91], v[252:253] neg_lo:[0,1] neg_hi:[0,1]
	v_pk_add_f32 v[92:93], v[92:93], v[252:253] neg_lo:[0,1] neg_hi:[0,1]
	v_pk_add_f32 v[94:95], v[94:95], v[252:253] neg_lo:[0,1] neg_hi:[0,1]
	v_pk_add_f32 v[96:97], v[96:97], v[252:253] neg_lo:[0,1] neg_hi:[0,1]
	v_pk_add_f32 v[98:99], v[98:99], v[252:253] neg_lo:[0,1] neg_hi:[0,1]
	v_pk_add_f32 v[100:101], v[100:101], v[252:253] neg_lo:[0,1] neg_hi:[0,1]
	v_pk_add_f32 v[102:103], v[102:103], v[252:253] neg_lo:[0,1] neg_hi:[0,1]
	v_pk_add_f32 v[104:105], v[104:105], v[252:253] neg_lo:[0,1] neg_hi:[0,1]
	v_pk_add_f32 v[106:107], v[106:107], v[252:253] neg_lo:[0,1] neg_hi:[0,1]
	v_pk_add_f32 v[108:109], v[108:109], v[252:253] neg_lo:[0,1] neg_hi:[0,1]
	v_pk_add_f32 v[110:111], v[110:111], v[252:253] neg_lo:[0,1] neg_hi:[0,1]
	v_pk_add_f32 v[112:113], v[112:113], v[252:253] neg_lo:[0,1] neg_hi:[0,1]
	v_pk_add_f32 v[114:115], v[114:115], v[252:253] neg_lo:[0,1] neg_hi:[0,1]
	v_mov_b64_e32 v[188:189], 0
	v_mov_b64_e32 v[190:191], 0
	v_mov_b64_e32 v[192:193], 0
	v_mov_b64_e32 v[194:195], 0
	v_mov_b64_e32 v[204:205], 0
	v_mov_b64_e32 v[206:207], 0
	v_mov_b64_e32 v[208:209], 0
	v_mov_b64_e32 v[210:211], 0
	s_sub_u32 s5, s8, s4
	s_lshr_b32 s5, s5, 12
	s_sub_u32 s5, s5, 64
	s_add_u32 s38, s5, 64
	s_cmp_lt_u32 s38, s11
	s_cselect_b32 s37, 1, 0
	s_cmp_gt_u32 s38, s31
	s_cselect_b32 s40, 2, 0
	s_or_b32 s37, s37, s40
	s_mov_b32 s35, s37
	v_mov_b32_e32 v251, 0
	s_cmp_eq_u32 s37, 1
	s_cselect_b64 vcc, -1, 0
	v_cndmask_b32_e32 v251, v251, v177, vcc
	s_cmp_eq_u32 s37, 2
	s_cselect_b64 vcc, -1, 0
	v_cndmask_b32_e32 v251, v251, v178, vcc
	v_sub_f32_e32 v2, v251, v186
	v_mov_b32_e32 v3, v2
	v_mov_b64_e32 v[4:5], v[2:3]
	v_mov_b64_e32 v[6:7], v[2:3]
	v_mov_b64_e32 v[8:9], v[2:3]
	v_mov_b64_e32 v[10:11], v[2:3]
	v_mov_b64_e32 v[12:13], v[2:3]
	v_mov_b64_e32 v[14:15], v[2:3]
	v_mov_b64_e32 v[16:17], v[2:3]
	s_nop 1
	s_cmp_eq_u32 s42, 0
	s_cbranch_scc1 .LatA_rareret_m0
	s_branch .LatA_rareret_x4
; #define LAS __attribute__((address_space(3)))
; __device__ __forceinline__ float max2f(float a, float b) { float r; asm("v_max_f32_e32 %0, %1, %2" : "=v"(r) : "v"(a), "v"(b)); return r; }
; __device__ __forceinline__ void attn_unit(LAS unsigned char* lds, const bf16_t* Z, bf16_t* A2, const float* tabg, int seq_base, int S, int h, int qb, float lam) {
;     ...
;         bool near = true; float cc = 0.f;
;         if (kv0 - (qlo + 31) >= 128) { near = false; cc = tabR; } else if (qlo - (kv0 + 63) >= 128) { near = false; cc = tabL; }
;         { const float coff = cc - mu;
;           if (__any(!(coff == coff_cur))) { coff_cur = coff;
; #pragma unroll
;               for (int r = 0; r < 16; ++r) cblk[r] = coff;
;               asm volatile("" : "+v"(cblk)); } }
;     ...
;         if (first || __any(mx > THR)) {
;             { auto rr = __builtin_amdgcn_permlane32_swap(__float_as_uint(mx), __float_as_uint(mx), false, false); mx = max2f(__uint_as_float(rr[0]), __uint_as_float(rr[1])); }
;             const float delta = first ? mx : fmaxf(mx, 0.f);
;             const float alpha = first ? 1.0f : __builtin_amdgcn_exp2f(-delta);
;             mu += delta; ls2 *= alpha;
;             if (!first) {
;                 asm volatile("" ::: "memory");
;                 scr[r32] = alpha;
;                 asm volatile("s_waitcnt lgkmcnt(0)" ::: "memory");
; #pragma unroll
;                 for (int g = 0; g < 4; ++g) { const f32x4 a4 = *(const LAS f32x4*)(scr + 8 * g + 4 * hi);
; #pragma unroll
;                     for (int d = 0; d < 4; ++d) { O[d][4 * g + 0] *= a4[0]; O[d][4 * g + 1] *= a4[1]; O[d][4 * g + 2] *= a4[2]; O[d][4 * g + 3] *= a4[3]; } }
;                 asm volatile("s_waitcnt lgkmcnt(0)" ::: "memory");
;             }
; #pragma unroll
;             for (int r = 0; r < 16; ++r) { p0[r] -= delta; p1[r] -= delta; }
;             asm volatile("" : "+v"(p0), "+v"(p1));
;         }
.LatA_rare_511:
	v_mov_b32_e32 v252, v251
	s_nop 1
	v_permlane32_swap_b32_e32 v251, v252
	v_max_f32_e32 v251, v251, v252
	v_max_f32_e32 v253, 0, v251
	v_exp_f32_e64 v254, -v253
	v_add_f32_e32 v186, v186, v253
	s_nop 0
	v_mul_f32_e32 v150, v150, v254
	v_mul_f32_e32 v151, v151, v254
	ds_write_b32 v184, v254
	s_waitcnt lgkmcnt(0)
	v_mfma_f32_32x32x16_bf16 v[20:35], v[84:87], v[132:135], v[20:35]
	v_mfma_f32_32x32x16_bf16 v[36:51], v[84:87], v[136:139], v[36:51]
	v_mfma_f32_32x32x16_bf16 v[52:67], v[84:87], v[140:143], v[52:67]
	v_mfma_f32_32x32x16_bf16 v[68:83], v[84:87], v[144:147], v[68:83]
	v_mfma_f32_32x32x16_bf16 v[20:35], v[88:91], v[220:223], v[20:35]
	v_mfma_f32_32x32x16_bf16 v[36:51], v[88:91], v[224:227], v[36:51]
	v_mfma_f32_32x32x16_bf16 v[52:67], v[88:91], v[232:235], v[52:67]
	ds_read_b64_tr_b16 v[132:133], v231 offset:20480
	ds_read_b64_tr_b16 v[134:135], v231 offset:22528
	ds_read_b64_tr_b16 v[136:137], v228 offset:24576
	ds_read_b64_tr_b16 v[138:139], v228 offset:26624
	ds_read_b64_tr_b16 v[140:141], v229 offset:24576
	ds_read_b64_tr_b16 v[142:143], v229 offset:26624
	ds_read_b64_tr_b16 v[144:145], v230 offset:24576
	ds_read_b64_tr_b16 v[146:147], v230 offset:26624
	ds_read_b64_tr_b16 v[220:221], v231 offset:24576
	ds_read_b64_tr_b16 v[222:223], v231 offset:26624
	ds_read_b64_tr_b16 v[224:225], v228 offset:28672
	ds_read_b64_tr_b16 v[226:227], v228 offset:30720
	ds_read_b64_tr_b16 v[232:233], v229 offset:28672
	ds_read_b64_tr_b16 v[234:235], v229 offset:30720
	s_waitcnt lgkmcnt(0)
	v_mfma_f32_32x32x16_bf16 v[68:83], v[88:91], v[132:135], v[68:83]
	v_mfma_f32_32x32x16_bf16 v[20:35], v[100:103], v[136:139], v[20:35]
	v_mfma_f32_32x32x16_bf16 v[36:51], v[100:103], v[140:143], v[36:51]
	v_mfma_f32_32x32x16_bf16 v[52:67], v[100:103], v[144:147], v[52:67]
	v_mfma_f32_32x32x16_bf16 v[68:83], v[100:103], v[220:223], v[68:83]
	v_mfma_f32_32x32x16_bf16 v[20:35], v[104:107], v[224:227], v[20:35]
	v_mfma_f32_32x32x16_bf16 v[36:51], v[104:107], v[232:235], v[36:51]
	ds_read_b64_tr_b16 v[132:133], v230 offset:28672
	ds_read_b64_tr_b16 v[134:135], v230 offset:30720
	ds_read_b64_tr_b16 v[136:137], v231 offset:28672
	ds_read_b64_tr_b16 v[138:139], v231 offset:30720
	s_waitcnt lgkmcnt(0)
	v_mfma_f32_32x32x16_bf16 v[52:67], v[104:107], v[132:135], v[52:67]
	v_mfma_f32_32x32x16_bf16 v[68:83], v[104:107], v[136:139], v[68:83]
	ds_read_b128 v[92:95], v185
	ds_read_b128 v[96:99], v185 offset:32
	ds_read_b128 v[108:111], v185 offset:64
	ds_read_b128 v[112:115], v185 offset:96
	s_waitcnt lgkmcnt(0)
	s_nop 15
	s_nop 15
	v_pk_mul_f32 v[20:21], v[20:21], v[92:93]
	v_pk_mul_f32 v[22:23], v[22:23], v[94:95]
	v_pk_mul_f32 v[24:25], v[24:25], v[96:97]
	v_pk_mul_f32 v[26:27], v[26:27], v[98:99]
	v_pk_mul_f32 v[28:29], v[28:29], v[108:109]
	v_pk_mul_f32 v[30:31], v[30:31], v[110:111]
	v_pk_mul_f32 v[32:33], v[32:33], v[112:113]
	v_pk_mul_f32 v[34:35], v[34:35], v[114:115]
	v_pk_mul_f32 v[36:37], v[36:37], v[92:93]
	v_pk_mul_f32 v[38:39], v[38:39], v[94:95]
	v_pk_mul_f32 v[40:41], v[40:41], v[96:97]
	v_pk_mul_f32 v[42:43], v[42:43], v[98:99]
	v_pk_mul_f32 v[44:45], v[44:45], v[108:109]
	v_pk_mul_f32 v[46:47], v[46:47], v[110:111]
	v_pk_mul_f32 v[48:49], v[48:49], v[112:113]
	v_pk_mul_f32 v[50:51], v[50:51], v[114:115]
	v_pk_mul_f32 v[52:53], v[52:53], v[92:93]
	v_pk_mul_f32 v[54:55], v[54:55], v[94:95]
	v_pk_mul_f32 v[56:57], v[56:57], v[96:97]
	v_pk_mul_f32 v[58:59], v[58:59], v[98:99]
	v_pk_mul_f32 v[60:61], v[60:61], v[108:109]
	v_pk_mul_f32 v[62:63], v[62:63], v[110:111]
	v_pk_mul_f32 v[64:65], v[64:65], v[112:113]
	v_pk_mul_f32 v[66:67], v[66:67], v[114:115]
	v_pk_mul_f32 v[68:69], v[68:69], v[92:93]
	v_pk_mul_f32 v[70:71], v[70:71], v[94:95]
	v_pk_mul_f32 v[72:73], v[72:73], v[96:97]
	v_pk_mul_f32 v[74:75], v[74:75], v[98:99]
	v_pk_mul_f32 v[76:77], v[76:77], v[108:109]
	v_pk_mul_f32 v[78:79], v[78:79], v[110:111]
	v_pk_mul_f32 v[80:81], v[80:81], v[112:113]
	v_pk_mul_f32 v[82:83], v[82:83], v[114:115]
	v_mov_b32_e32 v252, v253
	v_pk_add_f32 v[188:189], v[188:189], v[252:253] neg_lo:[0,1] neg_hi:[0,1]
	v_pk_add_f32 v[190:191], v[190:191], v[252:253] neg_lo:[0,1] neg_hi:[0,1]
	v_pk_add_f32 v[192:193], v[192:193], v[252:253] neg_lo:[0,1] neg_hi:[0,1]
	v_pk_add_f32 v[194:195], v[194:195], v[252:253] neg_lo:[0,1] neg_hi:[0,1]
	v_pk_add_f32 v[196:197], v[196:197], v[252:253] neg_lo:[0,1] neg_hi:[0,1]
	v_pk_add_f32 v[198:199], v[198:199], v[252:253] neg_lo:[0,1] neg_hi:[0,1]
	v_pk_add_f32 v[200:201], v[200:201], v[252:253] neg_lo:[0,1] neg_hi:[0,1]
	v_pk_add_f32 v[202:203], v[202:203], v[252:253] neg_lo:[0,1] neg_hi:[0,1]
	v_pk_add_f32 v[204:205], v[204:205], v[252:253] neg_lo:[0,1] neg_hi:[0,1]
	v_pk_add_f32 v[206:207], v[206:207], v[252:253] neg_lo:[0,1] neg_hi:[0,1]
	v_pk_add_f32 v[208:209], v[208:209], v[252:253] neg_lo:[0,1] neg_hi:[0,1]
	v_pk_add_f32 v[210:211], v[210:211], v[252:253] neg_lo:[0,1] neg_hi:[0,1]
	v_pk_add_f32 v[212:213], v[212:213], v[252:253] neg_lo:[0,1] neg_hi:[0,1]
	v_pk_add_f32 v[214:215], v[214:215], v[252:253] neg_lo:[0,1] neg_hi:[0,1]
	v_pk_add_f32 v[216:217], v[216:217], v[252:253] neg_lo:[0,1] neg_hi:[0,1]
	v_pk_add_f32 v[218:219], v[218:219], v[252:253] neg_lo:[0,1] neg_hi:[0,1]
	v_mov_b64_e32 v[84:85], 0
	v_mov_b64_e32 v[86:87], 0
	v_mov_b64_e32 v[88:89], 0
	v_mov_b64_e32 v[90:91], 0
	v_mov_b64_e32 v[100:101], 0
	v_mov_b64_e32 v[102:103], 0
	v_mov_b64_e32 v[104:105], 0
	v_mov_b64_e32 v[106:107], 0
	s_sub_u32 s5, s8, s4
	s_lshr_b32 s5, s5, 12
	s_sub_u32 s5, s5, 64
	s_add_u32 s38, s5, 64
	s_cmp_lt_u32 s38, s11
	s_cselect_b32 s37, 1, 0
	s_cmp_gt_u32 s38, s31
	s_cselect_b32 s40, 2, 0
	s_or_b32 s37, s37, s40
	s_mov_b32 s35, s37
	v_mov_b32_e32 v251, 0
	s_cmp_eq_u32 s37, 1
	s_cselect_b64 vcc, -1, 0
	v_cndmask_b32_e32 v251, v251, v177, vcc
	s_cmp_eq_u32 s37, 2
	s_cselect_b64 vcc, -1, 0
	v_cndmask_b32_e32 v251, v251, v178, vcc
	v_sub_f32_e32 v2, v251, v186
	v_mov_b32_e32 v3, v2
	v_mov_b64_e32 v[4:5], v[2:3]
	v_mov_b64_e32 v[6:7], v[2:3]
	v_mov_b64_e32 v[8:9], v[2:3]
	v_mov_b64_e32 v[10:11], v[2:3]
	v_mov_b64_e32 v[12:13], v[2:3]
	v_mov_b64_e32 v[14:15], v[2:3]
	v_mov_b64_e32 v[16:17], v[2:3]
	s_nop 1
	s_cmp_eq_u32 s42, 0
	s_cbranch_scc1 .LatA_rareret_m1
	s_branch .LatA_rareret_x3
; #define LAS __attribute__((address_space(3)))
; __device__ __forceinline__ float max2f(float a, float b) { float r; asm("v_max_f32_e32 %0, %1, %2" : "=v"(r) : "v"(a), "v"(b)); return r; }
; __device__ __forceinline__ void attn_unit(LAS unsigned char* lds, const bf16_t* Z, bf16_t* A2, const float* tabg, int seq_base, int S, int h, int qb, float lam) {
;     ...
;         bool near = true; float cc = 0.f;
;         if (kv0 - (qlo + 31) >= 128) { near = false; cc = tabR; } else if (qlo - (kv0 + 63) >= 128) { near = false; cc = tabL; }
;         { const float coff = cc - mu;
;           if (__any(!(coff == coff_cur))) { coff_cur = coff;
; #pragma unroll
;               for (int r = 0; r < 16; ++r) cblk[r] = coff;
;               asm volatile("" : "+v"(cblk)); } }
;     ...
;         if (first || __any(mx > THR)) {
;             { auto rr = __builtin_amdgcn_permlane32_swap(__float_as_uint(mx), __float_as_uint(mx), false, false); mx = max2f(__uint_as_float(rr[0]), __uint_as_float(rr[1])); }
;             const float delta = first ? mx : fmaxf(mx, 0.f);
;             const float alpha = first ? 1.0f : __builtin_amdgcn_exp2f(-delta);
;             mu += delta; ls2 *= alpha;
;             if (!first) {
;                 asm volatile("" ::: "memory");
;                 scr[r32] = alpha;
;                 asm volatile("s_waitcnt lgkmcnt(0)" ::: "memory");
; #pragma unroll
;                 for (int g = 0; g < 4; ++g) { const f32x4 a4 = *(const LAS f32x4*)(scr + 8 * g + 4 * hi);
; #pragma unroll
;                     for (int d = 0; d < 4; ++d) { O[d][4 * g + 0] *= a4[0]; O[d][4 * g + 1] *= a4[1]; O[d][4 * g + 2] *= a4[2]; O[d][4 * g + 3] *= a4[3]; } }
;                 asm volatile("s_waitcnt lgkmcnt(0)" ::: "memory");
;             }
; #pragma unroll
;             for (int r = 0; r < 16; ++r) { p0[r] -= delta; p1[r] -= delta; }
;             asm volatile("" : "+v"(p0), "+v"(p1));
;         }
.LatA_rare_011:
	v_mov_b32_e32 v252, v251
	s_nop 1
	v_permlane32_swap_b32_e32 v251, v252
	v_max_f32_e32 v251, v251, v252
	v_max_f32_e32 v253, 0, v251
	v_exp_f32_e64 v254, -v253
	v_add_f32_e32 v186, v186, v253
	s_nop 0
	v_mul_f32_e32 v150, v150, v254
	v_mul_f32_e32 v151, v151, v254
	ds_write_b32 v184, v254
	s_waitcnt lgkmcnt(0)
	v_mfma_f32_32x32x16_bf16 v[20:35], v[188:191], v[132:135], v[20:35]
	v_mfma_f32_32x32x16_bf16 v[36:51], v[188:191], v[136:139], v[36:51]
	v_mfma_f32_32x32x16_bf16 v[52:67], v[188:191], v[140:143], v[52:67]
	v_mfma_f32_32x32x16_bf16 v[68:83], v[188:191], v[144:147], v[68:83]
	v_mfma_f32_32x32x16_bf16 v[20:35], v[192:195], v[220:223], v[20:35]
	v_mfma_f32_32x32x16_bf16 v[36:51], v[192:195], v[224:227], v[36:51]
	v_mfma_f32_32x32x16_bf16 v[52:67], v[192:195], v[232:235], v[52:67]
	ds_read_b64_tr_b16 v[132:133], v231 offset:36864
	ds_read_b64_tr_b16 v[134:135], v231 offset:38912
	ds_read_b64_tr_b16 v[136:137], v228 offset:40960
	ds_read_b64_tr_b16 v[138:139], v228 offset:43008
	ds_read_b64_tr_b16 v[140:141], v229 offset:40960
	ds_read_b64_tr_b16 v[142:143], v229 offset:43008
	ds_read_b64_tr_b16 v[144:145], v230 offset:40960
	ds_read_b64_tr_b16 v[146:147], v230 offset:43008
	ds_read_b64_tr_b16 v[220:221], v231 offset:40960
	ds_read_b64_tr_b16 v[222:223], v231 offset:43008
	ds_read_b64_tr_b16 v[224:225], v228 offset:45056
	ds_read_b64_tr_b16 v[226:227], v228 offset:47104
	ds_read_b64_tr_b16 v[232:233], v229 offset:45056
	ds_read_b64_tr_b16 v[234:235], v229 offset:47104
	s_waitcnt lgkmcnt(0)
	v_mfma_f32_32x32x16_bf16 v[68:83], v[192:195], v[132:135], v[68:83]
	v_mfma_f32_32x32x16_bf16 v[20:35], v[204:207], v[136:139], v[20:35]
	v_mfma_f32_32x32x16_bf16 v[36:51], v[204:207], v[140:143], v[36:51]
	v_mfma_f32_32x32x16_bf16 v[52:67], v[204:207], v[144:147], v[52:67]
	v_mfma_f32_32x32x16_bf16 v[68:83], v[204:207], v[220:223], v[68:83]
	v_mfma_f32_32x32x16_bf16 v[20:35], v[208:211], v[224:227], v[20:35]
	v_mfma_f32_32x32x16_bf16 v[36:51], v[208:211], v[232:235], v[36:51]
	ds_read_b64_tr_b16 v[132:133], v230 offset:45056
	ds_read_b64_tr_b16 v[134:135], v230 offset:47104
	ds_read_b64_tr_b16 v[136:137], v231 offset:45056
	ds_read_b64_tr_b16 v[138:139], v231 offset:47104
	s_waitcnt lgkmcnt(0)
	v_mfma_f32_32x32x16_bf16 v[52:67], v[208:211], v[132:135], v[52:67]
	v_mfma_f32_32x32x16_bf16 v[68:83], v[208:211], v[136:139], v[68:83]
	ds_read_b128 v[196:199], v185
	ds_read_b128 v[200:203], v185 offset:32
	ds_read_b128 v[212:215], v185 offset:64
	ds_read_b128 v[216:219], v185 offset:96
	s_waitcnt lgkmcnt(0)
	s_nop 15
	s_nop 15
	v_pk_mul_f32 v[20:21], v[20:21], v[196:197]
	v_pk_mul_f32 v[22:23], v[22:23], v[198:199]
	v_pk_mul_f32 v[24:25], v[24:25], v[200:201]
	v_pk_mul_f32 v[26:27], v[26:27], v[202:203]
	v_pk_mul_f32 v[28:29], v[28:29], v[212:213]
	v_pk_mul_f32 v[30:31], v[30:31], v[214:215]
	v_pk_mul_f32 v[32:33], v[32:33], v[216:217]
	v_pk_mul_f32 v[34:35], v[34:35], v[218:219]
	v_pk_mul_f32 v[36:37], v[36:37], v[196:197]
	v_pk_mul_f32 v[38:39], v[38:39], v[198:199]
	v_pk_mul_f32 v[40:41], v[40:41], v[200:201]
	v_pk_mul_f32 v[42:43], v[42:43], v[202:203]
	v_pk_mul_f32 v[44:45], v[44:45], v[212:213]
	v_pk_mul_f32 v[46:47], v[46:47], v[214:215]
	v_pk_mul_f32 v[48:49], v[48:49], v[216:217]
	v_pk_mul_f32 v[50:51], v[50:51], v[218:219]
	v_pk_mul_f32 v[52:53], v[52:53], v[196:197]
	v_pk_mul_f32 v[54:55], v[54:55], v[198:199]
	v_pk_mul_f32 v[56:57], v[56:57], v[200:201]
	v_pk_mul_f32 v[58:59], v[58:59], v[202:203]
	v_pk_mul_f32 v[60:61], v[60:61], v[212:213]
	v_pk_mul_f32 v[62:63], v[62:63], v[214:215]
	v_pk_mul_f32 v[64:65], v[64:65], v[216:217]
	v_pk_mul_f32 v[66:67], v[66:67], v[218:219]
	v_pk_mul_f32 v[68:69], v[68:69], v[196:197]
	v_pk_mul_f32 v[70:71], v[70:71], v[198:199]
	v_pk_mul_f32 v[72:73], v[72:73], v[200:201]
	v_pk_mul_f32 v[74:75], v[74:75], v[202:203]
	v_pk_mul_f32 v[76:77], v[76:77], v[212:213]
	v_pk_mul_f32 v[78:79], v[78:79], v[214:215]
	v_pk_mul_f32 v[80:81], v[80:81], v[216:217]
	v_pk_mul_f32 v[82:83], v[82:83], v[218:219]
	v_mov_b32_e32 v252, v253
	v_pk_add_f32 v[84:85], v[84:85], v[252:253] neg_lo:[0,1] neg_hi:[0,1]
	v_pk_add_f32 v[86:87], v[86:87], v[252:253] neg_lo:[0,1] neg_hi:[0,1]
	v_pk_add_f32 v[88:89], v[88:89], v[252:253] neg_lo:[0,1] neg_hi:[0,1]
	v_pk_add_f32 v[90:91], v[90:91], v[252:253] neg_lo:[0,1] neg_hi:[0,1]
	v_pk_add_f32 v[92:93], v[92:93], v[252:253] neg_lo:[0,1] neg_hi:[0,1]
	v_pk_add_f32 v[94:95], v[94:95], v[252:253] neg_lo:[0,1] neg_hi:[0,1]
	v_pk_add_f32 v[96:97], v[96:97], v[252:253] neg_lo:[0,1] neg_hi:[0,1]
	v_pk_add_f32 v[98:99], v[98:99], v[252:253] neg_lo:[0,1] neg_hi:[0,1]
	v_pk_add_f32 v[100:101], v[100:101], v[252:253] neg_lo:[0,1] neg_hi:[0,1]
	v_pk_add_f32 v[102:103], v[102:103], v[252:253] neg_lo:[0,1] neg_hi:[0,1]
	v_pk_add_f32 v[104:105], v[104:105], v[252:253] neg_lo:[0,1] neg_hi:[0,1]
	v_pk_add_f32 v[106:107], v[106:107], v[252:253] neg_lo:[0,1] neg_hi:[0,1]
	v_pk_add_f32 v[108:109], v[108:109], v[252:253] neg_lo:[0,1] neg_hi:[0,1]
	v_pk_add_f32 v[110:111], v[110:111], v[252:253] neg_lo:[0,1] neg_hi:[0,1]
	v_pk_add_f32 v[112:113], v[112:113], v[252:253] neg_lo:[0,1] neg_hi:[0,1]
	v_pk_add_f32 v[114:115], v[114:115], v[252:253] neg_lo:[0,1] neg_hi:[0,1]
	v_mov_b64_e32 v[188:189], 0
	v_mov_b64_e32 v[190:191], 0
	v_mov_b64_e32 v[192:193], 0
	v_mov_b64_e32 v[194:195], 0
	v_mov_b64_e32 v[204:205], 0
	v_mov_b64_e32 v[206:207], 0
	v_mov_b64_e32 v[208:209], 0
	v_mov_b64_e32 v[210:211], 0
	s_sub_u32 s5, s8, s4
	s_lshr_b32 s5, s5, 12
	s_sub_u32 s5, s5, 64
	s_add_u32 s38, s5, 64
	s_cmp_lt_u32 s38, s11
	s_cselect_b32 s37, 1, 0
	s_cmp_gt_u32 s38, s31
	s_cselect_b32 s40, 2, 0
	s_or_b32 s37, s37, s40
	s_mov_b32 s35, s37
	v_mov_b32_e32 v251, 0
	s_cmp_eq_u32 s37, 1
	s_cselect_b64 vcc, -1, 0
	v_cndmask_b32_e32 v251, v251, v177, vcc
	s_cmp_eq_u32 s37, 2
	s_cselect_b64 vcc, -1, 0
	v_cndmask_b32_e32 v251, v251, v178, vcc
	v_sub_f32_e32 v2, v251, v186
	v_mov_b32_e32 v3, v2
	v_mov_b64_e32 v[4:5], v[2:3]
	v_mov_b64_e32 v[6:7], v[2:3]
	v_mov_b64_e32 v[8:9], v[2:3]
	v_mov_b64_e32 v[10:11], v[2:3]
	v_mov_b64_e32 v[12:13], v[2:3]
	v_mov_b64_e32 v[14:15], v[2:3]
	v_mov_b64_e32 v[16:17], v[2:3]
	s_nop 1
	s_cmp_eq_u32 s42, 0
	s_cbranch_scc1 .LatA_rareret_m2
	s_branch .LatA_rareret_x2
; #define LAS __attribute__((address_space(3)))
; __device__ __forceinline__ float max2f(float a, float b) { float r; asm("v_max_f32_e32 %0, %1, %2" : "=v"(r) : "v"(a), "v"(b)); return r; }
; __device__ __forceinline__ void attn_unit(LAS unsigned char* lds, const bf16_t* Z, bf16_t* A2, const float* tabg, int seq_base, int S, int h, int qb, float lam) {
;     ...
;         if (first || __any(mx > THR)) {
;             { auto rr = __builtin_amdgcn_permlane32_swap(__float_as_uint(mx), __float_as_uint(mx), false, false); mx = max2f(__uint_as_float(rr[0]), __uint_as_float(rr[1])); }
;             const float delta = first ? mx : fmaxf(mx, 0.f);
;             const float alpha = first ? 1.0f : __builtin_amdgcn_exp2f(-delta);
;             mu += delta; ls2 *= alpha;
;             if (!first) {
;                 asm volatile("" ::: "memory");
;                 scr[r32] = alpha;
;                 asm volatile("s_waitcnt lgkmcnt(0)" ::: "memory");
; #pragma unroll
;                 for (int g = 0; g < 4; ++g) { const f32x4 a4 = *(const LAS f32x4*)(scr + 8 * g + 4 * hi);
; #pragma unroll
;                     for (int d = 0; d < 4; ++d) { O[d][4 * g + 0] *= a4[0]; O[d][4 * g + 1] *= a4[1]; O[d][4 * g + 2] *= a4[2]; O[d][4 * g + 3] *= a4[3]; } }
;                 asm volatile("s_waitcnt lgkmcnt(0)" ::: "memory");
;             }
; #pragma unroll
;             for (int r = 0; r < 16; ++r) { p0[r] -= delta; p1[r] -= delta; }
;             asm volatile("" : "+v"(p0), "+v"(p1));
;         }
.LatA_rare_110:
	v_mov_b32_e32 v252, v251
	s_nop 1
	v_permlane32_swap_b32_e32 v251, v252
	v_max_f32_e32 v251, v251, v252
	v_max_f32_e32 v253, 0, v251
	v_exp_f32_e64 v254, -v253
	v_add_f32_e32 v186, v186, v253
	s_nop 0
	v_mul_f32_e32 v150, v150, v254
	v_mul_f32_e32 v151, v151, v254
	ds_write_b32 v184, v254
	s_waitcnt lgkmcnt(0)
	v_mfma_f32_32x32x16_bf16 v[20:35], v[84:87], v[132:135], v[20:35]
	v_mfma_f32_32x32x16_bf16 v[36:51], v[84:87], v[136:139], v[36:51]
	v_mfma_f32_32x32x16_bf16 v[52:67], v[84:87], v[140:143], v[52:67]
	v_mfma_f32_32x32x16_bf16 v[68:83], v[84:87], v[144:147], v[68:83]
	v_mfma_f32_32x32x16_bf16 v[20:35], v[88:91], v[220:223], v[20:35]
	v_mfma_f32_32x32x16_bf16 v[36:51], v[88:91], v[224:227], v[36:51]
	v_mfma_f32_32x32x16_bf16 v[52:67], v[88:91], v[232:235], v[52:67]
	ds_read_b64_tr_b16 v[132:133], v231 offset:4096
	ds_read_b64_tr_b16 v[134:135], v231 offset:6144
	ds_read_b64_tr_b16 v[136:137], v228 offset:8192
	ds_read_b64_tr_b16 v[138:139], v228 offset:10240
	ds_read_b64_tr_b16 v[140:141], v229 offset:8192
	ds_read_b64_tr_b16 v[142:143], v229 offset:10240
	ds_read_b64_tr_b16 v[144:145], v230 offset:8192
	ds_read_b64_tr_b16 v[146:147], v230 offset:10240
	ds_read_b64_tr_b16 v[220:221], v231 offset:8192
	ds_read_b64_tr_b16 v[222:223], v231 offset:10240
	ds_read_b64_tr_b16 v[224:225], v228 offset:12288
	ds_read_b64_tr_b16 v[226:227], v228 offset:14336
	ds_read_b64_tr_b16 v[232:233], v229 offset:12288
	ds_read_b64_tr_b16 v[234:235], v229 offset:14336
	s_waitcnt lgkmcnt(0)
	v_mfma_f32_32x32x16_bf16 v[68:83], v[88:91], v[132:135], v[68:83]
	v_mfma_f32_32x32x16_bf16 v[20:35], v[100:103], v[136:139], v[20:35]
	v_mfma_f32_32x32x16_bf16 v[36:51], v[100:103], v[140:143], v[36:51]
	v_mfma_f32_32x32x16_bf16 v[52:67], v[100:103], v[144:147], v[52:67]
	v_mfma_f32_32x32x16_bf16 v[68:83], v[100:103], v[220:223], v[68:83]
	v_mfma_f32_32x32x16_bf16 v[20:35], v[104:107], v[224:227], v[20:35]
	v_mfma_f32_32x32x16_bf16 v[36:51], v[104:107], v[232:235], v[36:51]
	ds_read_b64_tr_b16 v[132:133], v230 offset:12288
	ds_read_b64_tr_b16 v[134:135], v230 offset:14336
	ds_read_b64_tr_b16 v[136:137], v231 offset:12288
	ds_read_b64_tr_b16 v[138:139], v231 offset:14336
	s_waitcnt lgkmcnt(0)
	v_mfma_f32_32x32x16_bf16 v[52:67], v[104:107], v[132:135], v[52:67]
	v_mfma_f32_32x32x16_bf16 v[68:83], v[104:107], v[136:139], v[68:83]
	ds_read_b128 v[92:95], v185
	ds_read_b128 v[96:99], v185 offset:32
	ds_read_b128 v[108:111], v185 offset:64
	ds_read_b128 v[112:115], v185 offset:96
	s_waitcnt lgkmcnt(0)
	s_nop 15
	s_nop 15
	v_pk_mul_f32 v[20:21], v[20:21], v[92:93]
	v_pk_mul_f32 v[22:23], v[22:23], v[94:95]
	v_pk_mul_f32 v[24:25], v[24:25], v[96:97]
	v_pk_mul_f32 v[26:27], v[26:27], v[98:99]
	v_pk_mul_f32 v[28:29], v[28:29], v[108:109]
	v_pk_mul_f32 v[30:31], v[30:31], v[110:111]
	v_pk_mul_f32 v[32:33], v[32:33], v[112:113]
	v_pk_mul_f32 v[34:35], v[34:35], v[114:115]
	v_pk_mul_f32 v[36:37], v[36:37], v[92:93]
	v_pk_mul_f32 v[38:39], v[38:39], v[94:95]
	v_pk_mul_f32 v[40:41], v[40:41], v[96:97]
	v_pk_mul_f32 v[42:43], v[42:43], v[98:99]
	v_pk_mul_f32 v[44:45], v[44:45], v[108:109]
	v_pk_mul_f32 v[46:47], v[46:47], v[110:111]
	v_pk_mul_f32 v[48:49], v[48:49], v[112:113]
	v_pk_mul_f32 v[50:51], v[50:51], v[114:115]
	v_pk_mul_f32 v[52:53], v[52:53], v[92:93]
	v_pk_mul_f32 v[54:55], v[54:55], v[94:95]
	v_pk_mul_f32 v[56:57], v[56:57], v[96:97]
	v_pk_mul_f32 v[58:59], v[58:59], v[98:99]
	v_pk_mul_f32 v[60:61], v[60:61], v[108:109]
	v_pk_mul_f32 v[62:63], v[62:63], v[110:111]
	v_pk_mul_f32 v[64:65], v[64:65], v[112:113]
	v_pk_mul_f32 v[66:67], v[66:67], v[114:115]
	v_pk_mul_f32 v[68:69], v[68:69], v[92:93]
	v_pk_mul_f32 v[70:71], v[70:71], v[94:95]
	v_pk_mul_f32 v[72:73], v[72:73], v[96:97]
	v_pk_mul_f32 v[74:75], v[74:75], v[98:99]
	v_pk_mul_f32 v[76:77], v[76:77], v[108:109]
	v_pk_mul_f32 v[78:79], v[78:79], v[110:111]
	v_pk_mul_f32 v[80:81], v[80:81], v[112:113]
	v_pk_mul_f32 v[82:83], v[82:83], v[114:115]
	v_mov_b32_e32 v252, v253
	v_pk_add_f32 v[188:189], v[188:189], v[252:253] neg_lo:[0,1] neg_hi:[0,1]
	v_pk_add_f32 v[190:191], v[190:191], v[252:253] neg_lo:[0,1] neg_hi:[0,1]
	v_pk_add_f32 v[192:193], v[192:193], v[252:253] neg_lo:[0,1] neg_hi:[0,1]
	v_pk_add_f32 v[194:195], v[194:195], v[252:253] neg_lo:[0,1] neg_hi:[0,1]
	v_pk_add_f32 v[196:197], v[196:197], v[252:253] neg_lo:[0,1] neg_hi:[0,1]
	v_pk_add_f32 v[198:199], v[198:199], v[252:253] neg_lo:[0,1] neg_hi:[0,1]
	v_pk_add_f32 v[200:201], v[200:201], v[252:253] neg_lo:[0,1] neg_hi:[0,1]
	v_pk_add_f32 v[202:203], v[202:203], v[252:253] neg_lo:[0,1] neg_hi:[0,1]
	v_pk_add_f32 v[204:205], v[204:205], v[252:253] neg_lo:[0,1] neg_hi:[0,1]
	v_pk_add_f32 v[206:207], v[206:207], v[252:253] neg_lo:[0,1] neg_hi:[0,1]
	v_pk_add_f32 v[208:209], v[208:209], v[252:253] neg_lo:[0,1] neg_hi:[0,1]
	v_pk_add_f32 v[210:211], v[210:211], v[252:253] neg_lo:[0,1] neg_hi:[0,1]
	v_pk_add_f32 v[212:213], v[212:213], v[252:253] neg_lo:[0,1] neg_hi:[0,1]
	v_pk_add_f32 v[214:215], v[214:215], v[252:253] neg_lo:[0,1] neg_hi:[0,1]
	v_pk_add_f32 v[216:217], v[216:217], v[252:253] neg_lo:[0,1] neg_hi:[0,1]
	v_pk_add_f32 v[218:219], v[218:219], v[252:253] neg_lo:[0,1] neg_hi:[0,1]
	v_mov_b64_e32 v[84:85], 0
	v_mov_b64_e32 v[86:87], 0
	v_mov_b64_e32 v[88:89], 0
	v_mov_b64_e32 v[90:91], 0
	v_mov_b64_e32 v[100:101], 0
	v_mov_b64_e32 v[102:103], 0
	v_mov_b64_e32 v[104:105], 0
	v_mov_b64_e32 v[106:107], 0
	s_nop 1
	s_branch .LatA_rareret_x1

; __device__ __forceinline__ void attn_unit(LAS unsigned char* lds, const bf16_t* Z, bf16_t* A2, const float* tabg, int seq_base, int S, int h, int qb, float lam) {
;     const int tid = otid(), w = __builtin_amdgcn_readfirstlane(tid >> 6), lane = tid & 63, r32 = lane & 31, hi = lane >> 5, g4 = lane >> 4, i16 = lane & 15;
;     const int rg = w & 3, m = w >> 2;
;     LAS unsigned char* Kb = lds + OFF_K; LAS unsigned char* Vb = lds + OFF_V;
;     LAS float* scr = (LAS float*)(lds + OFF_SCR) + w * 64;
;     LAS float* tab = (LAS float*)(lds + OFF_TAB);
;     for (int i = tid; i < 449; i += 512) { int d = i - 224; d = d < -128 ? -128 : (d > 128 ? 128 : d); tab[i] = tabg[h * 257 + d + 128]; }
;     const int qlo = qb * 128 + rg * 32;
;     bf16x8 qf[4];
;     { const bf16_t* qrow = Z + (size_t)(seq_base + qlo + r32) * NZ + h * 128 + m * 64 + 8 * hi;
; #pragma unroll
;       for (int ds = 0; ds < 4; ++ds) qf[ds] = *(const bf16x8*)(qrow + 16 * ds); }
;     const char* kvbase = (const char*)(Z + (size_t)seq_base * NZ + h * 128);
;     unsigned koff[2], voff[2];
; #pragma unroll
;     for (int i = 0; i < 2; ++i) { const int row = (i * 8 + w) * 4 + (lane >> 4), cp = lane & 15;
;         koff[i] = (unsigned)(row * NZ + 512 + ((cp ^ (row & 15)) << 3)) * 2u; voff[i] = (unsigned)(row * NZ + 1024 + ((cp ^ (4 * (row & 3))) << 3)) * 2u; }
;     const unsigned kb_u = (unsigned)(size_t)Kb + (unsigned)w * 1024u, vb_u = (unsigned)(size_t)Vb + (unsigned)w * 1024u;
;     ...
;     ATT_STAGE(0, 0); ATT_STAGE(1, 1);
;     asm volatile("s_waitcnt vmcnt(4) lgkmcnt(0)" ::: "memory"); __builtin_amdgcn_s_barrier(); asm volatile("" ::: "memory");
; #pragma unroll
;     for (int ds = 0; ds < 4; ++ds) asm volatile("" : "+v"(qf[ds]));
;     const float tabL = tab[0], tabR = tab[448];
;     f32x16 O[4];
; #pragma unroll
;     for (int d = 0; d < 4; ++d)
; #pragma unroll
;         for (int r = 0; r < 16; ++r) O[d][r] = 0.f;
;     float mu = 0.f; f32x2 ls2 = {0.f, 0.f};
;     f32x16 cblk; float coff_cur = __builtin_nanf("");
; #pragma unroll
;     for (int r = 0; r < 16; ++r) cblk[r] = 0.f;
;     const int NT = S >> 6;
;     const unsigned kfo = r32 * 256 + ((unsigned)((m * 8 + hi) ^ (r32 & 15)) << 4);
;     const unsigned vj = (i16 >> 2) & 3;
;     const unsigned vfo = (4 * hi + (i16 >> 2)) * 256 + (vj << 6) + 32 * (g4 & 1) + 8 * (i16 & 3);
;     int bc = 0, bn = 2;
.LBB0_325:
	s_or_b64 exec, exec, s[8:9]
	s_lshl_b32 s9, s21, 6
	s_and_b32 s8, s25, 32
	s_and_b32 s9, s9, 64
	s_or_b32 s8, s9, s8
	s_ashr_i32 s15, s26, 6
	s_or_b32 s8, s8, s23
	s_and_b32 s17, s15, 3
	s_lshl_b32 s8, s8, 7
	s_waitcnt lgkmcnt(0)
	s_lshl_b32 s10, s17, 5
	s_or_b32 s11, s10, s8
	v_and_b32_e32 v148, 31, v68
	s_or_b32 s14, s11, 0x4000
	v_or_b32_e32 v2, s14, v148
	s_ashr_i32 s16, s26, 8
	v_lshlrev_b32_e32 v162, 12, v2
	v_lshl_add_u64 v[2:3], s[4:5], 0, v[162:163]
	s_lshl_b32 s48, s28, 8
	s_lshl_b32 s8, s16, 6
	v_bfe_u32 v159, v68, 5, 1
	v_lshl_add_u64 v[2:3], v[2:3], 0, s[48:49]
	s_ashr_i32 s9, s8, 31
	v_lshl_add_u64 v[2:3], s[8:9], 1, v[2:3]
	v_lshlrev_b32_e32 v162, 4, v159
	v_lshl_add_u64 v[2:3], v[2:3], 0, v[162:163]
	s_mov_b64 s[8:9], 0x7800000
	v_lshl_add_u64 v[4:5], v[2:3], 0, s[8:9]
	s_mov_b32 s8, 0x7800000
	v_add_co_u32_e32 v2, vcc, s8, v2
	v_readlane_b32 s8, v255, 29
	s_nop 0
	v_addc_co_u32_e32 v3, vcc, 0, v3, vcc
	global_load_dwordx4 v[116:119], v[2:3], off
	global_load_dwordx4 v[120:123], v[4:5], off offset:32
	global_load_dwordx4 v[124:127], v[4:5], off offset:64
	global_load_dwordx4 v[128:131], v[4:5], off offset:96
	v_mov_b32_e32 v3, s8
	v_readlane_b32 s8, v255, 30
	v_bfe_u32 v2, v68, 4, 2
	v_lshlrev_b32_e32 v35, 5, v2
	v_mov_b32_e32 v4, s8
	s_lshl_b32 s8, s15, 2
	v_or_b32_e32 v6, s8, v2
	v_bitop3_b32 v2, s8, v68, v2 bitop3:0x36
	s_add_u32 s29, s4, s48
	v_and_b32_e32 v34, 15, v68
	v_lshlrev_b32_e32 v6, 11, v6
	v_lshlrev_b32_e32 v2, 3, v2
	s_addc_u32 s30, s5, 0
	v_lshlrev_b32_e32 v5, 3, v34
	v_and_b32_e32 v2, 0x78, v2
	v_add_u32_e32 v8, 0x10000, v6
	s_add_u32 s8, s29, 0xb800000
	v_bitop3_b32 v7, v6, v35, v5 bitop3:0xf6
	v_or_b32_e32 v6, v2, v6
	v_or_b32_e32 v2, v2, v8
	v_bitop3_b32 v5, v8, v35, v5 bitop3:0xf6
	s_addc_u32 s9, s30, 0
	s_lshl_b32 s27, s15, 10
	s_add_i32 s15, 0, 0xc000
	v_lshl_or_b32 v149, v7, 1, v250
	v_lshl_or_b32 v160, v6, 1, v249
	v_lshl_or_b32 v161, v2, 1, v249
	v_lshl_or_b32 v176, v5, 1, v250
	s_add_i32 s25, s27, 0
	s_add_i32 s27, s27, s15
	s_mov_b32 s31, m0
	s_mov_b32 m0, s25
	s_nop 0
	global_load_lds_dwordx4 v160, s[8:9]
	s_mov_b32 m0, s27
	s_nop 0
	global_load_lds_dwordx4 v149, s[8:9]
	s_add_u32 m0, s25, 0x2000
	s_nop 0
	global_load_lds_dwordx4 v161, s[8:9]
	s_add_u32 m0, s27, 0x2000
	s_nop 0
	global_load_lds_dwordx4 v176, s[8:9]
	s_mov_b32 m0, s31
	s_add_u32 s8, s29, 0xb840000
	s_addc_u32 s9, s30, 0
	s_add_i32 s31, s25, 0x4000
	s_add_i32 s33, s27, 0x4000
	s_mov_b32 s34, m0
	s_mov_b32 m0, s31
	s_nop 0
	global_load_lds_dwordx4 v160, s[8:9]
	s_mov_b32 m0, s33
	s_nop 0
	global_load_lds_dwordx4 v149, s[8:9]
	s_add_u32 m0, s31, 0x2000
	s_nop 0
	global_load_lds_dwordx4 v161, s[8:9]
	s_add_u32 m0, s33, 0x2000
	s_nop 0
	global_load_lds_dwordx4 v176, s[8:9]
	s_mov_b32 m0, s34
	s_mov_b32 s32, m0
	s_add_u32 s8, s29, 0xb800000
	s_addc_u32 s9, s30, 0
	s_mov_b32 s4, s8
	s_add_u32 s8, s8, 0x40000
	s_addc_u32 s9, s9, 0
	s_add_u32 s22, s8, 0x40000
	s_addc_u32 s23, s9, 0
	s_add_u32 m0, s25, 0x8000
	v_add_u32_e32 v236, 0x80000, v160
	global_load_lds_dwordx4 v160, s[22:23]
	s_add_u32 m0, s25, 0xa000
	v_add_u32_e32 v237, 0x80000, v161
	global_load_lds_dwordx4 v161, s[22:23]
	s_lshl_b32 s15, s28, 7
	s_and_b32 s24, s26, 0x3fffffc0
	s_lshl_b32 s24, s24, 2
	s_add_i32 s28, s24, 0x18000
	v_and_b32_e32 v183, 63, v68
	v_lshl_add_u32 v185, v159, 4, s28
	v_lshl_add_u32 v184, v148, 2, s28
	s_add_i32 s33, s11, 0x9f
	v_add_lshl_u32 v251, s11, v148, 2
	v_lshlrev_b32_e32 v252, 4, v159
	v_sub_u32_e32 v162, v252, v251
	s_add_i32 s34, s11, 0xffffff41
	s_ashr_i32 s11, s34, 6
	s_add_i32 s11, s11, 1
	s_lshl_b32 s11, s11, 6
	s_max_i32 s11, s11, 0
	s_add_i32 s31, s33, 63
	s_andn2_b32 s31, s31, 63
	s_sub_u32 s31, s31, 64
	s_lshr_b32 s10, s11, 6
	s_sub_i32 s10, s10, 2
	s_max_i32 s10, s10, 0
	s_lshl_b32 s24, s16, 3
	v_lshlrev_b32_e32 v19, 8, v148
	v_bitop3_b32 v251, s24, v34, v159 bitop3:0x36
	v_lshlrev_b32_e32 v252, 2, v159
	v_lshrrev_b32_e32 v253, 2, v34
	v_lshlrev_b32_e32 v254, 3, v68
	v_lshl_add_u32 v19, v251, 4, v19
	v_or_b32_e32 v252, v252, v253
	v_and_b32_e32 v254, 24, v254
	v_and_b32_e32 v251, 32, v35
	v_lshlrev_b32_e32 v252, 8, v252
	v_lshl_or_b32 v253, v253, 6, v254
	v_xor_b32_e32 v180, 32, v19
	v_or3_b32 v179, v252, v251, v253
	v_xor_b32_e32 v181, 64, v19
	v_xor_b32_e32 v182, 0x60, v19
	v_add_u32_e32 v228, 0xc000, v179
	v_xor_b32_e32 v229, 0x40, v179
	v_add_u32_e32 v229, 0xc000, v229
	v_xor_b32_e32 v230, 0x80, v179
	v_add_u32_e32 v230, 0xc000, v230
	v_xor_b32_e32 v231, 0xc0, v179
	v_add_u32_e32 v231, 0xc000, v231
	v_mov_b64_e32 v[20:21], 0
	v_mov_b64_e32 v[22:23], 0
	v_mov_b64_e32 v[24:25], 0
	v_mov_b64_e32 v[26:27], 0
	v_mov_b64_e32 v[28:29], 0
	v_mov_b64_e32 v[30:31], 0
	v_mov_b64_e32 v[32:33], 0
	v_mov_b64_e32 v[34:35], 0
	v_mov_b64_e32 v[36:37], 0
	v_mov_b64_e32 v[38:39], 0
	v_mov_b64_e32 v[40:41], 0
	v_mov_b64_e32 v[42:43], 0
	v_mov_b64_e32 v[44:45], 0
	v_mov_b64_e32 v[46:47], 0
	v_mov_b64_e32 v[48:49], 0
	v_mov_b64_e32 v[50:51], 0
	v_mov_b64_e32 v[52:53], 0
	v_mov_b64_e32 v[54:55], 0
	v_mov_b64_e32 v[56:57], 0
	v_mov_b64_e32 v[58:59], 0
	v_mov_b64_e32 v[60:61], 0
	v_mov_b64_e32 v[62:63], 0
	v_mov_b64_e32 v[64:65], 0
	v_mov_b64_e32 v[66:67], 0
	v_mov_b64_e32 v[68:69], 0
	v_mov_b64_e32 v[70:71], 0
	v_mov_b64_e32 v[72:73], 0
	v_mov_b64_e32 v[74:75], 0
	v_mov_b64_e32 v[76:77], 0
	v_mov_b64_e32 v[78:79], 0
	v_mov_b64_e32 v[80:81], 0
	v_mov_b64_e32 v[82:83], 0
	v_mov_b64_e32 v[150:151], 0
	v_mov_b32_e32 v186, 0
	s_waitcnt vmcnt(6) lgkmcnt(0)
	s_barrier
; #define LAS __attribute__((address_space(3)))
; #define VREADS1(arr, d_) do { const unsigned ad_ = vbase ^ (unsigned)((d_) << 6); __builtin_amdgcn_sched_barrier(0); \
;         _Pragma("unroll") for (int ks_ = 0; ks_ < 4; ++ks_) { VTR(arr[ks_ * 2], ad_, ks_ * 4096); VTR(arr[ks_ * 2 + 1], ad_, ks_ * 4096 + 2048); } __builtin_amdgcn_sched_barrier(0); } while (0)
; __device__ __forceinline__ void attn_unit(LAS unsigned char* lds, const bf16_t* Z, bf16_t* A2, const float* tabg, int seq_base, int S, int h, int qb, float lam) {
;     ...
;         bool near = true; float cc = 0.f;
;         if (kv0 - (qlo + 31) >= 128) { near = false; cc = tabR; } else if (qlo - (kv0 + 63) >= 128) { near = false; cc = tabL; }
;         { const float coff = cc - mu;
;           if (__any(!(coff == coff_cur))) { coff_cur = coff;
; #pragma unroll
;               for (int r = 0; r < 16; ++r) cblk[r] = coff;
;               asm volatile("" : "+v"(cblk)); } }
;         f32x16 p0, p1;
;         {
;             bf16x8 kf[8];
; #pragma unroll
;             for (int ds = 0; ds < 4; ++ds) { kf[2 * ds] = *(const LAS bf16x8*)(Kt + (kfo ^ (unsigned)(ds << 5))); kf[2 * ds + 1] = *(const LAS bf16x8*)(Kt + 32 * 256 + (kfo ^ (unsigned)(ds << 5))); }
;             __builtin_amdgcn_sched_barrier(0);
;             p0 = __builtin_amdgcn_mfma_f32_32x32x16_bf16(kf[0], qf[0], cblk, 0, 0, 0);
;             p1 = __builtin_amdgcn_mfma_f32_32x32x16_bf16(kf[1], qf[0], cblk, 0, 0, 0);
; #pragma unroll
;             for (int ds = 1; ds < 4; ++ds) {
;                 p0 = __builtin_amdgcn_mfma_f32_32x32x16_bf16(kf[2 * ds], qf[ds], p0, 0, 0, 0);
;                 p1 = __builtin_amdgcn_mfma_f32_32x32x16_bf16(kf[2 * ds + 1], qf[ds], p1, 0, 0, 0);
;             }
;         }
;     ...
;         const unsigned vbase = (unsigned)(size_t)Vt + vfo;
;         s16x4 va[8], vb[8];
;         VREADS1(va, 0);
;         if (near) {
;             const LAS float* tp = tab + (kv0 + 4 * hi - (qlo + r32) + 224);
; #pragma unroll
;             for (int r = 0; r < 16; ++r) { p0[r] += tp[(r & 3) + 8 * (r >> 2)]; p1[r] += tp[32 + (r & 3) + 8 * (r >> 2)]; }
;         }
	v_mov_b32_e32 v187, 0x18800
	ds_read_b32 v177, v187
	ds_read_b32 v178, v187 offset:1792
	ds_read_b128 v[132:135], v19
	ds_read_b128 v[136:139], v19 offset:8192
	ds_read_b128 v[140:143], v180
	ds_read_b128 v[144:147], v180 offset:8192
	ds_read_b128 v[220:223], v181
	ds_read_b128 v[224:227], v181 offset:8192
	ds_read_b128 v[232:235], v182
	ds_read_b128 v[80:83], v182 offset:8192
	s_waitcnt lgkmcnt(8)
	s_cmp_eq_u32 s11, 0
	s_cselect_b32 s24, 0, 1
	s_mov_b32 s35, s24
	v_mov_b32_e32 v251, 0
	s_cmp_eq_u32 s24, 1
	s_cselect_b64 vcc, -1, 0
	v_cndmask_b32_e32 v251, v251, v177, vcc
	s_cmp_eq_u32 s24, 2
	s_cselect_b64 vcc, -1, 0
	v_cndmask_b32_e32 v251, v251, v178, vcc
	v_sub_f32_e32 v2, v251, v186
	v_mov_b32_e32 v3, v2
	v_mov_b64_e32 v[4:5], v[2:3]
	v_mov_b64_e32 v[6:7], v[2:3]
	v_mov_b64_e32 v[8:9], v[2:3]
	v_mov_b64_e32 v[10:11], v[2:3]
	v_mov_b64_e32 v[12:13], v[2:3]
	v_mov_b64_e32 v[14:15], v[2:3]
	v_mov_b64_e32 v[16:17], v[2:3]
	s_waitcnt lgkmcnt(7)
	v_mfma_f32_32x32x16_bf16 v[84:99], v[132:135], v[116:119], v[2:17]
	s_waitcnt lgkmcnt(6)
	v_mfma_f32_32x32x16_bf16 v[100:115], v[136:139], v[116:119], v[2:17]
	s_waitcnt lgkmcnt(5)
	v_mfma_f32_32x32x16_bf16 v[84:99], v[140:143], v[120:123], v[84:99]
	s_waitcnt lgkmcnt(4)
	v_mfma_f32_32x32x16_bf16 v[100:115], v[144:147], v[120:123], v[100:115]
	s_waitcnt lgkmcnt(3)
	v_mfma_f32_32x32x16_bf16 v[84:99], v[220:223], v[124:127], v[84:99]
	s_waitcnt lgkmcnt(2)
	v_mfma_f32_32x32x16_bf16 v[100:115], v[224:227], v[124:127], v[100:115]
	s_waitcnt lgkmcnt(1)
	v_mfma_f32_32x32x16_bf16 v[84:99], v[232:235], v[128:131], v[84:99]
	s_waitcnt lgkmcnt(0)
	v_mfma_f32_32x32x16_bf16 v[100:115], v[80:83], v[128:131], v[100:115]
	s_nop 15
	s_nop 15
	v_mov_b64_e32 v[80:81], 0
	v_mov_b64_e32 v[82:83], 0
	s_mov_b32 s5, 0
	s_cmp_lg_u32 s11, 0
	s_cbranch_scc1 .LatB_p0_nonear
	s_lshl_b32 s29, s5, 2
	s_add_i32 s29, s29, 0x18b80
	v_add_u32_e32 v187, s29, v162
	ds_read2_b32 v[132:133], v187 offset0:0 offset1:1
	ds_read2_b32 v[134:135], v187 offset0:2 offset1:3
	ds_read2_b32 v[136:137], v187 offset0:8 offset1:9
	ds_read2_b32 v[138:139], v187 offset0:10 offset1:11
	s_waitcnt lgkmcnt(0)
	v_pk_add_f32 v[84:85], v[84:85], v[132:133]
	v_pk_add_f32 v[86:87], v[86:87], v[134:135]
	v_pk_add_f32 v[88:89], v[88:89], v[136:137]
	v_pk_add_f32 v[90:91], v[90:91], v[138:139]
	ds_read2_b32 v[132:133], v187 offset0:16 offset1:17
	ds_read2_b32 v[134:135], v187 offset0:18 offset1:19
	ds_read2_b32 v[136:137], v187 offset0:24 offset1:25
	ds_read2_b32 v[138:139], v187 offset0:26 offset1:27
	s_waitcnt lgkmcnt(0)
	v_pk_add_f32 v[92:93], v[92:93], v[132:133]
	v_pk_add_f32 v[94:95], v[94:95], v[134:135]
	v_pk_add_f32 v[96:97], v[96:97], v[136:137]
	v_pk_add_f32 v[98:99], v[98:99], v[138:139]
	ds_read2_b32 v[132:133], v187 offset0:32 offset1:33
	ds_read2_b32 v[134:135], v187 offset0:34 offset1:35
	ds_read2_b32 v[136:137], v187 offset0:40 offset1:41
	ds_read2_b32 v[138:139], v187 offset0:42 offset1:43
	s_waitcnt lgkmcnt(0)
	v_pk_add_f32 v[100:101], v[100:101], v[132:133]
	v_pk_add_f32 v[102:103], v[102:103], v[134:135]
	v_pk_add_f32 v[104:105], v[104:105], v[136:137]
	v_pk_add_f32 v[106:107], v[106:107], v[138:139]
	ds_read2_b32 v[132:133], v187 offset0:48 offset1:49
	ds_read2_b32 v[134:135], v187 offset0:50 offset1:51
	ds_read2_b32 v[136:137], v187 offset0:56 offset1:57
	ds_read2_b32 v[138:139], v187 offset0:58 offset1:59
	s_waitcnt lgkmcnt(0)
	v_pk_add_f32 v[108:109], v[108:109], v[132:133]
	v_pk_add_f32 v[110:111], v[110:111], v[134:135]
	v_pk_add_f32 v[112:113], v[112:113], v[136:137]
	v_pk_add_f32 v[114:115], v[114:115], v[138:139]
; __device__ __forceinline__ void attn_unit(LAS unsigned char* lds, const bf16_t* Z, bf16_t* A2, const float* tabg, int seq_base, int S, int h, int qb, float lam) {
;     ...
;         if (t + 2 < NT) ATT_STAGE(t + 2, bn);
;         const LAS unsigned char* Kt = Kb + bc * KT; const LAS unsigned char* Vt = Vb + bc * VT;
;         const int kv0 = t * 64;
;         bool near = true; float cc = 0.f;
;         if (kv0 - (qlo + 31) >= 128) { near = false; cc = tabR; } else if (qlo - (kv0 + 63) >= 128) { near = false; cc = tabL; }
;         { const float coff = cc - mu;
;           if (__any(!(coff == coff_cur))) { coff_cur = coff;
; #pragma unroll
;               for (int r = 0; r < 16; ++r) cblk[r] = coff;
;               asm volatile("" : "+v"(cblk)); } }
;         f32x16 p0, p1;
;         {
;     ...
;         float mx = max2f(max16f(p0), max16f(p1));
;         const bool first = (t == 0);
;         if (first || __any(mx > THR)) {
;             { auto rr = __builtin_amdgcn_permlane32_swap(__float_as_uint(mx), __float_as_uint(mx), false, false); mx = max2f(__uint_as_float(rr[0]), __uint_as_float(rr[1])); }
;             const float delta = first ? mx : fmaxf(mx, 0.f);
;             const float alpha = first ? 1.0f : __builtin_amdgcn_exp2f(-delta);
;             mu += delta; ls2 *= alpha;
;             if (!first) {
;                 asm volatile("" ::: "memory");
;                 scr[r32] = alpha;
;                 asm volatile("s_waitcnt lgkmcnt(0)" ::: "memory");
; #pragma unroll
;                 for (int g = 0; g < 4; ++g) { const f32x4 a4 = *(const LAS f32x4*)(scr + 8 * g + 4 * hi);
; #pragma unroll
;                     for (int d = 0; d < 4; ++d) { O[d][4 * g + 0] *= a4[0]; O[d][4 * g + 1] *= a4[1]; O[d][4 * g + 2] *= a4[2]; O[d][4 * g + 3] *= a4[3]; } }
;                 asm volatile("s_waitcnt lgkmcnt(0)" ::: "memory");
;             }
; #pragma unroll
;             for (int r = 0; r < 16; ++r) { p0[r] -= delta; p1[r] -= delta; }
;             asm volatile("" : "+v"(p0), "+v"(p1));
;         }
; #pragma unroll
;         for (int r = 0; r < 16; ++r) { p0[r] = __builtin_amdgcn_exp2f(p0[r]); p1[r] = __builtin_amdgcn_exp2f(p1[r]); }
; #pragma unroll
;         for (int r = 0; r < 16; r += 2) { ls2 += (f32x2){p0[r], p0[r + 1]}; ls2 += (f32x2){p1[r], p1[r + 1]}; }
;         bf16x8 pa[4]; pa[0] = pack8(p0, 0); pa[1] = pack8(p0, 8); pa[2] = pack8(p1, 0); pa[3] = pack8(p1, 8);
.LatB_p0_nonear:
	v_max3_f32 v251, v84, v85, v86
	v_max3_f32 v252, v87, v88, v89
	v_max3_f32 v251, v251, v90, v91
	v_max3_f32 v252, v252, v92, v93
	v_max3_f32 v251, v251, v94, v95
	v_max3_f32 v252, v252, v96, v97
	v_max3_f32 v251, v251, v98, v99
	v_max3_f32 v252, v252, v100, v101
	v_max3_f32 v251, v251, v102, v103
	v_max3_f32 v252, v252, v104, v105
	v_max3_f32 v251, v251, v106, v107
	v_max3_f32 v252, v252, v108, v109
	v_max3_f32 v251, v251, v110, v111
	v_max3_f32 v252, v252, v112, v113
	v_max3_f32 v251, v251, v114, v115
	v_max_f32_e32 v251, v251, v252
	v_mov_b32_e32 v252, v251
	s_nop 1
	v_permlane32_swap_b32_e32 v251, v252
	v_max_f32_e32 v186, v251, v252
	v_sub_f32_e32 v84, v84, v186
	v_sub_f32_e32 v85, v85, v186
	v_sub_f32_e32 v86, v86, v186
	v_sub_f32_e32 v87, v87, v186
	v_sub_f32_e32 v88, v88, v186
	v_sub_f32_e32 v89, v89, v186
	v_sub_f32_e32 v90, v90, v186
	v_sub_f32_e32 v91, v91, v186
	v_sub_f32_e32 v92, v92, v186
	v_sub_f32_e32 v93, v93, v186
	v_sub_f32_e32 v94, v94, v186
	v_sub_f32_e32 v95, v95, v186
	v_sub_f32_e32 v96, v96, v186
	v_sub_f32_e32 v97, v97, v186
	v_sub_f32_e32 v98, v98, v186
	v_sub_f32_e32 v99, v99, v186
	v_sub_f32_e32 v100, v100, v186
	v_sub_f32_e32 v101, v101, v186
	v_sub_f32_e32 v102, v102, v186
	v_sub_f32_e32 v103, v103, v186
	v_sub_f32_e32 v104, v104, v186
	v_sub_f32_e32 v105, v105, v186
	v_sub_f32_e32 v106, v106, v186
	v_sub_f32_e32 v107, v107, v186
	v_sub_f32_e32 v108, v108, v186
	v_sub_f32_e32 v109, v109, v186
	v_sub_f32_e32 v110, v110, v186
	v_sub_f32_e32 v111, v111, v186
	v_sub_f32_e32 v112, v112, v186
	v_sub_f32_e32 v113, v113, v186
	v_sub_f32_e32 v114, v114, v186
	v_sub_f32_e32 v115, v115, v186
	s_add_u32 s29, s5, 64
	s_cmp_lt_u32 s29, s11
	s_cselect_b32 s24, 1, 0
	s_cmp_gt_u32 s29, s31
	s_cselect_b32 s30, 2, 0
	s_or_b32 s24, s24, s30
	s_mov_b32 s35, s24
	v_mov_b32_e32 v251, 0
	s_cmp_eq_u32 s24, 1
	s_cselect_b64 vcc, -1, 0
	v_cndmask_b32_e32 v251, v251, v177, vcc
	s_cmp_eq_u32 s24, 2
	s_cselect_b64 vcc, -1, 0
	v_cndmask_b32_e32 v251, v251, v178, vcc
	v_sub_f32_e32 v2, v251, v186
	v_mov_b32_e32 v3, v2
	v_mov_b64_e32 v[4:5], v[2:3]
	v_mov_b64_e32 v[6:7], v[2:3]
	v_mov_b64_e32 v[8:9], v[2:3]
	v_mov_b64_e32 v[10:11], v[2:3]
	v_mov_b64_e32 v[12:13], v[2:3]
	v_mov_b64_e32 v[14:15], v[2:3]
	v_mov_b64_e32 v[16:17], v[2:3]
	s_waitcnt vmcnt(0)
	s_barrier
	ds_read_b128 v[132:135], v19 offset:16384
	ds_read_b128 v[136:139], v19 offset:24576
	ds_read_b128 v[140:143], v180 offset:16384
	ds_read_b128 v[144:147], v180 offset:24576
	ds_read_b128 v[220:223], v181 offset:16384
	ds_read_b128 v[224:227], v181 offset:24576
	ds_read_b128 v[232:235], v182 offset:16384
	v_max3_f32 v251, v84, v85, v86
	v_max3_f32 v252, v87, v88, v89
	v_max3_f32 v251, v251, v90, v91
	v_max3_f32 v252, v252, v92, v93
	v_max3_f32 v251, v251, v94, v95
	v_max3_f32 v252, v252, v96, v97
	v_max3_f32 v251, v251, v98, v99
	v_max3_f32 v252, v252, v100, v101
	v_max3_f32 v251, v251, v102, v103
	v_max3_f32 v252, v252, v104, v105
	v_max3_f32 v251, v251, v106, v107
	v_max3_f32 v252, v252, v108, v109
	v_max3_f32 v251, v251, v110, v111
	v_max3_f32 v252, v252, v112, v113
	v_max3_f32 v251, v251, v114, v115
	v_max_f32_e32 v251, v251, v252
	v_cmp_lt_f32_e32 vcc, 0x41000000, v251
	s_cbranch_vccnz .LatB_rs_h0
.LatB_rareret_h0:
	s_waitcnt lgkmcnt(5)
	v_mfma_f32_32x32x16_bf16 v[188:203], v[132:135], v[116:119], v[2:17]
	ds_read_b128 v[132:135], v182 offset:24576
	v_exp_f32_e32 v84, v84
	v_exp_f32_e32 v85, v85
	v_exp_f32_e32 v86, v86
	v_exp_f32_e32 v87, v87
	v_pk_add_f32 v[150:151], v[150:151], v[84:85]
	v_pk_add_f32 v[150:151], v[150:151], v[86:87]
	v_exp_f32_e32 v88, v88
	s_mov_b32 m0, s25
	v_mfma_f32_32x32x16_bf16 v[204:219], v[136:139], v[116:119], v[2:17]
	global_load_lds_dwordx4 v236, s[8:9]
	v_exp_f32_e32 v89, v89
	v_cvt_pk_bf16_f32 v84, v84, v85
	v_cvt_pk_bf16_f32 v85, v86, v87
	v_exp_f32_e32 v90, v90
	v_exp_f32_e32 v91, v91
	v_pk_add_f32 v[150:151], v[150:151], v[88:89]
	v_pk_add_f32 v[150:151], v[150:151], v[90:91]
	v_cvt_pk_bf16_f32 v86, v88, v89
	v_cvt_pk_bf16_f32 v87, v90, v91
	s_waitcnt lgkmcnt(4)
	v_mfma_f32_32x32x16_bf16 v[188:203], v[140:143], v[120:123], v[188:203]
	v_exp_f32_e32 v92, v92
	v_exp_f32_e32 v93, v93
	v_exp_f32_e32 v94, v94
	v_exp_f32_e32 v95, v95
	v_pk_add_f32 v[150:151], v[150:151], v[92:93]
	v_pk_add_f32 v[150:151], v[150:151], v[94:95]
	v_exp_f32_e32 v96, v96
	s_add_u32 m0, s25, 0x2000
	v_mfma_f32_32x32x16_bf16 v[204:219], v[144:147], v[120:123], v[204:219]
	global_load_lds_dwordx4 v237, s[8:9]
	v_exp_f32_e32 v97, v97
	v_cvt_pk_bf16_f32 v88, v92, v93
	v_cvt_pk_bf16_f32 v89, v94, v95
	v_exp_f32_e32 v98, v98
	v_exp_f32_e32 v99, v99
	v_pk_add_f32 v[150:151], v[150:151], v[96:97]
	v_pk_add_f32 v[150:151], v[150:151], v[98:99]
	v_cvt_pk_bf16_f32 v90, v96, v97
	v_cvt_pk_bf16_f32 v91, v98, v99
	s_waitcnt lgkmcnt(2)
	v_mfma_f32_32x32x16_bf16 v[188:203], v[220:223], v[124:127], v[188:203]
	v_exp_f32_e32 v100, v100
	v_exp_f32_e32 v101, v101
	v_exp_f32_e32 v102, v102
	v_exp_f32_e32 v103, v103
	v_pk_add_f32 v[150:151], v[150:151], v[100:101]
	v_pk_add_f32 v[150:151], v[150:151], v[102:103]
	v_exp_f32_e32 v104, v104
	v_mfma_f32_32x32x16_bf16 v[204:219], v[224:227], v[124:127], v[204:219]
	v_exp_f32_e32 v105, v105
	v_cvt_pk_bf16_f32 v100, v100, v101
	v_cvt_pk_bf16_f32 v101, v102, v103
	v_exp_f32_e32 v106, v106
	v_exp_f32_e32 v107, v107
	v_pk_add_f32 v[150:151], v[150:151], v[104:105]
	v_pk_add_f32 v[150:151], v[150:151], v[106:107]
	v_cvt_pk_bf16_f32 v102, v104, v105
	v_cvt_pk_bf16_f32 v103, v106, v107
	s_waitcnt lgkmcnt(0)
	v_mfma_f32_32x32x16_bf16 v[188:203], v[232:235], v[128:131], v[188:203]
	v_exp_f32_e32 v108, v108
	v_exp_f32_e32 v109, v109
	v_exp_f32_e32 v110, v110
	v_exp_f32_e32 v111, v111
	v_pk_add_f32 v[150:151], v[150:151], v[108:109]
	v_pk_add_f32 v[150:151], v[150:151], v[110:111]
	v_exp_f32_e32 v112, v112
	v_mfma_f32_32x32x16_bf16 v[204:219], v[132:135], v[128:131], v[204:219]
	v_exp_f32_e32 v113, v113
	v_cvt_pk_bf16_f32 v104, v108, v109
	v_cvt_pk_bf16_f32 v105, v110, v111
	v_exp_f32_e32 v114, v114
	v_exp_f32_e32 v115, v115
	v_pk_add_f32 v[150:151], v[150:151], v[112:113]
	v_pk_add_f32 v[150:151], v[150:151], v[114:115]
	v_cvt_pk_bf16_f32 v106, v112, v113
	v_cvt_pk_bf16_f32 v107, v114, v115
	s_add_u32 s8, s8, 0x40000
	s_addc_u32 s9, s9, 0
	s_waitcnt vmcnt(2) lgkmcnt(0)
	s_barrier
	s_sub_u32 s10, s10, 1
	s_cbranch_scc1 .LatB_evs_h1

; __device__ __forceinline__ void attn_unit(LAS unsigned char* lds, const bf16_t* Z, bf16_t* A2, const float* tabg, int seq_base, int S, int h, int qb, float lam) {
;     ...
;         if (t + 2 < NT) ATT_STAGE(t + 2, bn);
;         const LAS unsigned char* Kt = Kb + bc * KT; const LAS unsigned char* Vt = Vb + bc * VT;
;         const int kv0 = t * 64;
;         bool near = true; float cc = 0.f;
;         if (kv0 - (qlo + 31) >= 128) { near = false; cc = tabR; } else if (qlo - (kv0 + 63) >= 128) { near = false; cc = tabL; }
;         { const float coff = cc - mu;
;           if (__any(!(coff == coff_cur))) { coff_cur = coff;
; #pragma unroll
;               for (int r = 0; r < 16; ++r) cblk[r] = coff;
;               asm volatile("" : "+v"(cblk)); } }
;         f32x16 p0, p1;
;         {
;             bf16x8 kf[8];
; #pragma unroll
;             for (int ds = 0; ds < 4; ++ds) { kf[2 * ds] = *(const LAS bf16x8*)(Kt + (kfo ^ (unsigned)(ds << 5))); kf[2 * ds + 1] = *(const LAS bf16x8*)(Kt + 32 * 256 + (kfo ^ (unsigned)(ds << 5))); }
;             __builtin_amdgcn_sched_barrier(0);
;             p0 = __builtin_amdgcn_mfma_f32_32x32x16_bf16(kf[0], qf[0], cblk, 0, 0, 0);
;             p1 = __builtin_amdgcn_mfma_f32_32x32x16_bf16(kf[1], qf[0], cblk, 0, 0, 0);
; #pragma unroll
;             for (int ds = 1; ds < 4; ++ds) {
;                 p0 = __builtin_amdgcn_mfma_f32_32x32x16_bf16(kf[2 * ds], qf[ds], p0, 0, 0, 0);
;                 p1 = __builtin_amdgcn_mfma_f32_32x32x16_bf16(kf[2 * ds + 1], qf[ds], p1, 0, 0, 0);
;             }
;     ...
; #pragma unroll
;         for (int r = 0; r < 16; ++r) { p0[r] = __builtin_amdgcn_exp2f(p0[r]); p1[r] = __builtin_amdgcn_exp2f(p1[r]); }
; #pragma unroll
;         for (int r = 0; r < 16; r += 2) { ls2 += (f32x2){p0[r], p0[r + 1]}; ls2 += (f32x2){p1[r], p1[r + 1]}; }
;         bf16x8 pa[4]; pa[0] = pack8(p0, 0); pa[1] = pack8(p0, 8); pa[2] = pack8(p1, 0); pa[3] = pack8(p1, 8);
;         LGKM0(); VREADS1(vb, 1); PV1(va, 0); LGKM0(); VREADS1(va, 2); PV1(vb, 1); LGKM0(); VREADS1(vb, 3); PV1(va, 2); LGKM0(); PV1(vb, 3);
;     ...
;         if (t + 2 < NT) asm volatile("s_waitcnt vmcnt(4) lgkmcnt(0)" ::: "memory"); else asm volatile("s_waitcnt vmcnt(0) lgkmcnt(0)" ::: "memory");
;         __builtin_amdgcn_s_barrier(); asm volatile("" ::: "memory");
;         bc = (bc == NST - 1) ? 0 : bc + 1; bn = (bn == NST - 1) ? 0 : bn + 1;
.LatB_rareret_h1:
	s_waitcnt lgkmcnt(10)
	v_mfma_f32_32x32x16_bf16 v[20:35], v[84:87], v[132:135], v[20:35]
	ds_read_b64_tr_b16 v[132:133], v231 offset:4096
	ds_read_b64_tr_b16 v[134:135], v231 offset:6144
	v_exp_f32_e32 v188, v188
	v_exp_f32_e32 v189, v189
	v_mfma_f32_32x32x16_bf16 v[36:51], v[84:87], v[136:139], v[36:51]
	ds_read_b64_tr_b16 v[136:137], v228 offset:8192
	ds_read_b64_tr_b16 v[138:139], v228 offset:10240
	v_exp_f32_e32 v190, v190
	v_exp_f32_e32 v191, v191
	s_waitcnt lgkmcnt(10)
	v_mfma_f32_32x32x16_bf16 v[52:67], v[84:87], v[140:143], v[52:67]
	ds_read_b64_tr_b16 v[140:141], v229 offset:8192
	ds_read_b64_tr_b16 v[142:143], v229 offset:10240
	v_pk_add_f32 v[150:151], v[150:151], v[188:189]
	v_pk_add_f32 v[150:151], v[150:151], v[190:191]
	v_exp_f32_e32 v192, v192
	s_add_u32 m0, s25, 0x4000
	v_mfma_f32_32x32x16_bf16 v[68:83], v[84:87], v[144:147], v[68:83]
	global_load_lds_dwordx4 v236, s[8:9]
	ds_read_b64_tr_b16 v[144:145], v230 offset:8192
	ds_read_b64_tr_b16 v[146:147], v230 offset:10240
	v_exp_f32_e32 v193, v193
	v_cvt_pk_bf16_f32 v188, v188, v189
	v_cvt_pk_bf16_f32 v189, v190, v191
	s_waitcnt lgkmcnt(10)
	v_mfma_f32_32x32x16_bf16 v[20:35], v[88:91], v[220:223], v[20:35]
	ds_read_b64_tr_b16 v[220:221], v231 offset:8192
	ds_read_b64_tr_b16 v[222:223], v231 offset:10240
	v_exp_f32_e32 v194, v194
	v_exp_f32_e32 v195, v195
	v_mfma_f32_32x32x16_bf16 v[36:51], v[88:91], v[224:227], v[36:51]
	ds_read_b64_tr_b16 v[224:225], v228 offset:12288
	ds_read_b64_tr_b16 v[226:227], v228 offset:14336
	v_pk_add_f32 v[150:151], v[150:151], v[192:193]
	v_pk_add_f32 v[150:151], v[150:151], v[194:195]
	v_cvt_pk_bf16_f32 v190, v192, v193
	v_cvt_pk_bf16_f32 v191, v194, v195
	s_waitcnt lgkmcnt(10)
	v_mfma_f32_32x32x16_bf16 v[52:67], v[88:91], v[232:235], v[52:67]
	ds_read_b64_tr_b16 v[232:233], v229 offset:12288
	ds_read_b64_tr_b16 v[234:235], v229 offset:14336
	v_exp_f32_e32 v196, v196
	v_exp_f32_e32 v197, v197
	s_add_u32 m0, s27, 0x8000
	v_mfma_f32_32x32x16_bf16 v[68:83], v[88:91], v[132:135], v[68:83]
	global_load_lds_dwordx4 v149, s[8:9]
	ds_read_b64_tr_b16 v[132:133], v230 offset:12288
	ds_read_b64_tr_b16 v[134:135], v230 offset:14336
	v_exp_f32_e32 v198, v198
	v_exp_f32_e32 v199, v199
	s_waitcnt lgkmcnt(10)
	v_mfma_f32_32x32x16_bf16 v[20:35], v[100:103], v[136:139], v[20:35]
	ds_read_b64_tr_b16 v[136:137], v231 offset:12288
	ds_read_b64_tr_b16 v[138:139], v231 offset:14336
	v_pk_add_f32 v[150:151], v[150:151], v[196:197]
	v_pk_add_f32 v[150:151], v[150:151], v[198:199]
	v_exp_f32_e32 v200, v200
	v_mfma_f32_32x32x16_bf16 v[36:51], v[100:103], v[140:143], v[36:51]
	ds_read_b128 v[140:143], v19 offset:32768
	v_exp_f32_e32 v201, v201
	v_cvt_pk_bf16_f32 v192, v196, v197
	v_cvt_pk_bf16_f32 v193, v198, v199
	s_waitcnt lgkmcnt(9)
	v_mfma_f32_32x32x16_bf16 v[52:67], v[100:103], v[144:147], v[52:67]
	ds_read_b128 v[144:147], v19 offset:40960
	v_exp_f32_e32 v202, v202
	v_exp_f32_e32 v203, v203
	s_add_u32 m0, s25, 0x6000
	v_mfma_f32_32x32x16_bf16 v[68:83], v[100:103], v[220:223], v[68:83]
	global_load_lds_dwordx4 v237, s[8:9]
	ds_read_b128 v[220:223], v180 offset:32768
	v_pk_add_f32 v[150:151], v[150:151], v[200:201]
	v_pk_add_f32 v[150:151], v[150:151], v[202:203]
	v_cvt_pk_bf16_f32 v194, v200, v201
	v_cvt_pk_bf16_f32 v195, v202, v203
	s_waitcnt lgkmcnt(7)
	v_mfma_f32_32x32x16_bf16 v[20:35], v[104:107], v[224:227], v[20:35]
	ds_read_b128 v[224:227], v180 offset:40960
	v_exp_f32_e32 v204, v204
	v_exp_f32_e32 v205, v205
	v_mfma_f32_32x32x16_bf16 v[36:51], v[104:107], v[232:235], v[36:51]
	ds_read_b128 v[232:235], v181 offset:32768
	v_exp_f32_e32 v206, v206
	v_exp_f32_e32 v207, v207
	s_waitcnt lgkmcnt(5)
	v_mfma_f32_32x32x16_bf16 v[52:67], v[104:107], v[132:135], v[52:67]
	ds_read_b128 v[132:135], v181 offset:40960
	v_pk_add_f32 v[150:151], v[150:151], v[204:205]
	v_pk_add_f32 v[150:151], v[150:151], v[206:207]
	v_exp_f32_e32 v208, v208
	s_add_u32 m0, s27, 0xa000
	v_mfma_f32_32x32x16_bf16 v[68:83], v[104:107], v[136:139], v[68:83]
	global_load_lds_dwordx4 v176, s[8:9]
	ds_read_b128 v[136:139], v182 offset:32768
	v_exp_f32_e32 v209, v209
	v_cvt_pk_bf16_f32 v204, v204, v205
	v_cvt_pk_bf16_f32 v205, v206, v207
	s_waitcnt lgkmcnt(5)
	v_mfma_f32_32x32x16_bf16 v[84:99], v[140:143], v[116:119], v[2:17]
	ds_read_b128 v[140:143], v182 offset:40960
	v_exp_f32_e32 v210, v210
	v_exp_f32_e32 v211, v211
	v_mfma_f32_32x32x16_bf16 v[100:115], v[144:147], v[116:119], v[2:17]
	v_pk_add_f32 v[150:151], v[150:151], v[208:209]
	v_pk_add_f32 v[150:151], v[150:151], v[210:211]
	v_cvt_pk_bf16_f32 v206, v208, v209
	v_cvt_pk_bf16_f32 v207, v210, v211
	s_waitcnt lgkmcnt(4)
	v_mfma_f32_32x32x16_bf16 v[84:99], v[220:223], v[120:123], v[84:99]
	v_exp_f32_e32 v212, v212
	v_exp_f32_e32 v213, v213
	v_mfma_f32_32x32x16_bf16 v[100:115], v[224:227], v[120:123], v[100:115]
	v_exp_f32_e32 v214, v214
	v_exp_f32_e32 v215, v215
	s_waitcnt lgkmcnt(2)
	v_mfma_f32_32x32x16_bf16 v[84:99], v[232:235], v[124:127], v[84:99]
	v_pk_add_f32 v[150:151], v[150:151], v[212:213]
	v_pk_add_f32 v[150:151], v[150:151], v[214:215]
	v_exp_f32_e32 v216, v216
	v_mfma_f32_32x32x16_bf16 v[100:115], v[132:135], v[124:127], v[100:115]
	v_exp_f32_e32 v217, v217
	v_cvt_pk_bf16_f32 v208, v212, v213
	v_cvt_pk_bf16_f32 v209, v214, v215
	s_waitcnt lgkmcnt(0)
	v_mfma_f32_32x32x16_bf16 v[84:99], v[136:139], v[128:131], v[84:99]
	v_exp_f32_e32 v218, v218
	v_exp_f32_e32 v219, v219
	v_mfma_f32_32x32x16_bf16 v[100:115], v[140:143], v[128:131], v[100:115]
	v_pk_add_f32 v[150:151], v[150:151], v[216:217]
	v_pk_add_f32 v[150:151], v[150:151], v[218:219]
	v_cvt_pk_bf16_f32 v210, v216, v217
	v_cvt_pk_bf16_f32 v211, v218, v219
	s_add_u32 s8, s8, 0x40000
	s_addc_u32 s9, s9, 0
	s_waitcnt vmcnt(4) lgkmcnt(0)
	s_barrier
	s_sub_u32 s10, s10, 1
	s_cbranch_scc1 .LatB_evs_h2

; __device__ __forceinline__ void attn_unit(LAS unsigned char* lds, const bf16_t* Z, bf16_t* A2, const float* tabg, int seq_base, int S, int h, int qb, float lam) {
;     ...
;         if (t + 2 < NT) ATT_STAGE(t + 2, bn);
;         const LAS unsigned char* Kt = Kb + bc * KT; const LAS unsigned char* Vt = Vb + bc * VT;
;         const int kv0 = t * 64;
;         bool near = true; float cc = 0.f;
;         if (kv0 - (qlo + 31) >= 128) { near = false; cc = tabR; } else if (qlo - (kv0 + 63) >= 128) { near = false; cc = tabL; }
;         { const float coff = cc - mu;
;           if (__any(!(coff == coff_cur))) { coff_cur = coff;
; #pragma unroll
;               for (int r = 0; r < 16; ++r) cblk[r] = coff;
;               asm volatile("" : "+v"(cblk)); } }
;         f32x16 p0, p1;
;         {
;             bf16x8 kf[8];
; #pragma unroll
;             for (int ds = 0; ds < 4; ++ds) { kf[2 * ds] = *(const LAS bf16x8*)(Kt + (kfo ^ (unsigned)(ds << 5))); kf[2 * ds + 1] = *(const LAS bf16x8*)(Kt + 32 * 256 + (kfo ^ (unsigned)(ds << 5))); }
;             __builtin_amdgcn_sched_barrier(0);
;             p0 = __builtin_amdgcn_mfma_f32_32x32x16_bf16(kf[0], qf[0], cblk, 0, 0, 0);
;             p1 = __builtin_amdgcn_mfma_f32_32x32x16_bf16(kf[1], qf[0], cblk, 0, 0, 0);
; #pragma unroll
;             for (int ds = 1; ds < 4; ++ds) {
;                 p0 = __builtin_amdgcn_mfma_f32_32x32x16_bf16(kf[2 * ds], qf[ds], p0, 0, 0, 0);
;                 p1 = __builtin_amdgcn_mfma_f32_32x32x16_bf16(kf[2 * ds + 1], qf[ds], p1, 0, 0, 0);
;             }
;     ...
; #pragma unroll
;         for (int r = 0; r < 16; ++r) { p0[r] = __builtin_amdgcn_exp2f(p0[r]); p1[r] = __builtin_amdgcn_exp2f(p1[r]); }
; #pragma unroll
;         for (int r = 0; r < 16; r += 2) { ls2 += (f32x2){p0[r], p0[r + 1]}; ls2 += (f32x2){p1[r], p1[r + 1]}; }
;         bf16x8 pa[4]; pa[0] = pack8(p0, 0); pa[1] = pack8(p0, 8); pa[2] = pack8(p1, 0); pa[3] = pack8(p1, 8);
;         LGKM0(); VREADS1(vb, 1); PV1(va, 0); LGKM0(); VREADS1(va, 2); PV1(vb, 1); LGKM0(); VREADS1(vb, 3); PV1(va, 2); LGKM0(); PV1(vb, 3);
;     ...
;         if (t + 2 < NT) asm volatile("s_waitcnt vmcnt(4) lgkmcnt(0)" ::: "memory"); else asm volatile("s_waitcnt vmcnt(0) lgkmcnt(0)" ::: "memory");
;         __builtin_amdgcn_s_barrier(); asm volatile("" ::: "memory");
;         bc = (bc == NST - 1) ? 0 : bc + 1; bn = (bn == NST - 1) ? 0 : bn + 1;
.LatB_rareret_h2:
	s_waitcnt lgkmcnt(10)
	v_mfma_f32_32x32x16_bf16 v[20:35], v[188:191], v[132:135], v[20:35]
	ds_read_b64_tr_b16 v[132:133], v231 offset:20480
	ds_read_b64_tr_b16 v[134:135], v231 offset:22528
	v_exp_f32_e32 v84, v84
	v_exp_f32_e32 v85, v85
	v_mfma_f32_32x32x16_bf16 v[36:51], v[188:191], v[136:139], v[36:51]
	ds_read_b64_tr_b16 v[136:137], v228 offset:24576
	ds_read_b64_tr_b16 v[138:139], v228 offset:26624
	v_exp_f32_e32 v86, v86
	v_exp_f32_e32 v87, v87
	s_waitcnt lgkmcnt(10)
	v_mfma_f32_32x32x16_bf16 v[52:67], v[188:191], v[140:143], v[52:67]
	ds_read_b64_tr_b16 v[140:141], v229 offset:24576
	ds_read_b64_tr_b16 v[142:143], v229 offset:26624
	v_pk_add_f32 v[150:151], v[150:151], v[84:85]
	v_pk_add_f32 v[150:151], v[150:151], v[86:87]
	v_exp_f32_e32 v88, v88
	s_add_u32 m0, s25, 0x8000
	v_mfma_f32_32x32x16_bf16 v[68:83], v[188:191], v[144:147], v[68:83]
	global_load_lds_dwordx4 v236, s[8:9]
	ds_read_b64_tr_b16 v[144:145], v230 offset:24576
	ds_read_b64_tr_b16 v[146:147], v230 offset:26624
	v_exp_f32_e32 v89, v89
	v_cvt_pk_bf16_f32 v84, v84, v85
	v_cvt_pk_bf16_f32 v85, v86, v87
	s_waitcnt lgkmcnt(10)
	v_mfma_f32_32x32x16_bf16 v[20:35], v[192:195], v[220:223], v[20:35]
	ds_read_b64_tr_b16 v[220:221], v231 offset:24576
	ds_read_b64_tr_b16 v[222:223], v231 offset:26624
	v_exp_f32_e32 v90, v90
	v_exp_f32_e32 v91, v91
	v_mfma_f32_32x32x16_bf16 v[36:51], v[192:195], v[224:227], v[36:51]
	ds_read_b64_tr_b16 v[224:225], v228 offset:28672
	ds_read_b64_tr_b16 v[226:227], v228 offset:30720
	v_pk_add_f32 v[150:151], v[150:151], v[88:89]
	v_pk_add_f32 v[150:151], v[150:151], v[90:91]
	v_cvt_pk_bf16_f32 v86, v88, v89
	v_cvt_pk_bf16_f32 v87, v90, v91
	s_waitcnt lgkmcnt(10)
	v_mfma_f32_32x32x16_bf16 v[52:67], v[192:195], v[232:235], v[52:67]
	ds_read_b64_tr_b16 v[232:233], v229 offset:28672
	ds_read_b64_tr_b16 v[234:235], v229 offset:30720
	v_exp_f32_e32 v92, v92
	v_exp_f32_e32 v93, v93
	s_mov_b32 m0, s27
	v_mfma_f32_32x32x16_bf16 v[68:83], v[192:195], v[132:135], v[68:83]
	global_load_lds_dwordx4 v149, s[8:9]
	ds_read_b64_tr_b16 v[132:133], v230 offset:28672
	ds_read_b64_tr_b16 v[134:135], v230 offset:30720
	v_exp_f32_e32 v94, v94
	v_exp_f32_e32 v95, v95
	s_waitcnt lgkmcnt(10)
	v_mfma_f32_32x32x16_bf16 v[20:35], v[204:207], v[136:139], v[20:35]
	ds_read_b64_tr_b16 v[136:137], v231 offset:28672
	ds_read_b64_tr_b16 v[138:139], v231 offset:30720
	v_pk_add_f32 v[150:151], v[150:151], v[92:93]
	v_pk_add_f32 v[150:151], v[150:151], v[94:95]
	v_exp_f32_e32 v96, v96
	v_mfma_f32_32x32x16_bf16 v[36:51], v[204:207], v[140:143], v[36:51]
	ds_read_b128 v[140:143], v19
	v_exp_f32_e32 v97, v97
	v_cvt_pk_bf16_f32 v88, v92, v93
	v_cvt_pk_bf16_f32 v89, v94, v95
	s_waitcnt lgkmcnt(9)
	v_mfma_f32_32x32x16_bf16 v[52:67], v[204:207], v[144:147], v[52:67]
	ds_read_b128 v[144:147], v19 offset:8192
	v_exp_f32_e32 v98, v98
	v_exp_f32_e32 v99, v99
	s_add_u32 m0, s25, 0xa000
	v_mfma_f32_32x32x16_bf16 v[68:83], v[204:207], v[220:223], v[68:83]
	global_load_lds_dwordx4 v237, s[8:9]
	ds_read_b128 v[220:223], v180
	v_pk_add_f32 v[150:151], v[150:151], v[96:97]
	v_pk_add_f32 v[150:151], v[150:151], v[98:99]
	v_cvt_pk_bf16_f32 v90, v96, v97
	v_cvt_pk_bf16_f32 v91, v98, v99
	s_waitcnt lgkmcnt(7)
	v_mfma_f32_32x32x16_bf16 v[20:35], v[208:211], v[224:227], v[20:35]
	ds_read_b128 v[224:227], v180 offset:8192
	v_exp_f32_e32 v100, v100
	v_exp_f32_e32 v101, v101
	v_mfma_f32_32x32x16_bf16 v[36:51], v[208:211], v[232:235], v[36:51]
	ds_read_b128 v[232:235], v181
	v_exp_f32_e32 v102, v102
	v_exp_f32_e32 v103, v103
	s_waitcnt lgkmcnt(5)
	v_mfma_f32_32x32x16_bf16 v[52:67], v[208:211], v[132:135], v[52:67]
	ds_read_b128 v[132:135], v181 offset:8192
	v_pk_add_f32 v[150:151], v[150:151], v[100:101]
	v_pk_add_f32 v[150:151], v[150:151], v[102:103]
	v_exp_f32_e32 v104, v104
	s_add_u32 m0, s27, 0x2000
	v_mfma_f32_32x32x16_bf16 v[68:83], v[208:211], v[136:139], v[68:83]
	global_load_lds_dwordx4 v176, s[8:9]
	ds_read_b128 v[136:139], v182
	v_exp_f32_e32 v105, v105
	v_cvt_pk_bf16_f32 v100, v100, v101
	v_cvt_pk_bf16_f32 v101, v102, v103
	s_waitcnt lgkmcnt(5)
	v_mfma_f32_32x32x16_bf16 v[188:203], v[140:143], v[116:119], v[2:17]
	ds_read_b128 v[140:143], v182 offset:8192
	v_exp_f32_e32 v106, v106
	v_exp_f32_e32 v107, v107
	v_mfma_f32_32x32x16_bf16 v[204:219], v[144:147], v[116:119], v[2:17]
	v_pk_add_f32 v[150:151], v[150:151], v[104:105]
	v_pk_add_f32 v[150:151], v[150:151], v[106:107]
	v_cvt_pk_bf16_f32 v102, v104, v105
	v_cvt_pk_bf16_f32 v103, v106, v107
	s_waitcnt lgkmcnt(4)
	v_mfma_f32_32x32x16_bf16 v[188:203], v[220:223], v[120:123], v[188:203]
	v_exp_f32_e32 v108, v108
	v_exp_f32_e32 v109, v109
	v_mfma_f32_32x32x16_bf16 v[204:219], v[224:227], v[120:123], v[204:219]
	v_exp_f32_e32 v110, v110
	v_exp_f32_e32 v111, v111
	s_waitcnt lgkmcnt(2)
	v_mfma_f32_32x32x16_bf16 v[188:203], v[232:235], v[124:127], v[188:203]
	v_pk_add_f32 v[150:151], v[150:151], v[108:109]
	v_pk_add_f32 v[150:151], v[150:151], v[110:111]
	v_exp_f32_e32 v112, v112
	v_mfma_f32_32x32x16_bf16 v[204:219], v[132:135], v[124:127], v[204:219]
	v_exp_f32_e32 v113, v113
	v_cvt_pk_bf16_f32 v104, v108, v109
	v_cvt_pk_bf16_f32 v105, v110, v111
	s_waitcnt lgkmcnt(0)
	v_mfma_f32_32x32x16_bf16 v[188:203], v[136:139], v[128:131], v[188:203]
	v_exp_f32_e32 v114, v114
	v_exp_f32_e32 v115, v115
	v_mfma_f32_32x32x16_bf16 v[204:219], v[140:143], v[128:131], v[204:219]
	v_pk_add_f32 v[150:151], v[150:151], v[112:113]
	v_pk_add_f32 v[150:151], v[150:151], v[114:115]
	v_cvt_pk_bf16_f32 v106, v112, v113
	v_cvt_pk_bf16_f32 v107, v114, v115
	s_add_u32 s8, s8, 0x40000
	s_addc_u32 s9, s9, 0
	s_waitcnt vmcnt(4) lgkmcnt(0)
	s_barrier
	s_sub_u32 s10, s10, 1
	s_cbranch_scc1 .LatB_evs_h3

; __device__ __forceinline__ void attn_unit(LAS unsigned char* lds, const bf16_t* Z, bf16_t* A2, const float* tabg, int seq_base, int S, int h, int qb, float lam) {
;     ...
;         if (t + 2 < NT) ATT_STAGE(t + 2, bn);
;         const LAS unsigned char* Kt = Kb + bc * KT; const LAS unsigned char* Vt = Vb + bc * VT;
;         const int kv0 = t * 64;
;         bool near = true; float cc = 0.f;
;         if (kv0 - (qlo + 31) >= 128) { near = false; cc = tabR; } else if (qlo - (kv0 + 63) >= 128) { near = false; cc = tabL; }
;         { const float coff = cc - mu;
;           if (__any(!(coff == coff_cur))) { coff_cur = coff;
; #pragma unroll
;               for (int r = 0; r < 16; ++r) cblk[r] = coff;
;               asm volatile("" : "+v"(cblk)); } }
;         f32x16 p0, p1;
;         {
;             bf16x8 kf[8];
; #pragma unroll
;             for (int ds = 0; ds < 4; ++ds) { kf[2 * ds] = *(const LAS bf16x8*)(Kt + (kfo ^ (unsigned)(ds << 5))); kf[2 * ds + 1] = *(const LAS bf16x8*)(Kt + 32 * 256 + (kfo ^ (unsigned)(ds << 5))); }
;             __builtin_amdgcn_sched_barrier(0);
;             p0 = __builtin_amdgcn_mfma_f32_32x32x16_bf16(kf[0], qf[0], cblk, 0, 0, 0);
;             p1 = __builtin_amdgcn_mfma_f32_32x32x16_bf16(kf[1], qf[0], cblk, 0, 0, 0);
; #pragma unroll
;             for (int ds = 1; ds < 4; ++ds) {
;                 p0 = __builtin_amdgcn_mfma_f32_32x32x16_bf16(kf[2 * ds], qf[ds], p0, 0, 0, 0);
;                 p1 = __builtin_amdgcn_mfma_f32_32x32x16_bf16(kf[2 * ds + 1], qf[ds], p1, 0, 0, 0);
;             }
;     ...
; #pragma unroll
;         for (int r = 0; r < 16; ++r) { p0[r] = __builtin_amdgcn_exp2f(p0[r]); p1[r] = __builtin_amdgcn_exp2f(p1[r]); }
; #pragma unroll
;         for (int r = 0; r < 16; r += 2) { ls2 += (f32x2){p0[r], p0[r + 1]}; ls2 += (f32x2){p1[r], p1[r + 1]}; }
;         bf16x8 pa[4]; pa[0] = pack8(p0, 0); pa[1] = pack8(p0, 8); pa[2] = pack8(p1, 0); pa[3] = pack8(p1, 8);
;         LGKM0(); VREADS1(vb, 1); PV1(va, 0); LGKM0(); VREADS1(va, 2); PV1(vb, 1); LGKM0(); VREADS1(vb, 3); PV1(va, 2); LGKM0(); PV1(vb, 3);
;     ...
;         if (t + 2 < NT) asm volatile("s_waitcnt vmcnt(4) lgkmcnt(0)" ::: "memory"); else asm volatile("s_waitcnt vmcnt(0) lgkmcnt(0)" ::: "memory");
;         __builtin_amdgcn_s_barrier(); asm volatile("" ::: "memory");
;         bc = (bc == NST - 1) ? 0 : bc + 1; bn = (bn == NST - 1) ? 0 : bn + 1;
.LatB_rareret_h3:
	s_waitcnt lgkmcnt(10)
	v_mfma_f32_32x32x16_bf16 v[20:35], v[84:87], v[132:135], v[20:35]
	ds_read_b64_tr_b16 v[132:133], v231 offset:36864
	ds_read_b64_tr_b16 v[134:135], v231 offset:38912
	v_exp_f32_e32 v188, v188
	v_exp_f32_e32 v189, v189
	v_mfma_f32_32x32x16_bf16 v[36:51], v[84:87], v[136:139], v[36:51]
	ds_read_b64_tr_b16 v[136:137], v228 offset:40960
	ds_read_b64_tr_b16 v[138:139], v228 offset:43008
	v_exp_f32_e32 v190, v190
	v_exp_f32_e32 v191, v191
	s_waitcnt lgkmcnt(10)
	v_mfma_f32_32x32x16_bf16 v[52:67], v[84:87], v[140:143], v[52:67]
	ds_read_b64_tr_b16 v[140:141], v229 offset:40960
	ds_read_b64_tr_b16 v[142:143], v229 offset:43008
	v_pk_add_f32 v[150:151], v[150:151], v[188:189]
	v_pk_add_f32 v[150:151], v[150:151], v[190:191]
	v_exp_f32_e32 v192, v192
	s_mov_b32 m0, s25
	v_mfma_f32_32x32x16_bf16 v[68:83], v[84:87], v[144:147], v[68:83]
	global_load_lds_dwordx4 v236, s[8:9]
	ds_read_b64_tr_b16 v[144:145], v230 offset:40960
	ds_read_b64_tr_b16 v[146:147], v230 offset:43008
	v_exp_f32_e32 v193, v193
	v_cvt_pk_bf16_f32 v188, v188, v189
	v_cvt_pk_bf16_f32 v189, v190, v191
	s_waitcnt lgkmcnt(10)
	v_mfma_f32_32x32x16_bf16 v[20:35], v[88:91], v[220:223], v[20:35]
	ds_read_b64_tr_b16 v[220:221], v231 offset:40960
	ds_read_b64_tr_b16 v[222:223], v231 offset:43008
	v_exp_f32_e32 v194, v194
	v_exp_f32_e32 v195, v195
	v_mfma_f32_32x32x16_bf16 v[36:51], v[88:91], v[224:227], v[36:51]
	ds_read_b64_tr_b16 v[224:225], v228 offset:45056
	ds_read_b64_tr_b16 v[226:227], v228 offset:47104
	v_pk_add_f32 v[150:151], v[150:151], v[192:193]
	v_pk_add_f32 v[150:151], v[150:151], v[194:195]
	v_cvt_pk_bf16_f32 v190, v192, v193
	v_cvt_pk_bf16_f32 v191, v194, v195
	s_waitcnt lgkmcnt(10)
	v_mfma_f32_32x32x16_bf16 v[52:67], v[88:91], v[232:235], v[52:67]
	ds_read_b64_tr_b16 v[232:233], v229 offset:45056
	ds_read_b64_tr_b16 v[234:235], v229 offset:47104
	v_exp_f32_e32 v196, v196
	v_exp_f32_e32 v197, v197
	s_add_u32 m0, s27, 0x4000
	v_mfma_f32_32x32x16_bf16 v[68:83], v[88:91], v[132:135], v[68:83]
	global_load_lds_dwordx4 v149, s[8:9]
	ds_read_b64_tr_b16 v[132:133], v230 offset:45056
	ds_read_b64_tr_b16 v[134:135], v230 offset:47104
	v_exp_f32_e32 v198, v198
	v_exp_f32_e32 v199, v199
	s_waitcnt lgkmcnt(10)
	v_mfma_f32_32x32x16_bf16 v[20:35], v[100:103], v[136:139], v[20:35]
	ds_read_b64_tr_b16 v[136:137], v231 offset:45056
	ds_read_b64_tr_b16 v[138:139], v231 offset:47104
	v_pk_add_f32 v[150:151], v[150:151], v[196:197]
	v_pk_add_f32 v[150:151], v[150:151], v[198:199]
	v_exp_f32_e32 v200, v200
	v_mfma_f32_32x32x16_bf16 v[36:51], v[100:103], v[140:143], v[36:51]
	ds_read_b128 v[140:143], v19 offset:16384
	v_exp_f32_e32 v201, v201
	v_cvt_pk_bf16_f32 v192, v196, v197
	v_cvt_pk_bf16_f32 v193, v198, v199
	s_waitcnt lgkmcnt(9)
	v_mfma_f32_32x32x16_bf16 v[52:67], v[100:103], v[144:147], v[52:67]
	ds_read_b128 v[144:147], v19 offset:24576
	v_exp_f32_e32 v202, v202
	v_exp_f32_e32 v203, v203
	s_add_u32 m0, s25, 0x2000
	v_mfma_f32_32x32x16_bf16 v[68:83], v[100:103], v[220:223], v[68:83]
	global_load_lds_dwordx4 v237, s[8:9]
	ds_read_b128 v[220:223], v180 offset:16384
	v_pk_add_f32 v[150:151], v[150:151], v[200:201]
	v_pk_add_f32 v[150:151], v[150:151], v[202:203]
	v_cvt_pk_bf16_f32 v194, v200, v201
	v_cvt_pk_bf16_f32 v195, v202, v203
	s_waitcnt lgkmcnt(7)
	v_mfma_f32_32x32x16_bf16 v[20:35], v[104:107], v[224:227], v[20:35]
	ds_read_b128 v[224:227], v180 offset:24576
	v_exp_f32_e32 v204, v204
	v_exp_f32_e32 v205, v205
	v_mfma_f32_32x32x16_bf16 v[36:51], v[104:107], v[232:235], v[36:51]
	ds_read_b128 v[232:235], v181 offset:16384
	v_exp_f32_e32 v206, v206
	v_exp_f32_e32 v207, v207
	s_waitcnt lgkmcnt(5)
	v_mfma_f32_32x32x16_bf16 v[52:67], v[104:107], v[132:135], v[52:67]
	ds_read_b128 v[132:135], v181 offset:24576
	v_pk_add_f32 v[150:151], v[150:151], v[204:205]
	v_pk_add_f32 v[150:151], v[150:151], v[206:207]
	v_exp_f32_e32 v208, v208
	s_add_u32 m0, s27, 0x6000
	v_mfma_f32_32x32x16_bf16 v[68:83], v[104:107], v[136:139], v[68:83]
	global_load_lds_dwordx4 v176, s[8:9]
	ds_read_b128 v[136:139], v182 offset:16384
	v_exp_f32_e32 v209, v209
	v_cvt_pk_bf16_f32 v204, v204, v205
	v_cvt_pk_bf16_f32 v205, v206, v207
	s_waitcnt lgkmcnt(5)
	v_mfma_f32_32x32x16_bf16 v[84:99], v[140:143], v[116:119], v[2:17]
	ds_read_b128 v[140:143], v182 offset:24576
	v_exp_f32_e32 v210, v210
	v_exp_f32_e32 v211, v211
	v_mfma_f32_32x32x16_bf16 v[100:115], v[144:147], v[116:119], v[2:17]
	v_pk_add_f32 v[150:151], v[150:151], v[208:209]
	v_pk_add_f32 v[150:151], v[150:151], v[210:211]
	v_cvt_pk_bf16_f32 v206, v208, v209
	v_cvt_pk_bf16_f32 v207, v210, v211
	s_waitcnt lgkmcnt(4)
	v_mfma_f32_32x32x16_bf16 v[84:99], v[220:223], v[120:123], v[84:99]
	v_exp_f32_e32 v212, v212
	v_exp_f32_e32 v213, v213
	v_mfma_f32_32x32x16_bf16 v[100:115], v[224:227], v[120:123], v[100:115]
	v_exp_f32_e32 v214, v214
	v_exp_f32_e32 v215, v215
	s_waitcnt lgkmcnt(2)
	v_mfma_f32_32x32x16_bf16 v[84:99], v[232:235], v[124:127], v[84:99]
	v_pk_add_f32 v[150:151], v[150:151], v[212:213]
	v_pk_add_f32 v[150:151], v[150:151], v[214:215]
	v_exp_f32_e32 v216, v216
	v_mfma_f32_32x32x16_bf16 v[100:115], v[132:135], v[124:127], v[100:115]
	v_exp_f32_e32 v217, v217
	v_cvt_pk_bf16_f32 v208, v212, v213
	v_cvt_pk_bf16_f32 v209, v214, v215
	s_waitcnt lgkmcnt(0)
	v_mfma_f32_32x32x16_bf16 v[84:99], v[136:139], v[128:131], v[84:99]
	v_exp_f32_e32 v218, v218
	v_exp_f32_e32 v219, v219
	v_mfma_f32_32x32x16_bf16 v[100:115], v[140:143], v[128:131], v[100:115]
	v_pk_add_f32 v[150:151], v[150:151], v[216:217]
	v_pk_add_f32 v[150:151], v[150:151], v[218:219]
	v_cvt_pk_bf16_f32 v210, v216, v217
	v_cvt_pk_bf16_f32 v211, v218, v219
	s_add_u32 s8, s8, 0x40000
	s_addc_u32 s9, s9, 0
	s_waitcnt vmcnt(4) lgkmcnt(0)
	s_barrier
	s_sub_u32 s10, s10, 1
	s_cbranch_scc1 .LatB_evs_h4

; __device__ __forceinline__ void attn_unit(LAS unsigned char* lds, const bf16_t* Z, bf16_t* A2, const float* tabg, int seq_base, int S, int h, int qb, float lam) {
;     ...
;         if (t + 2 < NT) ATT_STAGE(t + 2, bn);
;         const LAS unsigned char* Kt = Kb + bc * KT; const LAS unsigned char* Vt = Vb + bc * VT;
;         const int kv0 = t * 64;
;         bool near = true; float cc = 0.f;
;         if (kv0 - (qlo + 31) >= 128) { near = false; cc = tabR; } else if (qlo - (kv0 + 63) >= 128) { near = false; cc = tabL; }
;         { const float coff = cc - mu;
;           if (__any(!(coff == coff_cur))) { coff_cur = coff;
; #pragma unroll
;               for (int r = 0; r < 16; ++r) cblk[r] = coff;
;               asm volatile("" : "+v"(cblk)); } }
;         f32x16 p0, p1;
;         {
;             bf16x8 kf[8];
; #pragma unroll
;             for (int ds = 0; ds < 4; ++ds) { kf[2 * ds] = *(const LAS bf16x8*)(Kt + (kfo ^ (unsigned)(ds << 5))); kf[2 * ds + 1] = *(const LAS bf16x8*)(Kt + 32 * 256 + (kfo ^ (unsigned)(ds << 5))); }
;             __builtin_amdgcn_sched_barrier(0);
;             p0 = __builtin_amdgcn_mfma_f32_32x32x16_bf16(kf[0], qf[0], cblk, 0, 0, 0);
;             p1 = __builtin_amdgcn_mfma_f32_32x32x16_bf16(kf[1], qf[0], cblk, 0, 0, 0);
; #pragma unroll
;             for (int ds = 1; ds < 4; ++ds) {
;                 p0 = __builtin_amdgcn_mfma_f32_32x32x16_bf16(kf[2 * ds], qf[ds], p0, 0, 0, 0);
;                 p1 = __builtin_amdgcn_mfma_f32_32x32x16_bf16(kf[2 * ds + 1], qf[ds], p1, 0, 0, 0);
;             }
;     ...
; #pragma unroll
;         for (int r = 0; r < 16; ++r) { p0[r] = __builtin_amdgcn_exp2f(p0[r]); p1[r] = __builtin_amdgcn_exp2f(p1[r]); }
; #pragma unroll
;         for (int r = 0; r < 16; r += 2) { ls2 += (f32x2){p0[r], p0[r + 1]}; ls2 += (f32x2){p1[r], p1[r + 1]}; }
;         bf16x8 pa[4]; pa[0] = pack8(p0, 0); pa[1] = pack8(p0, 8); pa[2] = pack8(p1, 0); pa[3] = pack8(p1, 8);
;         LGKM0(); VREADS1(vb, 1); PV1(va, 0); LGKM0(); VREADS1(va, 2); PV1(vb, 1); LGKM0(); VREADS1(vb, 3); PV1(va, 2); LGKM0(); PV1(vb, 3);
;     ...
;         if (t + 2 < NT) asm volatile("s_waitcnt vmcnt(4) lgkmcnt(0)" ::: "memory"); else asm volatile("s_waitcnt vmcnt(0) lgkmcnt(0)" ::: "memory");
;         __builtin_amdgcn_s_barrier(); asm volatile("" ::: "memory");
;         bc = (bc == NST - 1) ? 0 : bc + 1; bn = (bn == NST - 1) ? 0 : bn + 1;
.LatB_rareret_h4:
	s_waitcnt lgkmcnt(10)
	v_mfma_f32_32x32x16_bf16 v[20:35], v[188:191], v[132:135], v[20:35]
	ds_read_b64_tr_b16 v[132:133], v231 offset:4096
	ds_read_b64_tr_b16 v[134:135], v231 offset:6144
	v_exp_f32_e32 v84, v84
	v_exp_f32_e32 v85, v85
	v_mfma_f32_32x32x16_bf16 v[36:51], v[188:191], v[136:139], v[36:51]
	ds_read_b64_tr_b16 v[136:137], v228 offset:8192
	ds_read_b64_tr_b16 v[138:139], v228 offset:10240
	v_exp_f32_e32 v86, v86
	v_exp_f32_e32 v87, v87
	s_waitcnt lgkmcnt(10)
	v_mfma_f32_32x32x16_bf16 v[52:67], v[188:191], v[140:143], v[52:67]
	ds_read_b64_tr_b16 v[140:141], v229 offset:8192
	ds_read_b64_tr_b16 v[142:143], v229 offset:10240
	v_pk_add_f32 v[150:151], v[150:151], v[84:85]
	v_pk_add_f32 v[150:151], v[150:151], v[86:87]
	v_exp_f32_e32 v88, v88
	s_add_u32 m0, s25, 0x4000
	v_mfma_f32_32x32x16_bf16 v[68:83], v[188:191], v[144:147], v[68:83]
	global_load_lds_dwordx4 v236, s[8:9]
	ds_read_b64_tr_b16 v[144:145], v230 offset:8192
	ds_read_b64_tr_b16 v[146:147], v230 offset:10240
	v_exp_f32_e32 v89, v89
	v_cvt_pk_bf16_f32 v84, v84, v85
	v_cvt_pk_bf16_f32 v85, v86, v87
	s_waitcnt lgkmcnt(10)
	v_mfma_f32_32x32x16_bf16 v[20:35], v[192:195], v[220:223], v[20:35]
	ds_read_b64_tr_b16 v[220:221], v231 offset:8192
	ds_read_b64_tr_b16 v[222:223], v231 offset:10240
	v_exp_f32_e32 v90, v90
	v_exp_f32_e32 v91, v91
	v_mfma_f32_32x32x16_bf16 v[36:51], v[192:195], v[224:227], v[36:51]
	ds_read_b64_tr_b16 v[224:225], v228 offset:12288
	ds_read_b64_tr_b16 v[226:227], v228 offset:14336
	v_pk_add_f32 v[150:151], v[150:151], v[88:89]
	v_pk_add_f32 v[150:151], v[150:151], v[90:91]
	v_cvt_pk_bf16_f32 v86, v88, v89
	v_cvt_pk_bf16_f32 v87, v90, v91
	s_waitcnt lgkmcnt(10)
	v_mfma_f32_32x32x16_bf16 v[52:67], v[192:195], v[232:235], v[52:67]
	ds_read_b64_tr_b16 v[232:233], v229 offset:12288
	ds_read_b64_tr_b16 v[234:235], v229 offset:14336
	v_exp_f32_e32 v92, v92
	v_exp_f32_e32 v93, v93
	s_add_u32 m0, s27, 0x8000
	v_mfma_f32_32x32x16_bf16 v[68:83], v[192:195], v[132:135], v[68:83]
	global_load_lds_dwordx4 v149, s[8:9]
	ds_read_b64_tr_b16 v[132:133], v230 offset:12288
	ds_read_b64_tr_b16 v[134:135], v230 offset:14336
	v_exp_f32_e32 v94, v94
	v_exp_f32_e32 v95, v95
	s_waitcnt lgkmcnt(10)
	v_mfma_f32_32x32x16_bf16 v[20:35], v[204:207], v[136:139], v[20:35]
	ds_read_b64_tr_b16 v[136:137], v231 offset:12288
	ds_read_b64_tr_b16 v[138:139], v231 offset:14336
	v_pk_add_f32 v[150:151], v[150:151], v[92:93]
	v_pk_add_f32 v[150:151], v[150:151], v[94:95]
	v_exp_f32_e32 v96, v96
	v_mfma_f32_32x32x16_bf16 v[36:51], v[204:207], v[140:143], v[36:51]
	ds_read_b128 v[140:143], v19 offset:32768
	v_exp_f32_e32 v97, v97
	v_cvt_pk_bf16_f32 v88, v92, v93
	v_cvt_pk_bf16_f32 v89, v94, v95
	s_waitcnt lgkmcnt(9)
	v_mfma_f32_32x32x16_bf16 v[52:67], v[204:207], v[144:147], v[52:67]
	ds_read_b128 v[144:147], v19 offset:40960
	v_exp_f32_e32 v98, v98
	v_exp_f32_e32 v99, v99
	s_add_u32 m0, s25, 0x6000
	v_mfma_f32_32x32x16_bf16 v[68:83], v[204:207], v[220:223], v[68:83]
	global_load_lds_dwordx4 v237, s[8:9]
	ds_read_b128 v[220:223], v180 offset:32768
	v_pk_add_f32 v[150:151], v[150:151], v[96:97]
	v_pk_add_f32 v[150:151], v[150:151], v[98:99]
	v_cvt_pk_bf16_f32 v90, v96, v97
	v_cvt_pk_bf16_f32 v91, v98, v99
	s_waitcnt lgkmcnt(7)
	v_mfma_f32_32x32x16_bf16 v[20:35], v[208:211], v[224:227], v[20:35]
	ds_read_b128 v[224:227], v180 offset:40960
	v_exp_f32_e32 v100, v100
	v_exp_f32_e32 v101, v101
	v_mfma_f32_32x32x16_bf16 v[36:51], v[208:211], v[232:235], v[36:51]
	ds_read_b128 v[232:235], v181 offset:32768
	v_exp_f32_e32 v102, v102
	v_exp_f32_e32 v103, v103
	s_waitcnt lgkmcnt(5)
	v_mfma_f32_32x32x16_bf16 v[52:67], v[208:211], v[132:135], v[52:67]
	ds_read_b128 v[132:135], v181 offset:40960
	v_pk_add_f32 v[150:151], v[150:151], v[100:101]
	v_pk_add_f32 v[150:151], v[150:151], v[102:103]
	v_exp_f32_e32 v104, v104
	s_add_u32 m0, s27, 0xa000
	v_mfma_f32_32x32x16_bf16 v[68:83], v[208:211], v[136:139], v[68:83]
	global_load_lds_dwordx4 v176, s[8:9]
	ds_read_b128 v[136:139], v182 offset:32768
	v_exp_f32_e32 v105, v105
	v_cvt_pk_bf16_f32 v100, v100, v101
	v_cvt_pk_bf16_f32 v101, v102, v103
	s_waitcnt lgkmcnt(5)
	v_mfma_f32_32x32x16_bf16 v[188:203], v[140:143], v[116:119], v[2:17]
	ds_read_b128 v[140:143], v182 offset:40960
	v_exp_f32_e32 v106, v106
	v_exp_f32_e32 v107, v107
	v_mfma_f32_32x32x16_bf16 v[204:219], v[144:147], v[116:119], v[2:17]
	v_pk_add_f32 v[150:151], v[150:151], v[104:105]
	v_pk_add_f32 v[150:151], v[150:151], v[106:107]
	v_cvt_pk_bf16_f32 v102, v104, v105
	v_cvt_pk_bf16_f32 v103, v106, v107
	s_waitcnt lgkmcnt(4)
	v_mfma_f32_32x32x16_bf16 v[188:203], v[220:223], v[120:123], v[188:203]
	v_exp_f32_e32 v108, v108
	v_exp_f32_e32 v109, v109
	v_mfma_f32_32x32x16_bf16 v[204:219], v[224:227], v[120:123], v[204:219]
	v_exp_f32_e32 v110, v110
	v_exp_f32_e32 v111, v111
	s_waitcnt lgkmcnt(2)
	v_mfma_f32_32x32x16_bf16 v[188:203], v[232:235], v[124:127], v[188:203]
	v_pk_add_f32 v[150:151], v[150:151], v[108:109]
	v_pk_add_f32 v[150:151], v[150:151], v[110:111]
	v_exp_f32_e32 v112, v112
	v_mfma_f32_32x32x16_bf16 v[204:219], v[132:135], v[124:127], v[204:219]
	v_exp_f32_e32 v113, v113
	v_cvt_pk_bf16_f32 v104, v108, v109
	v_cvt_pk_bf16_f32 v105, v110, v111
	s_waitcnt lgkmcnt(0)
	v_mfma_f32_32x32x16_bf16 v[188:203], v[136:139], v[128:131], v[188:203]
	v_exp_f32_e32 v114, v114
	v_exp_f32_e32 v115, v115
	v_mfma_f32_32x32x16_bf16 v[204:219], v[140:143], v[128:131], v[204:219]
	v_pk_add_f32 v[150:151], v[150:151], v[112:113]
	v_pk_add_f32 v[150:151], v[150:151], v[114:115]
	v_cvt_pk_bf16_f32 v106, v112, v113
	v_cvt_pk_bf16_f32 v107, v114, v115
	s_add_u32 s8, s8, 0x40000
	s_addc_u32 s9, s9, 0
	s_waitcnt vmcnt(4) lgkmcnt(0)
	s_barrier
	s_sub_u32 s10, s10, 1
	s_cbranch_scc1 .LatB_evs_h5

; __device__ __forceinline__ void attn_unit(LAS unsigned char* lds, const bf16_t* Z, bf16_t* A2, const float* tabg, int seq_base, int S, int h, int qb, float lam) {
;     ...
;         if (t + 2 < NT) ATT_STAGE(t + 2, bn);
;         const LAS unsigned char* Kt = Kb + bc * KT; const LAS unsigned char* Vt = Vb + bc * VT;
;         const int kv0 = t * 64;
;         bool near = true; float cc = 0.f;
;         if (kv0 - (qlo + 31) >= 128) { near = false; cc = tabR; } else if (qlo - (kv0 + 63) >= 128) { near = false; cc = tabL; }
;         { const float coff = cc - mu;
;           if (__any(!(coff == coff_cur))) { coff_cur = coff;
; #pragma unroll
;               for (int r = 0; r < 16; ++r) cblk[r] = coff;
;               asm volatile("" : "+v"(cblk)); } }
;         f32x16 p0, p1;
;         {
;             bf16x8 kf[8];
; #pragma unroll
;             for (int ds = 0; ds < 4; ++ds) { kf[2 * ds] = *(const LAS bf16x8*)(Kt + (kfo ^ (unsigned)(ds << 5))); kf[2 * ds + 1] = *(const LAS bf16x8*)(Kt + 32 * 256 + (kfo ^ (unsigned)(ds << 5))); }
;             __builtin_amdgcn_sched_barrier(0);
;             p0 = __builtin_amdgcn_mfma_f32_32x32x16_bf16(kf[0], qf[0], cblk, 0, 0, 0);
;             p1 = __builtin_amdgcn_mfma_f32_32x32x16_bf16(kf[1], qf[0], cblk, 0, 0, 0);
; #pragma unroll
;             for (int ds = 1; ds < 4; ++ds) {
;                 p0 = __builtin_amdgcn_mfma_f32_32x32x16_bf16(kf[2 * ds], qf[ds], p0, 0, 0, 0);
;                 p1 = __builtin_amdgcn_mfma_f32_32x32x16_bf16(kf[2 * ds + 1], qf[ds], p1, 0, 0, 0);
;             }
;     ...
; #pragma unroll
;         for (int r = 0; r < 16; ++r) { p0[r] = __builtin_amdgcn_exp2f(p0[r]); p1[r] = __builtin_amdgcn_exp2f(p1[r]); }
; #pragma unroll
;         for (int r = 0; r < 16; r += 2) { ls2 += (f32x2){p0[r], p0[r + 1]}; ls2 += (f32x2){p1[r], p1[r + 1]}; }
;         bf16x8 pa[4]; pa[0] = pack8(p0, 0); pa[1] = pack8(p0, 8); pa[2] = pack8(p1, 0); pa[3] = pack8(p1, 8);
;         LGKM0(); VREADS1(vb, 1); PV1(va, 0); LGKM0(); VREADS1(va, 2); PV1(vb, 1); LGKM0(); VREADS1(vb, 3); PV1(va, 2); LGKM0(); PV1(vb, 3);
;     ...
;         if (t + 2 < NT) asm volatile("s_waitcnt vmcnt(4) lgkmcnt(0)" ::: "memory"); else asm volatile("s_waitcnt vmcnt(0) lgkmcnt(0)" ::: "memory");
;         __builtin_amdgcn_s_barrier(); asm volatile("" ::: "memory");
;         bc = (bc == NST - 1) ? 0 : bc + 1; bn = (bn == NST - 1) ? 0 : bn + 1;
.LatB_rareret_h5:
	s_waitcnt lgkmcnt(10)
	v_mfma_f32_32x32x16_bf16 v[20:35], v[84:87], v[132:135], v[20:35]
	ds_read_b64_tr_b16 v[132:133], v231 offset:20480
	ds_read_b64_tr_b16 v[134:135], v231 offset:22528
	v_exp_f32_e32 v188, v188
	v_exp_f32_e32 v189, v189
	v_mfma_f32_32x32x16_bf16 v[36:51], v[84:87], v[136:139], v[36:51]
	ds_read_b64_tr_b16 v[136:137], v228 offset:24576
	ds_read_b64_tr_b16 v[138:139], v228 offset:26624
	v_exp_f32_e32 v190, v190
	v_exp_f32_e32 v191, v191
	s_waitcnt lgkmcnt(10)
	v_mfma_f32_32x32x16_bf16 v[52:67], v[84:87], v[140:143], v[52:67]
	ds_read_b64_tr_b16 v[140:141], v229 offset:24576
	ds_read_b64_tr_b16 v[142:143], v229 offset:26624
	v_pk_add_f32 v[150:151], v[150:151], v[188:189]
	v_pk_add_f32 v[150:151], v[150:151], v[190:191]
	v_exp_f32_e32 v192, v192
	s_add_u32 m0, s25, 0x8000
	v_mfma_f32_32x32x16_bf16 v[68:83], v[84:87], v[144:147], v[68:83]
	global_load_lds_dwordx4 v236, s[8:9]
	ds_read_b64_tr_b16 v[144:145], v230 offset:24576
	ds_read_b64_tr_b16 v[146:147], v230 offset:26624
	v_exp_f32_e32 v193, v193
	v_cvt_pk_bf16_f32 v188, v188, v189
	v_cvt_pk_bf16_f32 v189, v190, v191
	s_waitcnt lgkmcnt(10)
	v_mfma_f32_32x32x16_bf16 v[20:35], v[88:91], v[220:223], v[20:35]
	ds_read_b64_tr_b16 v[220:221], v231 offset:24576
	ds_read_b64_tr_b16 v[222:223], v231 offset:26624
	v_exp_f32_e32 v194, v194
	v_exp_f32_e32 v195, v195
	v_mfma_f32_32x32x16_bf16 v[36:51], v[88:91], v[224:227], v[36:51]
	ds_read_b64_tr_b16 v[224:225], v228 offset:28672
	ds_read_b64_tr_b16 v[226:227], v228 offset:30720
	v_pk_add_f32 v[150:151], v[150:151], v[192:193]
	v_pk_add_f32 v[150:151], v[150:151], v[194:195]
	v_cvt_pk_bf16_f32 v190, v192, v193
	v_cvt_pk_bf16_f32 v191, v194, v195
	s_waitcnt lgkmcnt(10)
	v_mfma_f32_32x32x16_bf16 v[52:67], v[88:91], v[232:235], v[52:67]
	ds_read_b64_tr_b16 v[232:233], v229 offset:28672
	ds_read_b64_tr_b16 v[234:235], v229 offset:30720
	v_exp_f32_e32 v196, v196
	v_exp_f32_e32 v197, v197
	s_mov_b32 m0, s27
	v_mfma_f32_32x32x16_bf16 v[68:83], v[88:91], v[132:135], v[68:83]
	global_load_lds_dwordx4 v149, s[8:9]
	ds_read_b64_tr_b16 v[132:133], v230 offset:28672
	ds_read_b64_tr_b16 v[134:135], v230 offset:30720
	v_exp_f32_e32 v198, v198
	v_exp_f32_e32 v199, v199
	s_waitcnt lgkmcnt(10)
	v_mfma_f32_32x32x16_bf16 v[20:35], v[100:103], v[136:139], v[20:35]
	ds_read_b64_tr_b16 v[136:137], v231 offset:28672
	ds_read_b64_tr_b16 v[138:139], v231 offset:30720
	v_pk_add_f32 v[150:151], v[150:151], v[196:197]
	v_pk_add_f32 v[150:151], v[150:151], v[198:199]
	v_exp_f32_e32 v200, v200
	v_mfma_f32_32x32x16_bf16 v[36:51], v[100:103], v[140:143], v[36:51]
	ds_read_b128 v[140:143], v19
	v_exp_f32_e32 v201, v201
	v_cvt_pk_bf16_f32 v192, v196, v197
	v_cvt_pk_bf16_f32 v193, v198, v199
	s_waitcnt lgkmcnt(9)
	v_mfma_f32_32x32x16_bf16 v[52:67], v[100:103], v[144:147], v[52:67]
	ds_read_b128 v[144:147], v19 offset:8192
	v_exp_f32_e32 v202, v202
	v_exp_f32_e32 v203, v203
	s_add_u32 m0, s25, 0xa000
	v_mfma_f32_32x32x16_bf16 v[68:83], v[100:103], v[220:223], v[68:83]
	global_load_lds_dwordx4 v237, s[8:9]
	ds_read_b128 v[220:223], v180
	v_pk_add_f32 v[150:151], v[150:151], v[200:201]
	v_pk_add_f32 v[150:151], v[150:151], v[202:203]
	v_cvt_pk_bf16_f32 v194, v200, v201
	v_cvt_pk_bf16_f32 v195, v202, v203
	s_waitcnt lgkmcnt(7)
	v_mfma_f32_32x32x16_bf16 v[20:35], v[104:107], v[224:227], v[20:35]
	ds_read_b128 v[224:227], v180 offset:8192
	v_exp_f32_e32 v204, v204
	v_exp_f32_e32 v205, v205
	v_mfma_f32_32x32x16_bf16 v[36:51], v[104:107], v[232:235], v[36:51]
	ds_read_b128 v[232:235], v181
	v_exp_f32_e32 v206, v206
	v_exp_f32_e32 v207, v207
	s_waitcnt lgkmcnt(5)
	v_mfma_f32_32x32x16_bf16 v[52:67], v[104:107], v[132:135], v[52:67]
	ds_read_b128 v[132:135], v181 offset:8192
	v_pk_add_f32 v[150:151], v[150:151], v[204:205]
	v_pk_add_f32 v[150:151], v[150:151], v[206:207]
	v_exp_f32_e32 v208, v208
	s_add_u32 m0, s27, 0x2000
	v_mfma_f32_32x32x16_bf16 v[68:83], v[104:107], v[136:139], v[68:83]
	global_load_lds_dwordx4 v176, s[8:9]
	ds_read_b128 v[136:139], v182
	v_exp_f32_e32 v209, v209
	v_cvt_pk_bf16_f32 v204, v204, v205
	v_cvt_pk_bf16_f32 v205, v206, v207
	s_waitcnt lgkmcnt(5)
	v_mfma_f32_32x32x16_bf16 v[84:99], v[140:143], v[116:119], v[2:17]
	ds_read_b128 v[140:143], v182 offset:8192
	v_exp_f32_e32 v210, v210
	v_exp_f32_e32 v211, v211
	v_mfma_f32_32x32x16_bf16 v[100:115], v[144:147], v[116:119], v[2:17]
	v_pk_add_f32 v[150:151], v[150:151], v[208:209]
	v_pk_add_f32 v[150:151], v[150:151], v[210:211]
	v_cvt_pk_bf16_f32 v206, v208, v209
	v_cvt_pk_bf16_f32 v207, v210, v211
	s_waitcnt lgkmcnt(4)
	v_mfma_f32_32x32x16_bf16 v[84:99], v[220:223], v[120:123], v[84:99]
	v_exp_f32_e32 v212, v212
	v_exp_f32_e32 v213, v213
	v_mfma_f32_32x32x16_bf16 v[100:115], v[224:227], v[120:123], v[100:115]
	v_exp_f32_e32 v214, v214
	v_exp_f32_e32 v215, v215
	s_waitcnt lgkmcnt(2)
	v_mfma_f32_32x32x16_bf16 v[84:99], v[232:235], v[124:127], v[84:99]
	v_pk_add_f32 v[150:151], v[150:151], v[212:213]
	v_pk_add_f32 v[150:151], v[150:151], v[214:215]
	v_exp_f32_e32 v216, v216
	v_mfma_f32_32x32x16_bf16 v[100:115], v[132:135], v[124:127], v[100:115]
	v_exp_f32_e32 v217, v217
	v_cvt_pk_bf16_f32 v208, v212, v213
	v_cvt_pk_bf16_f32 v209, v214, v215
	s_waitcnt lgkmcnt(0)
	v_mfma_f32_32x32x16_bf16 v[84:99], v[136:139], v[128:131], v[84:99]
	v_exp_f32_e32 v218, v218
	v_exp_f32_e32 v219, v219
	v_mfma_f32_32x32x16_bf16 v[100:115], v[140:143], v[128:131], v[100:115]
	v_pk_add_f32 v[150:151], v[150:151], v[216:217]
	v_pk_add_f32 v[150:151], v[150:151], v[218:219]
	v_cvt_pk_bf16_f32 v210, v216, v217
	v_cvt_pk_bf16_f32 v211, v218, v219
	s_add_u32 s8, s8, 0x40000
	s_addc_u32 s9, s9, 0
	s_waitcnt vmcnt(4) lgkmcnt(0)
	s_barrier
	s_movk_i32 s36, 41

; __device__ __forceinline__ void attn_unit(LAS unsigned char* lds, const bf16_t* Z, bf16_t* A2, const float* tabg, int seq_base, int S, int h, int qb, float lam) {
;     ...
;         if (t + 2 < NT) ATT_STAGE(t + 2, bn);
;         const LAS unsigned char* Kt = Kb + bc * KT; const LAS unsigned char* Vt = Vb + bc * VT;
;         const int kv0 = t * 64;
;         bool near = true; float cc = 0.f;
;         if (kv0 - (qlo + 31) >= 128) { near = false; cc = tabR; } else if (qlo - (kv0 + 63) >= 128) { near = false; cc = tabL; }
;         { const float coff = cc - mu;
;           if (__any(!(coff == coff_cur))) { coff_cur = coff;
; #pragma unroll
;               for (int r = 0; r < 16; ++r) cblk[r] = coff;
;               asm volatile("" : "+v"(cblk)); } }
;         f32x16 p0, p1;
;         {
;             bf16x8 kf[8];
; #pragma unroll
;             for (int ds = 0; ds < 4; ++ds) { kf[2 * ds] = *(const LAS bf16x8*)(Kt + (kfo ^ (unsigned)(ds << 5))); kf[2 * ds + 1] = *(const LAS bf16x8*)(Kt + 32 * 256 + (kfo ^ (unsigned)(ds << 5))); }
;             __builtin_amdgcn_sched_barrier(0);
;             p0 = __builtin_amdgcn_mfma_f32_32x32x16_bf16(kf[0], qf[0], cblk, 0, 0, 0);
;             p1 = __builtin_amdgcn_mfma_f32_32x32x16_bf16(kf[1], qf[0], cblk, 0, 0, 0);
; #pragma unroll
;             for (int ds = 1; ds < 4; ++ds) {
;                 p0 = __builtin_amdgcn_mfma_f32_32x32x16_bf16(kf[2 * ds], qf[ds], p0, 0, 0, 0);
;                 p1 = __builtin_amdgcn_mfma_f32_32x32x16_bf16(kf[2 * ds + 1], qf[ds], p1, 0, 0, 0);
;             }
;     ...
; #pragma unroll
;         for (int r = 0; r < 16; ++r) { p0[r] = __builtin_amdgcn_exp2f(p0[r]); p1[r] = __builtin_amdgcn_exp2f(p1[r]); }
; #pragma unroll
;         for (int r = 0; r < 16; r += 2) { ls2 += (f32x2){p0[r], p0[r + 1]}; ls2 += (f32x2){p1[r], p1[r + 1]}; }
;         bf16x8 pa[4]; pa[0] = pack8(p0, 0); pa[1] = pack8(p0, 8); pa[2] = pack8(p1, 0); pa[3] = pack8(p1, 8);
;         LGKM0(); VREADS1(vb, 1); PV1(va, 0); LGKM0(); VREADS1(va, 2); PV1(vb, 1); LGKM0(); VREADS1(vb, 3); PV1(va, 2); LGKM0(); PV1(vb, 3);
;     ...
;         if (t + 2 < NT) asm volatile("s_waitcnt vmcnt(4) lgkmcnt(0)" ::: "memory"); else asm volatile("s_waitcnt vmcnt(0) lgkmcnt(0)" ::: "memory");
;         __builtin_amdgcn_s_barrier(); asm volatile("" ::: "memory");
;         bc = (bc == NST - 1) ? 0 : bc + 1; bn = (bn == NST - 1) ? 0 : bn + 1;
.LatB_rareret_m0:
	s_waitcnt lgkmcnt(10)
	v_mfma_f32_32x32x16_bf16 v[20:35], v[188:191], v[132:135], v[20:35]
	ds_read_b64_tr_b16 v[132:133], v231 offset:36864
	ds_read_b64_tr_b16 v[134:135], v231 offset:38912
	v_exp_f32_e32 v84, v84
	v_exp_f32_e32 v85, v85
	v_mfma_f32_32x32x16_bf16 v[36:51], v[188:191], v[136:139], v[36:51]
	ds_read_b64_tr_b16 v[136:137], v228 offset:40960
	ds_read_b64_tr_b16 v[138:139], v228 offset:43008
	v_exp_f32_e32 v86, v86
	v_exp_f32_e32 v87, v87
	s_waitcnt lgkmcnt(10)
	v_mfma_f32_32x32x16_bf16 v[52:67], v[188:191], v[140:143], v[52:67]
	ds_read_b64_tr_b16 v[140:141], v229 offset:40960
	ds_read_b64_tr_b16 v[142:143], v229 offset:43008
	v_pk_add_f32 v[150:151], v[150:151], v[84:85]
	v_pk_add_f32 v[150:151], v[150:151], v[86:87]
	v_exp_f32_e32 v88, v88
	s_mov_b32 m0, s25
	v_mfma_f32_32x32x16_bf16 v[68:83], v[188:191], v[144:147], v[68:83]
	global_load_lds_dwordx4 v236, s[8:9]
	ds_read_b64_tr_b16 v[144:145], v230 offset:40960
	ds_read_b64_tr_b16 v[146:147], v230 offset:43008
	v_exp_f32_e32 v89, v89
	v_cvt_pk_bf16_f32 v84, v84, v85
	v_cvt_pk_bf16_f32 v85, v86, v87
	s_waitcnt lgkmcnt(10)
	v_mfma_f32_32x32x16_bf16 v[20:35], v[192:195], v[220:223], v[20:35]
	ds_read_b64_tr_b16 v[220:221], v231 offset:40960
	ds_read_b64_tr_b16 v[222:223], v231 offset:43008
	v_exp_f32_e32 v90, v90
	v_exp_f32_e32 v91, v91
	v_mfma_f32_32x32x16_bf16 v[36:51], v[192:195], v[224:227], v[36:51]
	ds_read_b64_tr_b16 v[224:225], v228 offset:45056
	ds_read_b64_tr_b16 v[226:227], v228 offset:47104
	v_pk_add_f32 v[150:151], v[150:151], v[88:89]
	v_pk_add_f32 v[150:151], v[150:151], v[90:91]
	v_cvt_pk_bf16_f32 v86, v88, v89
	v_cvt_pk_bf16_f32 v87, v90, v91
	s_waitcnt lgkmcnt(10)
	v_mfma_f32_32x32x16_bf16 v[52:67], v[192:195], v[232:235], v[52:67]
	ds_read_b64_tr_b16 v[232:233], v229 offset:45056
	ds_read_b64_tr_b16 v[234:235], v229 offset:47104
	v_exp_f32_e32 v92, v92
	v_exp_f32_e32 v93, v93
	s_add_u32 m0, s27, 0x4000
	v_mfma_f32_32x32x16_bf16 v[68:83], v[192:195], v[132:135], v[68:83]
	global_load_lds_dwordx4 v149, s[8:9]
	ds_read_b64_tr_b16 v[132:133], v230 offset:45056
	ds_read_b64_tr_b16 v[134:135], v230 offset:47104
	v_exp_f32_e32 v94, v94
	v_exp_f32_e32 v95, v95
	s_waitcnt lgkmcnt(10)
	v_mfma_f32_32x32x16_bf16 v[20:35], v[204:207], v[136:139], v[20:35]
	ds_read_b64_tr_b16 v[136:137], v231 offset:45056
	ds_read_b64_tr_b16 v[138:139], v231 offset:47104
	v_pk_add_f32 v[150:151], v[150:151], v[92:93]
	v_pk_add_f32 v[150:151], v[150:151], v[94:95]
	v_exp_f32_e32 v96, v96
	v_mfma_f32_32x32x16_bf16 v[36:51], v[204:207], v[140:143], v[36:51]
	ds_read_b128 v[140:143], v19 offset:16384
	v_exp_f32_e32 v97, v97
	v_cvt_pk_bf16_f32 v88, v92, v93
	v_cvt_pk_bf16_f32 v89, v94, v95
	s_waitcnt lgkmcnt(9)
	v_mfma_f32_32x32x16_bf16 v[52:67], v[204:207], v[144:147], v[52:67]
	ds_read_b128 v[144:147], v19 offset:24576
	v_exp_f32_e32 v98, v98
	v_exp_f32_e32 v99, v99
	s_add_u32 m0, s25, 0x2000
	v_mfma_f32_32x32x16_bf16 v[68:83], v[204:207], v[220:223], v[68:83]
	global_load_lds_dwordx4 v237, s[8:9]
	ds_read_b128 v[220:223], v180 offset:16384
	v_pk_add_f32 v[150:151], v[150:151], v[96:97]
	v_pk_add_f32 v[150:151], v[150:151], v[98:99]
	v_cvt_pk_bf16_f32 v90, v96, v97
	v_cvt_pk_bf16_f32 v91, v98, v99
	s_waitcnt lgkmcnt(7)
	v_mfma_f32_32x32x16_bf16 v[20:35], v[208:211], v[224:227], v[20:35]
	ds_read_b128 v[224:227], v180 offset:24576
	v_exp_f32_e32 v100, v100
	v_exp_f32_e32 v101, v101
	v_mfma_f32_32x32x16_bf16 v[36:51], v[208:211], v[232:235], v[36:51]
	ds_read_b128 v[232:235], v181 offset:16384
	v_exp_f32_e32 v102, v102
	v_exp_f32_e32 v103, v103
	s_waitcnt lgkmcnt(5)
	v_mfma_f32_32x32x16_bf16 v[52:67], v[208:211], v[132:135], v[52:67]
	ds_read_b128 v[132:135], v181 offset:24576
	v_pk_add_f32 v[150:151], v[150:151], v[100:101]
	v_pk_add_f32 v[150:151], v[150:151], v[102:103]
	v_exp_f32_e32 v104, v104
	s_add_u32 m0, s27, 0x6000
	v_mfma_f32_32x32x16_bf16 v[68:83], v[208:211], v[136:139], v[68:83]
	global_load_lds_dwordx4 v176, s[8:9]
	ds_read_b128 v[136:139], v182 offset:16384
	v_exp_f32_e32 v105, v105
	v_cvt_pk_bf16_f32 v100, v100, v101
	v_cvt_pk_bf16_f32 v101, v102, v103
	s_waitcnt lgkmcnt(5)
	v_mfma_f32_32x32x16_bf16 v[188:203], v[140:143], v[116:119], v[2:17]
	ds_read_b128 v[140:143], v182 offset:24576
	v_exp_f32_e32 v106, v106
	v_exp_f32_e32 v107, v107
	v_mfma_f32_32x32x16_bf16 v[204:219], v[144:147], v[116:119], v[2:17]
	v_pk_add_f32 v[150:151], v[150:151], v[104:105]
	v_pk_add_f32 v[150:151], v[150:151], v[106:107]
	v_cvt_pk_bf16_f32 v102, v104, v105
	v_cvt_pk_bf16_f32 v103, v106, v107
	s_waitcnt lgkmcnt(4)
	v_mfma_f32_32x32x16_bf16 v[188:203], v[220:223], v[120:123], v[188:203]
	v_exp_f32_e32 v108, v108
	v_exp_f32_e32 v109, v109
	v_mfma_f32_32x32x16_bf16 v[204:219], v[224:227], v[120:123], v[204:219]
	v_exp_f32_e32 v110, v110
	v_exp_f32_e32 v111, v111
	s_waitcnt lgkmcnt(2)
	v_mfma_f32_32x32x16_bf16 v[188:203], v[232:235], v[124:127], v[188:203]
	v_pk_add_f32 v[150:151], v[150:151], v[108:109]
	v_pk_add_f32 v[150:151], v[150:151], v[110:111]
	v_exp_f32_e32 v112, v112
	v_mfma_f32_32x32x16_bf16 v[204:219], v[132:135], v[124:127], v[204:219]
	v_exp_f32_e32 v113, v113
	v_cvt_pk_bf16_f32 v104, v108, v109
	v_cvt_pk_bf16_f32 v105, v110, v111
	s_waitcnt lgkmcnt(0)
	v_mfma_f32_32x32x16_bf16 v[188:203], v[136:139], v[128:131], v[188:203]
	v_exp_f32_e32 v114, v114
	v_exp_f32_e32 v115, v115
	v_mfma_f32_32x32x16_bf16 v[204:219], v[140:143], v[128:131], v[204:219]
	v_pk_add_f32 v[150:151], v[150:151], v[112:113]
	v_pk_add_f32 v[150:151], v[150:151], v[114:115]
	v_cvt_pk_bf16_f32 v106, v112, v113
	v_cvt_pk_bf16_f32 v107, v114, v115
	s_add_u32 s8, s8, 0x40000
	s_addc_u32 s9, s9, 0
	s_waitcnt vmcnt(4) lgkmcnt(0)
	s_barrier
	s_sub_u32 s10, s10, 1
	s_cbranch_scc1 .LatB_evs_m1

; __device__ __forceinline__ void attn_unit(LAS unsigned char* lds, const bf16_t* Z, bf16_t* A2, const float* tabg, int seq_base, int S, int h, int qb, float lam) {
;     ...
;         if (t + 2 < NT) ATT_STAGE(t + 2, bn);
;         const LAS unsigned char* Kt = Kb + bc * KT; const LAS unsigned char* Vt = Vb + bc * VT;
;         const int kv0 = t * 64;
;         bool near = true; float cc = 0.f;
;         if (kv0 - (qlo + 31) >= 128) { near = false; cc = tabR; } else if (qlo - (kv0 + 63) >= 128) { near = false; cc = tabL; }
;         { const float coff = cc - mu;
;           if (__any(!(coff == coff_cur))) { coff_cur = coff;
; #pragma unroll
;               for (int r = 0; r < 16; ++r) cblk[r] = coff;
;               asm volatile("" : "+v"(cblk)); } }
;         f32x16 p0, p1;
;         {
;             bf16x8 kf[8];
; #pragma unroll
;             for (int ds = 0; ds < 4; ++ds) { kf[2 * ds] = *(const LAS bf16x8*)(Kt + (kfo ^ (unsigned)(ds << 5))); kf[2 * ds + 1] = *(const LAS bf16x8*)(Kt + 32 * 256 + (kfo ^ (unsigned)(ds << 5))); }
;             __builtin_amdgcn_sched_barrier(0);
;             p0 = __builtin_amdgcn_mfma_f32_32x32x16_bf16(kf[0], qf[0], cblk, 0, 0, 0);
;             p1 = __builtin_amdgcn_mfma_f32_32x32x16_bf16(kf[1], qf[0], cblk, 0, 0, 0);
; #pragma unroll
;             for (int ds = 1; ds < 4; ++ds) {
;                 p0 = __builtin_amdgcn_mfma_f32_32x32x16_bf16(kf[2 * ds], qf[ds], p0, 0, 0, 0);
;                 p1 = __builtin_amdgcn_mfma_f32_32x32x16_bf16(kf[2 * ds + 1], qf[ds], p1, 0, 0, 0);
;             }
;     ...
; #pragma unroll
;         for (int r = 0; r < 16; ++r) { p0[r] = __builtin_amdgcn_exp2f(p0[r]); p1[r] = __builtin_amdgcn_exp2f(p1[r]); }
; #pragma unroll
;         for (int r = 0; r < 16; r += 2) { ls2 += (f32x2){p0[r], p0[r + 1]}; ls2 += (f32x2){p1[r], p1[r + 1]}; }
;         bf16x8 pa[4]; pa[0] = pack8(p0, 0); pa[1] = pack8(p0, 8); pa[2] = pack8(p1, 0); pa[3] = pack8(p1, 8);
;         LGKM0(); VREADS1(vb, 1); PV1(va, 0); LGKM0(); VREADS1(va, 2); PV1(vb, 1); LGKM0(); VREADS1(vb, 3); PV1(va, 2); LGKM0(); PV1(vb, 3);
;     ...
;         if (t + 2 < NT) asm volatile("s_waitcnt vmcnt(4) lgkmcnt(0)" ::: "memory"); else asm volatile("s_waitcnt vmcnt(0) lgkmcnt(0)" ::: "memory");
;         __builtin_amdgcn_s_barrier(); asm volatile("" ::: "memory");
;         bc = (bc == NST - 1) ? 0 : bc + 1; bn = (bn == NST - 1) ? 0 : bn + 1;
.LatB_rareret_m5:
	s_waitcnt lgkmcnt(10)
	v_mfma_f32_32x32x16_bf16 v[20:35], v[84:87], v[132:135], v[20:35]
	ds_read_b64_tr_b16 v[132:133], v231 offset:20480
	ds_read_b64_tr_b16 v[134:135], v231 offset:22528
	v_exp_f32_e32 v188, v188
	v_exp_f32_e32 v189, v189
	v_mfma_f32_32x32x16_bf16 v[36:51], v[84:87], v[136:139], v[36:51]
	ds_read_b64_tr_b16 v[136:137], v228 offset:24576
	ds_read_b64_tr_b16 v[138:139], v228 offset:26624
	v_exp_f32_e32 v190, v190
	v_exp_f32_e32 v191, v191
	s_waitcnt lgkmcnt(10)
	v_mfma_f32_32x32x16_bf16 v[52:67], v[84:87], v[140:143], v[52:67]
	ds_read_b64_tr_b16 v[140:141], v229 offset:24576
	ds_read_b64_tr_b16 v[142:143], v229 offset:26624
	v_pk_add_f32 v[150:151], v[150:151], v[188:189]
	v_pk_add_f32 v[150:151], v[150:151], v[190:191]
	v_exp_f32_e32 v192, v192
	s_add_u32 m0, s25, 0x8000
	v_mfma_f32_32x32x16_bf16 v[68:83], v[84:87], v[144:147], v[68:83]
	global_load_lds_dwordx4 v236, s[8:9]
	ds_read_b64_tr_b16 v[144:145], v230 offset:24576
	ds_read_b64_tr_b16 v[146:147], v230 offset:26624
	v_exp_f32_e32 v193, v193
	v_cvt_pk_bf16_f32 v188, v188, v189
	v_cvt_pk_bf16_f32 v189, v190, v191
	s_waitcnt lgkmcnt(10)
	v_mfma_f32_32x32x16_bf16 v[20:35], v[88:91], v[220:223], v[20:35]
	ds_read_b64_tr_b16 v[220:221], v231 offset:24576
	ds_read_b64_tr_b16 v[222:223], v231 offset:26624
	v_exp_f32_e32 v194, v194
	v_exp_f32_e32 v195, v195
	v_mfma_f32_32x32x16_bf16 v[36:51], v[88:91], v[224:227], v[36:51]
	ds_read_b64_tr_b16 v[224:225], v228 offset:28672
	ds_read_b64_tr_b16 v[226:227], v228 offset:30720
	v_pk_add_f32 v[150:151], v[150:151], v[192:193]
	v_pk_add_f32 v[150:151], v[150:151], v[194:195]
	v_cvt_pk_bf16_f32 v190, v192, v193
	v_cvt_pk_bf16_f32 v191, v194, v195
	s_waitcnt lgkmcnt(10)
	v_mfma_f32_32x32x16_bf16 v[52:67], v[88:91], v[232:235], v[52:67]
	ds_read_b64_tr_b16 v[232:233], v229 offset:28672
	ds_read_b64_tr_b16 v[234:235], v229 offset:30720
	v_exp_f32_e32 v196, v196
	v_exp_f32_e32 v197, v197
	s_mov_b32 m0, s27
	v_mfma_f32_32x32x16_bf16 v[68:83], v[88:91], v[132:135], v[68:83]
	global_load_lds_dwordx4 v149, s[8:9]
	ds_read_b64_tr_b16 v[132:133], v230 offset:28672
	ds_read_b64_tr_b16 v[134:135], v230 offset:30720
	v_exp_f32_e32 v198, v198
	v_exp_f32_e32 v199, v199
	s_waitcnt lgkmcnt(10)
	v_mfma_f32_32x32x16_bf16 v[20:35], v[100:103], v[136:139], v[20:35]
	ds_read_b64_tr_b16 v[136:137], v231 offset:28672
	ds_read_b64_tr_b16 v[138:139], v231 offset:30720
	v_pk_add_f32 v[150:151], v[150:151], v[196:197]
	v_pk_add_f32 v[150:151], v[150:151], v[198:199]
	v_exp_f32_e32 v200, v200
	v_mfma_f32_32x32x16_bf16 v[36:51], v[100:103], v[140:143], v[36:51]
	ds_read_b128 v[140:143], v19
	v_exp_f32_e32 v201, v201
	v_cvt_pk_bf16_f32 v192, v196, v197
	v_cvt_pk_bf16_f32 v193, v198, v199
	s_waitcnt lgkmcnt(9)
	v_mfma_f32_32x32x16_bf16 v[52:67], v[100:103], v[144:147], v[52:67]
	ds_read_b128 v[144:147], v19 offset:8192
	v_exp_f32_e32 v202, v202
	v_exp_f32_e32 v203, v203
	s_add_u32 m0, s25, 0xa000
	v_mfma_f32_32x32x16_bf16 v[68:83], v[100:103], v[220:223], v[68:83]
	global_load_lds_dwordx4 v237, s[8:9]
	ds_read_b128 v[220:223], v180
	v_pk_add_f32 v[150:151], v[150:151], v[200:201]
	v_pk_add_f32 v[150:151], v[150:151], v[202:203]
	v_cvt_pk_bf16_f32 v194, v200, v201
	v_cvt_pk_bf16_f32 v195, v202, v203
	s_waitcnt lgkmcnt(7)
	v_mfma_f32_32x32x16_bf16 v[20:35], v[104:107], v[224:227], v[20:35]
	ds_read_b128 v[224:227], v180 offset:8192
	v_exp_f32_e32 v204, v204
	v_exp_f32_e32 v205, v205
	v_mfma_f32_32x32x16_bf16 v[36:51], v[104:107], v[232:235], v[36:51]
	ds_read_b128 v[232:235], v181
	v_exp_f32_e32 v206, v206
	v_exp_f32_e32 v207, v207
	s_waitcnt lgkmcnt(5)
	v_mfma_f32_32x32x16_bf16 v[52:67], v[104:107], v[132:135], v[52:67]
	ds_read_b128 v[132:135], v181 offset:8192
	v_pk_add_f32 v[150:151], v[150:151], v[204:205]
	v_pk_add_f32 v[150:151], v[150:151], v[206:207]
	v_exp_f32_e32 v208, v208
	s_add_u32 m0, s27, 0x2000
	v_mfma_f32_32x32x16_bf16 v[68:83], v[104:107], v[136:139], v[68:83]
	global_load_lds_dwordx4 v176, s[8:9]
	ds_read_b128 v[136:139], v182
	v_exp_f32_e32 v209, v209
	v_cvt_pk_bf16_f32 v204, v204, v205
	v_cvt_pk_bf16_f32 v205, v206, v207
	s_waitcnt lgkmcnt(5)
	v_mfma_f32_32x32x16_bf16 v[84:99], v[140:143], v[116:119], v[2:17]
	ds_read_b128 v[140:143], v182 offset:8192
	v_exp_f32_e32 v210, v210
	v_exp_f32_e32 v211, v211
	v_mfma_f32_32x32x16_bf16 v[100:115], v[144:147], v[116:119], v[2:17]
	v_pk_add_f32 v[150:151], v[150:151], v[208:209]
	v_pk_add_f32 v[150:151], v[150:151], v[210:211]
	v_cvt_pk_bf16_f32 v206, v208, v209
	v_cvt_pk_bf16_f32 v207, v210, v211
	s_waitcnt lgkmcnt(4)
	v_mfma_f32_32x32x16_bf16 v[84:99], v[220:223], v[120:123], v[84:99]
	v_exp_f32_e32 v212, v212
	v_exp_f32_e32 v213, v213
	v_mfma_f32_32x32x16_bf16 v[100:115], v[224:227], v[120:123], v[100:115]
	v_exp_f32_e32 v214, v214
	v_exp_f32_e32 v215, v215
	s_waitcnt lgkmcnt(2)
	v_mfma_f32_32x32x16_bf16 v[84:99], v[232:235], v[124:127], v[84:99]
	v_pk_add_f32 v[150:151], v[150:151], v[212:213]
	v_pk_add_f32 v[150:151], v[150:151], v[214:215]
	v_exp_f32_e32 v216, v216
	v_mfma_f32_32x32x16_bf16 v[100:115], v[132:135], v[124:127], v[100:115]
	v_exp_f32_e32 v217, v217
	v_cvt_pk_bf16_f32 v208, v212, v213
	v_cvt_pk_bf16_f32 v209, v214, v215
	s_waitcnt lgkmcnt(0)
	v_mfma_f32_32x32x16_bf16 v[84:99], v[136:139], v[128:131], v[84:99]
	v_exp_f32_e32 v218, v218
	v_exp_f32_e32 v219, v219
	v_mfma_f32_32x32x16_bf16 v[100:115], v[140:143], v[128:131], v[100:115]
	v_pk_add_f32 v[150:151], v[150:151], v[216:217]
	v_pk_add_f32 v[150:151], v[150:151], v[218:219]
	v_cvt_pk_bf16_f32 v210, v216, v217
	v_cvt_pk_bf16_f32 v211, v218, v219
	s_add_u32 s8, s8, 0x40000
	s_addc_u32 s9, s9, 0
	s_waitcnt vmcnt(4) lgkmcnt(0)
	s_barrier
	s_sub_u32 s36, s36, 1
	s_cmp_lg_u32 s36, 0
	s_cbranch_scc1 .LatB_loop
	s_sub_u32 s10, s10, 1
	s_cbranch_scc1 .LatB_evs_x4

; __device__ __forceinline__ void attn_unit(LAS unsigned char* lds, const bf16_t* Z, bf16_t* A2, const float* tabg, int seq_base, int S, int h, int qb, float lam) {
;     ...
;         if (t + 2 < NT) ATT_STAGE(t + 2, bn);
;         const LAS unsigned char* Kt = Kb + bc * KT; const LAS unsigned char* Vt = Vb + bc * VT;
;         const int kv0 = t * 64;
;         bool near = true; float cc = 0.f;
;         if (kv0 - (qlo + 31) >= 128) { near = false; cc = tabR; } else if (qlo - (kv0 + 63) >= 128) { near = false; cc = tabL; }
;         { const float coff = cc - mu;
;           if (__any(!(coff == coff_cur))) { coff_cur = coff;
; #pragma unroll
;               for (int r = 0; r < 16; ++r) cblk[r] = coff;
;               asm volatile("" : "+v"(cblk)); } }
;         f32x16 p0, p1;
;         {
;             bf16x8 kf[8];
; #pragma unroll
;             for (int ds = 0; ds < 4; ++ds) { kf[2 * ds] = *(const LAS bf16x8*)(Kt + (kfo ^ (unsigned)(ds << 5))); kf[2 * ds + 1] = *(const LAS bf16x8*)(Kt + 32 * 256 + (kfo ^ (unsigned)(ds << 5))); }
;             __builtin_amdgcn_sched_barrier(0);
;             p0 = __builtin_amdgcn_mfma_f32_32x32x16_bf16(kf[0], qf[0], cblk, 0, 0, 0);
;             p1 = __builtin_amdgcn_mfma_f32_32x32x16_bf16(kf[1], qf[0], cblk, 0, 0, 0);
; #pragma unroll
;             for (int ds = 1; ds < 4; ++ds) {
;                 p0 = __builtin_amdgcn_mfma_f32_32x32x16_bf16(kf[2 * ds], qf[ds], p0, 0, 0, 0);
;                 p1 = __builtin_amdgcn_mfma_f32_32x32x16_bf16(kf[2 * ds + 1], qf[ds], p1, 0, 0, 0);
;             }
;     ...
; #pragma unroll
;         for (int r = 0; r < 16; ++r) { p0[r] = __builtin_amdgcn_exp2f(p0[r]); p1[r] = __builtin_amdgcn_exp2f(p1[r]); }
; #pragma unroll
;         for (int r = 0; r < 16; r += 2) { ls2 += (f32x2){p0[r], p0[r + 1]}; ls2 += (f32x2){p1[r], p1[r + 1]}; }
;         bf16x8 pa[4]; pa[0] = pack8(p0, 0); pa[1] = pack8(p0, 8); pa[2] = pack8(p1, 0); pa[3] = pack8(p1, 8);
;         LGKM0(); VREADS1(vb, 1); PV1(va, 0); LGKM0(); VREADS1(va, 2); PV1(vb, 1); LGKM0(); VREADS1(vb, 3); PV1(va, 2); LGKM0(); PV1(vb, 3);
;     ...
;         if (t + 2 < NT) asm volatile("s_waitcnt vmcnt(4) lgkmcnt(0)" ::: "memory"); else asm volatile("s_waitcnt vmcnt(0) lgkmcnt(0)" ::: "memory");
;         __builtin_amdgcn_s_barrier(); asm volatile("" ::: "memory");
;         bc = (bc == NST - 1) ? 0 : bc + 1; bn = (bn == NST - 1) ? 0 : bn + 1;
.LatB_rareret_x3:
	s_waitcnt lgkmcnt(10)
	v_mfma_f32_32x32x16_bf16 v[20:35], v[84:87], v[132:135], v[20:35]
	ds_read_b64_tr_b16 v[132:133], v231 offset:4096
	ds_read_b64_tr_b16 v[134:135], v231 offset:6144
	v_exp_f32_e32 v188, v188
	v_exp_f32_e32 v189, v189
	v_mfma_f32_32x32x16_bf16 v[36:51], v[84:87], v[136:139], v[36:51]
	ds_read_b64_tr_b16 v[136:137], v228 offset:8192
	ds_read_b64_tr_b16 v[138:139], v228 offset:10240
	v_exp_f32_e32 v190, v190
	v_exp_f32_e32 v191, v191
	s_waitcnt lgkmcnt(10)
	v_mfma_f32_32x32x16_bf16 v[52:67], v[84:87], v[140:143], v[52:67]
	ds_read_b64_tr_b16 v[140:141], v229 offset:8192
	ds_read_b64_tr_b16 v[142:143], v229 offset:10240
	v_pk_add_f32 v[150:151], v[150:151], v[188:189]
	v_pk_add_f32 v[150:151], v[150:151], v[190:191]
	v_exp_f32_e32 v192, v192
	v_mfma_f32_32x32x16_bf16 v[68:83], v[84:87], v[144:147], v[68:83]
	ds_read_b64_tr_b16 v[144:145], v230 offset:8192
	ds_read_b64_tr_b16 v[146:147], v230 offset:10240
	v_exp_f32_e32 v193, v193
	v_cvt_pk_bf16_f32 v188, v188, v189
	v_cvt_pk_bf16_f32 v189, v190, v191
	s_waitcnt lgkmcnt(10)
	v_mfma_f32_32x32x16_bf16 v[20:35], v[88:91], v[220:223], v[20:35]
	ds_read_b64_tr_b16 v[220:221], v231 offset:8192
	ds_read_b64_tr_b16 v[222:223], v231 offset:10240
	v_exp_f32_e32 v194, v194
	v_exp_f32_e32 v195, v195
	v_mfma_f32_32x32x16_bf16 v[36:51], v[88:91], v[224:227], v[36:51]
	ds_read_b64_tr_b16 v[224:225], v228 offset:12288
	ds_read_b64_tr_b16 v[226:227], v228 offset:14336
	v_pk_add_f32 v[150:151], v[150:151], v[192:193]
	v_pk_add_f32 v[150:151], v[150:151], v[194:195]
	v_cvt_pk_bf16_f32 v190, v192, v193
	v_cvt_pk_bf16_f32 v191, v194, v195
	s_waitcnt lgkmcnt(10)
	v_mfma_f32_32x32x16_bf16 v[52:67], v[88:91], v[232:235], v[52:67]
	ds_read_b64_tr_b16 v[232:233], v229 offset:12288
	ds_read_b64_tr_b16 v[234:235], v229 offset:14336
	v_exp_f32_e32 v196, v196
	v_exp_f32_e32 v197, v197
	s_add_u32 m0, s27, 0x8000
	v_mfma_f32_32x32x16_bf16 v[68:83], v[88:91], v[132:135], v[68:83]
	global_load_lds_dwordx4 v149, s[8:9]
	ds_read_b64_tr_b16 v[132:133], v230 offset:12288
	ds_read_b64_tr_b16 v[134:135], v230 offset:14336
	v_exp_f32_e32 v198, v198
	v_exp_f32_e32 v199, v199
	s_waitcnt lgkmcnt(10)
	v_mfma_f32_32x32x16_bf16 v[20:35], v[100:103], v[136:139], v[20:35]
	ds_read_b64_tr_b16 v[136:137], v231 offset:12288
	ds_read_b64_tr_b16 v[138:139], v231 offset:14336
	v_pk_add_f32 v[150:151], v[150:151], v[196:197]
	v_pk_add_f32 v[150:151], v[150:151], v[198:199]
	v_exp_f32_e32 v200, v200
	v_mfma_f32_32x32x16_bf16 v[36:51], v[100:103], v[140:143], v[36:51]
	ds_read_b128 v[140:143], v19 offset:32768
	v_exp_f32_e32 v201, v201
	v_cvt_pk_bf16_f32 v192, v196, v197
	v_cvt_pk_bf16_f32 v193, v198, v199
	s_waitcnt lgkmcnt(9)
	v_mfma_f32_32x32x16_bf16 v[52:67], v[100:103], v[144:147], v[52:67]
	ds_read_b128 v[144:147], v19 offset:40960
	v_exp_f32_e32 v202, v202
	v_exp_f32_e32 v203, v203
	v_mfma_f32_32x32x16_bf16 v[68:83], v[100:103], v[220:223], v[68:83]
	ds_read_b128 v[220:223], v180 offset:32768
	v_pk_add_f32 v[150:151], v[150:151], v[200:201]
	v_pk_add_f32 v[150:151], v[150:151], v[202:203]
	v_cvt_pk_bf16_f32 v194, v200, v201
	v_cvt_pk_bf16_f32 v195, v202, v203
	s_waitcnt lgkmcnt(7)
	v_mfma_f32_32x32x16_bf16 v[20:35], v[104:107], v[224:227], v[20:35]
	ds_read_b128 v[224:227], v180 offset:40960
	v_exp_f32_e32 v204, v204
	v_exp_f32_e32 v205, v205
	v_mfma_f32_32x32x16_bf16 v[36:51], v[104:107], v[232:235], v[36:51]
	ds_read_b128 v[232:235], v181 offset:32768
	v_exp_f32_e32 v206, v206
	v_exp_f32_e32 v207, v207
	s_waitcnt lgkmcnt(5)
	v_mfma_f32_32x32x16_bf16 v[52:67], v[104:107], v[132:135], v[52:67]
	ds_read_b128 v[132:135], v181 offset:40960
	v_pk_add_f32 v[150:151], v[150:151], v[204:205]
	v_pk_add_f32 v[150:151], v[150:151], v[206:207]
	v_exp_f32_e32 v208, v208
	s_add_u32 m0, s27, 0xa000
	v_mfma_f32_32x32x16_bf16 v[68:83], v[104:107], v[136:139], v[68:83]
	global_load_lds_dwordx4 v176, s[8:9]
	ds_read_b128 v[136:139], v182 offset:32768
	v_exp_f32_e32 v209, v209
	v_cvt_pk_bf16_f32 v204, v204, v205
	v_cvt_pk_bf16_f32 v205, v206, v207
	s_waitcnt lgkmcnt(5)
	v_mfma_f32_32x32x16_bf16 v[84:99], v[140:143], v[116:119], v[2:17]
	ds_read_b128 v[140:143], v182 offset:40960
	v_exp_f32_e32 v210, v210
	v_exp_f32_e32 v211, v211
	v_mfma_f32_32x32x16_bf16 v[100:115], v[144:147], v[116:119], v[2:17]
	v_pk_add_f32 v[150:151], v[150:151], v[208:209]
	v_pk_add_f32 v[150:151], v[150:151], v[210:211]
	v_cvt_pk_bf16_f32 v206, v208, v209
	v_cvt_pk_bf16_f32 v207, v210, v211
	s_waitcnt lgkmcnt(4)
	v_mfma_f32_32x32x16_bf16 v[84:99], v[220:223], v[120:123], v[84:99]
	v_exp_f32_e32 v212, v212
	v_exp_f32_e32 v213, v213
	v_mfma_f32_32x32x16_bf16 v[100:115], v[224:227], v[120:123], v[100:115]
	v_exp_f32_e32 v214, v214
	v_exp_f32_e32 v215, v215
	s_waitcnt lgkmcnt(2)
	v_mfma_f32_32x32x16_bf16 v[84:99], v[232:235], v[124:127], v[84:99]
	v_pk_add_f32 v[150:151], v[150:151], v[212:213]
	v_pk_add_f32 v[150:151], v[150:151], v[214:215]
	v_exp_f32_e32 v216, v216
	v_mfma_f32_32x32x16_bf16 v[100:115], v[132:135], v[124:127], v[100:115]
	v_exp_f32_e32 v217, v217
	v_cvt_pk_bf16_f32 v208, v212, v213
	v_cvt_pk_bf16_f32 v209, v214, v215
	s_waitcnt lgkmcnt(0)
	v_mfma_f32_32x32x16_bf16 v[84:99], v[136:139], v[128:131], v[84:99]
	v_exp_f32_e32 v218, v218
	v_exp_f32_e32 v219, v219
	v_mfma_f32_32x32x16_bf16 v[100:115], v[140:143], v[128:131], v[100:115]
	v_pk_add_f32 v[150:151], v[150:151], v[216:217]
	v_pk_add_f32 v[150:151], v[150:151], v[218:219]
	v_cvt_pk_bf16_f32 v210, v216, v217
	v_cvt_pk_bf16_f32 v211, v218, v219
	s_add_u32 s8, s8, 0x40000
	s_addc_u32 s9, s9, 0
	s_waitcnt vmcnt(2) lgkmcnt(0)
	s_barrier
	s_sub_u32 s10, s10, 1
	s_cbranch_scc1 .LatB_evs_x2

; __device__ __forceinline__ void attn_unit(LAS unsigned char* lds, const bf16_t* Z, bf16_t* A2, const float* tabg, int seq_base, int S, int h, int qb, float lam) {
;     ...
;         if (t + 2 < NT) ATT_STAGE(t + 2, bn);
;         const LAS unsigned char* Kt = Kb + bc * KT; const LAS unsigned char* Vt = Vb + bc * VT;
;         const int kv0 = t * 64;
;         bool near = true; float cc = 0.f;
;         if (kv0 - (qlo + 31) >= 128) { near = false; cc = tabR; } else if (qlo - (kv0 + 63) >= 128) { near = false; cc = tabL; }
;         { const float coff = cc - mu;
;           if (__any(!(coff == coff_cur))) { coff_cur = coff;
; #pragma unroll
;               for (int r = 0; r < 16; ++r) cblk[r] = coff;
;               asm volatile("" : "+v"(cblk)); } }
;         f32x16 p0, p1;
;         {
;             bf16x8 kf[8];
; #pragma unroll
;             for (int ds = 0; ds < 4; ++ds) { kf[2 * ds] = *(const LAS bf16x8*)(Kt + (kfo ^ (unsigned)(ds << 5))); kf[2 * ds + 1] = *(const LAS bf16x8*)(Kt + 32 * 256 + (kfo ^ (unsigned)(ds << 5))); }
;             __builtin_amdgcn_sched_barrier(0);
;             p0 = __builtin_amdgcn_mfma_f32_32x32x16_bf16(kf[0], qf[0], cblk, 0, 0, 0);
;             p1 = __builtin_amdgcn_mfma_f32_32x32x16_bf16(kf[1], qf[0], cblk, 0, 0, 0);
; #pragma unroll
;             for (int ds = 1; ds < 4; ++ds) {
;                 p0 = __builtin_amdgcn_mfma_f32_32x32x16_bf16(kf[2 * ds], qf[ds], p0, 0, 0, 0);
;                 p1 = __builtin_amdgcn_mfma_f32_32x32x16_bf16(kf[2 * ds + 1], qf[ds], p1, 0, 0, 0);
;             }
;     ...
; #pragma unroll
;         for (int r = 0; r < 16; ++r) { p0[r] = __builtin_amdgcn_exp2f(p0[r]); p1[r] = __builtin_amdgcn_exp2f(p1[r]); }
; #pragma unroll
;         for (int r = 0; r < 16; r += 2) { ls2 += (f32x2){p0[r], p0[r + 1]}; ls2 += (f32x2){p1[r], p1[r + 1]}; }
;         bf16x8 pa[4]; pa[0] = pack8(p0, 0); pa[1] = pack8(p0, 8); pa[2] = pack8(p1, 0); pa[3] = pack8(p1, 8);
;         LGKM0(); VREADS1(vb, 1); PV1(va, 0); LGKM0(); VREADS1(va, 2); PV1(vb, 1); LGKM0(); VREADS1(vb, 3); PV1(va, 2); LGKM0(); PV1(vb, 3);
;     ...
;         if (t + 2 < NT) asm volatile("s_waitcnt vmcnt(4) lgkmcnt(0)" ::: "memory"); else asm volatile("s_waitcnt vmcnt(0) lgkmcnt(0)" ::: "memory");
;         __builtin_amdgcn_s_barrier(); asm volatile("" ::: "memory");
;         bc = (bc == NST - 1) ? 0 : bc + 1; bn = (bn == NST - 1) ? 0 : bn + 1;
.LatB_rareret_x2:
	s_waitcnt lgkmcnt(10)
	v_mfma_f32_32x32x16_bf16 v[20:35], v[188:191], v[132:135], v[20:35]
	ds_read_b64_tr_b16 v[132:133], v231 offset:20480
	ds_read_b64_tr_b16 v[134:135], v231 offset:22528
	v_exp_f32_e32 v84, v84
	v_exp_f32_e32 v85, v85
	v_mfma_f32_32x32x16_bf16 v[36:51], v[188:191], v[136:139], v[36:51]
	ds_read_b64_tr_b16 v[136:137], v228 offset:24576
	ds_read_b64_tr_b16 v[138:139], v228 offset:26624
	v_exp_f32_e32 v86, v86
	v_exp_f32_e32 v87, v87
	s_waitcnt lgkmcnt(10)
	v_mfma_f32_32x32x16_bf16 v[52:67], v[188:191], v[140:143], v[52:67]
	ds_read_b64_tr_b16 v[140:141], v229 offset:24576
	ds_read_b64_tr_b16 v[142:143], v229 offset:26624
	v_pk_add_f32 v[150:151], v[150:151], v[84:85]
	v_pk_add_f32 v[150:151], v[150:151], v[86:87]
	v_exp_f32_e32 v88, v88
	v_mfma_f32_32x32x16_bf16 v[68:83], v[188:191], v[144:147], v[68:83]
	ds_read_b64_tr_b16 v[144:145], v230 offset:24576
	ds_read_b64_tr_b16 v[146:147], v230 offset:26624
	v_exp_f32_e32 v89, v89
	v_cvt_pk_bf16_f32 v84, v84, v85
	v_cvt_pk_bf16_f32 v85, v86, v87
	s_waitcnt lgkmcnt(10)
	v_mfma_f32_32x32x16_bf16 v[20:35], v[192:195], v[220:223], v[20:35]
	ds_read_b64_tr_b16 v[220:221], v231 offset:24576
	ds_read_b64_tr_b16 v[222:223], v231 offset:26624
	v_exp_f32_e32 v90, v90
	v_exp_f32_e32 v91, v91
	v_mfma_f32_32x32x16_bf16 v[36:51], v[192:195], v[224:227], v[36:51]
	ds_read_b64_tr_b16 v[224:225], v228 offset:28672
	ds_read_b64_tr_b16 v[226:227], v228 offset:30720
	v_pk_add_f32 v[150:151], v[150:151], v[88:89]
	v_pk_add_f32 v[150:151], v[150:151], v[90:91]
	v_cvt_pk_bf16_f32 v86, v88, v89
	v_cvt_pk_bf16_f32 v87, v90, v91
	s_waitcnt lgkmcnt(10)
	v_mfma_f32_32x32x16_bf16 v[52:67], v[192:195], v[232:235], v[52:67]
	ds_read_b64_tr_b16 v[232:233], v229 offset:28672
	ds_read_b64_tr_b16 v[234:235], v229 offset:30720
	v_exp_f32_e32 v92, v92
	v_exp_f32_e32 v93, v93
	s_mov_b32 m0, s27
	v_mfma_f32_32x32x16_bf16 v[68:83], v[192:195], v[132:135], v[68:83]
	global_load_lds_dwordx4 v149, s[8:9]
	ds_read_b64_tr_b16 v[132:133], v230 offset:28672
	ds_read_b64_tr_b16 v[134:135], v230 offset:30720
	v_exp_f32_e32 v94, v94
	v_exp_f32_e32 v95, v95
	s_waitcnt lgkmcnt(10)
	v_mfma_f32_32x32x16_bf16 v[20:35], v[204:207], v[136:139], v[20:35]
	ds_read_b64_tr_b16 v[136:137], v231 offset:28672
	ds_read_b64_tr_b16 v[138:139], v231 offset:30720
	v_pk_add_f32 v[150:151], v[150:151], v[92:93]
	v_pk_add_f32 v[150:151], v[150:151], v[94:95]
	v_exp_f32_e32 v96, v96
	v_mfma_f32_32x32x16_bf16 v[36:51], v[204:207], v[140:143], v[36:51]
	ds_read_b128 v[140:143], v19
	v_exp_f32_e32 v97, v97
	v_cvt_pk_bf16_f32 v88, v92, v93
	v_cvt_pk_bf16_f32 v89, v94, v95
	s_waitcnt lgkmcnt(9)
	v_mfma_f32_32x32x16_bf16 v[52:67], v[204:207], v[144:147], v[52:67]
	ds_read_b128 v[144:147], v19 offset:8192
	v_exp_f32_e32 v98, v98
	v_exp_f32_e32 v99, v99
	v_mfma_f32_32x32x16_bf16 v[68:83], v[204:207], v[220:223], v[68:83]
	ds_read_b128 v[220:223], v180
	v_pk_add_f32 v[150:151], v[150:151], v[96:97]
	v_pk_add_f32 v[150:151], v[150:151], v[98:99]
	v_cvt_pk_bf16_f32 v90, v96, v97
	v_cvt_pk_bf16_f32 v91, v98, v99
	s_waitcnt lgkmcnt(7)
	v_mfma_f32_32x32x16_bf16 v[20:35], v[208:211], v[224:227], v[20:35]
	ds_read_b128 v[224:227], v180 offset:8192
	v_exp_f32_e32 v100, v100
	v_exp_f32_e32 v101, v101
	v_mfma_f32_32x32x16_bf16 v[36:51], v[208:211], v[232:235], v[36:51]
	ds_read_b128 v[232:235], v181
	v_exp_f32_e32 v102, v102
	v_exp_f32_e32 v103, v103
	s_waitcnt lgkmcnt(5)
	v_mfma_f32_32x32x16_bf16 v[52:67], v[208:211], v[132:135], v[52:67]
	ds_read_b128 v[132:135], v181 offset:8192
	v_pk_add_f32 v[150:151], v[150:151], v[100:101]
	v_pk_add_f32 v[150:151], v[150:151], v[102:103]
	v_exp_f32_e32 v104, v104
	s_add_u32 m0, s27, 0x2000
	v_mfma_f32_32x32x16_bf16 v[68:83], v[208:211], v[136:139], v[68:83]
	global_load_lds_dwordx4 v176, s[8:9]
	ds_read_b128 v[136:139], v182
	v_exp_f32_e32 v105, v105
	v_cvt_pk_bf16_f32 v100, v100, v101
	v_cvt_pk_bf16_f32 v101, v102, v103
	s_waitcnt lgkmcnt(5)
	v_mfma_f32_32x32x16_bf16 v[188:203], v[140:143], v[116:119], v[2:17]
	ds_read_b128 v[140:143], v182 offset:8192
	v_exp_f32_e32 v106, v106
	v_exp_f32_e32 v107, v107
	v_mfma_f32_32x32x16_bf16 v[204:219], v[144:147], v[116:119], v[2:17]
	v_pk_add_f32 v[150:151], v[150:151], v[104:105]
	v_pk_add_f32 v[150:151], v[150:151], v[106:107]
	v_cvt_pk_bf16_f32 v102, v104, v105
	v_cvt_pk_bf16_f32 v103, v106, v107
	s_waitcnt lgkmcnt(4)
	v_mfma_f32_32x32x16_bf16 v[188:203], v[220:223], v[120:123], v[188:203]
	v_exp_f32_e32 v108, v108
	v_exp_f32_e32 v109, v109
	v_mfma_f32_32x32x16_bf16 v[204:219], v[224:227], v[120:123], v[204:219]
	v_exp_f32_e32 v110, v110
	v_exp_f32_e32 v111, v111
	s_waitcnt lgkmcnt(2)
	v_mfma_f32_32x32x16_bf16 v[188:203], v[232:235], v[124:127], v[188:203]
	v_pk_add_f32 v[150:151], v[150:151], v[108:109]
	v_pk_add_f32 v[150:151], v[150:151], v[110:111]
	v_exp_f32_e32 v112, v112
	v_mfma_f32_32x32x16_bf16 v[204:219], v[132:135], v[124:127], v[204:219]
	v_exp_f32_e32 v113, v113
	v_cvt_pk_bf16_f32 v104, v108, v109
	v_cvt_pk_bf16_f32 v105, v110, v111
	s_waitcnt lgkmcnt(0)
	v_mfma_f32_32x32x16_bf16 v[188:203], v[136:139], v[128:131], v[188:203]
	v_exp_f32_e32 v114, v114
	v_exp_f32_e32 v115, v115
	v_mfma_f32_32x32x16_bf16 v[204:219], v[140:143], v[128:131], v[204:219]
	v_pk_add_f32 v[150:151], v[150:151], v[112:113]
	v_pk_add_f32 v[150:151], v[150:151], v[114:115]
	v_cvt_pk_bf16_f32 v106, v112, v113
	v_cvt_pk_bf16_f32 v107, v114, v115
	s_add_u32 s8, s8, 0x40000
	s_addc_u32 s9, s9, 0
	s_waitcnt vmcnt(2) lgkmcnt(0)
	s_barrier
	s_sub_u32 s10, s10, 1
	s_cbranch_scc1 .LatB_evs_x1

; #define VREADS1(arr, d_) do { const unsigned ad_ = vbase ^ (unsigned)((d_) << 6); __builtin_amdgcn_sched_barrier(0); \
;         _Pragma("unroll") for (int ks_ = 0; ks_ < 4; ++ks_) { VTR(arr[ks_ * 2], ad_, ks_ * 4096); VTR(arr[ks_ * 2 + 1], ad_, ks_ * 4096 + 2048); } __builtin_amdgcn_sched_barrier(0); } while (0)
; #define PV1(arr, d_) do { _Pragma("unroll") for (int ks_ = 0; ks_ < 4; ++ks_) { const s16x4 lo_ = arr[ks_ * 2], hh_ = arr[ks_ * 2 + 1]; \
;         const bf16x8 bv_ = (bf16x8){lo_[0], lo_[1], lo_[2], lo_[3], hh_[0], hh_[1], hh_[2], hh_[3]}; \
;         O[d_] = __builtin_amdgcn_mfma_f32_32x32x16_bf16(pa[ks_], bv_, O[d_], 0, 0, 0); } __builtin_amdgcn_sched_barrier(0); } while (0)
; #define LGKM0() do { __builtin_amdgcn_sched_barrier(0); asm volatile("s_waitcnt lgkmcnt(0)" ::: "memory"); __builtin_amdgcn_sched_barrier(0); } while (0)
; __device__ __forceinline__ void attn_unit(LAS unsigned char* lds, const bf16_t* Z, bf16_t* A2, const float* tabg, int seq_base, int S, int h, int qb, float lam) {
;     ...
; #pragma unroll
;         for (int r = 0; r < 16; ++r) { p0[r] = __builtin_amdgcn_exp2f(p0[r]); p1[r] = __builtin_amdgcn_exp2f(p1[r]); }
; #pragma unroll
;         for (int r = 0; r < 16; r += 2) { ls2 += (f32x2){p0[r], p0[r + 1]}; ls2 += (f32x2){p1[r], p1[r + 1]}; }
;         bf16x8 pa[4]; pa[0] = pack8(p0, 0); pa[1] = pack8(p0, 8); pa[2] = pack8(p1, 0); pa[3] = pack8(p1, 8);
;         LGKM0(); VREADS1(vb, 1); PV1(va, 0); LGKM0(); VREADS1(va, 2); PV1(vb, 1); LGKM0(); VREADS1(vb, 3); PV1(va, 2); LGKM0(); PV1(vb, 3);
;     ...
;         if (t + 2 < NT) asm volatile("s_waitcnt vmcnt(4) lgkmcnt(0)" ::: "memory"); else asm volatile("s_waitcnt vmcnt(0) lgkmcnt(0)" ::: "memory");
;         __builtin_amdgcn_s_barrier(); asm volatile("" ::: "memory");
;         bc = (bc == NST - 1) ? 0 : bc + 1; bn = (bn == NST - 1) ? 0 : bn + 1;
.LatB_rareret_x1:
	s_waitcnt lgkmcnt(10)
	v_mfma_f32_32x32x16_bf16 v[20:35], v[84:87], v[132:135], v[20:35]
	ds_read_b64_tr_b16 v[132:133], v231 offset:36864
	ds_read_b64_tr_b16 v[134:135], v231 offset:38912
	v_exp_f32_e32 v188, v188
	v_exp_f32_e32 v189, v189
	v_exp_f32_e32 v190, v190
	v_mfma_f32_32x32x16_bf16 v[36:51], v[84:87], v[136:139], v[36:51]
	ds_read_b64_tr_b16 v[136:137], v228 offset:40960
	ds_read_b64_tr_b16 v[138:139], v228 offset:43008
	v_exp_f32_e32 v191, v191
	v_pk_add_f32 v[150:151], v[150:151], v[188:189]
	v_pk_add_f32 v[150:151], v[150:151], v[190:191]
	v_exp_f32_e32 v192, v192
	s_waitcnt lgkmcnt(10)
	v_mfma_f32_32x32x16_bf16 v[52:67], v[84:87], v[140:143], v[52:67]
	ds_read_b64_tr_b16 v[140:141], v229 offset:40960
	ds_read_b64_tr_b16 v[142:143], v229 offset:43008
	v_exp_f32_e32 v193, v193
	v_cvt_pk_bf16_f32 v188, v188, v189
	v_cvt_pk_bf16_f32 v189, v190, v191
	v_exp_f32_e32 v194, v194
	v_mfma_f32_32x32x16_bf16 v[68:83], v[84:87], v[144:147], v[68:83]
	ds_read_b64_tr_b16 v[144:145], v230 offset:40960
	ds_read_b64_tr_b16 v[146:147], v230 offset:43008
	v_exp_f32_e32 v195, v195
	v_pk_add_f32 v[150:151], v[150:151], v[192:193]
	v_pk_add_f32 v[150:151], v[150:151], v[194:195]
	v_cvt_pk_bf16_f32 v190, v192, v193
	v_cvt_pk_bf16_f32 v191, v194, v195
	s_waitcnt lgkmcnt(10)
	v_mfma_f32_32x32x16_bf16 v[20:35], v[88:91], v[220:223], v[20:35]
	ds_read_b64_tr_b16 v[220:221], v231 offset:40960
	ds_read_b64_tr_b16 v[222:223], v231 offset:43008
	v_exp_f32_e32 v196, v196
	v_exp_f32_e32 v197, v197
	v_exp_f32_e32 v198, v198
	v_mfma_f32_32x32x16_bf16 v[36:51], v[88:91], v[224:227], v[36:51]
	ds_read_b64_tr_b16 v[224:225], v228 offset:45056
	ds_read_b64_tr_b16 v[226:227], v228 offset:47104
	v_exp_f32_e32 v199, v199
	v_pk_add_f32 v[150:151], v[150:151], v[196:197]
	v_pk_add_f32 v[150:151], v[150:151], v[198:199]
	v_exp_f32_e32 v200, v200
	s_waitcnt lgkmcnt(10)
	v_mfma_f32_32x32x16_bf16 v[52:67], v[88:91], v[232:235], v[52:67]
	ds_read_b64_tr_b16 v[232:233], v229 offset:45056
	ds_read_b64_tr_b16 v[234:235], v229 offset:47104
	v_exp_f32_e32 v201, v201
	v_cvt_pk_bf16_f32 v192, v196, v197
	v_cvt_pk_bf16_f32 v193, v198, v199
	v_exp_f32_e32 v202, v202
	v_mfma_f32_32x32x16_bf16 v[68:83], v[88:91], v[132:135], v[68:83]
	ds_read_b64_tr_b16 v[132:133], v230 offset:45056
	ds_read_b64_tr_b16 v[134:135], v230 offset:47104
	v_exp_f32_e32 v203, v203
	v_pk_add_f32 v[150:151], v[150:151], v[200:201]
	v_pk_add_f32 v[150:151], v[150:151], v[202:203]
	v_cvt_pk_bf16_f32 v194, v200, v201
	v_cvt_pk_bf16_f32 v195, v202, v203
	s_waitcnt lgkmcnt(10)
	v_mfma_f32_32x32x16_bf16 v[20:35], v[100:103], v[136:139], v[20:35]
	ds_read_b64_tr_b16 v[136:137], v231 offset:45056
	ds_read_b64_tr_b16 v[138:139], v231 offset:47104
	v_exp_f32_e32 v204, v204
	v_exp_f32_e32 v205, v205
	v_exp_f32_e32 v206, v206
	v_mfma_f32_32x32x16_bf16 v[36:51], v[100:103], v[140:143], v[36:51]
	v_exp_f32_e32 v207, v207
	v_pk_add_f32 v[150:151], v[150:151], v[204:205]
	v_pk_add_f32 v[150:151], v[150:151], v[206:207]
	v_exp_f32_e32 v208, v208
	s_waitcnt lgkmcnt(8)
	v_mfma_f32_32x32x16_bf16 v[52:67], v[100:103], v[144:147], v[52:67]
	v_exp_f32_e32 v209, v209
	v_cvt_pk_bf16_f32 v204, v204, v205
	v_cvt_pk_bf16_f32 v205, v206, v207
	v_exp_f32_e32 v210, v210
	v_mfma_f32_32x32x16_bf16 v[68:83], v[100:103], v[220:223], v[68:83]
	v_exp_f32_e32 v211, v211
	v_pk_add_f32 v[150:151], v[150:151], v[208:209]
	v_pk_add_f32 v[150:151], v[150:151], v[210:211]
	v_cvt_pk_bf16_f32 v206, v208, v209
	v_cvt_pk_bf16_f32 v207, v210, v211
	s_waitcnt lgkmcnt(4)
	v_mfma_f32_32x32x16_bf16 v[20:35], v[104:107], v[224:227], v[20:35]
	v_exp_f32_e32 v212, v212
	v_exp_f32_e32 v213, v213
	v_exp_f32_e32 v214, v214
	v_mfma_f32_32x32x16_bf16 v[36:51], v[104:107], v[232:235], v[36:51]
	v_exp_f32_e32 v215, v215
	v_pk_add_f32 v[150:151], v[150:151], v[212:213]
	v_pk_add_f32 v[150:151], v[150:151], v[214:215]
	v_exp_f32_e32 v216, v216
	s_waitcnt lgkmcnt(0)
	v_mfma_f32_32x32x16_bf16 v[52:67], v[104:107], v[132:135], v[52:67]
	v_exp_f32_e32 v217, v217
	v_cvt_pk_bf16_f32 v208, v212, v213
	v_cvt_pk_bf16_f32 v209, v214, v215
	v_exp_f32_e32 v218, v218
	v_mfma_f32_32x32x16_bf16 v[68:83], v[104:107], v[136:139], v[68:83]
	v_exp_f32_e32 v219, v219
	v_pk_add_f32 v[150:151], v[150:151], v[216:217]
	v_pk_add_f32 v[150:151], v[150:151], v[218:219]
	v_cvt_pk_bf16_f32 v210, v216, v217
	v_cvt_pk_bf16_f32 v211, v218, v219
	s_add_u32 s8, s8, 0x40000
	s_addc_u32 s9, s9, 0
	s_waitcnt vmcnt(0) lgkmcnt(0)
	s_barrier
; #define VREADS1(arr, d_) do { const unsigned ad_ = vbase ^ (unsigned)((d_) << 6); __builtin_amdgcn_sched_barrier(0); \
;         _Pragma("unroll") for (int ks_ = 0; ks_ < 4; ++ks_) { VTR(arr[ks_ * 2], ad_, ks_ * 4096); VTR(arr[ks_ * 2 + 1], ad_, ks_ * 4096 + 2048); } __builtin_amdgcn_sched_barrier(0); } while (0)
; #define PV1(arr, d_) do { _Pragma("unroll") for (int ks_ = 0; ks_ < 4; ++ks_) { const s16x4 lo_ = arr[ks_ * 2], hh_ = arr[ks_ * 2 + 1]; \
;         const bf16x8 bv_ = (bf16x8){lo_[0], lo_[1], lo_[2], lo_[3], hh_[0], hh_[1], hh_[2], hh_[3]}; \
;         O[d_] = __builtin_amdgcn_mfma_f32_32x32x16_bf16(pa[ks_], bv_, O[d_], 0, 0, 0); } __builtin_amdgcn_sched_barrier(0); } while (0)
; #define LGKM0() do { __builtin_amdgcn_sched_barrier(0); asm volatile("s_waitcnt lgkmcnt(0)" ::: "memory"); __builtin_amdgcn_sched_barrier(0); } while (0)
; __device__ __forceinline__ void attn_unit(LAS unsigned char* lds, const bf16_t* Z, bf16_t* A2, const float* tabg, int seq_base, int S, int h, int qb, float lam) {
;     ...
;         LGKM0(); VREADS1(vb, 1); PV1(va, 0); LGKM0(); VREADS1(va, 2); PV1(vb, 1); LGKM0(); VREADS1(vb, 3); PV1(va, 2); LGKM0(); PV1(vb, 3);
;     ...
;         if (t + 2 < NT) asm volatile("s_waitcnt vmcnt(4) lgkmcnt(0)" ::: "memory"); else asm volatile("s_waitcnt vmcnt(0) lgkmcnt(0)" ::: "memory");
;         __builtin_amdgcn_s_barrier(); asm volatile("" ::: "memory");
	ds_read_b64_tr_b16 v[132:133], v228 offset:0
	ds_read_b64_tr_b16 v[134:135], v228 offset:2048
	ds_read_b64_tr_b16 v[136:137], v229 offset:0
	ds_read_b64_tr_b16 v[138:139], v229 offset:2048
	ds_read_b64_tr_b16 v[140:141], v230 offset:0
	ds_read_b64_tr_b16 v[142:143], v230 offset:2048
	ds_read_b64_tr_b16 v[144:145], v231 offset:0
	ds_read_b64_tr_b16 v[146:147], v231 offset:2048
	ds_read_b64_tr_b16 v[220:221], v228 offset:4096
	ds_read_b64_tr_b16 v[222:223], v228 offset:6144
	ds_read_b64_tr_b16 v[224:225], v229 offset:4096
	ds_read_b64_tr_b16 v[226:227], v229 offset:6144
	ds_read_b64_tr_b16 v[232:233], v230 offset:4096
	ds_read_b64_tr_b16 v[234:235], v230 offset:6144
	s_waitcnt lgkmcnt(10)
	v_mfma_f32_32x32x16_bf16 v[20:35], v[188:191], v[132:135], v[20:35]
	ds_read_b64_tr_b16 v[132:133], v231 offset:4096
	ds_read_b64_tr_b16 v[134:135], v231 offset:6144
	v_mfma_f32_32x32x16_bf16 v[36:51], v[188:191], v[136:139], v[36:51]
	ds_read_b64_tr_b16 v[136:137], v228 offset:8192
	ds_read_b64_tr_b16 v[138:139], v228 offset:10240
	s_waitcnt lgkmcnt(10)
	v_mfma_f32_32x32x16_bf16 v[52:67], v[188:191], v[140:143], v[52:67]
	ds_read_b64_tr_b16 v[140:141], v229 offset:8192
	ds_read_b64_tr_b16 v[142:143], v229 offset:10240
	v_mfma_f32_32x32x16_bf16 v[68:83], v[188:191], v[144:147], v[68:83]
	ds_read_b64_tr_b16 v[144:145], v230 offset:8192
	ds_read_b64_tr_b16 v[146:147], v230 offset:10240
	s_waitcnt lgkmcnt(10)
	v_mfma_f32_32x32x16_bf16 v[20:35], v[192:195], v[220:223], v[20:35]
	ds_read_b64_tr_b16 v[220:221], v231 offset:8192
	ds_read_b64_tr_b16 v[222:223], v231 offset:10240
	v_mfma_f32_32x32x16_bf16 v[36:51], v[192:195], v[224:227], v[36:51]
	ds_read_b64_tr_b16 v[224:225], v228 offset:12288
	ds_read_b64_tr_b16 v[226:227], v228 offset:14336
	s_waitcnt lgkmcnt(10)
	v_mfma_f32_32x32x16_bf16 v[52:67], v[192:195], v[232:235], v[52:67]
	ds_read_b64_tr_b16 v[232:233], v229 offset:12288
	ds_read_b64_tr_b16 v[234:235], v229 offset:14336
	v_mfma_f32_32x32x16_bf16 v[68:83], v[192:195], v[132:135], v[68:83]
	ds_read_b64_tr_b16 v[132:133], v230 offset:12288
	ds_read_b64_tr_b16 v[134:135], v230 offset:14336
	s_waitcnt lgkmcnt(10)
	v_mfma_f32_32x32x16_bf16 v[20:35], v[204:207], v[136:139], v[20:35]
	ds_read_b64_tr_b16 v[136:137], v231 offset:12288
	ds_read_b64_tr_b16 v[138:139], v231 offset:14336
	v_mfma_f32_32x32x16_bf16 v[36:51], v[204:207], v[140:143], v[36:51]
	s_waitcnt lgkmcnt(8)
	v_mfma_f32_32x32x16_bf16 v[52:67], v[204:207], v[144:147], v[52:67]
	v_mfma_f32_32x32x16_bf16 v[68:83], v[204:207], v[220:223], v[68:83]
	s_waitcnt lgkmcnt(4)
	v_mfma_f32_32x32x16_bf16 v[20:35], v[208:211], v[224:227], v[20:35]
	v_mfma_f32_32x32x16_bf16 v[36:51], v[208:211], v[232:235], v[36:51]
	s_waitcnt lgkmcnt(0)
	v_mfma_f32_32x32x16_bf16 v[52:67], v[208:211], v[132:135], v[52:67]
	v_mfma_f32_32x32x16_bf16 v[68:83], v[208:211], v[136:139], v[68:83]
	s_waitcnt lgkmcnt(0)
	s_barrier
	s_mov_b32 m0, s32
	s_nop 15
	s_branch .LatB_done
.LatB_rs_h0:
	s_mov_b32 s22, 0
	s_branch .LatB_rare_001

; __device__ __forceinline__ void attn_unit(LAS unsigned char* lds, const bf16_t* Z, bf16_t* A2, const float* tabg, int seq_base, int S, int h, int qb, float lam) {
;     ...
;         bool near = true; float cc = 0.f;
;         if (kv0 - (qlo + 31) >= 128) { near = false; cc = tabR; } else if (qlo - (kv0 + 63) >= 128) { near = false; cc = tabL; }
;         { const float coff = cc - mu;
;           if (__any(!(coff == coff_cur))) { coff_cur = coff;
; #pragma unroll
;               for (int r = 0; r < 16; ++r) cblk[r] = coff;
;               asm volatile("" : "+v"(cblk)); } }
.LatB_evs_h3:
	s_mov_b32 s22, 1
	s_branch .LatB_ev_11

; __device__ __forceinline__ void attn_unit(LAS unsigned char* lds, const bf16_t* Z, bf16_t* A2, const float* tabg, int seq_base, int S, int h, int qb, float lam) {
;     ...
;         bool near = true; float cc = 0.f;
;         if (kv0 - (qlo + 31) >= 128) { near = false; cc = tabR; } else if (qlo - (kv0 + 63) >= 128) { near = false; cc = tabL; }
;         { const float coff = cc - mu;
;           if (__any(!(coff == coff_cur))) { coff_cur = coff;
; #pragma unroll
;               for (int r = 0; r < 16; ++r) cblk[r] = coff;
;               asm volatile("" : "+v"(cblk)); } }
.LatB_evs_h5:
	s_mov_b32 s22, 2
	s_branch .LatB_ev_11

; __device__ __forceinline__ void attn_unit(LAS unsigned char* lds, const bf16_t* Z, bf16_t* A2, const float* tabg, int seq_base, int S, int h, int qb, float lam) {
;     ...
;         bool near = true; float cc = 0.f;
;         if (kv0 - (qlo + 31) >= 128) { near = false; cc = tabR; } else if (qlo - (kv0 + 63) >= 128) { near = false; cc = tabL; }
;         { const float coff = cc - mu;
;           if (__any(!(coff == coff_cur))) { coff_cur = coff;
; #pragma unroll
;               for (int r = 0; r < 16; ++r) cblk[r] = coff;
;               asm volatile("" : "+v"(cblk)); } }
.LatB_evs_m1:
	s_mov_b32 s22, 3
	s_branch .LatB_ev_11

; __device__ __forceinline__ void attn_unit(LAS unsigned char* lds, const bf16_t* Z, bf16_t* A2, const float* tabg, int seq_base, int S, int h, int qb, float lam) {
;     ...
;         bool near = true; float cc = 0.f;
;         if (kv0 - (qlo + 31) >= 128) { near = false; cc = tabR; } else if (qlo - (kv0 + 63) >= 128) { near = false; cc = tabL; }
;         { const float coff = cc - mu;
;           if (__any(!(coff == coff_cur))) { coff_cur = coff;
; #pragma unroll
;               for (int r = 0; r < 16; ++r) cblk[r] = coff;
;               asm volatile("" : "+v"(cblk)); } }
.LatB_evs_m3:
	s_mov_b32 s22, 4
	s_branch .LatB_ev_11

; __device__ __forceinline__ void attn_unit(LAS unsigned char* lds, const bf16_t* Z, bf16_t* A2, const float* tabg, int seq_base, int S, int h, int qb, float lam) {
;     ...
;         bool near = true; float cc = 0.f;
;         if (kv0 - (qlo + 31) >= 128) { near = false; cc = tabR; } else if (qlo - (kv0 + 63) >= 128) { near = false; cc = tabL; }
;         { const float coff = cc - mu;
;           if (__any(!(coff == coff_cur))) { coff_cur = coff;
; #pragma unroll
;               for (int r = 0; r < 16; ++r) cblk[r] = coff;
;               asm volatile("" : "+v"(cblk)); } }
.LatB_evs_m5:
	s_mov_b32 s22, 5
	s_branch .LatB_ev_11

; __device__ __forceinline__ void attn_unit(LAS unsigned char* lds, const bf16_t* Z, bf16_t* A2, const float* tabg, int seq_base, int S, int h, int qb, float lam) {
;     ...
;         bool near = true; float cc = 0.f;
;         if (kv0 - (qlo + 31) >= 128) { near = false; cc = tabR; } else if (qlo - (kv0 + 63) >= 128) { near = false; cc = tabL; }
;         { const float coff = cc - mu;
;           if (__any(!(coff == coff_cur))) { coff_cur = coff;
; #pragma unroll
;               for (int r = 0; r < 16; ++r) cblk[r] = coff;
;               asm volatile("" : "+v"(cblk)); } }
.LatB_evs_x3:
	s_mov_b32 s22, 6
	s_branch .LatB_ev_11

; #define LAS __attribute__((address_space(3)))
; #define VREADS1(arr, d_) do { const unsigned ad_ = vbase ^ (unsigned)((d_) << 6); __builtin_amdgcn_sched_barrier(0); \
;         _Pragma("unroll") for (int ks_ = 0; ks_ < 4; ++ks_) { VTR(arr[ks_ * 2], ad_, ks_ * 4096); VTR(arr[ks_ * 2 + 1], ad_, ks_ * 4096 + 2048); } __builtin_amdgcn_sched_barrier(0); } while (0)
; __device__ __forceinline__ void attn_unit(LAS unsigned char* lds, const bf16_t* Z, bf16_t* A2, const float* tabg, int seq_base, int S, int h, int qb, float lam) {
;     ...
;         bool near = true; float cc = 0.f;
;         if (kv0 - (qlo + 31) >= 128) { near = false; cc = tabR; } else if (qlo - (kv0 + 63) >= 128) { near = false; cc = tabL; }
;         { const float coff = cc - mu;
;           if (__any(!(coff == coff_cur))) { coff_cur = coff;
; #pragma unroll
;               for (int r = 0; r < 16; ++r) cblk[r] = coff;
;               asm volatile("" : "+v"(cblk)); } }
;         f32x16 p0, p1;
;         {
;             bf16x8 kf[8];
; #pragma unroll
;             for (int ds = 0; ds < 4; ++ds) { kf[2 * ds] = *(const LAS bf16x8*)(Kt + (kfo ^ (unsigned)(ds << 5))); kf[2 * ds + 1] = *(const LAS bf16x8*)(Kt + 32 * 256 + (kfo ^ (unsigned)(ds << 5))); }
;             __builtin_amdgcn_sched_barrier(0);
;             p0 = __builtin_amdgcn_mfma_f32_32x32x16_bf16(kf[0], qf[0], cblk, 0, 0, 0);
;             p1 = __builtin_amdgcn_mfma_f32_32x32x16_bf16(kf[1], qf[0], cblk, 0, 0, 0);
; #pragma unroll
;             for (int ds = 1; ds < 4; ++ds) {
;                 p0 = __builtin_amdgcn_mfma_f32_32x32x16_bf16(kf[2 * ds], qf[ds], p0, 0, 0, 0);
;                 p1 = __builtin_amdgcn_mfma_f32_32x32x16_bf16(kf[2 * ds + 1], qf[ds], p1, 0, 0, 0);
;             }
;         }
;     ...
;         const unsigned vbase = (unsigned)(size_t)Vt + vfo;
;         s16x4 va[8], vb[8];
;         VREADS1(va, 0);
;         if (near) {
;             const LAS float* tp = tab + (kv0 + 4 * hi - (qlo + r32) + 224);
; #pragma unroll
;             for (int r = 0; r < 16; ++r) { p0[r] += tp[(r & 3) + 8 * (r >> 2)]; p1[r] += tp[32 + (r & 3) + 8 * (r >> 2)]; }
;         }
.LatB_ev_11:
	s_sub_u32 s5, s8, s4
	s_lshr_b32 s5, s5, 12
	s_sub_u32 s5, s5, 64
	s_cmp_ge_u32 s5, s11
	s_cselect_b32 s24, 1, 0
	s_cmp_le_u32 s5, s31
	s_cselect_b32 s29, 1, 0
	s_and_b32 s24, s24, s29
	s_add_u32 s29, s5, 64
	s_cmp_le_u32 s29, s31
	s_cselect_b32 s10, 0, 0x7fffffff
	s_cmp_eq_u32 s24, 0
	s_cbranch_scc1 .LatB_evnn_11
	s_lshl_b32 s29, s5, 2
	s_add_i32 s29, s29, 0x18b80
	v_add_u32_e32 v187, s29, v162
	ds_read2_b32 v[132:133], v187 offset0:0 offset1:1
	ds_read2_b32 v[134:135], v187 offset0:2 offset1:3
	ds_read2_b32 v[136:137], v187 offset0:8 offset1:9
	ds_read2_b32 v[138:139], v187 offset0:10 offset1:11
	s_waitcnt lgkmcnt(0)
	v_pk_add_f32 v[188:189], v[188:189], v[132:133]
	v_pk_add_f32 v[190:191], v[190:191], v[134:135]
	v_pk_add_f32 v[192:193], v[192:193], v[136:137]
	v_pk_add_f32 v[194:195], v[194:195], v[138:139]
	ds_read2_b32 v[132:133], v187 offset0:16 offset1:17
	ds_read2_b32 v[134:135], v187 offset0:18 offset1:19
	ds_read2_b32 v[136:137], v187 offset0:24 offset1:25
	ds_read2_b32 v[138:139], v187 offset0:26 offset1:27
	s_waitcnt lgkmcnt(0)
	v_pk_add_f32 v[196:197], v[196:197], v[132:133]
	v_pk_add_f32 v[198:199], v[198:199], v[134:135]
	v_pk_add_f32 v[200:201], v[200:201], v[136:137]
	v_pk_add_f32 v[202:203], v[202:203], v[138:139]
	ds_read2_b32 v[132:133], v187 offset0:32 offset1:33
	ds_read2_b32 v[134:135], v187 offset0:34 offset1:35
	ds_read2_b32 v[136:137], v187 offset0:40 offset1:41
	ds_read2_b32 v[138:139], v187 offset0:42 offset1:43
	s_waitcnt lgkmcnt(0)
	v_pk_add_f32 v[204:205], v[204:205], v[132:133]
	v_pk_add_f32 v[206:207], v[206:207], v[134:135]
	v_pk_add_f32 v[208:209], v[208:209], v[136:137]
	v_pk_add_f32 v[210:211], v[210:211], v[138:139]
	ds_read2_b32 v[132:133], v187 offset0:48 offset1:49
	ds_read2_b32 v[134:135], v187 offset0:50 offset1:51
	ds_read2_b32 v[136:137], v187 offset0:56 offset1:57
	ds_read2_b32 v[138:139], v187 offset0:58 offset1:59
	s_waitcnt lgkmcnt(0)
	v_pk_add_f32 v[212:213], v[212:213], v[132:133]
	v_pk_add_f32 v[214:215], v[214:215], v[134:135]
	v_pk_add_f32 v[216:217], v[216:217], v[136:137]
	v_pk_add_f32 v[218:219], v[218:219], v[138:139]
.LatB_evnn_11:
	s_add_u32 s29, s5, 64
	s_cmp_lt_u32 s29, s11
	s_cselect_b32 s24, 1, 0
	s_cmp_gt_u32 s29, s31
	s_cselect_b32 s30, 2, 0
	s_or_b32 s24, s24, s30
	s_cmp_eq_u32 s24, s35
	s_cbranch_scc1 .LatB_evdisp_11
	s_mov_b32 s35, s24
	v_mov_b32_e32 v251, 0
	s_cmp_eq_u32 s24, 1
	s_cselect_b64 vcc, -1, 0
	v_cndmask_b32_e32 v251, v251, v177, vcc
	s_cmp_eq_u32 s24, 2
	s_cselect_b64 vcc, -1, 0
	v_cndmask_b32_e32 v251, v251, v178, vcc
	v_sub_f32_e32 v2, v251, v186
	v_mov_b32_e32 v3, v2
	v_mov_b64_e32 v[4:5], v[2:3]
	v_mov_b64_e32 v[6:7], v[2:3]
	v_mov_b64_e32 v[8:9], v[2:3]
	v_mov_b64_e32 v[10:11], v[2:3]
	v_mov_b64_e32 v[12:13], v[2:3]
	v_mov_b64_e32 v[14:15], v[2:3]
	v_mov_b64_e32 v[16:17], v[2:3]
.LatB_evdisp_11:
	s_cmp_eq_u32 s22, 0
	s_cbranch_scc1 .LatB_evret_h1
	s_cmp_eq_u32 s22, 1
	s_cbranch_scc1 .LatB_evret_h3
	s_cmp_eq_u32 s22, 2
	s_cbranch_scc1 .LatB_evret_h5
	s_cmp_eq_u32 s22, 3
	s_cbranch_scc1 .LatB_evret_m1
	s_cmp_eq_u32 s22, 4
	s_cbranch_scc1 .LatB_evret_m3
	s_cmp_eq_u32 s22, 5
	s_cbranch_scc1 .LatB_evret_m5
	s_branch .LatB_evret_x3
.LatB_ev_01:
	s_sub_u32 s5, s8, s4
	s_lshr_b32 s5, s5, 12
	s_sub_u32 s5, s5, 64
	s_cmp_ge_u32 s5, s11
	s_cselect_b32 s24, 1, 0
	s_cmp_le_u32 s5, s31
	s_cselect_b32 s29, 1, 0
	s_and_b32 s24, s24, s29
	s_add_u32 s29, s5, 64
	s_cmp_le_u32 s29, s31
	s_cselect_b32 s10, 0, 0x7fffffff
	s_cmp_eq_u32 s24, 0
	s_cbranch_scc1 .LatB_evnn_01
	s_lshl_b32 s29, s5, 2
	s_add_i32 s29, s29, 0x18b80
	v_add_u32_e32 v187, s29, v162
	ds_read2_b32 v[132:133], v187 offset0:0 offset1:1
	ds_read2_b32 v[134:135], v187 offset0:2 offset1:3
	ds_read2_b32 v[136:137], v187 offset0:8 offset1:9
	ds_read2_b32 v[138:139], v187 offset0:10 offset1:11
	s_waitcnt lgkmcnt(0)
	v_pk_add_f32 v[84:85], v[84:85], v[132:133]
	v_pk_add_f32 v[86:87], v[86:87], v[134:135]
	v_pk_add_f32 v[88:89], v[88:89], v[136:137]
	v_pk_add_f32 v[90:91], v[90:91], v[138:139]
	ds_read2_b32 v[132:133], v187 offset0:16 offset1:17
	ds_read2_b32 v[134:135], v187 offset0:18 offset1:19
	ds_read2_b32 v[136:137], v187 offset0:24 offset1:25
	ds_read2_b32 v[138:139], v187 offset0:26 offset1:27
	s_waitcnt lgkmcnt(0)
	v_pk_add_f32 v[92:93], v[92:93], v[132:133]
	v_pk_add_f32 v[94:95], v[94:95], v[134:135]
	v_pk_add_f32 v[96:97], v[96:97], v[136:137]
	v_pk_add_f32 v[98:99], v[98:99], v[138:139]
	ds_read2_b32 v[132:133], v187 offset0:32 offset1:33
	ds_read2_b32 v[134:135], v187 offset0:34 offset1:35
	ds_read2_b32 v[136:137], v187 offset0:40 offset1:41
	ds_read2_b32 v[138:139], v187 offset0:42 offset1:43
	s_waitcnt lgkmcnt(0)
	v_pk_add_f32 v[100:101], v[100:101], v[132:133]
	v_pk_add_f32 v[102:103], v[102:103], v[134:135]
	v_pk_add_f32 v[104:105], v[104:105], v[136:137]
	v_pk_add_f32 v[106:107], v[106:107], v[138:139]
	ds_read2_b32 v[132:133], v187 offset0:48 offset1:49
	ds_read2_b32 v[134:135], v187 offset0:50 offset1:51
	ds_read2_b32 v[136:137], v187 offset0:56 offset1:57
	ds_read2_b32 v[138:139], v187 offset0:58 offset1:59
	s_waitcnt lgkmcnt(0)
	v_pk_add_f32 v[108:109], v[108:109], v[132:133]
	v_pk_add_f32 v[110:111], v[110:111], v[134:135]
	v_pk_add_f32 v[112:113], v[112:113], v[136:137]
	v_pk_add_f32 v[114:115], v[114:115], v[138:139]

; #define LAS __attribute__((address_space(3)))
; __device__ __forceinline__ float max2f(float a, float b) { float r; asm("v_max_f32_e32 %0, %1, %2" : "=v"(r) : "v"(a), "v"(b)); return r; }
; __device__ __forceinline__ void attn_unit(LAS unsigned char* lds, const bf16_t* Z, bf16_t* A2, const float* tabg, int seq_base, int S, int h, int qb, float lam) {
;     ...
;         bool near = true; float cc = 0.f;
;         if (kv0 - (qlo + 31) >= 128) { near = false; cc = tabR; } else if (qlo - (kv0 + 63) >= 128) { near = false; cc = tabL; }
;         { const float coff = cc - mu;
;           if (__any(!(coff == coff_cur))) { coff_cur = coff;
; #pragma unroll
;               for (int r = 0; r < 16; ++r) cblk[r] = coff;
;               asm volatile("" : "+v"(cblk)); } }
;     ...
;         if (first || __any(mx > THR)) {
;             { auto rr = __builtin_amdgcn_permlane32_swap(__float_as_uint(mx), __float_as_uint(mx), false, false); mx = max2f(__uint_as_float(rr[0]), __uint_as_float(rr[1])); }
;             const float delta = first ? mx : fmaxf(mx, 0.f);
;             const float alpha = first ? 1.0f : __builtin_amdgcn_exp2f(-delta);
;             mu += delta; ls2 *= alpha;
;             if (!first) {
;                 asm volatile("" ::: "memory");
;                 scr[r32] = alpha;
;                 asm volatile("s_waitcnt lgkmcnt(0)" ::: "memory");
; #pragma unroll
;                 for (int g = 0; g < 4; ++g) { const f32x4 a4 = *(const LAS f32x4*)(scr + 8 * g + 4 * hi);
; #pragma unroll
;                     for (int d = 0; d < 4; ++d) { O[d][4 * g + 0] *= a4[0]; O[d][4 * g + 1] *= a4[1]; O[d][4 * g + 2] *= a4[2]; O[d][4 * g + 3] *= a4[3]; } }
;                 asm volatile("s_waitcnt lgkmcnt(0)" ::: "memory");
;             }
; #pragma unroll
;             for (int r = 0; r < 16; ++r) { p0[r] -= delta; p1[r] -= delta; }
;             asm volatile("" : "+v"(p0), "+v"(p1));
;         }
.LatB_rare_001:
	v_mov_b32_e32 v252, v251
	s_nop 1
	v_permlane32_swap_b32_e32 v251, v252
	v_max_f32_e32 v251, v251, v252
	v_max_f32_e32 v253, 0, v251
	v_exp_f32_e64 v254, -v253
	v_add_f32_e32 v186, v186, v253
	s_nop 0
	v_mul_f32_e32 v150, v150, v254
	v_mul_f32_e32 v151, v151, v254
	ds_write_b32 v184, v254
	s_waitcnt lgkmcnt(0)
	ds_read_b128 v[196:199], v185
	ds_read_b128 v[200:203], v185 offset:32
	ds_read_b128 v[212:215], v185 offset:64
	ds_read_b128 v[216:219], v185 offset:96
	s_waitcnt lgkmcnt(0)
	s_nop 15
	s_nop 15
	v_pk_mul_f32 v[20:21], v[20:21], v[196:197]
	v_pk_mul_f32 v[22:23], v[22:23], v[198:199]
	v_pk_mul_f32 v[24:25], v[24:25], v[200:201]
	v_pk_mul_f32 v[26:27], v[26:27], v[202:203]
	v_pk_mul_f32 v[28:29], v[28:29], v[212:213]
	v_pk_mul_f32 v[30:31], v[30:31], v[214:215]
	v_pk_mul_f32 v[32:33], v[32:33], v[216:217]
	v_pk_mul_f32 v[34:35], v[34:35], v[218:219]
	v_pk_mul_f32 v[36:37], v[36:37], v[196:197]
	v_pk_mul_f32 v[38:39], v[38:39], v[198:199]
	v_pk_mul_f32 v[40:41], v[40:41], v[200:201]
	v_pk_mul_f32 v[42:43], v[42:43], v[202:203]
	v_pk_mul_f32 v[44:45], v[44:45], v[212:213]
	v_pk_mul_f32 v[46:47], v[46:47], v[214:215]
	v_pk_mul_f32 v[48:49], v[48:49], v[216:217]
	v_pk_mul_f32 v[50:51], v[50:51], v[218:219]
	v_pk_mul_f32 v[52:53], v[52:53], v[196:197]
	v_pk_mul_f32 v[54:55], v[54:55], v[198:199]
	v_pk_mul_f32 v[56:57], v[56:57], v[200:201]
	v_pk_mul_f32 v[58:59], v[58:59], v[202:203]
	v_pk_mul_f32 v[60:61], v[60:61], v[212:213]
	v_pk_mul_f32 v[62:63], v[62:63], v[214:215]
	v_pk_mul_f32 v[64:65], v[64:65], v[216:217]
	v_pk_mul_f32 v[66:67], v[66:67], v[218:219]
	v_pk_mul_f32 v[68:69], v[68:69], v[196:197]
	v_pk_mul_f32 v[70:71], v[70:71], v[198:199]
	v_pk_mul_f32 v[72:73], v[72:73], v[200:201]
	v_pk_mul_f32 v[74:75], v[74:75], v[202:203]
	v_pk_mul_f32 v[76:77], v[76:77], v[212:213]
	v_pk_mul_f32 v[78:79], v[78:79], v[214:215]
	v_pk_mul_f32 v[80:81], v[80:81], v[216:217]
	v_pk_mul_f32 v[82:83], v[82:83], v[218:219]
	v_mov_b32_e32 v252, v253
	v_pk_add_f32 v[84:85], v[84:85], v[252:253] neg_lo:[0,1] neg_hi:[0,1]
	v_pk_add_f32 v[86:87], v[86:87], v[252:253] neg_lo:[0,1] neg_hi:[0,1]
	v_pk_add_f32 v[88:89], v[88:89], v[252:253] neg_lo:[0,1] neg_hi:[0,1]
	v_pk_add_f32 v[90:91], v[90:91], v[252:253] neg_lo:[0,1] neg_hi:[0,1]
	v_pk_add_f32 v[92:93], v[92:93], v[252:253] neg_lo:[0,1] neg_hi:[0,1]
	v_pk_add_f32 v[94:95], v[94:95], v[252:253] neg_lo:[0,1] neg_hi:[0,1]
	v_pk_add_f32 v[96:97], v[96:97], v[252:253] neg_lo:[0,1] neg_hi:[0,1]
	v_pk_add_f32 v[98:99], v[98:99], v[252:253] neg_lo:[0,1] neg_hi:[0,1]
	v_pk_add_f32 v[100:101], v[100:101], v[252:253] neg_lo:[0,1] neg_hi:[0,1]
	v_pk_add_f32 v[102:103], v[102:103], v[252:253] neg_lo:[0,1] neg_hi:[0,1]
	v_pk_add_f32 v[104:105], v[104:105], v[252:253] neg_lo:[0,1] neg_hi:[0,1]
	v_pk_add_f32 v[106:107], v[106:107], v[252:253] neg_lo:[0,1] neg_hi:[0,1]
	v_pk_add_f32 v[108:109], v[108:109], v[252:253] neg_lo:[0,1] neg_hi:[0,1]
	v_pk_add_f32 v[110:111], v[110:111], v[252:253] neg_lo:[0,1] neg_hi:[0,1]
	v_pk_add_f32 v[112:113], v[112:113], v[252:253] neg_lo:[0,1] neg_hi:[0,1]
	v_pk_add_f32 v[114:115], v[114:115], v[252:253] neg_lo:[0,1] neg_hi:[0,1]
	s_sub_u32 s5, s8, s4
	s_lshr_b32 s5, s5, 12
	s_sub_u32 s5, s5, 64
	s_add_u32 s29, s5, 64
	s_cmp_lt_u32 s29, s11
	s_cselect_b32 s24, 1, 0
	s_cmp_gt_u32 s29, s31
	s_cselect_b32 s30, 2, 0
	s_or_b32 s24, s24, s30
	s_mov_b32 s35, s24
	v_mov_b32_e32 v251, 0
	s_cmp_eq_u32 s24, 1
	s_cselect_b64 vcc, -1, 0
	v_cndmask_b32_e32 v251, v251, v177, vcc
	s_cmp_eq_u32 s24, 2
	s_cselect_b64 vcc, -1, 0
	v_cndmask_b32_e32 v251, v251, v178, vcc
	v_sub_f32_e32 v2, v251, v186
	v_mov_b32_e32 v3, v2
	v_mov_b64_e32 v[4:5], v[2:3]
	v_mov_b64_e32 v[6:7], v[2:3]
	v_mov_b64_e32 v[8:9], v[2:3]
	v_mov_b64_e32 v[10:11], v[2:3]
	v_mov_b64_e32 v[12:13], v[2:3]
	v_mov_b64_e32 v[14:15], v[2:3]
	v_mov_b64_e32 v[16:17], v[2:3]
	s_nop 1
	s_branch .LatB_rareret_h0
.LatB_rare_111:
	v_mov_b32_e32 v252, v251
	s_nop 1
	v_permlane32_swap_b32_e32 v251, v252
	v_max_f32_e32 v251, v251, v252
	v_max_f32_e32 v253, 0, v251
	v_exp_f32_e64 v254, -v253
	v_add_f32_e32 v186, v186, v253
	s_nop 0
	v_mul_f32_e32 v150, v150, v254
	v_mul_f32_e32 v151, v151, v254
	ds_write_b32 v184, v254
	s_waitcnt lgkmcnt(0)
	v_mfma_f32_32x32x16_bf16 v[20:35], v[84:87], v[132:135], v[20:35]
	v_mfma_f32_32x32x16_bf16 v[36:51], v[84:87], v[136:139], v[36:51]
	v_mfma_f32_32x32x16_bf16 v[52:67], v[84:87], v[140:143], v[52:67]
	v_mfma_f32_32x32x16_bf16 v[68:83], v[84:87], v[144:147], v[68:83]
	v_mfma_f32_32x32x16_bf16 v[20:35], v[88:91], v[220:223], v[20:35]
	v_mfma_f32_32x32x16_bf16 v[36:51], v[88:91], v[224:227], v[36:51]
	v_mfma_f32_32x32x16_bf16 v[52:67], v[88:91], v[232:235], v[52:67]
	ds_read_b64_tr_b16 v[132:133], v231 offset:4096
	ds_read_b64_tr_b16 v[134:135], v231 offset:6144
	ds_read_b64_tr_b16 v[136:137], v228 offset:8192
	ds_read_b64_tr_b16 v[138:139], v228 offset:10240
	ds_read_b64_tr_b16 v[140:141], v229 offset:8192
	ds_read_b64_tr_b16 v[142:143], v229 offset:10240
	ds_read_b64_tr_b16 v[144:145], v230 offset:8192
	ds_read_b64_tr_b16 v[146:147], v230 offset:10240
	ds_read_b64_tr_b16 v[220:221], v231 offset:8192
	ds_read_b64_tr_b16 v[222:223], v231 offset:10240
	ds_read_b64_tr_b16 v[224:225], v228 offset:12288
	ds_read_b64_tr_b16 v[226:227], v228 offset:14336
	ds_read_b64_tr_b16 v[232:233], v229 offset:12288
	ds_read_b64_tr_b16 v[234:235], v229 offset:14336
	s_waitcnt lgkmcnt(0)
; #define LAS __attribute__((address_space(3)))
; __device__ __forceinline__ float max2f(float a, float b) { float r; asm("v_max_f32_e32 %0, %1, %2" : "=v"(r) : "v"(a), "v"(b)); return r; }
; #define VREADS1(arr, d_) do { const unsigned ad_ = vbase ^ (unsigned)((d_) << 6); __builtin_amdgcn_sched_barrier(0); \
;         _Pragma("unroll") for (int ks_ = 0; ks_ < 4; ++ks_) { VTR(arr[ks_ * 2], ad_, ks_ * 4096); VTR(arr[ks_ * 2 + 1], ad_, ks_ * 4096 + 2048); } __builtin_amdgcn_sched_barrier(0); } while (0)
; #define PV1(arr, d_) do { _Pragma("unroll") for (int ks_ = 0; ks_ < 4; ++ks_) { const s16x4 lo_ = arr[ks_ * 2], hh_ = arr[ks_ * 2 + 1]; \
;         const bf16x8 bv_ = (bf16x8){lo_[0], lo_[1], lo_[2], lo_[3], hh_[0], hh_[1], hh_[2], hh_[3]}; \
;         O[d_] = __builtin_amdgcn_mfma_f32_32x32x16_bf16(pa[ks_], bv_, O[d_], 0, 0, 0); } __builtin_amdgcn_sched_barrier(0); } while (0)
; __device__ __forceinline__ void attn_unit(LAS unsigned char* lds, const bf16_t* Z, bf16_t* A2, const float* tabg, int seq_base, int S, int h, int qb, float lam) {
;     ...
;         if (first || __any(mx > THR)) {
;             { auto rr = __builtin_amdgcn_permlane32_swap(__float_as_uint(mx), __float_as_uint(mx), false, false); mx = max2f(__uint_as_float(rr[0]), __uint_as_float(rr[1])); }
;             const float delta = first ? mx : fmaxf(mx, 0.f);
;             const float alpha = first ? 1.0f : __builtin_amdgcn_exp2f(-delta);
;             mu += delta; ls2 *= alpha;
;             if (!first) {
;                 asm volatile("" ::: "memory");
;                 scr[r32] = alpha;
;                 asm volatile("s_waitcnt lgkmcnt(0)" ::: "memory");
; #pragma unroll
;                 for (int g = 0; g < 4; ++g) { const f32x4 a4 = *(const LAS f32x4*)(scr + 8 * g + 4 * hi);
; #pragma unroll
;                     for (int d = 0; d < 4; ++d) { O[d][4 * g + 0] *= a4[0]; O[d][4 * g + 1] *= a4[1]; O[d][4 * g + 2] *= a4[2]; O[d][4 * g + 3] *= a4[3]; } }
;                 asm volatile("s_waitcnt lgkmcnt(0)" ::: "memory");
;             }
; #pragma unroll
;             for (int r = 0; r < 16; ++r) { p0[r] -= delta; p1[r] -= delta; }
;             asm volatile("" : "+v"(p0), "+v"(p1));
;         }
;     ...
;         LGKM0(); VREADS1(vb, 1); PV1(va, 0); LGKM0(); VREADS1(va, 2); PV1(vb, 1); LGKM0(); VREADS1(vb, 3); PV1(va, 2); LGKM0(); PV1(vb, 3);
	v_mfma_f32_32x32x16_bf16 v[68:83], v[88:91], v[132:135], v[68:83]
	v_mfma_f32_32x32x16_bf16 v[20:35], v[100:103], v[136:139], v[20:35]
	v_mfma_f32_32x32x16_bf16 v[36:51], v[100:103], v[140:143], v[36:51]
	v_mfma_f32_32x32x16_bf16 v[52:67], v[100:103], v[144:147], v[52:67]
	v_mfma_f32_32x32x16_bf16 v[68:83], v[100:103], v[220:223], v[68:83]
	v_mfma_f32_32x32x16_bf16 v[20:35], v[104:107], v[224:227], v[20:35]
	v_mfma_f32_32x32x16_bf16 v[36:51], v[104:107], v[232:235], v[36:51]
	ds_read_b64_tr_b16 v[132:133], v230 offset:12288
	ds_read_b64_tr_b16 v[134:135], v230 offset:14336
	ds_read_b64_tr_b16 v[136:137], v231 offset:12288
	ds_read_b64_tr_b16 v[138:139], v231 offset:14336
	s_waitcnt lgkmcnt(0)
	v_mfma_f32_32x32x16_bf16 v[52:67], v[104:107], v[132:135], v[52:67]
	v_mfma_f32_32x32x16_bf16 v[68:83], v[104:107], v[136:139], v[68:83]
	ds_read_b128 v[92:95], v185
	ds_read_b128 v[96:99], v185 offset:32
	ds_read_b128 v[108:111], v185 offset:64
	ds_read_b128 v[112:115], v185 offset:96
	s_waitcnt lgkmcnt(0)
	s_nop 15
	s_nop 15
	v_pk_mul_f32 v[20:21], v[20:21], v[92:93]
	v_pk_mul_f32 v[22:23], v[22:23], v[94:95]
	v_pk_mul_f32 v[24:25], v[24:25], v[96:97]
	v_pk_mul_f32 v[26:27], v[26:27], v[98:99]
	v_pk_mul_f32 v[28:29], v[28:29], v[108:109]
	v_pk_mul_f32 v[30:31], v[30:31], v[110:111]
	v_pk_mul_f32 v[32:33], v[32:33], v[112:113]
	v_pk_mul_f32 v[34:35], v[34:35], v[114:115]
	v_pk_mul_f32 v[36:37], v[36:37], v[92:93]
	v_pk_mul_f32 v[38:39], v[38:39], v[94:95]
	v_pk_mul_f32 v[40:41], v[40:41], v[96:97]
	v_pk_mul_f32 v[42:43], v[42:43], v[98:99]
	v_pk_mul_f32 v[44:45], v[44:45], v[108:109]
	v_pk_mul_f32 v[46:47], v[46:47], v[110:111]
	v_pk_mul_f32 v[48:49], v[48:49], v[112:113]
	v_pk_mul_f32 v[50:51], v[50:51], v[114:115]
	v_pk_mul_f32 v[52:53], v[52:53], v[92:93]
	v_pk_mul_f32 v[54:55], v[54:55], v[94:95]
	v_pk_mul_f32 v[56:57], v[56:57], v[96:97]
	v_pk_mul_f32 v[58:59], v[58:59], v[98:99]
	v_pk_mul_f32 v[60:61], v[60:61], v[108:109]
	v_pk_mul_f32 v[62:63], v[62:63], v[110:111]
	v_pk_mul_f32 v[64:65], v[64:65], v[112:113]
	v_pk_mul_f32 v[66:67], v[66:67], v[114:115]
	v_pk_mul_f32 v[68:69], v[68:69], v[92:93]
	v_pk_mul_f32 v[70:71], v[70:71], v[94:95]
	v_pk_mul_f32 v[72:73], v[72:73], v[96:97]
	v_pk_mul_f32 v[74:75], v[74:75], v[98:99]
	v_pk_mul_f32 v[76:77], v[76:77], v[108:109]
	v_pk_mul_f32 v[78:79], v[78:79], v[110:111]
	v_pk_mul_f32 v[80:81], v[80:81], v[112:113]
	v_pk_mul_f32 v[82:83], v[82:83], v[114:115]
	v_mov_b32_e32 v252, v253
	v_pk_add_f32 v[188:189], v[188:189], v[252:253] neg_lo:[0,1] neg_hi:[0,1]
	v_pk_add_f32 v[190:191], v[190:191], v[252:253] neg_lo:[0,1] neg_hi:[0,1]
	v_pk_add_f32 v[192:193], v[192:193], v[252:253] neg_lo:[0,1] neg_hi:[0,1]
	v_pk_add_f32 v[194:195], v[194:195], v[252:253] neg_lo:[0,1] neg_hi:[0,1]
	v_pk_add_f32 v[196:197], v[196:197], v[252:253] neg_lo:[0,1] neg_hi:[0,1]
	v_pk_add_f32 v[198:199], v[198:199], v[252:253] neg_lo:[0,1] neg_hi:[0,1]
	v_pk_add_f32 v[200:201], v[200:201], v[252:253] neg_lo:[0,1] neg_hi:[0,1]
	v_pk_add_f32 v[202:203], v[202:203], v[252:253] neg_lo:[0,1] neg_hi:[0,1]
	v_pk_add_f32 v[204:205], v[204:205], v[252:253] neg_lo:[0,1] neg_hi:[0,1]
	v_pk_add_f32 v[206:207], v[206:207], v[252:253] neg_lo:[0,1] neg_hi:[0,1]
	v_pk_add_f32 v[208:209], v[208:209], v[252:253] neg_lo:[0,1] neg_hi:[0,1]
	v_pk_add_f32 v[210:211], v[210:211], v[252:253] neg_lo:[0,1] neg_hi:[0,1]
	v_pk_add_f32 v[212:213], v[212:213], v[252:253] neg_lo:[0,1] neg_hi:[0,1]
	v_pk_add_f32 v[214:215], v[214:215], v[252:253] neg_lo:[0,1] neg_hi:[0,1]
	v_pk_add_f32 v[216:217], v[216:217], v[252:253] neg_lo:[0,1] neg_hi:[0,1]
	v_pk_add_f32 v[218:219], v[218:219], v[252:253] neg_lo:[0,1] neg_hi:[0,1]
	v_mov_b64_e32 v[84:85], 0
	v_mov_b64_e32 v[86:87], 0
	v_mov_b64_e32 v[88:89], 0
	v_mov_b64_e32 v[90:91], 0
	v_mov_b64_e32 v[100:101], 0
	v_mov_b64_e32 v[102:103], 0
	v_mov_b64_e32 v[104:105], 0
	v_mov_b64_e32 v[106:107], 0
	s_sub_u32 s5, s8, s4
	s_lshr_b32 s5, s5, 12
	s_sub_u32 s5, s5, 64
	s_add_u32 s29, s5, 64
	s_cmp_lt_u32 s29, s11
	s_cselect_b32 s24, 1, 0
	s_cmp_gt_u32 s29, s31
	s_cselect_b32 s30, 2, 0
	s_or_b32 s24, s24, s30
	s_mov_b32 s35, s24
	v_mov_b32_e32 v251, 0
	s_cmp_eq_u32 s24, 1
	s_cselect_b64 vcc, -1, 0
	v_cndmask_b32_e32 v251, v251, v177, vcc
	s_cmp_eq_u32 s24, 2
	s_cselect_b64 vcc, -1, 0
	v_cndmask_b32_e32 v251, v251, v178, vcc
	v_sub_f32_e32 v2, v251, v186
	v_mov_b32_e32 v3, v2
	v_mov_b64_e32 v[4:5], v[2:3]
	v_mov_b64_e32 v[6:7], v[2:3]
	v_mov_b64_e32 v[8:9], v[2:3]
	v_mov_b64_e32 v[10:11], v[2:3]
	v_mov_b64_e32 v[12:13], v[2:3]
	v_mov_b64_e32 v[14:15], v[2:3]
	v_mov_b64_e32 v[16:17], v[2:3]
	s_nop 1
	s_cmp_eq_u32 s22, 0
	s_cbranch_scc1 .LatB_rareret_h1
	s_cmp_eq_u32 s22, 1
	s_cbranch_scc1 .LatB_rareret_m1
	s_branch .LatB_rareret_x3
; #define LAS __attribute__((address_space(3)))
; __device__ __forceinline__ float max2f(float a, float b) { float r; asm("v_max_f32_e32 %0, %1, %2" : "=v"(r) : "v"(a), "v"(b)); return r; }
; __device__ __forceinline__ void attn_unit(LAS unsigned char* lds, const bf16_t* Z, bf16_t* A2, const float* tabg, int seq_base, int S, int h, int qb, float lam) {
;     ...
;         if (kv0 - (qlo + 31) >= 128) { near = false; cc = tabR; } else if (qlo - (kv0 + 63) >= 128) { near = false; cc = tabL; }
;         { const float coff = cc - mu;
;           if (__any(!(coff == coff_cur))) { coff_cur = coff;
; #pragma unroll
;               for (int r = 0; r < 16; ++r) cblk[r] = coff;
;               asm volatile("" : "+v"(cblk)); } }
;     ...
;         if (first || __any(mx > THR)) {
;             { auto rr = __builtin_amdgcn_permlane32_swap(__float_as_uint(mx), __float_as_uint(mx), false, false); mx = max2f(__uint_as_float(rr[0]), __uint_as_float(rr[1])); }
;             const float delta = first ? mx : fmaxf(mx, 0.f);
;             const float alpha = first ? 1.0f : __builtin_amdgcn_exp2f(-delta);
;             mu += delta; ls2 *= alpha;
;             if (!first) {
;                 asm volatile("" ::: "memory");
;                 scr[r32] = alpha;
;                 asm volatile("s_waitcnt lgkmcnt(0)" ::: "memory");
; #pragma unroll
;                 for (int g = 0; g < 4; ++g) { const f32x4 a4 = *(const LAS f32x4*)(scr + 8 * g + 4 * hi);
; #pragma unroll
;                     for (int d = 0; d < 4; ++d) { O[d][4 * g + 0] *= a4[0]; O[d][4 * g + 1] *= a4[1]; O[d][4 * g + 2] *= a4[2]; O[d][4 * g + 3] *= a4[3]; } }
;                 asm volatile("s_waitcnt lgkmcnt(0)" ::: "memory");
;             }
; #pragma unroll
;             for (int r = 0; r < 16; ++r) { p0[r] -= delta; p1[r] -= delta; }
;             asm volatile("" : "+v"(p0), "+v"(p1));
;         }
; #pragma unroll
;         for (int r = 0; r < 16; ++r) { p0[r] = __builtin_amdgcn_exp2f(p0[r]); p1[r] = __builtin_amdgcn_exp2f(p1[r]); }
; #pragma unroll
;         for (int r = 0; r < 16; r += 2) { ls2 += (f32x2){p0[r], p0[r + 1]}; ls2 += (f32x2){p1[r], p1[r + 1]}; }
;         bf16x8 pa[4]; pa[0] = pack8(p0, 0); pa[1] = pack8(p0, 8); pa[2] = pack8(p1, 0); pa[3] = pack8(p1, 8);
;         LGKM0(); VREADS1(vb, 1); PV1(va, 0); LGKM0(); VREADS1(va, 2); PV1(vb, 1); LGKM0(); VREADS1(vb, 3); PV1(va, 2); LGKM0(); PV1(vb, 3);
.LatB_rare_211:
	v_mov_b32_e32 v252, v251
	s_nop 1
	v_permlane32_swap_b32_e32 v251, v252
	v_max_f32_e32 v251, v251, v252
	v_max_f32_e32 v253, 0, v251
	v_exp_f32_e64 v254, -v253
	v_add_f32_e32 v186, v186, v253
	s_nop 0
	v_mul_f32_e32 v150, v150, v254
	v_mul_f32_e32 v151, v151, v254
	ds_write_b32 v184, v254
	s_waitcnt lgkmcnt(0)
	v_mfma_f32_32x32x16_bf16 v[20:35], v[188:191], v[132:135], v[20:35]
	v_mfma_f32_32x32x16_bf16 v[36:51], v[188:191], v[136:139], v[36:51]
	v_mfma_f32_32x32x16_bf16 v[52:67], v[188:191], v[140:143], v[52:67]
	v_mfma_f32_32x32x16_bf16 v[68:83], v[188:191], v[144:147], v[68:83]
	v_mfma_f32_32x32x16_bf16 v[20:35], v[192:195], v[220:223], v[20:35]
	v_mfma_f32_32x32x16_bf16 v[36:51], v[192:195], v[224:227], v[36:51]
	v_mfma_f32_32x32x16_bf16 v[52:67], v[192:195], v[232:235], v[52:67]
	ds_read_b64_tr_b16 v[132:133], v231 offset:20480
	ds_read_b64_tr_b16 v[134:135], v231 offset:22528
	ds_read_b64_tr_b16 v[136:137], v228 offset:24576
	ds_read_b64_tr_b16 v[138:139], v228 offset:26624
	ds_read_b64_tr_b16 v[140:141], v229 offset:24576
	ds_read_b64_tr_b16 v[142:143], v229 offset:26624
	ds_read_b64_tr_b16 v[144:145], v230 offset:24576
	ds_read_b64_tr_b16 v[146:147], v230 offset:26624
	ds_read_b64_tr_b16 v[220:221], v231 offset:24576
	ds_read_b64_tr_b16 v[222:223], v231 offset:26624
	ds_read_b64_tr_b16 v[224:225], v228 offset:28672
	ds_read_b64_tr_b16 v[226:227], v228 offset:30720
	ds_read_b64_tr_b16 v[232:233], v229 offset:28672
	ds_read_b64_tr_b16 v[234:235], v229 offset:30720
	s_waitcnt lgkmcnt(0)
	v_mfma_f32_32x32x16_bf16 v[68:83], v[192:195], v[132:135], v[68:83]
	v_mfma_f32_32x32x16_bf16 v[20:35], v[204:207], v[136:139], v[20:35]
	v_mfma_f32_32x32x16_bf16 v[36:51], v[204:207], v[140:143], v[36:51]
	v_mfma_f32_32x32x16_bf16 v[52:67], v[204:207], v[144:147], v[52:67]
	v_mfma_f32_32x32x16_bf16 v[68:83], v[204:207], v[220:223], v[68:83]
	v_mfma_f32_32x32x16_bf16 v[20:35], v[208:211], v[224:227], v[20:35]
	v_mfma_f32_32x32x16_bf16 v[36:51], v[208:211], v[232:235], v[36:51]
	ds_read_b64_tr_b16 v[132:133], v230 offset:28672
	ds_read_b64_tr_b16 v[134:135], v230 offset:30720
	ds_read_b64_tr_b16 v[136:137], v231 offset:28672
	ds_read_b64_tr_b16 v[138:139], v231 offset:30720
	s_waitcnt lgkmcnt(0)
	v_mfma_f32_32x32x16_bf16 v[52:67], v[208:211], v[132:135], v[52:67]
	v_mfma_f32_32x32x16_bf16 v[68:83], v[208:211], v[136:139], v[68:83]
	ds_read_b128 v[196:199], v185
	ds_read_b128 v[200:203], v185 offset:32
	ds_read_b128 v[212:215], v185 offset:64
	ds_read_b128 v[216:219], v185 offset:96
	s_waitcnt lgkmcnt(0)
	s_nop 15
	s_nop 15
	v_pk_mul_f32 v[20:21], v[20:21], v[196:197]
	v_pk_mul_f32 v[22:23], v[22:23], v[198:199]
	v_pk_mul_f32 v[24:25], v[24:25], v[200:201]
	v_pk_mul_f32 v[26:27], v[26:27], v[202:203]
	v_pk_mul_f32 v[28:29], v[28:29], v[212:213]
	v_pk_mul_f32 v[30:31], v[30:31], v[214:215]
	v_pk_mul_f32 v[32:33], v[32:33], v[216:217]
	v_pk_mul_f32 v[34:35], v[34:35], v[218:219]
	v_pk_mul_f32 v[36:37], v[36:37], v[196:197]
	v_pk_mul_f32 v[38:39], v[38:39], v[198:199]
	v_pk_mul_f32 v[40:41], v[40:41], v[200:201]
	v_pk_mul_f32 v[42:43], v[42:43], v[202:203]
	v_pk_mul_f32 v[44:45], v[44:45], v[212:213]
	v_pk_mul_f32 v[46:47], v[46:47], v[214:215]
	v_pk_mul_f32 v[48:49], v[48:49], v[216:217]
	v_pk_mul_f32 v[50:51], v[50:51], v[218:219]
	v_pk_mul_f32 v[52:53], v[52:53], v[196:197]
	v_pk_mul_f32 v[54:55], v[54:55], v[198:199]
	v_pk_mul_f32 v[56:57], v[56:57], v[200:201]
	v_pk_mul_f32 v[58:59], v[58:59], v[202:203]
	v_pk_mul_f32 v[60:61], v[60:61], v[212:213]
	v_pk_mul_f32 v[62:63], v[62:63], v[214:215]
	v_pk_mul_f32 v[64:65], v[64:65], v[216:217]
	v_pk_mul_f32 v[66:67], v[66:67], v[218:219]
	v_pk_mul_f32 v[68:69], v[68:69], v[196:197]
	v_pk_mul_f32 v[70:71], v[70:71], v[198:199]
	v_pk_mul_f32 v[72:73], v[72:73], v[200:201]
	v_pk_mul_f32 v[74:75], v[74:75], v[202:203]
	v_pk_mul_f32 v[76:77], v[76:77], v[212:213]
	v_pk_mul_f32 v[78:79], v[78:79], v[214:215]
	v_pk_mul_f32 v[80:81], v[80:81], v[216:217]
	v_pk_mul_f32 v[82:83], v[82:83], v[218:219]
	v_mov_b32_e32 v252, v253
	v_pk_add_f32 v[84:85], v[84:85], v[252:253] neg_lo:[0,1] neg_hi:[0,1]
	v_pk_add_f32 v[86:87], v[86:87], v[252:253] neg_lo:[0,1] neg_hi:[0,1]
	v_pk_add_f32 v[88:89], v[88:89], v[252:253] neg_lo:[0,1] neg_hi:[0,1]
	v_pk_add_f32 v[90:91], v[90:91], v[252:253] neg_lo:[0,1] neg_hi:[0,1]
	v_pk_add_f32 v[92:93], v[92:93], v[252:253] neg_lo:[0,1] neg_hi:[0,1]
	v_pk_add_f32 v[94:95], v[94:95], v[252:253] neg_lo:[0,1] neg_hi:[0,1]
	v_pk_add_f32 v[96:97], v[96:97], v[252:253] neg_lo:[0,1] neg_hi:[0,1]
	v_pk_add_f32 v[98:99], v[98:99], v[252:253] neg_lo:[0,1] neg_hi:[0,1]
	v_pk_add_f32 v[100:101], v[100:101], v[252:253] neg_lo:[0,1] neg_hi:[0,1]
	v_pk_add_f32 v[102:103], v[102:103], v[252:253] neg_lo:[0,1] neg_hi:[0,1]
	v_pk_add_f32 v[104:105], v[104:105], v[252:253] neg_lo:[0,1] neg_hi:[0,1]
	v_pk_add_f32 v[106:107], v[106:107], v[252:253] neg_lo:[0,1] neg_hi:[0,1]
	v_pk_add_f32 v[108:109], v[108:109], v[252:253] neg_lo:[0,1] neg_hi:[0,1]
	v_pk_add_f32 v[110:111], v[110:111], v[252:253] neg_lo:[0,1] neg_hi:[0,1]
	v_pk_add_f32 v[112:113], v[112:113], v[252:253] neg_lo:[0,1] neg_hi:[0,1]
	v_pk_add_f32 v[114:115], v[114:115], v[252:253] neg_lo:[0,1] neg_hi:[0,1]
	v_mov_b64_e32 v[188:189], 0
	v_mov_b64_e32 v[190:191], 0
	v_mov_b64_e32 v[192:193], 0
	v_mov_b64_e32 v[194:195], 0
	v_mov_b64_e32 v[204:205], 0
	v_mov_b64_e32 v[206:207], 0
	v_mov_b64_e32 v[208:209], 0
	v_mov_b64_e32 v[210:211], 0
	s_sub_u32 s5, s8, s4
	s_lshr_b32 s5, s5, 12
	s_sub_u32 s5, s5, 64
	s_add_u32 s29, s5, 64
	s_cmp_lt_u32 s29, s11
	s_cselect_b32 s24, 1, 0
	s_cmp_gt_u32 s29, s31
	s_cselect_b32 s30, 2, 0
	s_or_b32 s24, s24, s30
	s_mov_b32 s35, s24
	v_mov_b32_e32 v251, 0
	s_cmp_eq_u32 s24, 1
	s_cselect_b64 vcc, -1, 0
	v_cndmask_b32_e32 v251, v251, v177, vcc
	s_cmp_eq_u32 s24, 2
	s_cselect_b64 vcc, -1, 0
	v_cndmask_b32_e32 v251, v251, v178, vcc
	v_sub_f32_e32 v2, v251, v186
	v_mov_b32_e32 v3, v2
	v_mov_b64_e32 v[4:5], v[2:3]
	v_mov_b64_e32 v[6:7], v[2:3]
	v_mov_b64_e32 v[8:9], v[2:3]
	v_mov_b64_e32 v[10:11], v[2:3]
	v_mov_b64_e32 v[12:13], v[2:3]
	v_mov_b64_e32 v[14:15], v[2:3]
	v_mov_b64_e32 v[16:17], v[2:3]
	s_nop 1
	s_cmp_eq_u32 s22, 0
	s_cbranch_scc1 .LatB_rareret_h2
	s_cmp_eq_u32 s22, 1
	s_cbranch_scc1 .LatB_rareret_m2
	s_branch .LatB_rareret_x2
; #define LAS __attribute__((address_space(3)))
; __device__ __forceinline__ float max2f(float a, float b) { float r; asm("v_max_f32_e32 %0, %1, %2" : "=v"(r) : "v"(a), "v"(b)); return r; }
; __device__ __forceinline__ void attn_unit(LAS unsigned char* lds, const bf16_t* Z, bf16_t* A2, const float* tabg, int seq_base, int S, int h, int qb, float lam) {
;     ...
;         if (kv0 - (qlo + 31) >= 128) { near = false; cc = tabR; } else if (qlo - (kv0 + 63) >= 128) { near = false; cc = tabL; }
;         { const float coff = cc - mu;
;           if (__any(!(coff == coff_cur))) { coff_cur = coff;
; #pragma unroll
;               for (int r = 0; r < 16; ++r) cblk[r] = coff;
;               asm volatile("" : "+v"(cblk)); } }
;     ...
;         if (first || __any(mx > THR)) {
;             { auto rr = __builtin_amdgcn_permlane32_swap(__float_as_uint(mx), __float_as_uint(mx), false, false); mx = max2f(__uint_as_float(rr[0]), __uint_as_float(rr[1])); }
;             const float delta = first ? mx : fmaxf(mx, 0.f);
;             const float alpha = first ? 1.0f : __builtin_amdgcn_exp2f(-delta);
;             mu += delta; ls2 *= alpha;
;             if (!first) {
;                 asm volatile("" ::: "memory");
;                 scr[r32] = alpha;
;                 asm volatile("s_waitcnt lgkmcnt(0)" ::: "memory");
; #pragma unroll
;                 for (int g = 0; g < 4; ++g) { const f32x4 a4 = *(const LAS f32x4*)(scr + 8 * g + 4 * hi);
; #pragma unroll
;                     for (int d = 0; d < 4; ++d) { O[d][4 * g + 0] *= a4[0]; O[d][4 * g + 1] *= a4[1]; O[d][4 * g + 2] *= a4[2]; O[d][4 * g + 3] *= a4[3]; } }
;                 asm volatile("s_waitcnt lgkmcnt(0)" ::: "memory");
;             }
; #pragma unroll
;             for (int r = 0; r < 16; ++r) { p0[r] -= delta; p1[r] -= delta; }
;             asm volatile("" : "+v"(p0), "+v"(p1));
;         }
; #pragma unroll
;         for (int r = 0; r < 16; ++r) { p0[r] = __builtin_amdgcn_exp2f(p0[r]); p1[r] = __builtin_amdgcn_exp2f(p1[r]); }
; #pragma unroll
;         for (int r = 0; r < 16; r += 2) { ls2 += (f32x2){p0[r], p0[r + 1]}; ls2 += (f32x2){p1[r], p1[r + 1]}; }
;         bf16x8 pa[4]; pa[0] = pack8(p0, 0); pa[1] = pack8(p0, 8); pa[2] = pack8(p1, 0); pa[3] = pack8(p1, 8);
;         LGKM0(); VREADS1(vb, 1); PV1(va, 0); LGKM0(); VREADS1(va, 2); PV1(vb, 1); LGKM0(); VREADS1(vb, 3); PV1(va, 2); LGKM0(); PV1(vb, 3);
.LatB_rare_311:
	v_mov_b32_e32 v252, v251
	s_nop 1
	v_permlane32_swap_b32_e32 v251, v252
	v_max_f32_e32 v251, v251, v252
	v_max_f32_e32 v253, 0, v251
	v_exp_f32_e64 v254, -v253
	v_add_f32_e32 v186, v186, v253
	s_nop 0
	v_mul_f32_e32 v150, v150, v254
	v_mul_f32_e32 v151, v151, v254
	ds_write_b32 v184, v254
	s_waitcnt lgkmcnt(0)
	v_mfma_f32_32x32x16_bf16 v[20:35], v[84:87], v[132:135], v[20:35]
	v_mfma_f32_32x32x16_bf16 v[36:51], v[84:87], v[136:139], v[36:51]
	v_mfma_f32_32x32x16_bf16 v[52:67], v[84:87], v[140:143], v[52:67]
	v_mfma_f32_32x32x16_bf16 v[68:83], v[84:87], v[144:147], v[68:83]
	v_mfma_f32_32x32x16_bf16 v[20:35], v[88:91], v[220:223], v[20:35]
	v_mfma_f32_32x32x16_bf16 v[36:51], v[88:91], v[224:227], v[36:51]
	v_mfma_f32_32x32x16_bf16 v[52:67], v[88:91], v[232:235], v[52:67]
	ds_read_b64_tr_b16 v[132:133], v231 offset:36864
	ds_read_b64_tr_b16 v[134:135], v231 offset:38912
	ds_read_b64_tr_b16 v[136:137], v228 offset:40960
	ds_read_b64_tr_b16 v[138:139], v228 offset:43008
	ds_read_b64_tr_b16 v[140:141], v229 offset:40960
	ds_read_b64_tr_b16 v[142:143], v229 offset:43008
	ds_read_b64_tr_b16 v[144:145], v230 offset:40960
	ds_read_b64_tr_b16 v[146:147], v230 offset:43008
	ds_read_b64_tr_b16 v[220:221], v231 offset:40960
	ds_read_b64_tr_b16 v[222:223], v231 offset:43008
	ds_read_b64_tr_b16 v[224:225], v228 offset:45056
	ds_read_b64_tr_b16 v[226:227], v228 offset:47104
	ds_read_b64_tr_b16 v[232:233], v229 offset:45056
	ds_read_b64_tr_b16 v[234:235], v229 offset:47104
	s_waitcnt lgkmcnt(0)
	v_mfma_f32_32x32x16_bf16 v[68:83], v[88:91], v[132:135], v[68:83]
	v_mfma_f32_32x32x16_bf16 v[20:35], v[100:103], v[136:139], v[20:35]
	v_mfma_f32_32x32x16_bf16 v[36:51], v[100:103], v[140:143], v[36:51]
	v_mfma_f32_32x32x16_bf16 v[52:67], v[100:103], v[144:147], v[52:67]
	v_mfma_f32_32x32x16_bf16 v[68:83], v[100:103], v[220:223], v[68:83]
	v_mfma_f32_32x32x16_bf16 v[20:35], v[104:107], v[224:227], v[20:35]
	v_mfma_f32_32x32x16_bf16 v[36:51], v[104:107], v[232:235], v[36:51]
	ds_read_b64_tr_b16 v[132:133], v230 offset:45056
	ds_read_b64_tr_b16 v[134:135], v230 offset:47104
	ds_read_b64_tr_b16 v[136:137], v231 offset:45056
	ds_read_b64_tr_b16 v[138:139], v231 offset:47104
	s_waitcnt lgkmcnt(0)
	v_mfma_f32_32x32x16_bf16 v[52:67], v[104:107], v[132:135], v[52:67]
	v_mfma_f32_32x32x16_bf16 v[68:83], v[104:107], v[136:139], v[68:83]
	ds_read_b128 v[92:95], v185
	ds_read_b128 v[96:99], v185 offset:32
	ds_read_b128 v[108:111], v185 offset:64
	ds_read_b128 v[112:115], v185 offset:96
	s_waitcnt lgkmcnt(0)
	s_nop 15
	s_nop 15
	v_pk_mul_f32 v[20:21], v[20:21], v[92:93]
	v_pk_mul_f32 v[22:23], v[22:23], v[94:95]
	v_pk_mul_f32 v[24:25], v[24:25], v[96:97]
	v_pk_mul_f32 v[26:27], v[26:27], v[98:99]
	v_pk_mul_f32 v[28:29], v[28:29], v[108:109]
	v_pk_mul_f32 v[30:31], v[30:31], v[110:111]
	v_pk_mul_f32 v[32:33], v[32:33], v[112:113]
	v_pk_mul_f32 v[34:35], v[34:35], v[114:115]
	v_pk_mul_f32 v[36:37], v[36:37], v[92:93]
	v_pk_mul_f32 v[38:39], v[38:39], v[94:95]
	v_pk_mul_f32 v[40:41], v[40:41], v[96:97]
	v_pk_mul_f32 v[42:43], v[42:43], v[98:99]
	v_pk_mul_f32 v[44:45], v[44:45], v[108:109]
	v_pk_mul_f32 v[46:47], v[46:47], v[110:111]
	v_pk_mul_f32 v[48:49], v[48:49], v[112:113]
	v_pk_mul_f32 v[50:51], v[50:51], v[114:115]
	v_pk_mul_f32 v[52:53], v[52:53], v[92:93]
	v_pk_mul_f32 v[54:55], v[54:55], v[94:95]
	v_pk_mul_f32 v[56:57], v[56:57], v[96:97]
	v_pk_mul_f32 v[58:59], v[58:59], v[98:99]
	v_pk_mul_f32 v[60:61], v[60:61], v[108:109]
	v_pk_mul_f32 v[62:63], v[62:63], v[110:111]
	v_pk_mul_f32 v[64:65], v[64:65], v[112:113]
	v_pk_mul_f32 v[66:67], v[66:67], v[114:115]
	v_pk_mul_f32 v[68:69], v[68:69], v[92:93]
	v_pk_mul_f32 v[70:71], v[70:71], v[94:95]
	v_pk_mul_f32 v[72:73], v[72:73], v[96:97]
	v_pk_mul_f32 v[74:75], v[74:75], v[98:99]
	v_pk_mul_f32 v[76:77], v[76:77], v[108:109]
	v_pk_mul_f32 v[78:79], v[78:79], v[110:111]
	v_pk_mul_f32 v[80:81], v[80:81], v[112:113]
	v_pk_mul_f32 v[82:83], v[82:83], v[114:115]
	v_mov_b32_e32 v252, v253
	v_pk_add_f32 v[188:189], v[188:189], v[252:253] neg_lo:[0,1] neg_hi:[0,1]
	v_pk_add_f32 v[190:191], v[190:191], v[252:253] neg_lo:[0,1] neg_hi:[0,1]
	v_pk_add_f32 v[192:193], v[192:193], v[252:253] neg_lo:[0,1] neg_hi:[0,1]
	v_pk_add_f32 v[194:195], v[194:195], v[252:253] neg_lo:[0,1] neg_hi:[0,1]
	v_pk_add_f32 v[196:197], v[196:197], v[252:253] neg_lo:[0,1] neg_hi:[0,1]
	v_pk_add_f32 v[198:199], v[198:199], v[252:253] neg_lo:[0,1] neg_hi:[0,1]
	v_pk_add_f32 v[200:201], v[200:201], v[252:253] neg_lo:[0,1] neg_hi:[0,1]
	v_pk_add_f32 v[202:203], v[202:203], v[252:253] neg_lo:[0,1] neg_hi:[0,1]
	v_pk_add_f32 v[204:205], v[204:205], v[252:253] neg_lo:[0,1] neg_hi:[0,1]
	v_pk_add_f32 v[206:207], v[206:207], v[252:253] neg_lo:[0,1] neg_hi:[0,1]
	v_pk_add_f32 v[208:209], v[208:209], v[252:253] neg_lo:[0,1] neg_hi:[0,1]
	v_pk_add_f32 v[210:211], v[210:211], v[252:253] neg_lo:[0,1] neg_hi:[0,1]
	v_pk_add_f32 v[212:213], v[212:213], v[252:253] neg_lo:[0,1] neg_hi:[0,1]
	v_pk_add_f32 v[214:215], v[214:215], v[252:253] neg_lo:[0,1] neg_hi:[0,1]
	v_pk_add_f32 v[216:217], v[216:217], v[252:253] neg_lo:[0,1] neg_hi:[0,1]
	v_pk_add_f32 v[218:219], v[218:219], v[252:253] neg_lo:[0,1] neg_hi:[0,1]
	v_mov_b64_e32 v[84:85], 0
	v_mov_b64_e32 v[86:87], 0
	v_mov_b64_e32 v[88:89], 0
	v_mov_b64_e32 v[90:91], 0
	v_mov_b64_e32 v[100:101], 0
	v_mov_b64_e32 v[102:103], 0
	v_mov_b64_e32 v[104:105], 0
	v_mov_b64_e32 v[106:107], 0
	s_sub_u32 s5, s8, s4
	s_lshr_b32 s5, s5, 12
	s_sub_u32 s5, s5, 64
	s_add_u32 s29, s5, 64
	s_cmp_lt_u32 s29, s11
	s_cselect_b32 s24, 1, 0
	s_cmp_gt_u32 s29, s31
	s_cselect_b32 s30, 2, 0
	s_or_b32 s24, s24, s30
	s_mov_b32 s35, s24
	v_mov_b32_e32 v251, 0
	s_cmp_eq_u32 s24, 1
	s_cselect_b64 vcc, -1, 0
	v_cndmask_b32_e32 v251, v251, v177, vcc
	s_cmp_eq_u32 s24, 2
	s_cselect_b64 vcc, -1, 0
	v_cndmask_b32_e32 v251, v251, v178, vcc
	v_sub_f32_e32 v2, v251, v186
	v_mov_b32_e32 v3, v2
	v_mov_b64_e32 v[4:5], v[2:3]
	v_mov_b64_e32 v[6:7], v[2:3]
	v_mov_b64_e32 v[8:9], v[2:3]
	v_mov_b64_e32 v[10:11], v[2:3]
	v_mov_b64_e32 v[12:13], v[2:3]
	v_mov_b64_e32 v[14:15], v[2:3]
	v_mov_b64_e32 v[16:17], v[2:3]
	s_nop 1
	s_cmp_eq_u32 s22, 0
	s_cbranch_scc1 .LatB_rareret_h3
	s_branch .LatB_rareret_m3
; #define LAS __attribute__((address_space(3)))
; __device__ __forceinline__ float max2f(float a, float b) { float r; asm("v_max_f32_e32 %0, %1, %2" : "=v"(r) : "v"(a), "v"(b)); return r; }
; __device__ __forceinline__ void attn_unit(LAS unsigned char* lds, const bf16_t* Z, bf16_t* A2, const float* tabg, int seq_base, int S, int h, int qb, float lam) {
;     ...
;         if (kv0 - (qlo + 31) >= 128) { near = false; cc = tabR; } else if (qlo - (kv0 + 63) >= 128) { near = false; cc = tabL; }
;         { const float coff = cc - mu;
;           if (__any(!(coff == coff_cur))) { coff_cur = coff;
; #pragma unroll
;               for (int r = 0; r < 16; ++r) cblk[r] = coff;
;               asm volatile("" : "+v"(cblk)); } }
;     ...
;         if (first || __any(mx > THR)) {
;             { auto rr = __builtin_amdgcn_permlane32_swap(__float_as_uint(mx), __float_as_uint(mx), false, false); mx = max2f(__uint_as_float(rr[0]), __uint_as_float(rr[1])); }
;             const float delta = first ? mx : fmaxf(mx, 0.f);
;             const float alpha = first ? 1.0f : __builtin_amdgcn_exp2f(-delta);
;             mu += delta; ls2 *= alpha;
;             if (!first) {
;                 asm volatile("" ::: "memory");
;                 scr[r32] = alpha;
;                 asm volatile("s_waitcnt lgkmcnt(0)" ::: "memory");
; #pragma unroll
;                 for (int g = 0; g < 4; ++g) { const f32x4 a4 = *(const LAS f32x4*)(scr + 8 * g + 4 * hi);
; #pragma unroll
;                     for (int d = 0; d < 4; ++d) { O[d][4 * g + 0] *= a4[0]; O[d][4 * g + 1] *= a4[1]; O[d][4 * g + 2] *= a4[2]; O[d][4 * g + 3] *= a4[3]; } }
;                 asm volatile("s_waitcnt lgkmcnt(0)" ::: "memory");
;             }
; #pragma unroll
;             for (int r = 0; r < 16; ++r) { p0[r] -= delta; p1[r] -= delta; }
;             asm volatile("" : "+v"(p0), "+v"(p1));
;         }
; #pragma unroll
;         for (int r = 0; r < 16; ++r) { p0[r] = __builtin_amdgcn_exp2f(p0[r]); p1[r] = __builtin_amdgcn_exp2f(p1[r]); }
; #pragma unroll
;         for (int r = 0; r < 16; r += 2) { ls2 += (f32x2){p0[r], p0[r + 1]}; ls2 += (f32x2){p1[r], p1[r + 1]}; }
;         bf16x8 pa[4]; pa[0] = pack8(p0, 0); pa[1] = pack8(p0, 8); pa[2] = pack8(p1, 0); pa[3] = pack8(p1, 8);
;         LGKM0(); VREADS1(vb, 1); PV1(va, 0); LGKM0(); VREADS1(va, 2); PV1(vb, 1); LGKM0(); VREADS1(vb, 3); PV1(va, 2); LGKM0(); PV1(vb, 3);
.LatB_rare_411:
	v_mov_b32_e32 v252, v251
	s_nop 1
	v_permlane32_swap_b32_e32 v251, v252
	v_max_f32_e32 v251, v251, v252
	v_max_f32_e32 v253, 0, v251
	v_exp_f32_e64 v254, -v253
	v_add_f32_e32 v186, v186, v253
	s_nop 0
	v_mul_f32_e32 v150, v150, v254
	v_mul_f32_e32 v151, v151, v254
	ds_write_b32 v184, v254
	s_waitcnt lgkmcnt(0)
	v_mfma_f32_32x32x16_bf16 v[20:35], v[188:191], v[132:135], v[20:35]
	v_mfma_f32_32x32x16_bf16 v[36:51], v[188:191], v[136:139], v[36:51]
	v_mfma_f32_32x32x16_bf16 v[52:67], v[188:191], v[140:143], v[52:67]
	v_mfma_f32_32x32x16_bf16 v[68:83], v[188:191], v[144:147], v[68:83]
	v_mfma_f32_32x32x16_bf16 v[20:35], v[192:195], v[220:223], v[20:35]
	v_mfma_f32_32x32x16_bf16 v[36:51], v[192:195], v[224:227], v[36:51]
	v_mfma_f32_32x32x16_bf16 v[52:67], v[192:195], v[232:235], v[52:67]
	ds_read_b64_tr_b16 v[132:133], v231 offset:4096
	ds_read_b64_tr_b16 v[134:135], v231 offset:6144
	ds_read_b64_tr_b16 v[136:137], v228 offset:8192
	ds_read_b64_tr_b16 v[138:139], v228 offset:10240
	ds_read_b64_tr_b16 v[140:141], v229 offset:8192
	ds_read_b64_tr_b16 v[142:143], v229 offset:10240
	ds_read_b64_tr_b16 v[144:145], v230 offset:8192
	ds_read_b64_tr_b16 v[146:147], v230 offset:10240
	ds_read_b64_tr_b16 v[220:221], v231 offset:8192
	ds_read_b64_tr_b16 v[222:223], v231 offset:10240
	ds_read_b64_tr_b16 v[224:225], v228 offset:12288
	ds_read_b64_tr_b16 v[226:227], v228 offset:14336
	ds_read_b64_tr_b16 v[232:233], v229 offset:12288
	ds_read_b64_tr_b16 v[234:235], v229 offset:14336
	s_waitcnt lgkmcnt(0)
	v_mfma_f32_32x32x16_bf16 v[68:83], v[192:195], v[132:135], v[68:83]
	v_mfma_f32_32x32x16_bf16 v[20:35], v[204:207], v[136:139], v[20:35]
	v_mfma_f32_32x32x16_bf16 v[36:51], v[204:207], v[140:143], v[36:51]
	v_mfma_f32_32x32x16_bf16 v[52:67], v[204:207], v[144:147], v[52:67]
	v_mfma_f32_32x32x16_bf16 v[68:83], v[204:207], v[220:223], v[68:83]
	v_mfma_f32_32x32x16_bf16 v[20:35], v[208:211], v[224:227], v[20:35]
	v_mfma_f32_32x32x16_bf16 v[36:51], v[208:211], v[232:235], v[36:51]
	ds_read_b64_tr_b16 v[132:133], v230 offset:12288
	ds_read_b64_tr_b16 v[134:135], v230 offset:14336
	ds_read_b64_tr_b16 v[136:137], v231 offset:12288
	ds_read_b64_tr_b16 v[138:139], v231 offset:14336
	s_waitcnt lgkmcnt(0)
	v_mfma_f32_32x32x16_bf16 v[52:67], v[208:211], v[132:135], v[52:67]
	v_mfma_f32_32x32x16_bf16 v[68:83], v[208:211], v[136:139], v[68:83]
	ds_read_b128 v[196:199], v185
	ds_read_b128 v[200:203], v185 offset:32
	ds_read_b128 v[212:215], v185 offset:64
	ds_read_b128 v[216:219], v185 offset:96
	s_waitcnt lgkmcnt(0)
	s_nop 15
	s_nop 15
	v_pk_mul_f32 v[20:21], v[20:21], v[196:197]
	v_pk_mul_f32 v[22:23], v[22:23], v[198:199]
	v_pk_mul_f32 v[24:25], v[24:25], v[200:201]
	v_pk_mul_f32 v[26:27], v[26:27], v[202:203]
	v_pk_mul_f32 v[28:29], v[28:29], v[212:213]
	v_pk_mul_f32 v[30:31], v[30:31], v[214:215]
	v_pk_mul_f32 v[32:33], v[32:33], v[216:217]
	v_pk_mul_f32 v[34:35], v[34:35], v[218:219]
	v_pk_mul_f32 v[36:37], v[36:37], v[196:197]
	v_pk_mul_f32 v[38:39], v[38:39], v[198:199]
	v_pk_mul_f32 v[40:41], v[40:41], v[200:201]
	v_pk_mul_f32 v[42:43], v[42:43], v[202:203]
	v_pk_mul_f32 v[44:45], v[44:45], v[212:213]
	v_pk_mul_f32 v[46:47], v[46:47], v[214:215]
	v_pk_mul_f32 v[48:49], v[48:49], v[216:217]
	v_pk_mul_f32 v[50:51], v[50:51], v[218:219]
	v_pk_mul_f32 v[52:53], v[52:53], v[196:197]
	v_pk_mul_f32 v[54:55], v[54:55], v[198:199]
	v_pk_mul_f32 v[56:57], v[56:57], v[200:201]
	v_pk_mul_f32 v[58:59], v[58:59], v[202:203]
	v_pk_mul_f32 v[60:61], v[60:61], v[212:213]
	v_pk_mul_f32 v[62:63], v[62:63], v[214:215]
	v_pk_mul_f32 v[64:65], v[64:65], v[216:217]
	v_pk_mul_f32 v[66:67], v[66:67], v[218:219]
	v_pk_mul_f32 v[68:69], v[68:69], v[196:197]
	v_pk_mul_f32 v[70:71], v[70:71], v[198:199]
	v_pk_mul_f32 v[72:73], v[72:73], v[200:201]
	v_pk_mul_f32 v[74:75], v[74:75], v[202:203]
	v_pk_mul_f32 v[76:77], v[76:77], v[212:213]
	v_pk_mul_f32 v[78:79], v[78:79], v[214:215]
	v_pk_mul_f32 v[80:81], v[80:81], v[216:217]
	v_pk_mul_f32 v[82:83], v[82:83], v[218:219]
	v_mov_b32_e32 v252, v253
	v_pk_add_f32 v[84:85], v[84:85], v[252:253] neg_lo:[0,1] neg_hi:[0,1]
	v_pk_add_f32 v[86:87], v[86:87], v[252:253] neg_lo:[0,1] neg_hi:[0,1]
	v_pk_add_f32 v[88:89], v[88:89], v[252:253] neg_lo:[0,1] neg_hi:[0,1]
	v_pk_add_f32 v[90:91], v[90:91], v[252:253] neg_lo:[0,1] neg_hi:[0,1]
	v_pk_add_f32 v[92:93], v[92:93], v[252:253] neg_lo:[0,1] neg_hi:[0,1]
	v_pk_add_f32 v[94:95], v[94:95], v[252:253] neg_lo:[0,1] neg_hi:[0,1]
	v_pk_add_f32 v[96:97], v[96:97], v[252:253] neg_lo:[0,1] neg_hi:[0,1]
	v_pk_add_f32 v[98:99], v[98:99], v[252:253] neg_lo:[0,1] neg_hi:[0,1]
	v_pk_add_f32 v[100:101], v[100:101], v[252:253] neg_lo:[0,1] neg_hi:[0,1]
	v_pk_add_f32 v[102:103], v[102:103], v[252:253] neg_lo:[0,1] neg_hi:[0,1]
	v_pk_add_f32 v[104:105], v[104:105], v[252:253] neg_lo:[0,1] neg_hi:[0,1]
	v_pk_add_f32 v[106:107], v[106:107], v[252:253] neg_lo:[0,1] neg_hi:[0,1]
	v_pk_add_f32 v[108:109], v[108:109], v[252:253] neg_lo:[0,1] neg_hi:[0,1]
	v_pk_add_f32 v[110:111], v[110:111], v[252:253] neg_lo:[0,1] neg_hi:[0,1]
	v_pk_add_f32 v[112:113], v[112:113], v[252:253] neg_lo:[0,1] neg_hi:[0,1]
	v_pk_add_f32 v[114:115], v[114:115], v[252:253] neg_lo:[0,1] neg_hi:[0,1]
	v_mov_b64_e32 v[188:189], 0
	v_mov_b64_e32 v[190:191], 0
	v_mov_b64_e32 v[192:193], 0
	v_mov_b64_e32 v[194:195], 0
	v_mov_b64_e32 v[204:205], 0
	v_mov_b64_e32 v[206:207], 0
	v_mov_b64_e32 v[208:209], 0
	v_mov_b64_e32 v[210:211], 0
	s_sub_u32 s5, s8, s4
	s_lshr_b32 s5, s5, 12
	s_sub_u32 s5, s5, 64
	s_add_u32 s29, s5, 64
	s_cmp_lt_u32 s29, s11
	s_cselect_b32 s24, 1, 0
	s_cmp_gt_u32 s29, s31
	s_cselect_b32 s30, 2, 0
	s_or_b32 s24, s24, s30
	s_mov_b32 s35, s24
	v_mov_b32_e32 v251, 0
	s_cmp_eq_u32 s24, 1
	s_cselect_b64 vcc, -1, 0
	v_cndmask_b32_e32 v251, v251, v177, vcc
	s_cmp_eq_u32 s24, 2
	s_cselect_b64 vcc, -1, 0
	v_cndmask_b32_e32 v251, v251, v178, vcc
	v_sub_f32_e32 v2, v251, v186
	v_mov_b32_e32 v3, v2
	v_mov_b64_e32 v[4:5], v[2:3]
	v_mov_b64_e32 v[6:7], v[2:3]
	v_mov_b64_e32 v[8:9], v[2:3]
	v_mov_b64_e32 v[10:11], v[2:3]
	v_mov_b64_e32 v[12:13], v[2:3]
	v_mov_b64_e32 v[14:15], v[2:3]
	v_mov_b64_e32 v[16:17], v[2:3]
	s_nop 1
	s_cmp_eq_u32 s22, 0
	s_cbranch_scc1 .LatB_rareret_h4
	s_branch .LatB_rareret_m4
; #define LAS __attribute__((address_space(3)))
; __device__ __forceinline__ float max2f(float a, float b) { float r; asm("v_max_f32_e32 %0, %1, %2" : "=v"(r) : "v"(a), "v"(b)); return r; }
; __device__ __forceinline__ void attn_unit(LAS unsigned char* lds, const bf16_t* Z, bf16_t* A2, const float* tabg, int seq_base, int S, int h, int qb, float lam) {
;     ...
;         if (kv0 - (qlo + 31) >= 128) { near = false; cc = tabR; } else if (qlo - (kv0 + 63) >= 128) { near = false; cc = tabL; }
;         { const float coff = cc - mu;
;           if (__any(!(coff == coff_cur))) { coff_cur = coff;
; #pragma unroll
;               for (int r = 0; r < 16; ++r) cblk[r] = coff;
;               asm volatile("" : "+v"(cblk)); } }
;     ...
;         if (first || __any(mx > THR)) {
;             { auto rr = __builtin_amdgcn_permlane32_swap(__float_as_uint(mx), __float_as_uint(mx), false, false); mx = max2f(__uint_as_float(rr[0]), __uint_as_float(rr[1])); }
;             const float delta = first ? mx : fmaxf(mx, 0.f);
;             const float alpha = first ? 1.0f : __builtin_amdgcn_exp2f(-delta);
;             mu += delta; ls2 *= alpha;
;             if (!first) {
;                 asm volatile("" ::: "memory");
;                 scr[r32] = alpha;
;                 asm volatile("s_waitcnt lgkmcnt(0)" ::: "memory");
; #pragma unroll
;                 for (int g = 0; g < 4; ++g) { const f32x4 a4 = *(const LAS f32x4*)(scr + 8 * g + 4 * hi);
; #pragma unroll
;                     for (int d = 0; d < 4; ++d) { O[d][4 * g + 0] *= a4[0]; O[d][4 * g + 1] *= a4[1]; O[d][4 * g + 2] *= a4[2]; O[d][4 * g + 3] *= a4[3]; } }
;                 asm volatile("s_waitcnt lgkmcnt(0)" ::: "memory");
;             }
; #pragma unroll
;             for (int r = 0; r < 16; ++r) { p0[r] -= delta; p1[r] -= delta; }
;             asm volatile("" : "+v"(p0), "+v"(p1));
;         }
; #pragma unroll
;         for (int r = 0; r < 16; ++r) { p0[r] = __builtin_amdgcn_exp2f(p0[r]); p1[r] = __builtin_amdgcn_exp2f(p1[r]); }
; #pragma unroll
;         for (int r = 0; r < 16; r += 2) { ls2 += (f32x2){p0[r], p0[r + 1]}; ls2 += (f32x2){p1[r], p1[r + 1]}; }
;         bf16x8 pa[4]; pa[0] = pack8(p0, 0); pa[1] = pack8(p0, 8); pa[2] = pack8(p1, 0); pa[3] = pack8(p1, 8);
;         LGKM0(); VREADS1(vb, 1); PV1(va, 0); LGKM0(); VREADS1(va, 2); PV1(vb, 1); LGKM0(); VREADS1(vb, 3); PV1(va, 2); LGKM0(); PV1(vb, 3);
.LatB_rare_511:
	v_mov_b32_e32 v252, v251
	s_nop 1
	v_permlane32_swap_b32_e32 v251, v252
	v_max_f32_e32 v251, v251, v252
	v_max_f32_e32 v253, 0, v251
	v_exp_f32_e64 v254, -v253
	v_add_f32_e32 v186, v186, v253
	s_nop 0
	v_mul_f32_e32 v150, v150, v254
	v_mul_f32_e32 v151, v151, v254
	ds_write_b32 v184, v254
	s_waitcnt lgkmcnt(0)
	v_mfma_f32_32x32x16_bf16 v[20:35], v[84:87], v[132:135], v[20:35]
	v_mfma_f32_32x32x16_bf16 v[36:51], v[84:87], v[136:139], v[36:51]
	v_mfma_f32_32x32x16_bf16 v[52:67], v[84:87], v[140:143], v[52:67]
	v_mfma_f32_32x32x16_bf16 v[68:83], v[84:87], v[144:147], v[68:83]
	v_mfma_f32_32x32x16_bf16 v[20:35], v[88:91], v[220:223], v[20:35]
	v_mfma_f32_32x32x16_bf16 v[36:51], v[88:91], v[224:227], v[36:51]
	v_mfma_f32_32x32x16_bf16 v[52:67], v[88:91], v[232:235], v[52:67]
	ds_read_b64_tr_b16 v[132:133], v231 offset:20480
	ds_read_b64_tr_b16 v[134:135], v231 offset:22528
	ds_read_b64_tr_b16 v[136:137], v228 offset:24576
	ds_read_b64_tr_b16 v[138:139], v228 offset:26624
	ds_read_b64_tr_b16 v[140:141], v229 offset:24576
	ds_read_b64_tr_b16 v[142:143], v229 offset:26624
	ds_read_b64_tr_b16 v[144:145], v230 offset:24576
	ds_read_b64_tr_b16 v[146:147], v230 offset:26624
	ds_read_b64_tr_b16 v[220:221], v231 offset:24576
	ds_read_b64_tr_b16 v[222:223], v231 offset:26624
	ds_read_b64_tr_b16 v[224:225], v228 offset:28672
	ds_read_b64_tr_b16 v[226:227], v228 offset:30720
	ds_read_b64_tr_b16 v[232:233], v229 offset:28672
	ds_read_b64_tr_b16 v[234:235], v229 offset:30720
	s_waitcnt lgkmcnt(0)
	v_mfma_f32_32x32x16_bf16 v[68:83], v[88:91], v[132:135], v[68:83]
	v_mfma_f32_32x32x16_bf16 v[20:35], v[100:103], v[136:139], v[20:35]
	v_mfma_f32_32x32x16_bf16 v[36:51], v[100:103], v[140:143], v[36:51]
	v_mfma_f32_32x32x16_bf16 v[52:67], v[100:103], v[144:147], v[52:67]
	v_mfma_f32_32x32x16_bf16 v[68:83], v[100:103], v[220:223], v[68:83]
	v_mfma_f32_32x32x16_bf16 v[20:35], v[104:107], v[224:227], v[20:35]
	v_mfma_f32_32x32x16_bf16 v[36:51], v[104:107], v[232:235], v[36:51]
	ds_read_b64_tr_b16 v[132:133], v230 offset:28672
	ds_read_b64_tr_b16 v[134:135], v230 offset:30720
	ds_read_b64_tr_b16 v[136:137], v231 offset:28672
	ds_read_b64_tr_b16 v[138:139], v231 offset:30720
	s_waitcnt lgkmcnt(0)
	v_mfma_f32_32x32x16_bf16 v[52:67], v[104:107], v[132:135], v[52:67]
	v_mfma_f32_32x32x16_bf16 v[68:83], v[104:107], v[136:139], v[68:83]
	ds_read_b128 v[92:95], v185
	ds_read_b128 v[96:99], v185 offset:32
	ds_read_b128 v[108:111], v185 offset:64
	ds_read_b128 v[112:115], v185 offset:96
	s_waitcnt lgkmcnt(0)
	s_nop 15
	s_nop 15
	v_pk_mul_f32 v[20:21], v[20:21], v[92:93]
	v_pk_mul_f32 v[22:23], v[22:23], v[94:95]
	v_pk_mul_f32 v[24:25], v[24:25], v[96:97]
	v_pk_mul_f32 v[26:27], v[26:27], v[98:99]
	v_pk_mul_f32 v[28:29], v[28:29], v[108:109]
	v_pk_mul_f32 v[30:31], v[30:31], v[110:111]
	v_pk_mul_f32 v[32:33], v[32:33], v[112:113]
	v_pk_mul_f32 v[34:35], v[34:35], v[114:115]
	v_pk_mul_f32 v[36:37], v[36:37], v[92:93]
	v_pk_mul_f32 v[38:39], v[38:39], v[94:95]
	v_pk_mul_f32 v[40:41], v[40:41], v[96:97]
	v_pk_mul_f32 v[42:43], v[42:43], v[98:99]
	v_pk_mul_f32 v[44:45], v[44:45], v[108:109]
	v_pk_mul_f32 v[46:47], v[46:47], v[110:111]
	v_pk_mul_f32 v[48:49], v[48:49], v[112:113]
	v_pk_mul_f32 v[50:51], v[50:51], v[114:115]
	v_pk_mul_f32 v[52:53], v[52:53], v[92:93]
	v_pk_mul_f32 v[54:55], v[54:55], v[94:95]
	v_pk_mul_f32 v[56:57], v[56:57], v[96:97]
	v_pk_mul_f32 v[58:59], v[58:59], v[98:99]
	v_pk_mul_f32 v[60:61], v[60:61], v[108:109]
	v_pk_mul_f32 v[62:63], v[62:63], v[110:111]
	v_pk_mul_f32 v[64:65], v[64:65], v[112:113]
	v_pk_mul_f32 v[66:67], v[66:67], v[114:115]
	v_pk_mul_f32 v[68:69], v[68:69], v[92:93]
	v_pk_mul_f32 v[70:71], v[70:71], v[94:95]
	v_pk_mul_f32 v[72:73], v[72:73], v[96:97]
	v_pk_mul_f32 v[74:75], v[74:75], v[98:99]
	v_pk_mul_f32 v[76:77], v[76:77], v[108:109]
	v_pk_mul_f32 v[78:79], v[78:79], v[110:111]
	v_pk_mul_f32 v[80:81], v[80:81], v[112:113]
	v_pk_mul_f32 v[82:83], v[82:83], v[114:115]
	v_mov_b32_e32 v252, v253
	v_pk_add_f32 v[188:189], v[188:189], v[252:253] neg_lo:[0,1] neg_hi:[0,1]
	v_pk_add_f32 v[190:191], v[190:191], v[252:253] neg_lo:[0,1] neg_hi:[0,1]
	v_pk_add_f32 v[192:193], v[192:193], v[252:253] neg_lo:[0,1] neg_hi:[0,1]
	v_pk_add_f32 v[194:195], v[194:195], v[252:253] neg_lo:[0,1] neg_hi:[0,1]
	v_pk_add_f32 v[196:197], v[196:197], v[252:253] neg_lo:[0,1] neg_hi:[0,1]
	v_pk_add_f32 v[198:199], v[198:199], v[252:253] neg_lo:[0,1] neg_hi:[0,1]
	v_pk_add_f32 v[200:201], v[200:201], v[252:253] neg_lo:[0,1] neg_hi:[0,1]
	v_pk_add_f32 v[202:203], v[202:203], v[252:253] neg_lo:[0,1] neg_hi:[0,1]
	v_pk_add_f32 v[204:205], v[204:205], v[252:253] neg_lo:[0,1] neg_hi:[0,1]
	v_pk_add_f32 v[206:207], v[206:207], v[252:253] neg_lo:[0,1] neg_hi:[0,1]
	v_pk_add_f32 v[208:209], v[208:209], v[252:253] neg_lo:[0,1] neg_hi:[0,1]
	v_pk_add_f32 v[210:211], v[210:211], v[252:253] neg_lo:[0,1] neg_hi:[0,1]
	v_pk_add_f32 v[212:213], v[212:213], v[252:253] neg_lo:[0,1] neg_hi:[0,1]
	v_pk_add_f32 v[214:215], v[214:215], v[252:253] neg_lo:[0,1] neg_hi:[0,1]
	v_pk_add_f32 v[216:217], v[216:217], v[252:253] neg_lo:[0,1] neg_hi:[0,1]
	v_pk_add_f32 v[218:219], v[218:219], v[252:253] neg_lo:[0,1] neg_hi:[0,1]
	v_mov_b64_e32 v[84:85], 0
	v_mov_b64_e32 v[86:87], 0
	v_mov_b64_e32 v[88:89], 0
	v_mov_b64_e32 v[90:91], 0
	v_mov_b64_e32 v[100:101], 0
	v_mov_b64_e32 v[102:103], 0
	v_mov_b64_e32 v[104:105], 0
	v_mov_b64_e32 v[106:107], 0
	s_sub_u32 s5, s8, s4
	s_lshr_b32 s5, s5, 12
	s_sub_u32 s5, s5, 64
	s_add_u32 s29, s5, 64
	s_cmp_lt_u32 s29, s11
	s_cselect_b32 s24, 1, 0
	s_cmp_gt_u32 s29, s31
	s_cselect_b32 s30, 2, 0
	s_or_b32 s24, s24, s30
	s_mov_b32 s35, s24
	v_mov_b32_e32 v251, 0
	s_cmp_eq_u32 s24, 1
	s_cselect_b64 vcc, -1, 0
	v_cndmask_b32_e32 v251, v251, v177, vcc
	s_cmp_eq_u32 s24, 2
	s_cselect_b64 vcc, -1, 0
	v_cndmask_b32_e32 v251, v251, v178, vcc
	v_sub_f32_e32 v2, v251, v186
	v_mov_b32_e32 v3, v2
	v_mov_b64_e32 v[4:5], v[2:3]
	v_mov_b64_e32 v[6:7], v[2:3]
	v_mov_b64_e32 v[8:9], v[2:3]
	v_mov_b64_e32 v[10:11], v[2:3]
	v_mov_b64_e32 v[12:13], v[2:3]
	v_mov_b64_e32 v[14:15], v[2:3]
	v_mov_b64_e32 v[16:17], v[2:3]
	s_nop 1
	s_cmp_eq_u32 s22, 0
	s_cbranch_scc1 .LatB_rareret_h5
	s_branch .LatB_rareret_m5
; #define LAS __attribute__((address_space(3)))
; __device__ __forceinline__ float max2f(float a, float b) { float r; asm("v_max_f32_e32 %0, %1, %2" : "=v"(r) : "v"(a), "v"(b)); return r; }
; __device__ __forceinline__ void attn_unit(LAS unsigned char* lds, const bf16_t* Z, bf16_t* A2, const float* tabg, int seq_base, int S, int h, int qb, float lam) {
;     ...
;         if (kv0 - (qlo + 31) >= 128) { near = false; cc = tabR; } else if (qlo - (kv0 + 63) >= 128) { near = false; cc = tabL; }
;         { const float coff = cc - mu;
;           if (__any(!(coff == coff_cur))) { coff_cur = coff;
; #pragma unroll
;               for (int r = 0; r < 16; ++r) cblk[r] = coff;
;               asm volatile("" : "+v"(cblk)); } }
;     ...
;         if (first || __any(mx > THR)) {
;             { auto rr = __builtin_amdgcn_permlane32_swap(__float_as_uint(mx), __float_as_uint(mx), false, false); mx = max2f(__uint_as_float(rr[0]), __uint_as_float(rr[1])); }
;             const float delta = first ? mx : fmaxf(mx, 0.f);
;             const float alpha = first ? 1.0f : __builtin_amdgcn_exp2f(-delta);
;             mu += delta; ls2 *= alpha;
;             if (!first) {
;                 asm volatile("" ::: "memory");
;                 scr[r32] = alpha;
;                 asm volatile("s_waitcnt lgkmcnt(0)" ::: "memory");
; #pragma unroll
;                 for (int g = 0; g < 4; ++g) { const f32x4 a4 = *(const LAS f32x4*)(scr + 8 * g + 4 * hi);
; #pragma unroll
;                     for (int d = 0; d < 4; ++d) { O[d][4 * g + 0] *= a4[0]; O[d][4 * g + 1] *= a4[1]; O[d][4 * g + 2] *= a4[2]; O[d][4 * g + 3] *= a4[3]; } }
;                 asm volatile("s_waitcnt lgkmcnt(0)" ::: "memory");
;             }
; #pragma unroll
;             for (int r = 0; r < 16; ++r) { p0[r] -= delta; p1[r] -= delta; }
;             asm volatile("" : "+v"(p0), "+v"(p1));
;         }
; #pragma unroll
;         for (int r = 0; r < 16; ++r) { p0[r] = __builtin_amdgcn_exp2f(p0[r]); p1[r] = __builtin_amdgcn_exp2f(p1[r]); }
; #pragma unroll
;         for (int r = 0; r < 16; r += 2) { ls2 += (f32x2){p0[r], p0[r + 1]}; ls2 += (f32x2){p1[r], p1[r + 1]}; }
;         bf16x8 pa[4]; pa[0] = pack8(p0, 0); pa[1] = pack8(p0, 8); pa[2] = pack8(p1, 0); pa[3] = pack8(p1, 8);
;         LGKM0(); VREADS1(vb, 1); PV1(va, 0); LGKM0(); VREADS1(va, 2); PV1(vb, 1); LGKM0(); VREADS1(vb, 3); PV1(va, 2); LGKM0(); PV1(vb, 3);
.LatB_rare_011:
	v_mov_b32_e32 v252, v251
	s_nop 1
	v_permlane32_swap_b32_e32 v251, v252
	v_max_f32_e32 v251, v251, v252
	v_max_f32_e32 v253, 0, v251
	v_exp_f32_e64 v254, -v253
	v_add_f32_e32 v186, v186, v253
	s_nop 0
	v_mul_f32_e32 v150, v150, v254
	v_mul_f32_e32 v151, v151, v254
	ds_write_b32 v184, v254
	s_waitcnt lgkmcnt(0)
	v_mfma_f32_32x32x16_bf16 v[20:35], v[188:191], v[132:135], v[20:35]
	v_mfma_f32_32x32x16_bf16 v[36:51], v[188:191], v[136:139], v[36:51]
	v_mfma_f32_32x32x16_bf16 v[52:67], v[188:191], v[140:143], v[52:67]
	v_mfma_f32_32x32x16_bf16 v[68:83], v[188:191], v[144:147], v[68:83]
	v_mfma_f32_32x32x16_bf16 v[20:35], v[192:195], v[220:223], v[20:35]
	v_mfma_f32_32x32x16_bf16 v[36:51], v[192:195], v[224:227], v[36:51]
	v_mfma_f32_32x32x16_bf16 v[52:67], v[192:195], v[232:235], v[52:67]
	ds_read_b64_tr_b16 v[132:133], v231 offset:36864
	ds_read_b64_tr_b16 v[134:135], v231 offset:38912
	ds_read_b64_tr_b16 v[136:137], v228 offset:40960
	ds_read_b64_tr_b16 v[138:139], v228 offset:43008
	ds_read_b64_tr_b16 v[140:141], v229 offset:40960
	ds_read_b64_tr_b16 v[142:143], v229 offset:43008
	ds_read_b64_tr_b16 v[144:145], v230 offset:40960
	ds_read_b64_tr_b16 v[146:147], v230 offset:43008
	ds_read_b64_tr_b16 v[220:221], v231 offset:40960
	ds_read_b64_tr_b16 v[222:223], v231 offset:43008
	ds_read_b64_tr_b16 v[224:225], v228 offset:45056
	ds_read_b64_tr_b16 v[226:227], v228 offset:47104
	ds_read_b64_tr_b16 v[232:233], v229 offset:45056
	ds_read_b64_tr_b16 v[234:235], v229 offset:47104
	s_waitcnt lgkmcnt(0)
	v_mfma_f32_32x32x16_bf16 v[68:83], v[192:195], v[132:135], v[68:83]
	v_mfma_f32_32x32x16_bf16 v[20:35], v[204:207], v[136:139], v[20:35]
	v_mfma_f32_32x32x16_bf16 v[36:51], v[204:207], v[140:143], v[36:51]
	v_mfma_f32_32x32x16_bf16 v[52:67], v[204:207], v[144:147], v[52:67]
	v_mfma_f32_32x32x16_bf16 v[68:83], v[204:207], v[220:223], v[68:83]
	v_mfma_f32_32x32x16_bf16 v[20:35], v[208:211], v[224:227], v[20:35]
	v_mfma_f32_32x32x16_bf16 v[36:51], v[208:211], v[232:235], v[36:51]
	ds_read_b64_tr_b16 v[132:133], v230 offset:45056
	ds_read_b64_tr_b16 v[134:135], v230 offset:47104
	ds_read_b64_tr_b16 v[136:137], v231 offset:45056
	ds_read_b64_tr_b16 v[138:139], v231 offset:47104
	s_waitcnt lgkmcnt(0)
	v_mfma_f32_32x32x16_bf16 v[52:67], v[208:211], v[132:135], v[52:67]
	v_mfma_f32_32x32x16_bf16 v[68:83], v[208:211], v[136:139], v[68:83]
	ds_read_b128 v[196:199], v185
	ds_read_b128 v[200:203], v185 offset:32
	ds_read_b128 v[212:215], v185 offset:64
	ds_read_b128 v[216:219], v185 offset:96
	s_waitcnt lgkmcnt(0)
	s_nop 15
	s_nop 15
	v_pk_mul_f32 v[20:21], v[20:21], v[196:197]
	v_pk_mul_f32 v[22:23], v[22:23], v[198:199]
	v_pk_mul_f32 v[24:25], v[24:25], v[200:201]
	v_pk_mul_f32 v[26:27], v[26:27], v[202:203]
	v_pk_mul_f32 v[28:29], v[28:29], v[212:213]
	v_pk_mul_f32 v[30:31], v[30:31], v[214:215]
	v_pk_mul_f32 v[32:33], v[32:33], v[216:217]
	v_pk_mul_f32 v[34:35], v[34:35], v[218:219]
	v_pk_mul_f32 v[36:37], v[36:37], v[196:197]
	v_pk_mul_f32 v[38:39], v[38:39], v[198:199]
	v_pk_mul_f32 v[40:41], v[40:41], v[200:201]
	v_pk_mul_f32 v[42:43], v[42:43], v[202:203]
	v_pk_mul_f32 v[44:45], v[44:45], v[212:213]
	v_pk_mul_f32 v[46:47], v[46:47], v[214:215]
	v_pk_mul_f32 v[48:49], v[48:49], v[216:217]
	v_pk_mul_f32 v[50:51], v[50:51], v[218:219]
	v_pk_mul_f32 v[52:53], v[52:53], v[196:197]
	v_pk_mul_f32 v[54:55], v[54:55], v[198:199]
	v_pk_mul_f32 v[56:57], v[56:57], v[200:201]
	v_pk_mul_f32 v[58:59], v[58:59], v[202:203]
	v_pk_mul_f32 v[60:61], v[60:61], v[212:213]
	v_pk_mul_f32 v[62:63], v[62:63], v[214:215]
	v_pk_mul_f32 v[64:65], v[64:65], v[216:217]
	v_pk_mul_f32 v[66:67], v[66:67], v[218:219]
	v_pk_mul_f32 v[68:69], v[68:69], v[196:197]
	v_pk_mul_f32 v[70:71], v[70:71], v[198:199]
	v_pk_mul_f32 v[72:73], v[72:73], v[200:201]
	v_pk_mul_f32 v[74:75], v[74:75], v[202:203]
	v_pk_mul_f32 v[76:77], v[76:77], v[212:213]
	v_pk_mul_f32 v[78:79], v[78:79], v[214:215]
	v_pk_mul_f32 v[80:81], v[80:81], v[216:217]
	v_pk_mul_f32 v[82:83], v[82:83], v[218:219]
	v_mov_b32_e32 v252, v253
	v_pk_add_f32 v[84:85], v[84:85], v[252:253] neg_lo:[0,1] neg_hi:[0,1]
	v_pk_add_f32 v[86:87], v[86:87], v[252:253] neg_lo:[0,1] neg_hi:[0,1]
	v_pk_add_f32 v[88:89], v[88:89], v[252:253] neg_lo:[0,1] neg_hi:[0,1]
	v_pk_add_f32 v[90:91], v[90:91], v[252:253] neg_lo:[0,1] neg_hi:[0,1]
	v_pk_add_f32 v[92:93], v[92:93], v[252:253] neg_lo:[0,1] neg_hi:[0,1]
	v_pk_add_f32 v[94:95], v[94:95], v[252:253] neg_lo:[0,1] neg_hi:[0,1]
	v_pk_add_f32 v[96:97], v[96:97], v[252:253] neg_lo:[0,1] neg_hi:[0,1]
	v_pk_add_f32 v[98:99], v[98:99], v[252:253] neg_lo:[0,1] neg_hi:[0,1]
	v_pk_add_f32 v[100:101], v[100:101], v[252:253] neg_lo:[0,1] neg_hi:[0,1]
	v_pk_add_f32 v[102:103], v[102:103], v[252:253] neg_lo:[0,1] neg_hi:[0,1]
	v_pk_add_f32 v[104:105], v[104:105], v[252:253] neg_lo:[0,1] neg_hi:[0,1]
	v_pk_add_f32 v[106:107], v[106:107], v[252:253] neg_lo:[0,1] neg_hi:[0,1]
	v_pk_add_f32 v[108:109], v[108:109], v[252:253] neg_lo:[0,1] neg_hi:[0,1]
	v_pk_add_f32 v[110:111], v[110:111], v[252:253] neg_lo:[0,1] neg_hi:[0,1]
	v_pk_add_f32 v[112:113], v[112:113], v[252:253] neg_lo:[0,1] neg_hi:[0,1]
	v_pk_add_f32 v[114:115], v[114:115], v[252:253] neg_lo:[0,1] neg_hi:[0,1]
	v_mov_b64_e32 v[188:189], 0
	v_mov_b64_e32 v[190:191], 0
	v_mov_b64_e32 v[192:193], 0
	v_mov_b64_e32 v[194:195], 0
	v_mov_b64_e32 v[204:205], 0
	v_mov_b64_e32 v[206:207], 0
	v_mov_b64_e32 v[208:209], 0
	v_mov_b64_e32 v[210:211], 0
	s_sub_u32 s5, s8, s4
	s_lshr_b32 s5, s5, 12
	s_sub_u32 s5, s5, 64
	s_add_u32 s29, s5, 64
	s_cmp_lt_u32 s29, s11
	s_cselect_b32 s24, 1, 0
	s_cmp_gt_u32 s29, s31
	s_cselect_b32 s30, 2, 0
	s_or_b32 s24, s24, s30
	s_mov_b32 s35, s24
	v_mov_b32_e32 v251, 0
	s_cmp_eq_u32 s24, 1
	s_cselect_b64 vcc, -1, 0
	v_cndmask_b32_e32 v251, v251, v177, vcc
	s_cmp_eq_u32 s24, 2
	s_cselect_b64 vcc, -1, 0
	v_cndmask_b32_e32 v251, v251, v178, vcc
	v_sub_f32_e32 v2, v251, v186
	v_mov_b32_e32 v3, v2
	v_mov_b64_e32 v[4:5], v[2:3]
	v_mov_b64_e32 v[6:7], v[2:3]
	v_mov_b64_e32 v[8:9], v[2:3]
	v_mov_b64_e32 v[10:11], v[2:3]
	v_mov_b64_e32 v[12:13], v[2:3]
	v_mov_b64_e32 v[14:15], v[2:3]
	v_mov_b64_e32 v[16:17], v[2:3]
	s_nop 1
	s_cmp_eq_u32 s22, 0
	s_cbranch_scc1 .LatB_rareret_m0
	s_branch .LatB_rareret_x4
; #define LAS __attribute__((address_space(3)))
; __device__ __forceinline__ float max2f(float a, float b) { float r; asm("v_max_f32_e32 %0, %1, %2" : "=v"(r) : "v"(a), "v"(b)); return r; }
; #define VREADS1(arr, d_) do { const unsigned ad_ = vbase ^ (unsigned)((d_) << 6); __builtin_amdgcn_sched_barrier(0); \
;         _Pragma("unroll") for (int ks_ = 0; ks_ < 4; ++ks_) { VTR(arr[ks_ * 2], ad_, ks_ * 4096); VTR(arr[ks_ * 2 + 1], ad_, ks_ * 4096 + 2048); } __builtin_amdgcn_sched_barrier(0); } while (0)
; __device__ __forceinline__ void attn_unit(LAS unsigned char* lds, const bf16_t* Z, bf16_t* A2, const float* tabg, int seq_base, int S, int h, int qb, float lam) {
;     ...
;         if (first || __any(mx > THR)) {
;             { auto rr = __builtin_amdgcn_permlane32_swap(__float_as_uint(mx), __float_as_uint(mx), false, false); mx = max2f(__uint_as_float(rr[0]), __uint_as_float(rr[1])); }
;             const float delta = first ? mx : fmaxf(mx, 0.f);
;             const float alpha = first ? 1.0f : __builtin_amdgcn_exp2f(-delta);
;             mu += delta; ls2 *= alpha;
;             if (!first) {
;                 asm volatile("" ::: "memory");
;                 scr[r32] = alpha;
;                 asm volatile("s_waitcnt lgkmcnt(0)" ::: "memory");
; #pragma unroll
;                 for (int g = 0; g < 4; ++g) { const f32x4 a4 = *(const LAS f32x4*)(scr + 8 * g + 4 * hi);
; #pragma unroll
;                     for (int d = 0; d < 4; ++d) { O[d][4 * g + 0] *= a4[0]; O[d][4 * g + 1] *= a4[1]; O[d][4 * g + 2] *= a4[2]; O[d][4 * g + 3] *= a4[3]; } }
;                 asm volatile("s_waitcnt lgkmcnt(0)" ::: "memory");
;             }
; #pragma unroll
;             for (int r = 0; r < 16; ++r) { p0[r] -= delta; p1[r] -= delta; }
;             asm volatile("" : "+v"(p0), "+v"(p1));
;         }
; #pragma unroll
;         for (int r = 0; r < 16; ++r) { p0[r] = __builtin_amdgcn_exp2f(p0[r]); p1[r] = __builtin_amdgcn_exp2f(p1[r]); }
; #pragma unroll
;         for (int r = 0; r < 16; r += 2) { ls2 += (f32x2){p0[r], p0[r + 1]}; ls2 += (f32x2){p1[r], p1[r + 1]}; }
;         bf16x8 pa[4]; pa[0] = pack8(p0, 0); pa[1] = pack8(p0, 8); pa[2] = pack8(p1, 0); pa[3] = pack8(p1, 8);
;         LGKM0(); VREADS1(vb, 1); PV1(va, 0); LGKM0(); VREADS1(va, 2); PV1(vb, 1); LGKM0(); VREADS1(vb, 3); PV1(va, 2); LGKM0(); PV1(vb, 3);
.LatB_rare_310:
	v_mov_b32_e32 v252, v251
	s_nop 1
	v_permlane32_swap_b32_e32 v251, v252
	v_max_f32_e32 v251, v251, v252
	v_max_f32_e32 v253, 0, v251
	v_exp_f32_e64 v254, -v253
	v_add_f32_e32 v186, v186, v253
	s_nop 0
	v_mul_f32_e32 v150, v150, v254
	v_mul_f32_e32 v151, v151, v254
	ds_write_b32 v184, v254
	s_waitcnt lgkmcnt(0)
	v_mfma_f32_32x32x16_bf16 v[20:35], v[84:87], v[132:135], v[20:35]
	v_mfma_f32_32x32x16_bf16 v[36:51], v[84:87], v[136:139], v[36:51]
	v_mfma_f32_32x32x16_bf16 v[52:67], v[84:87], v[140:143], v[52:67]
	v_mfma_f32_32x32x16_bf16 v[68:83], v[84:87], v[144:147], v[68:83]
	v_mfma_f32_32x32x16_bf16 v[20:35], v[88:91], v[220:223], v[20:35]
	v_mfma_f32_32x32x16_bf16 v[36:51], v[88:91], v[224:227], v[36:51]
	v_mfma_f32_32x32x16_bf16 v[52:67], v[88:91], v[232:235], v[52:67]
	ds_read_b64_tr_b16 v[132:133], v231 offset:36864
	ds_read_b64_tr_b16 v[134:135], v231 offset:38912
	ds_read_b64_tr_b16 v[136:137], v228 offset:40960
	ds_read_b64_tr_b16 v[138:139], v228 offset:43008
	ds_read_b64_tr_b16 v[140:141], v229 offset:40960
	ds_read_b64_tr_b16 v[142:143], v229 offset:43008
	ds_read_b64_tr_b16 v[144:145], v230 offset:40960
	ds_read_b64_tr_b16 v[146:147], v230 offset:43008
	ds_read_b64_tr_b16 v[220:221], v231 offset:40960
	ds_read_b64_tr_b16 v[222:223], v231 offset:43008
	ds_read_b64_tr_b16 v[224:225], v228 offset:45056
	ds_read_b64_tr_b16 v[226:227], v228 offset:47104
	ds_read_b64_tr_b16 v[232:233], v229 offset:45056
	ds_read_b64_tr_b16 v[234:235], v229 offset:47104
	s_waitcnt lgkmcnt(0)
	v_mfma_f32_32x32x16_bf16 v[68:83], v[88:91], v[132:135], v[68:83]
	v_mfma_f32_32x32x16_bf16 v[20:35], v[100:103], v[136:139], v[20:35]
	v_mfma_f32_32x32x16_bf16 v[36:51], v[100:103], v[140:143], v[36:51]
	v_mfma_f32_32x32x16_bf16 v[52:67], v[100:103], v[144:147], v[52:67]
	v_mfma_f32_32x32x16_bf16 v[68:83], v[100:103], v[220:223], v[68:83]
	v_mfma_f32_32x32x16_bf16 v[20:35], v[104:107], v[224:227], v[20:35]
	v_mfma_f32_32x32x16_bf16 v[36:51], v[104:107], v[232:235], v[36:51]
	ds_read_b64_tr_b16 v[132:133], v230 offset:45056
	ds_read_b64_tr_b16 v[134:135], v230 offset:47104
	ds_read_b64_tr_b16 v[136:137], v231 offset:45056
	ds_read_b64_tr_b16 v[138:139], v231 offset:47104
	s_waitcnt lgkmcnt(0)
	v_mfma_f32_32x32x16_bf16 v[52:67], v[104:107], v[132:135], v[52:67]
	v_mfma_f32_32x32x16_bf16 v[68:83], v[104:107], v[136:139], v[68:83]
	ds_read_b128 v[92:95], v185
	ds_read_b128 v[96:99], v185 offset:32
	ds_read_b128 v[108:111], v185 offset:64
	ds_read_b128 v[112:115], v185 offset:96
	s_waitcnt lgkmcnt(0)
	s_nop 15
	s_nop 15
	v_pk_mul_f32 v[20:21], v[20:21], v[92:93]
	v_pk_mul_f32 v[22:23], v[22:23], v[94:95]
	v_pk_mul_f32 v[24:25], v[24:25], v[96:97]
	v_pk_mul_f32 v[26:27], v[26:27], v[98:99]
	v_pk_mul_f32 v[28:29], v[28:29], v[108:109]
	v_pk_mul_f32 v[30:31], v[30:31], v[110:111]
	v_pk_mul_f32 v[32:33], v[32:33], v[112:113]
	v_pk_mul_f32 v[34:35], v[34:35], v[114:115]
	v_pk_mul_f32 v[36:37], v[36:37], v[92:93]
	v_pk_mul_f32 v[38:39], v[38:39], v[94:95]
	v_pk_mul_f32 v[40:41], v[40:41], v[96:97]
	v_pk_mul_f32 v[42:43], v[42:43], v[98:99]
	v_pk_mul_f32 v[44:45], v[44:45], v[108:109]
	v_pk_mul_f32 v[46:47], v[46:47], v[110:111]
	v_pk_mul_f32 v[48:49], v[48:49], v[112:113]
	v_pk_mul_f32 v[50:51], v[50:51], v[114:115]
	v_pk_mul_f32 v[52:53], v[52:53], v[92:93]
	v_pk_mul_f32 v[54:55], v[54:55], v[94:95]
	v_pk_mul_f32 v[56:57], v[56:57], v[96:97]
	v_pk_mul_f32 v[58:59], v[58:59], v[98:99]
	v_pk_mul_f32 v[60:61], v[60:61], v[108:109]
	v_pk_mul_f32 v[62:63], v[62:63], v[110:111]
	v_pk_mul_f32 v[64:65], v[64:65], v[112:113]
	v_pk_mul_f32 v[66:67], v[66:67], v[114:115]
	v_pk_mul_f32 v[68:69], v[68:69], v[92:93]
	v_pk_mul_f32 v[70:71], v[70:71], v[94:95]
	v_pk_mul_f32 v[72:73], v[72:73], v[96:97]
	v_pk_mul_f32 v[74:75], v[74:75], v[98:99]
	v_pk_mul_f32 v[76:77], v[76:77], v[108:109]
	v_pk_mul_f32 v[78:79], v[78:79], v[110:111]
	v_pk_mul_f32 v[80:81], v[80:81], v[112:113]
	v_pk_mul_f32 v[82:83], v[82:83], v[114:115]
	v_mov_b32_e32 v252, v253
	v_pk_add_f32 v[188:189], v[188:189], v[252:253] neg_lo:[0,1] neg_hi:[0,1]
	v_pk_add_f32 v[190:191], v[190:191], v[252:253] neg_lo:[0,1] neg_hi:[0,1]
	v_pk_add_f32 v[192:193], v[192:193], v[252:253] neg_lo:[0,1] neg_hi:[0,1]
	v_pk_add_f32 v[194:195], v[194:195], v[252:253] neg_lo:[0,1] neg_hi:[0,1]
	v_pk_add_f32 v[196:197], v[196:197], v[252:253] neg_lo:[0,1] neg_hi:[0,1]
	v_pk_add_f32 v[198:199], v[198:199], v[252:253] neg_lo:[0,1] neg_hi:[0,1]
	v_pk_add_f32 v[200:201], v[200:201], v[252:253] neg_lo:[0,1] neg_hi:[0,1]
	v_pk_add_f32 v[202:203], v[202:203], v[252:253] neg_lo:[0,1] neg_hi:[0,1]
	v_pk_add_f32 v[204:205], v[204:205], v[252:253] neg_lo:[0,1] neg_hi:[0,1]
	v_pk_add_f32 v[206:207], v[206:207], v[252:253] neg_lo:[0,1] neg_hi:[0,1]
	v_pk_add_f32 v[208:209], v[208:209], v[252:253] neg_lo:[0,1] neg_hi:[0,1]
	v_pk_add_f32 v[210:211], v[210:211], v[252:253] neg_lo:[0,1] neg_hi:[0,1]
	v_pk_add_f32 v[212:213], v[212:213], v[252:253] neg_lo:[0,1] neg_hi:[0,1]
	v_pk_add_f32 v[214:215], v[214:215], v[252:253] neg_lo:[0,1] neg_hi:[0,1]
	v_pk_add_f32 v[216:217], v[216:217], v[252:253] neg_lo:[0,1] neg_hi:[0,1]
	v_pk_add_f32 v[218:219], v[218:219], v[252:253] neg_lo:[0,1] neg_hi:[0,1]
	v_mov_b64_e32 v[84:85], 0
	v_mov_b64_e32 v[86:87], 0
	v_mov_b64_e32 v[88:89], 0
	v_mov_b64_e32 v[90:91], 0
	v_mov_b64_e32 v[100:101], 0
	v_mov_b64_e32 v[102:103], 0
	v_mov_b64_e32 v[104:105], 0
	v_mov_b64_e32 v[106:107], 0
	s_nop 1
	s_branch .LatB_rareret_x1
.Ltr_960:
	s_branch .LBB0_960
